# GEMM load segments: s_setprio 1 placed between the second m0 write and its LDS-DMA, replacing the s_nop hazard spacer (one instruction fewer per load segment)
# baseline (speedup 1.0000x reference)
; #define PG8_STAGE(bufoff, gbase, voff) do { _Pragma("unroll") for (int _i = 0; _i < 2; ++_i) \
;         __builtin_amdgcn_global_load_lds((const unsigned*)((const char*)(gbase) + (voff)[_i]), (LAS unsigned*)(lds + (bufoff) + ldsw + _i * 8192), 16, 0, 0); } while (0)
; #define PG8_LDA(dst, b, h) do { _Pragma("unroll") for (int m = 0; m < 4; ++m) _Pragma("unroll") for (int k = 0; k < 2; ++k) dst[m][k] = *(const LAS bf16x8*)(lds + PG8_SA(b, h) + aoff + m * 2048 + k * 1024); } while (0)
; #define PG8_LDB(dst, b, h) do { _Pragma("unroll") for (int n = 0; n < 2; ++n) _Pragma("unroll") for (int k = 0; k < 2; ++k) dst[n][k] = *(const LAS bf16x8*)(lds + PG8_SB(b, h) + boff + n * 2048 + k * 1024); } while (0)
; #define PG8_MMA(ai, bj, At, Bt) do { __builtin_amdgcn_s_setprio(1); _Pragma("unroll") for (int m = 0; m < 4; ++m) _Pragma("unroll") for (int n = 0; n < 2; ++n) _Pragma("unroll") for (int k = 0; k < 2; ++k) \
;         acc[ai][bj][m][n] = __builtin_amdgcn_mfma_f32_16x16x32_bf16(Bt[n][k], At[m][k], acc[ai][bj][m][n], 0, 0, 0); __builtin_amdgcn_s_setprio(0); } while (0)
; #define PG8_WAIT_V(n) asm volatile("s_waitcnt vmcnt(" #n ")" ::: "memory")
; #define PG8_BAR __builtin_amdgcn_s_barrier()
; template <class Map, class Epi>
; DI void gemm_phase(LAS unsigned char* lds, const Map& MP, const Epi& E, const int nM, const int nN, const int K, const int lda, const int ldb) {
;     ...
;             const char* a1 = cA + (size_t)(t + 1) * kstep;
;             const char* a2 = last ? nA : cA + (size_t)(t + 2) * kstep; const char* b2 = last ? nB : cB + (size_t)(t + 2) * kstep;
;             const char* a3 = a2 + kstep; const char* b3 = b2 + kstep;
;             PG8_LDB(B0, 0, 0); PG8_SCHED; PG8_LDA(At, 0, 0); PG8_STAGE(PG8_SA(1, 1), a1 + hstepA, voffA);
;             PG8_WAIT_L(8); PG8_BAR; PG8_WAIT_L(0); PG8_MMA(0, 0, At, B0); PG8_BAR; PG8_SCHED;
;             PG8_LDB(B1, 0, 1); PG8_STAGE(PG8_SB(0, 0), b2, voffB);
;             PG8_BAR; PG8_WAIT_L(0); PG8_MMA(0, 1, At, B1); PG8_BAR;
;             PG8_LDA(At, 0, 1); PG8_STAGE(PG8_SA(0, 0), a2, voffA);
;             PG8_BAR; PG8_WAIT_L(0); PG8_MMA(1, 0, At, B0); PG8_BAR; PG8_SCHED;
;             PG8_STAGE(PG8_SB(0, 1), b2 + hstepB, voffB);
;             PG8_WAIT_V(6); PG8_BAR; PG8_MMA(1, 1, At, B1); PG8_BAR;
;             PG8_LDB(B0, 1, 0); PG8_SCHED; PG8_LDA(At, 1, 0); PG8_STAGE(PG8_SA(0, 1), a2 + hstepA, voffA);
.LBB1_229:
	s_add_u32 s26, s24, 0xfff80080
	s_addc_u32 s27, s25, -1
	s_cmp_eq_u32 s57, 4
	s_cselect_b32 s29, s17, s27
	s_cselect_b32 s28, s43, s26
	s_cselect_b32 s27, s53, s56
	s_cselect_b32 s26, s54, s55
	s_add_i32 m0, s2, 0xc000
	ds_read_b128 v[160:163], v168
	ds_read_b128 v[170:173], v168 offset:1024
	ds_read_b128 v[174:177], v168 offset:2048
	ds_read_b128 v[178:181], v168 offset:3072
	ds_read_b128 v[182:185], v168 offset:4096
	ds_read_b128 v[186:189], v168 offset:5120
	ds_read_b128 v[190:193], v168 offset:6144
	ds_read_b128 v[198:201], v168 offset:7168
	global_load_lds_dwordx4 v154, s[24:25]
	s_add_i32 m0, s2, 0xe000
	s_setprio 1
	global_load_lds_dwordx4 v152, s[24:25]
	s_waitcnt lgkmcnt(8)
	s_barrier
	s_waitcnt lgkmcnt(7)
	v_mfma_f32_16x16x32_bf16 v[140:143], v[72:75], v[160:163], v[140:143]
	v_mfma_f32_16x16x32_bf16 v[136:139], v[80:83], v[160:163], v[136:139]
	s_waitcnt lgkmcnt(5)
	v_mfma_f32_16x16x32_bf16 v[124:127], v[72:75], v[174:177], v[124:127]
	v_mfma_f32_16x16x32_bf16 v[120:123], v[80:83], v[174:177], v[120:123]
	s_waitcnt lgkmcnt(3)
	v_mfma_f32_16x16x32_bf16 v[108:111], v[72:75], v[182:185], v[108:111]
	v_mfma_f32_16x16x32_bf16 v[104:107], v[80:83], v[182:185], v[104:107]
	s_waitcnt lgkmcnt(1)
	v_mfma_f32_16x16x32_bf16 v[92:95], v[72:75], v[190:193], v[92:95]
	v_mfma_f32_16x16x32_bf16 v[88:91], v[80:83], v[190:193], v[88:91]
	v_mfma_f32_16x16x32_bf16 v[140:143], v[76:79], v[170:173], v[140:143]
	s_add_i32 s58, s48, s34
	v_mfma_f32_16x16x32_bf16 v[136:139], v[84:87], v[170:173], v[136:139]
	v_lshl_add_u64 v[194:195], s[26:27], 0, v[148:149]
	v_mfma_f32_16x16x32_bf16 v[124:127], v[76:79], v[178:181], v[124:127]
	v_lshl_add_u64 v[218:219], s[26:27], 0, v[144:145]
	v_mfma_f32_16x16x32_bf16 v[120:123], v[84:87], v[178:181], v[120:123]
	v_mfma_f32_16x16x32_bf16 v[108:111], v[76:79], v[186:189], v[108:111]
	v_mfma_f32_16x16x32_bf16 v[104:107], v[84:87], v[186:189], v[104:107]
	s_waitcnt lgkmcnt(0)
	v_mfma_f32_16x16x32_bf16 v[92:95], v[76:79], v[198:201], v[92:95]
	v_mfma_f32_16x16x32_bf16 v[88:91], v[84:87], v[198:201], v[88:91]
	s_barrier
	s_setprio 0
	s_mov_b32 m0, s58
	ds_read_b128 v[202:205], v169
	ds_read_b128 v[206:209], v169 offset:1024
	ds_read_b128 v[210:213], v169 offset:2048
	ds_read_b128 v[214:217], v169 offset:3072
	global_load_lds_dwordx4 v[194:195], off
	s_add_i32 m0, s58, 0x2000
	s_setprio 1
	global_load_lds_dwordx4 v[218:219], off
	s_barrier
	s_waitcnt lgkmcnt(3)
	v_mfma_f32_16x16x32_bf16 v[132:135], v[202:205], v[160:163], v[132:135]
	s_waitcnt lgkmcnt(1)
	v_mfma_f32_16x16x32_bf16 v[128:131], v[210:213], v[160:163], v[128:131]
	v_mfma_f32_16x16x32_bf16 v[116:119], v[202:205], v[174:177], v[116:119]
	v_mfma_f32_16x16x32_bf16 v[112:115], v[210:213], v[174:177], v[112:115]
	v_mfma_f32_16x16x32_bf16 v[100:103], v[202:205], v[182:185], v[100:103]
	v_mfma_f32_16x16x32_bf16 v[96:99], v[210:213], v[182:185], v[96:99]
	v_mfma_f32_16x16x32_bf16 v[68:71], v[202:205], v[190:193], v[68:71]
	v_mfma_f32_16x16x32_bf16 v[64:67], v[210:213], v[190:193], v[64:67]
	v_mfma_f32_16x16x32_bf16 v[132:135], v[206:209], v[170:173], v[132:135]
	v_lshl_add_u64 v[222:223], s[28:29], 0, v[146:147]
	s_mov_b32 m0, s2
	s_waitcnt lgkmcnt(0)
	v_mfma_f32_16x16x32_bf16 v[128:131], v[214:217], v[170:173], v[128:131]
	v_lshl_add_u64 v[220:221], s[28:29], 0, v[150:151]
	v_mfma_f32_16x16x32_bf16 v[116:119], v[206:209], v[178:181], v[116:119]
	v_mfma_f32_16x16x32_bf16 v[112:115], v[214:217], v[178:181], v[112:115]
	v_mfma_f32_16x16x32_bf16 v[100:103], v[206:209], v[186:189], v[100:103]
	v_mfma_f32_16x16x32_bf16 v[96:99], v[214:217], v[186:189], v[96:99]
	v_mfma_f32_16x16x32_bf16 v[68:71], v[206:209], v[198:201], v[68:71]
	v_mfma_f32_16x16x32_bf16 v[64:67], v[214:217], v[198:201], v[64:67]
	s_barrier
	s_setprio 0
	ds_read_b128 v[160:163], v168 offset:16384
	ds_read_b128 v[170:173], v168 offset:17408
	ds_read_b128 v[174:177], v168 offset:18432
	ds_read_b128 v[178:181], v168 offset:19456
	ds_read_b128 v[182:185], v168 offset:20480
	ds_read_b128 v[186:189], v168 offset:21504
	ds_read_b128 v[190:193], v168 offset:22528
	ds_read_b128 v[198:201], v168 offset:23552
	global_load_lds_dwordx4 v[220:221], off
	s_mov_b32 m0, s4
	s_setprio 1
	global_load_lds_dwordx4 v[222:223], off
	s_waitcnt vmcnt(10)
	s_barrier
	s_waitcnt lgkmcnt(7)
	v_mfma_f32_16x16x32_bf16 v[60:63], v[72:75], v[160:163], v[60:63]
	v_mfma_f32_16x16x32_bf16 v[56:59], v[80:83], v[160:163], v[56:59]
	s_waitcnt lgkmcnt(5)
	v_mfma_f32_16x16x32_bf16 v[44:47], v[72:75], v[174:177], v[44:47]
	v_mfma_f32_16x16x32_bf16 v[40:43], v[80:83], v[174:177], v[40:43]
	s_waitcnt lgkmcnt(3)
	v_mfma_f32_16x16x32_bf16 v[28:31], v[72:75], v[182:185], v[28:31]
	v_mfma_f32_16x16x32_bf16 v[24:27], v[80:83], v[182:185], v[24:27]
	s_waitcnt lgkmcnt(1)
	v_mfma_f32_16x16x32_bf16 v[12:15], v[72:75], v[190:193], v[12:15]
	v_mfma_f32_16x16x32_bf16 v[8:11], v[80:83], v[190:193], v[8:11]
	v_mfma_f32_16x16x32_bf16 v[60:63], v[76:79], v[170:173], v[60:63]
	s_add_u32 s58, s26, 0x20000
	s_addc_u32 s59, s27, 0
	v_mfma_f32_16x16x32_bf16 v[56:59], v[84:87], v[170:173], v[56:59]
	s_add_i32 s60, s49, s34
	v_mfma_f32_16x16x32_bf16 v[44:47], v[76:79], v[178:181], v[44:47]
	v_mfma_f32_16x16x32_bf16 v[40:43], v[84:87], v[178:181], v[40:43]
	v_mfma_f32_16x16x32_bf16 v[28:31], v[76:79], v[186:189], v[28:31]
	v_mfma_f32_16x16x32_bf16 v[24:27], v[84:87], v[186:189], v[24:27]
	s_waitcnt lgkmcnt(0)
	v_mfma_f32_16x16x32_bf16 v[12:15], v[76:79], v[198:201], v[12:15]
	v_mfma_f32_16x16x32_bf16 v[8:11], v[84:87], v[198:201], v[8:11]
	s_barrier
	s_setprio 0
	s_mov_b32 m0, s60
	s_nop 0
	global_load_lds_dwordx4 v148, s[58:59]
	s_add_i32 m0, s60, 0x2000
	s_setprio 1
	global_load_lds_dwordx4 v144, s[58:59]
	s_waitcnt vmcnt(6)
	s_barrier
; #define PG8_STAGE(bufoff, gbase, voff) do { _Pragma("unroll") for (int _i = 0; _i < 2; ++_i) \
;         __builtin_amdgcn_global_load_lds((const unsigned*)((const char*)(gbase) + (voff)[_i]), (LAS unsigned*)(lds + (bufoff) + ldsw + _i * 8192), 16, 0, 0); } while (0)
; #define PG8_LDA(dst, b, h) do { _Pragma("unroll") for (int m = 0; m < 4; ++m) _Pragma("unroll") for (int k = 0; k < 2; ++k) dst[m][k] = *(const LAS bf16x8*)(lds + PG8_SA(b, h) + aoff + m * 2048 + k * 1024); } while (0)
; #define PG8_LDB(dst, b, h) do { _Pragma("unroll") for (int n = 0; n < 2; ++n) _Pragma("unroll") for (int k = 0; k < 2; ++k) dst[n][k] = *(const LAS bf16x8*)(lds + PG8_SB(b, h) + boff + n * 2048 + k * 1024); } while (0)
; #define PG8_MMA(ai, bj, At, Bt) do { __builtin_amdgcn_s_setprio(1); _Pragma("unroll") for (int m = 0; m < 4; ++m) _Pragma("unroll") for (int n = 0; n < 2; ++n) _Pragma("unroll") for (int k = 0; k < 2; ++k) \
;         acc[ai][bj][m][n] = __builtin_amdgcn_mfma_f32_16x16x32_bf16(Bt[n][k], At[m][k], acc[ai][bj][m][n], 0, 0, 0); __builtin_amdgcn_s_setprio(0); } while (0)
; #define PG8_WAIT_V(n) asm volatile("s_waitcnt vmcnt(" #n ")" ::: "memory")
; #define PG8_WAIT_L(n) asm volatile("s_waitcnt lgkmcnt(" #n ")" ::: "memory")
; #define PG8_BAR __builtin_amdgcn_s_barrier()
; #define PG8_SCHED __builtin_amdgcn_sched_barrier(0)
; template <class Map, class Epi>
; DI void gemm_phase(LAS unsigned char* lds, const Map& MP, const Epi& E, const int nM, const int nN, const int K, const int lda, const int ldb) {
;     ...
;             PG8_STAGE(PG8_SB(0, 1), b2 + hstepB, voffB);
;             PG8_WAIT_V(6); PG8_BAR; PG8_MMA(1, 1, At, B1); PG8_BAR;
;             PG8_LDB(B0, 1, 0); PG8_SCHED; PG8_LDA(At, 1, 0); PG8_STAGE(PG8_SA(0, 1), a2 + hstepA, voffA);
;             PG8_WAIT_L(8); PG8_BAR; PG8_WAIT_L(0); PG8_MMA(0, 0, At, B0); PG8_BAR; PG8_SCHED;
;             PG8_LDB(B1, 1, 1); PG8_STAGE(PG8_SB(1, 0), b3, voffB);
;             PG8_BAR; PG8_WAIT_L(0); PG8_MMA(0, 1, At, B1); PG8_BAR;
;             PG8_LDA(At, 1, 1); PG8_STAGE(PG8_SA(1, 0), a3, voffA);
;             PG8_BAR; PG8_WAIT_L(0); PG8_MMA(1, 0, At, B0); PG8_BAR; PG8_SCHED;
	v_mfma_f32_16x16x32_bf16 v[52:55], v[202:205], v[160:163], v[52:55]
	v_mfma_f32_16x16x32_bf16 v[48:51], v[210:213], v[160:163], v[48:51]
	s_add_i32 s58, 0, 0x18000
	v_add_u32_e32 v84, s58, v166
	ds_read_b128 v[72:75], v84
	v_mfma_f32_16x16x32_bf16 v[36:39], v[202:205], v[174:177], v[36:39]
	v_mfma_f32_16x16x32_bf16 v[32:35], v[210:213], v[174:177], v[32:35]
	ds_read_b128 v[76:79], v84 offset:1024
	v_mfma_f32_16x16x32_bf16 v[20:23], v[202:205], v[182:185], v[20:23]
	v_mfma_f32_16x16x32_bf16 v[16:19], v[210:213], v[182:185], v[16:19]
	ds_read_b128 v[80:83], v84 offset:2048
	v_mfma_f32_16x16x32_bf16 v[4:7], v[202:205], v[190:193], v[4:7]
	v_mfma_f32_16x16x32_bf16 v[0:3], v[210:213], v[190:193], v[0:3]
	ds_read_b128 v[84:87], v84 offset:3072
	v_mfma_f32_16x16x32_bf16 v[52:55], v[206:209], v[170:173], v[52:55]
	s_add_u32 s28, s28, 0x80000
	s_addc_u32 s29, s29, 0
	v_mfma_f32_16x16x32_bf16 v[48:51], v[214:217], v[170:173], v[48:51]
	v_mfma_f32_16x16x32_bf16 v[36:39], v[206:209], v[178:181], v[36:39]
	v_mfma_f32_16x16x32_bf16 v[32:35], v[214:217], v[178:181], v[32:35]
	v_mfma_f32_16x16x32_bf16 v[20:23], v[206:209], v[186:189], v[20:23]
	v_mfma_f32_16x16x32_bf16 v[16:19], v[214:217], v[186:189], v[16:19]
	v_mfma_f32_16x16x32_bf16 v[4:7], v[206:209], v[198:201], v[4:7]
	v_mfma_f32_16x16x32_bf16 v[0:3], v[214:217], v[198:201], v[0:3]
	s_barrier
	s_setprio 0
	s_mov_b32 m0, s5
	ds_read_b128 v[160:163], v168 offset:32768
	ds_read_b128 v[170:173], v168 offset:33792
	ds_read_b128 v[174:177], v168 offset:34816
	ds_read_b128 v[178:181], v168 offset:35840
	ds_read_b128 v[182:185], v168 offset:36864
	ds_read_b128 v[186:189], v168 offset:37888
	ds_read_b128 v[190:193], v168 offset:38912
	ds_read_b128 v[198:201], v168 offset:39936
	global_load_lds_dwordx4 v150, s[28:29]
	s_mov_b32 m0, s23
	s_setprio 1
	global_load_lds_dwordx4 v146, s[28:29]
	s_waitcnt lgkmcnt(8)
	s_barrier
	s_waitcnt lgkmcnt(7)
	v_mfma_f32_16x16x32_bf16 v[140:143], v[72:75], v[160:163], v[140:143]
	v_mfma_f32_16x16x32_bf16 v[136:139], v[80:83], v[160:163], v[136:139]
	s_waitcnt lgkmcnt(5)
	v_mfma_f32_16x16x32_bf16 v[124:127], v[72:75], v[174:177], v[124:127]
	v_mfma_f32_16x16x32_bf16 v[120:123], v[80:83], v[174:177], v[120:123]
	s_waitcnt lgkmcnt(3)
	v_mfma_f32_16x16x32_bf16 v[108:111], v[72:75], v[182:185], v[108:111]
	v_mfma_f32_16x16x32_bf16 v[104:107], v[80:83], v[182:185], v[104:107]
	s_waitcnt lgkmcnt(1)
	v_mfma_f32_16x16x32_bf16 v[92:95], v[72:75], v[190:193], v[92:95]
	v_mfma_f32_16x16x32_bf16 v[88:91], v[80:83], v[190:193], v[88:91]
	v_mfma_f32_16x16x32_bf16 v[140:143], v[76:79], v[170:173], v[140:143]
	s_add_i32 s28, 0, 0x1c000
	v_mfma_f32_16x16x32_bf16 v[136:139], v[84:87], v[170:173], v[136:139]
	s_add_i32 s29, s58, s34
	v_mfma_f32_16x16x32_bf16 v[124:127], v[76:79], v[178:181], v[124:127]
	v_add_u32_e32 v196, s28, v166
	v_mfma_f32_16x16x32_bf16 v[120:123], v[84:87], v[178:181], v[120:123]
	v_lshl_add_u64 v[194:195], v[194:195], 0, s[12:13]
	v_mfma_f32_16x16x32_bf16 v[108:111], v[76:79], v[186:189], v[108:111]
	v_mfma_f32_16x16x32_bf16 v[104:107], v[84:87], v[186:189], v[104:107]
	s_waitcnt lgkmcnt(0)
	v_mfma_f32_16x16x32_bf16 v[92:95], v[76:79], v[198:201], v[92:95]
	v_mfma_f32_16x16x32_bf16 v[88:91], v[84:87], v[198:201], v[88:91]
	s_barrier
	s_setprio 0
	s_mov_b32 m0, s29
	ds_read_b128 v[202:205], v196
	ds_read_b128 v[206:209], v196 offset:1024
	ds_read_b128 v[210:213], v196 offset:2048
	ds_read_b128 v[214:217], v196 offset:3072
	global_load_lds_dwordx4 v[194:195], off
	v_lshl_add_u64 v[194:195], v[218:219], 0, s[12:13]
	s_add_i32 m0, s29, 0x2000
	s_setprio 1
	global_load_lds_dwordx4 v[194:195], off
	s_barrier
	s_waitcnt lgkmcnt(3)
	v_mfma_f32_16x16x32_bf16 v[132:135], v[202:205], v[160:163], v[132:135]
	s_waitcnt lgkmcnt(1)
	v_mfma_f32_16x16x32_bf16 v[128:131], v[210:213], v[160:163], v[128:131]
	v_mfma_f32_16x16x32_bf16 v[116:119], v[202:205], v[174:177], v[116:119]
	v_mfma_f32_16x16x32_bf16 v[112:115], v[210:213], v[174:177], v[112:115]
	v_mfma_f32_16x16x32_bf16 v[100:103], v[202:205], v[182:185], v[100:103]
	v_mfma_f32_16x16x32_bf16 v[96:99], v[210:213], v[182:185], v[96:99]
	v_mfma_f32_16x16x32_bf16 v[68:71], v[202:205], v[190:193], v[68:71]
	v_mfma_f32_16x16x32_bf16 v[64:67], v[210:213], v[190:193], v[64:67]
	v_mfma_f32_16x16x32_bf16 v[132:135], v[206:209], v[170:173], v[132:135]
	s_mov_b32 m0, s39
	s_waitcnt lgkmcnt(0)
	v_mfma_f32_16x16x32_bf16 v[128:131], v[214:217], v[170:173], v[128:131]
	v_lshl_add_u64 v[194:195], v[220:221], 0, s[12:13]
	v_mfma_f32_16x16x32_bf16 v[116:119], v[206:209], v[178:181], v[116:119]
	v_mfma_f32_16x16x32_bf16 v[112:115], v[214:217], v[178:181], v[112:115]
	v_mfma_f32_16x16x32_bf16 v[100:103], v[206:209], v[186:189], v[100:103]
	v_mfma_f32_16x16x32_bf16 v[96:99], v[214:217], v[186:189], v[96:99]
	v_mfma_f32_16x16x32_bf16 v[68:71], v[206:209], v[198:201], v[68:71]
	v_mfma_f32_16x16x32_bf16 v[64:67], v[214:217], v[198:201], v[64:67]
	s_barrier
; #define PG8_STAGE(bufoff, gbase, voff) do { _Pragma("unroll") for (int _i = 0; _i < 2; ++_i) \
;         __builtin_amdgcn_global_load_lds((const unsigned*)((const char*)(gbase) + (voff)[_i]), (LAS unsigned*)(lds + (bufoff) + ldsw + _i * 8192), 16, 0, 0); } while (0)
; #define PG8_LDA(dst, b, h) do { _Pragma("unroll") for (int m = 0; m < 4; ++m) _Pragma("unroll") for (int k = 0; k < 2; ++k) dst[m][k] = *(const LAS bf16x8*)(lds + PG8_SA(b, h) + aoff + m * 2048 + k * 1024); } while (0)
; #define PG8_MMA(ai, bj, At, Bt) do { __builtin_amdgcn_s_setprio(1); _Pragma("unroll") for (int m = 0; m < 4; ++m) _Pragma("unroll") for (int n = 0; n < 2; ++n) _Pragma("unroll") for (int k = 0; k < 2; ++k) \
;         acc[ai][bj][m][n] = __builtin_amdgcn_mfma_f32_16x16x32_bf16(Bt[n][k], At[m][k], acc[ai][bj][m][n], 0, 0, 0); __builtin_amdgcn_s_setprio(0); } while (0)
; #define PG8_WAIT_V(n) asm volatile("s_waitcnt vmcnt(" #n ")" ::: "memory")
; #define PG8_WAIT_L(n) asm volatile("s_waitcnt lgkmcnt(" #n ")" ::: "memory")
; #define PG8_BAR __builtin_amdgcn_s_barrier()
; #define PG8_SCHED __builtin_amdgcn_sched_barrier(0)
;     DI void operator()(const f32x4 (&acc)[2][2][4][2], const Unit& u, int wr, int wc, int fr, int fq) const {
;         const int row0 = u.pm * BM + wr * 64 + fr, col0 = u.pn * BM + wc * 32 + 8 * fq;
;         f32x4 sc[2][2];
; #pragma unroll
;         for (int bj = 0; bj < 2; ++bj)
; #pragma unroll
;             for (int n = 0; n < 2; ++n) sc[bj][n] = scale ? *(const f32x4*)(scale + col0 + bj * HALF + 4 * n) : (f32x4){1.f, 1.f, 1.f, 1.f};
; template <class Map, class Epi>
; DI void gemm_phase(LAS unsigned char* lds, const Map& MP, const Epi& E, const int nM, const int nN, const int K, const int lda, const int ldb) {
;     ...
;             PG8_LDA(At, 1, 1); PG8_STAGE(PG8_SA(1, 0), a3, voffA);
;             PG8_BAR; PG8_WAIT_L(0); PG8_MMA(1, 0, At, B0); PG8_BAR; PG8_SCHED;
;             PG8_STAGE(PG8_SB(1, 1), b3 + hstepB, voffB);
;             PG8_WAIT_V(6); PG8_BAR; PG8_MMA(1, 1, At, B1); PG8_BAR;
	s_setprio 0
	ds_read_b128 v[160:163], v168 offset:49152
	ds_read_b128 v[170:173], v168 offset:50176
	ds_read_b128 v[174:177], v168 offset:51200
	ds_read_b128 v[178:181], v168 offset:52224
	ds_read_b128 v[182:185], v168 offset:53248
	ds_read_b128 v[186:189], v168 offset:54272
	ds_read_b128 v[190:193], v168 offset:55296
	ds_read_b128 v[198:201], v168 offset:56320
	global_load_lds_dwordx4 v[194:195], off
	v_lshl_add_u64 v[194:195], v[222:223], 0, s[12:13]
	s_mov_b32 m0, s46
	s_setprio 1
	global_load_lds_dwordx4 v[194:195], off
	s_waitcnt vmcnt(10)
	s_barrier
	s_waitcnt lgkmcnt(7)
	v_mfma_f32_16x16x32_bf16 v[60:63], v[72:75], v[160:163], v[60:63]
	v_mfma_f32_16x16x32_bf16 v[56:59], v[80:83], v[160:163], v[56:59]
	s_waitcnt lgkmcnt(5)
	v_mfma_f32_16x16x32_bf16 v[44:47], v[72:75], v[174:177], v[44:47]
	v_mfma_f32_16x16x32_bf16 v[40:43], v[80:83], v[174:177], v[40:43]
	s_waitcnt lgkmcnt(3)
	v_mfma_f32_16x16x32_bf16 v[28:31], v[72:75], v[182:185], v[28:31]
	v_mfma_f32_16x16x32_bf16 v[24:27], v[80:83], v[182:185], v[24:27]
	s_waitcnt lgkmcnt(1)
	v_mfma_f32_16x16x32_bf16 v[12:15], v[72:75], v[190:193], v[12:15]
	v_mfma_f32_16x16x32_bf16 v[8:11], v[80:83], v[190:193], v[8:11]
	v_mfma_f32_16x16x32_bf16 v[60:63], v[76:79], v[170:173], v[60:63]
	s_add_u32 s26, s26, 0x20080
	s_addc_u32 s27, s27, 0
	v_mfma_f32_16x16x32_bf16 v[56:59], v[84:87], v[170:173], v[56:59]
	s_add_i32 s28, s28, s34
	v_mfma_f32_16x16x32_bf16 v[44:47], v[76:79], v[178:181], v[44:47]
	v_mfma_f32_16x16x32_bf16 v[40:43], v[84:87], v[178:181], v[40:43]
	v_mfma_f32_16x16x32_bf16 v[28:31], v[76:79], v[186:189], v[28:31]
	v_mfma_f32_16x16x32_bf16 v[24:27], v[84:87], v[186:189], v[24:27]
	s_waitcnt lgkmcnt(0)
	v_mfma_f32_16x16x32_bf16 v[12:15], v[76:79], v[198:201], v[12:15]
	v_mfma_f32_16x16x32_bf16 v[8:11], v[84:87], v[198:201], v[8:11]
	s_barrier
	s_setprio 0
	s_mov_b32 m0, s28
	s_nop 0
	global_load_lds_dwordx4 v148, s[26:27]
	s_add_i32 m0, s28, 0x2000
	s_setprio 1
	global_load_lds_dwordx4 v144, s[26:27]
	s_waitcnt vmcnt(6)
	s_barrier
	v_mfma_f32_16x16x32_bf16 v[52:55], v[202:205], v[160:163], v[52:55]
	v_mfma_f32_16x16x32_bf16 v[48:51], v[210:213], v[160:163], v[48:51]
	ds_read_b128 v[72:75], v167
	v_mfma_f32_16x16x32_bf16 v[36:39], v[202:205], v[174:177], v[36:39]
	v_mfma_f32_16x16x32_bf16 v[32:35], v[210:213], v[174:177], v[32:35]
	ds_read_b128 v[76:79], v167 offset:1024
	v_mfma_f32_16x16x32_bf16 v[20:23], v[202:205], v[182:185], v[20:23]
	v_mfma_f32_16x16x32_bf16 v[16:19], v[210:213], v[182:185], v[16:19]
	ds_read_b128 v[80:83], v167 offset:2048
	v_mfma_f32_16x16x32_bf16 v[4:7], v[202:205], v[190:193], v[4:7]
	v_mfma_f32_16x16x32_bf16 v[0:3], v[210:213], v[190:193], v[0:3]
	ds_read_b128 v[84:87], v167 offset:3072
	v_mfma_f32_16x16x32_bf16 v[52:55], v[206:209], v[170:173], v[52:55]
	s_add_i32 s57, s57, 2
	v_mfma_f32_16x16x32_bf16 v[48:51], v[214:217], v[170:173], v[48:51]
	s_add_u32 s55, s55, 0x100
	s_addc_u32 s56, s56, 0
	v_mfma_f32_16x16x32_bf16 v[36:39], v[206:209], v[178:181], v[36:39]
	s_add_u32 s24, s24, 0x100
	s_addc_u32 s25, s25, 0
	v_mfma_f32_16x16x32_bf16 v[32:35], v[214:217], v[178:181], v[32:35]
	s_cmp_gt_u32 s57, 5
	v_mfma_f32_16x16x32_bf16 v[20:23], v[206:209], v[186:189], v[20:23]
	v_mfma_f32_16x16x32_bf16 v[16:19], v[214:217], v[186:189], v[16:19]
	v_mfma_f32_16x16x32_bf16 v[4:7], v[206:209], v[198:201], v[4:7]
	v_mfma_f32_16x16x32_bf16 v[0:3], v[214:217], v[198:201], v[0:3]
	s_barrier
	s_setprio 0
	s_cbranch_scc0 .LBB1_229
	s_waitcnt lgkmcnt(0)
	s_lshl_b32 s17, s42, 8
	v_mov_b32_e32 v170, v164
	v_mov_b32_e32 v72, v165
	s_or_b32 s17, s17, s38
	v_mov_b32_e32 v80, 1.0
	v_lshl_add_u32 v160, v72, 3, s17
	v_ashrrev_i32_e32 v161, 31, v160
	v_cndmask_b32_e64 v72, 0, 1, s[14:15]
	v_lshl_add_u64 v[162:163], v[160:161], 2, s[8:9]
	v_cmp_ne_u32_e64 s[42:43], 1, v72
	s_andn2_b64 vcc, exec, s[14:15]
	v_mov_b32_e32 v84, 1.0
	v_mov_b32_e32 v85, 1.0
	v_mov_b32_e32 v86, 1.0
	v_mov_b32_e32 v87, 1.0
	s_cbranch_vccnz .LBB1_232
	global_load_dwordx4 v[84:87], v[162:163], off

; #define PG8_STAGE(bufoff, gbase, voff) do { _Pragma("unroll") for (int _i = 0; _i < 2; ++_i) \
;         __builtin_amdgcn_global_load_lds((const unsigned*)((const char*)(gbase) + (voff)[_i]), (LAS unsigned*)(lds + (bufoff) + ldsw + _i * 8192), 16, 0, 0); } while (0)
; #define PG8_LDA(dst, b, h) do { _Pragma("unroll") for (int m = 0; m < 4; ++m) _Pragma("unroll") for (int k = 0; k < 2; ++k) dst[m][k] = *(const LAS bf16x8*)(lds + PG8_SA(b, h) + aoff + m * 2048 + k * 1024); } while (0)
; #define PG8_LDB(dst, b, h) do { _Pragma("unroll") for (int n = 0; n < 2; ++n) _Pragma("unroll") for (int k = 0; k < 2; ++k) dst[n][k] = *(const LAS bf16x8*)(lds + PG8_SB(b, h) + boff + n * 2048 + k * 1024); } while (0)
; #define PG8_MMA(ai, bj, At, Bt) do { __builtin_amdgcn_s_setprio(1); _Pragma("unroll") for (int m = 0; m < 4; ++m) _Pragma("unroll") for (int n = 0; n < 2; ++n) _Pragma("unroll") for (int k = 0; k < 2; ++k) \
;         acc[ai][bj][m][n] = __builtin_amdgcn_mfma_f32_16x16x32_bf16(Bt[n][k], At[m][k], acc[ai][bj][m][n], 0, 0, 0); __builtin_amdgcn_s_setprio(0); } while (0)
; #define PG8_WAIT_V(n) asm volatile("s_waitcnt vmcnt(" #n ")" ::: "memory")
; #define PG8_BAR __builtin_amdgcn_s_barrier()
; template <class Map, class Epi>
; DI void gemm_phase(LAS unsigned char* lds, const Map& MP, const Epi& E, const int nM, const int nN, const int K, const int lda, const int ldb) {
;     ...
;             const char* a1 = cA + (size_t)(t + 1) * kstep;
;             const char* a2 = last ? nA : cA + (size_t)(t + 2) * kstep; const char* b2 = last ? nB : cB + (size_t)(t + 2) * kstep;
;             const char* a3 = a2 + kstep; const char* b3 = b2 + kstep;
;             PG8_LDB(B0, 0, 0); PG8_SCHED; PG8_LDA(At, 0, 0); PG8_STAGE(PG8_SA(1, 1), a1 + hstepA, voffA);
;             PG8_WAIT_L(8); PG8_BAR; PG8_WAIT_L(0); PG8_MMA(0, 0, At, B0); PG8_BAR; PG8_SCHED;
;             PG8_LDB(B1, 0, 1); PG8_STAGE(PG8_SB(0, 0), b2, voffB);
;             PG8_BAR; PG8_WAIT_L(0); PG8_MMA(0, 1, At, B1); PG8_BAR;
;             PG8_LDA(At, 0, 1); PG8_STAGE(PG8_SA(0, 0), a2, voffA);
;             PG8_BAR; PG8_WAIT_L(0); PG8_MMA(1, 0, At, B0); PG8_BAR; PG8_SCHED;
;             PG8_STAGE(PG8_SB(0, 1), b2 + hstepB, voffB);
;             PG8_WAIT_V(6); PG8_BAR; PG8_MMA(1, 1, At, B1); PG8_BAR;
;             PG8_LDB(B0, 1, 0); PG8_SCHED; PG8_LDA(At, 1, 0); PG8_STAGE(PG8_SA(0, 1), a2 + hstepA, voffA);
.LBB1_380:
	s_add_u32 s28, s44, 0xfff80080
	s_addc_u32 s29, s45, -1
	s_cmp_eq_u32 vcc_hi, 28
	s_cselect_b32 s47, s23, s29
	s_cselect_b32 s46, s61, s28
	s_cselect_b32 s29, s21, vcc_lo
	s_cselect_b32 s28, s58, s59
	s_add_i32 m0, s38, 0xc000
	ds_read_b128 v[96:99], v190
	ds_read_b128 v[100:103], v190 offset:1024
	ds_read_b128 v[108:111], v190 offset:2048
	ds_read_b128 v[112:115], v190 offset:3072
	ds_read_b128 v[160:163], v190 offset:4096
	ds_read_b128 v[164:167], v190 offset:5120
	ds_read_b128 v[198:201], v190 offset:6144
	ds_read_b128 v[202:205], v190 offset:7168
	global_load_lds_dwordx4 v178, s[44:45]
	s_add_i32 m0, s38, 0xe000
	s_setprio 1
	global_load_lds_dwordx4 v176, s[44:45]
	s_waitcnt lgkmcnt(8)
	s_barrier
	s_waitcnt lgkmcnt(7)
	v_mfma_f32_16x16x32_bf16 v[148:151], v[80:83], v[96:99], v[148:151]
	v_mfma_f32_16x16x32_bf16 v[144:147], v[88:91], v[96:99], v[144:147]
	s_waitcnt lgkmcnt(5)
	v_mfma_f32_16x16x32_bf16 v[136:139], v[80:83], v[108:111], v[136:139]
	v_mfma_f32_16x16x32_bf16 v[128:131], v[88:91], v[108:111], v[128:131]
	s_waitcnt lgkmcnt(3)
	v_mfma_f32_16x16x32_bf16 v[120:123], v[80:83], v[160:163], v[120:123]
	v_mfma_f32_16x16x32_bf16 v[104:107], v[88:91], v[160:163], v[104:107]
	s_waitcnt lgkmcnt(1)
	v_mfma_f32_16x16x32_bf16 v[76:79], v[80:83], v[198:201], v[76:79]
	v_mfma_f32_16x16x32_bf16 v[72:75], v[88:91], v[198:201], v[72:75]
	v_mfma_f32_16x16x32_bf16 v[148:151], v[84:87], v[100:103], v[148:151]
	s_add_i32 s68, s5, s37
	v_mfma_f32_16x16x32_bf16 v[144:147], v[92:95], v[100:103], v[144:147]
	v_lshl_add_u64 v[184:185], s[28:29], 0, v[172:173]
	v_mfma_f32_16x16x32_bf16 v[136:139], v[84:87], v[112:115], v[136:139]
	v_lshl_add_u64 v[194:195], s[28:29], 0, v[168:169]
	v_mfma_f32_16x16x32_bf16 v[128:131], v[92:95], v[112:115], v[128:131]
	v_mfma_f32_16x16x32_bf16 v[120:123], v[84:87], v[164:167], v[120:123]
	v_mfma_f32_16x16x32_bf16 v[104:107], v[92:95], v[164:167], v[104:107]
	s_waitcnt lgkmcnt(0)
	v_mfma_f32_16x16x32_bf16 v[76:79], v[84:87], v[202:205], v[76:79]
	v_mfma_f32_16x16x32_bf16 v[72:75], v[92:95], v[202:205], v[72:75]
	s_barrier
	s_setprio 0
	s_mov_b32 m0, s68
	ds_read_b128 v[206:209], v191
	ds_read_b128 v[210:213], v191 offset:1024
	ds_read_b128 v[214:217], v191 offset:2048
	ds_read_b128 v[218:221], v191 offset:3072
	global_load_lds_dwordx4 v[184:185], off
	s_add_i32 m0, s68, 0x2000
	s_setprio 1
	global_load_lds_dwordx4 v[194:195], off
	s_barrier
	s_waitcnt lgkmcnt(3)
	v_mfma_f32_16x16x32_bf16 v[156:159], v[206:209], v[96:99], v[156:159]
	s_waitcnt lgkmcnt(1)
	v_mfma_f32_16x16x32_bf16 v[96:99], v[214:217], v[96:99], v[152:155]
	v_mfma_f32_16x16x32_bf16 v[156:159], v[210:213], v[100:103], v[156:159]
	s_waitcnt lgkmcnt(0)
	v_mfma_f32_16x16x32_bf16 v[96:99], v[218:221], v[100:103], v[96:99]
	v_mfma_f32_16x16x32_bf16 v[100:103], v[206:209], v[108:111], v[140:143]
	v_mfma_f32_16x16x32_bf16 v[108:111], v[214:217], v[108:111], v[132:135]
	v_mfma_f32_16x16x32_bf16 v[116:119], v[214:217], v[160:163], v[116:119]
	v_mfma_f32_16x16x32_bf16 v[68:71], v[206:209], v[198:201], v[68:71]
	v_mfma_f32_16x16x32_bf16 v[64:67], v[214:217], v[198:201], v[64:67]
	v_lshl_add_u64 v[234:235], s[46:47], 0, v[170:171]
	s_mov_b32 m0, s38
	v_mfma_f32_16x16x32_bf16 v[100:103], v[210:213], v[112:115], v[100:103]
	v_lshl_add_u64 v[226:227], s[46:47], 0, v[174:175]
	v_mfma_f32_16x16x32_bf16 v[108:111], v[218:221], v[112:115], v[108:111]
	v_mfma_f32_16x16x32_bf16 v[112:115], v[206:209], v[160:163], v[124:127]
	v_mfma_f32_16x16x32_bf16 v[116:119], v[218:221], v[164:167], v[116:119]
	v_mfma_f32_16x16x32_bf16 v[68:71], v[210:213], v[202:205], v[68:71]
	v_mfma_f32_16x16x32_bf16 v[64:67], v[218:221], v[202:205], v[64:67]
	v_mfma_f32_16x16x32_bf16 v[112:115], v[210:213], v[164:167], v[112:115]
	s_barrier
	s_setprio 0
	ds_read_b128 v[124:127], v190 offset:16384
	ds_read_b128 v[132:135], v190 offset:17408
	ds_read_b128 v[140:143], v190 offset:18432
	ds_read_b128 v[152:155], v190 offset:19456
	ds_read_b128 v[160:163], v190 offset:20480
	ds_read_b128 v[164:167], v190 offset:21504
	ds_read_b128 v[198:201], v190 offset:22528
	ds_read_b128 v[202:205], v190 offset:23552
	global_load_lds_dwordx4 v[226:227], off
	s_mov_b32 m0, s39
	s_setprio 1
	global_load_lds_dwordx4 v[234:235], off
	s_waitcnt vmcnt(10)
	s_barrier
	s_waitcnt lgkmcnt(7)
	v_mfma_f32_16x16x32_bf16 v[60:63], v[80:83], v[124:127], v[60:63]
	v_mfma_f32_16x16x32_bf16 v[48:51], v[88:91], v[124:127], v[48:51]
	s_waitcnt lgkmcnt(5)
	v_mfma_f32_16x16x32_bf16 v[40:43], v[80:83], v[140:143], v[40:43]
	v_mfma_f32_16x16x32_bf16 v[32:35], v[88:91], v[140:143], v[32:35]
	s_waitcnt lgkmcnt(3)
	v_mfma_f32_16x16x32_bf16 v[24:27], v[80:83], v[160:163], v[24:27]
	v_mfma_f32_16x16x32_bf16 v[16:19], v[88:91], v[160:163], v[16:19]
	s_waitcnt lgkmcnt(1)
	v_mfma_f32_16x16x32_bf16 v[12:15], v[80:83], v[198:201], v[12:15]
	v_mfma_f32_16x16x32_bf16 v[8:11], v[88:91], v[198:201], v[8:11]
	v_mfma_f32_16x16x32_bf16 v[60:63], v[84:87], v[132:135], v[60:63]
	s_add_u32 s68, s28, 0x80000
	s_addc_u32 s69, s29, 0
	v_mfma_f32_16x16x32_bf16 v[48:51], v[92:95], v[132:135], v[48:51]
	s_add_i32 s70, s2, s37
	v_mfma_f32_16x16x32_bf16 v[40:43], v[84:87], v[152:155], v[40:43]
	v_mfma_f32_16x16x32_bf16 v[32:35], v[92:95], v[152:155], v[32:35]
	v_mfma_f32_16x16x32_bf16 v[24:27], v[84:87], v[164:167], v[24:27]
	v_mfma_f32_16x16x32_bf16 v[16:19], v[92:95], v[164:167], v[16:19]
	s_waitcnt lgkmcnt(0)
	v_mfma_f32_16x16x32_bf16 v[12:15], v[84:87], v[202:205], v[12:15]
	v_mfma_f32_16x16x32_bf16 v[8:11], v[92:95], v[202:205], v[8:11]
	s_barrier
	s_setprio 0
	s_mov_b32 m0, s70
	s_nop 0
	global_load_lds_dwordx4 v172, s[68:69]
	s_add_i32 m0, s70, 0x2000
	s_setprio 1
	global_load_lds_dwordx4 v168, s[68:69]
	s_waitcnt vmcnt(6)
	s_barrier
; #define PG8_STAGE(bufoff, gbase, voff) do { _Pragma("unroll") for (int _i = 0; _i < 2; ++_i) \
;         __builtin_amdgcn_global_load_lds((const unsigned*)((const char*)(gbase) + (voff)[_i]), (LAS unsigned*)(lds + (bufoff) + ldsw + _i * 8192), 16, 0, 0); } while (0)
; #define PG8_LDA(dst, b, h) do { _Pragma("unroll") for (int m = 0; m < 4; ++m) _Pragma("unroll") for (int k = 0; k < 2; ++k) dst[m][k] = *(const LAS bf16x8*)(lds + PG8_SA(b, h) + aoff + m * 2048 + k * 1024); } while (0)
; #define PG8_LDB(dst, b, h) do { _Pragma("unroll") for (int n = 0; n < 2; ++n) _Pragma("unroll") for (int k = 0; k < 2; ++k) dst[n][k] = *(const LAS bf16x8*)(lds + PG8_SB(b, h) + boff + n * 2048 + k * 1024); } while (0)
; #define PG8_MMA(ai, bj, At, Bt) do { __builtin_amdgcn_s_setprio(1); _Pragma("unroll") for (int m = 0; m < 4; ++m) _Pragma("unroll") for (int n = 0; n < 2; ++n) _Pragma("unroll") for (int k = 0; k < 2; ++k) \
;         acc[ai][bj][m][n] = __builtin_amdgcn_mfma_f32_16x16x32_bf16(Bt[n][k], At[m][k], acc[ai][bj][m][n], 0, 0, 0); __builtin_amdgcn_s_setprio(0); } while (0)
; #define PG8_WAIT_V(n) asm volatile("s_waitcnt vmcnt(" #n ")" ::: "memory")
; #define PG8_WAIT_L(n) asm volatile("s_waitcnt lgkmcnt(" #n ")" ::: "memory")
; #define PG8_BAR __builtin_amdgcn_s_barrier()
; #define PG8_SCHED __builtin_amdgcn_sched_barrier(0)
; template <class Map, class Epi>
; DI void gemm_phase(LAS unsigned char* lds, const Map& MP, const Epi& E, const int nM, const int nN, const int K, const int lda, const int ldb) {
;     ...
;             PG8_STAGE(PG8_SB(0, 1), b2 + hstepB, voffB);
;             PG8_WAIT_V(6); PG8_BAR; PG8_MMA(1, 1, At, B1); PG8_BAR;
;             PG8_LDB(B0, 1, 0); PG8_SCHED; PG8_LDA(At, 1, 0); PG8_STAGE(PG8_SA(0, 1), a2 + hstepA, voffA);
;             PG8_WAIT_L(8); PG8_BAR; PG8_WAIT_L(0); PG8_MMA(0, 0, At, B0); PG8_BAR; PG8_SCHED;
;             PG8_LDB(B1, 1, 1); PG8_STAGE(PG8_SB(1, 0), b3, voffB);
;             PG8_BAR; PG8_WAIT_L(0); PG8_MMA(0, 1, At, B1); PG8_BAR;
;             PG8_LDA(At, 1, 1); PG8_STAGE(PG8_SA(1, 0), a3, voffA);
;             PG8_BAR; PG8_WAIT_L(0); PG8_MMA(1, 0, At, B0); PG8_BAR; PG8_SCHED;
;             PG8_STAGE(PG8_SB(1, 1), b3 + hstepB, voffB);
	v_mfma_f32_16x16x32_bf16 v[56:59], v[206:209], v[124:127], v[56:59]
	v_mfma_f32_16x16x32_bf16 v[52:55], v[214:217], v[124:127], v[52:55]
	s_add_i32 s68, 0, 0x18000
	v_add_u32_e32 v92, s68, v188
	ds_read_b128 v[80:83], v92
	v_mfma_f32_16x16x32_bf16 v[44:47], v[206:209], v[140:143], v[44:47]
	v_mfma_f32_16x16x32_bf16 v[36:39], v[214:217], v[140:143], v[36:39]
	ds_read_b128 v[84:87], v92 offset:1024
	v_mfma_f32_16x16x32_bf16 v[28:31], v[206:209], v[160:163], v[28:31]
	v_mfma_f32_16x16x32_bf16 v[20:23], v[214:217], v[160:163], v[20:23]
	ds_read_b128 v[88:91], v92 offset:2048
	v_mfma_f32_16x16x32_bf16 v[4:7], v[206:209], v[198:201], v[4:7]
	v_mfma_f32_16x16x32_bf16 v[0:3], v[214:217], v[198:201], v[0:3]
	ds_read_b128 v[92:95], v92 offset:3072
	v_mfma_f32_16x16x32_bf16 v[56:59], v[210:213], v[132:135], v[56:59]
	s_add_u32 s46, s46, 0x80000
	s_addc_u32 s47, s47, 0
	v_mfma_f32_16x16x32_bf16 v[52:55], v[218:221], v[132:135], v[52:55]
	v_mfma_f32_16x16x32_bf16 v[44:47], v[210:213], v[152:155], v[44:47]
	v_mfma_f32_16x16x32_bf16 v[36:39], v[218:221], v[152:155], v[36:39]
	v_mfma_f32_16x16x32_bf16 v[28:31], v[210:213], v[164:167], v[28:31]
	v_mfma_f32_16x16x32_bf16 v[20:23], v[218:221], v[164:167], v[20:23]
	v_mfma_f32_16x16x32_bf16 v[4:7], v[210:213], v[202:205], v[4:7]
	v_mfma_f32_16x16x32_bf16 v[0:3], v[218:221], v[202:205], v[0:3]
	s_barrier
	s_setprio 0
	s_mov_b32 m0, s56
	ds_read_b128 v[124:127], v190 offset:32768
	ds_read_b128 v[132:135], v190 offset:33792
	ds_read_b128 v[160:163], v190 offset:34816
	ds_read_b128 v[164:167], v190 offset:35840
	ds_read_b128 v[198:201], v190 offset:36864
	ds_read_b128 v[202:205], v190 offset:37888
	ds_read_b128 v[206:209], v190 offset:38912
	ds_read_b128 v[210:213], v190 offset:39936
	global_load_lds_dwordx4 v174, s[46:47]
	s_mov_b32 m0, s57
	s_setprio 1
	global_load_lds_dwordx4 v170, s[46:47]
	s_waitcnt lgkmcnt(8)
	s_barrier
	s_waitcnt lgkmcnt(7)
	v_mfma_f32_16x16x32_bf16 v[140:143], v[80:83], v[124:127], v[148:151]
	s_waitcnt lgkmcnt(6)
	v_mfma_f32_16x16x32_bf16 v[148:151], v[84:87], v[132:135], v[140:143]
	v_mfma_f32_16x16x32_bf16 v[140:143], v[88:91], v[124:127], v[144:147]
	s_waitcnt lgkmcnt(5)
	v_mfma_f32_16x16x32_bf16 v[136:139], v[80:83], v[160:163], v[136:139]
	v_mfma_f32_16x16x32_bf16 v[128:131], v[88:91], v[160:163], v[128:131]
	s_waitcnt lgkmcnt(3)
	v_mfma_f32_16x16x32_bf16 v[120:123], v[80:83], v[198:201], v[120:123]
	v_mfma_f32_16x16x32_bf16 v[104:107], v[88:91], v[198:201], v[104:107]
	s_waitcnt lgkmcnt(1)
	v_mfma_f32_16x16x32_bf16 v[76:79], v[80:83], v[206:209], v[76:79]
	v_mfma_f32_16x16x32_bf16 v[72:75], v[88:91], v[206:209], v[72:75]
	s_add_i32 s46, 0, 0x1c000
	v_mfma_f32_16x16x32_bf16 v[144:147], v[92:95], v[132:135], v[140:143]
	v_add_u32_e32 v140, s46, v188
	v_mfma_f32_16x16x32_bf16 v[136:139], v[84:87], v[164:167], v[136:139]
	s_add_i32 s47, s68, s37
	v_mfma_f32_16x16x32_bf16 v[128:131], v[92:95], v[164:167], v[128:131]
	v_mfma_f32_16x16x32_bf16 v[120:123], v[84:87], v[202:205], v[120:123]
	v_mfma_f32_16x16x32_bf16 v[104:107], v[92:95], v[202:205], v[104:107]
	s_waitcnt lgkmcnt(0)
	v_mfma_f32_16x16x32_bf16 v[76:79], v[84:87], v[210:213], v[76:79]
	v_mfma_f32_16x16x32_bf16 v[72:75], v[92:95], v[210:213], v[72:75]
	s_barrier
	s_setprio 0
	ds_read_b128 v[214:217], v140
	ds_read_b128 v[218:221], v140 offset:1024
	ds_read_b128 v[222:225], v140 offset:2048
	ds_read_b128 v[230:233], v140 offset:3072
	v_lshl_add_u64 v[140:141], v[184:185], 0, s[14:15]
	s_mov_b32 m0, s47
	s_nop 0
	global_load_lds_dwordx4 v[140:141], off
	v_lshl_add_u64 v[140:141], v[194:195], 0, s[14:15]
	s_add_i32 m0, s47, 0x2000
	s_setprio 1
	global_load_lds_dwordx4 v[140:141], off
	s_barrier
	s_waitcnt lgkmcnt(1)
	v_mfma_f32_16x16x32_bf16 v[96:99], v[222:225], v[124:127], v[96:99]
	v_mfma_f32_16x16x32_bf16 v[140:143], v[214:217], v[124:127], v[156:159]
	s_waitcnt lgkmcnt(0)
	v_mfma_f32_16x16x32_bf16 v[152:155], v[230:233], v[132:135], v[96:99]
	v_mfma_f32_16x16x32_bf16 v[96:99], v[214:217], v[160:163], v[100:103]
	v_mfma_f32_16x16x32_bf16 v[156:159], v[218:221], v[132:135], v[140:143]
	v_mfma_f32_16x16x32_bf16 v[140:143], v[218:221], v[164:167], v[96:99]
	v_mfma_f32_16x16x32_bf16 v[96:99], v[222:225], v[160:163], v[108:111]
	v_mfma_f32_16x16x32_bf16 v[132:135], v[230:233], v[164:167], v[96:99]
	v_mfma_f32_16x16x32_bf16 v[96:99], v[214:217], v[198:201], v[112:115]
	s_mov_b32 m0, s62
	v_mfma_f32_16x16x32_bf16 v[124:127], v[218:221], v[202:205], v[96:99]
	v_lshl_add_u64 v[184:185], v[226:227], 0, s[14:15]
	v_mfma_f32_16x16x32_bf16 v[96:99], v[222:225], v[198:201], v[116:119]
	v_mfma_f32_16x16x32_bf16 v[68:71], v[214:217], v[206:209], v[68:71]
	v_mfma_f32_16x16x32_bf16 v[64:67], v[222:225], v[206:209], v[64:67]
	v_mfma_f32_16x16x32_bf16 v[116:119], v[230:233], v[202:205], v[96:99]
	v_mfma_f32_16x16x32_bf16 v[68:71], v[218:221], v[210:213], v[68:71]
	v_mfma_f32_16x16x32_bf16 v[64:67], v[230:233], v[210:213], v[64:67]
	s_barrier
	s_setprio 0
	ds_read_b128 v[96:99], v190 offset:49152
	ds_read_b128 v[100:103], v190 offset:50176
	ds_read_b128 v[108:111], v190 offset:51200
	ds_read_b128 v[112:115], v190 offset:52224
	ds_read_b128 v[160:163], v190 offset:53248
	ds_read_b128 v[164:167], v190 offset:54272
	ds_read_b128 v[198:201], v190 offset:55296
	ds_read_b128 v[202:205], v190 offset:56320
	global_load_lds_dwordx4 v[184:185], off
	v_lshl_add_u64 v[184:185], v[234:235], 0, s[14:15]
	s_mov_b32 m0, s63
	s_setprio 1
	global_load_lds_dwordx4 v[184:185], off
	s_waitcnt vmcnt(10)
	s_barrier
; #define PG8_STAGE(bufoff, gbase, voff) do { _Pragma("unroll") for (int _i = 0; _i < 2; ++_i) \
;         __builtin_amdgcn_global_load_lds((const unsigned*)((const char*)(gbase) + (voff)[_i]), (LAS unsigned*)(lds + (bufoff) + ldsw + _i * 8192), 16, 0, 0); } while (0)
; #define PG8_MMA(ai, bj, At, Bt) do { __builtin_amdgcn_s_setprio(1); _Pragma("unroll") for (int m = 0; m < 4; ++m) _Pragma("unroll") for (int n = 0; n < 2; ++n) _Pragma("unroll") for (int k = 0; k < 2; ++k) \
;         acc[ai][bj][m][n] = __builtin_amdgcn_mfma_f32_16x16x32_bf16(Bt[n][k], At[m][k], acc[ai][bj][m][n], 0, 0, 0); __builtin_amdgcn_s_setprio(0); } while (0)
; #define PG8_WAIT_V(n) asm volatile("s_waitcnt vmcnt(" #n ")" ::: "memory")
; #define PG8_WAIT_L(n) asm volatile("s_waitcnt lgkmcnt(" #n ")" ::: "memory")
; #define PG8_BAR __builtin_amdgcn_s_barrier()
; #define PG8_SCHED __builtin_amdgcn_sched_barrier(0)
; template <class Map, class Epi>
; DI void gemm_phase(LAS unsigned char* lds, const Map& MP, const Epi& E, const int nM, const int nN, const int K, const int lda, const int ldb) {
;     ...
;             PG8_BAR; PG8_WAIT_L(0); PG8_MMA(1, 0, At, B0); PG8_BAR; PG8_SCHED;
;             PG8_STAGE(PG8_SB(1, 1), b3 + hstepB, voffB);
;             PG8_WAIT_V(6); PG8_BAR; PG8_MMA(1, 1, At, B1); PG8_BAR;
	s_waitcnt lgkmcnt(7)
	v_mfma_f32_16x16x32_bf16 v[60:63], v[80:83], v[96:99], v[60:63]
	v_mfma_f32_16x16x32_bf16 v[48:51], v[88:91], v[96:99], v[48:51]
	s_waitcnt lgkmcnt(5)
	v_mfma_f32_16x16x32_bf16 v[40:43], v[80:83], v[108:111], v[40:43]
	v_mfma_f32_16x16x32_bf16 v[32:35], v[88:91], v[108:111], v[32:35]
	s_waitcnt lgkmcnt(3)
	v_mfma_f32_16x16x32_bf16 v[24:27], v[80:83], v[160:163], v[24:27]
	v_mfma_f32_16x16x32_bf16 v[16:19], v[88:91], v[160:163], v[16:19]
	s_waitcnt lgkmcnt(1)
	v_mfma_f32_16x16x32_bf16 v[12:15], v[80:83], v[198:201], v[12:15]
	v_mfma_f32_16x16x32_bf16 v[8:11], v[88:91], v[198:201], v[8:11]
	v_mfma_f32_16x16x32_bf16 v[60:63], v[84:87], v[100:103], v[60:63]
	s_add_u32 s28, s28, 0x80080
	s_addc_u32 s29, s29, 0
	v_mfma_f32_16x16x32_bf16 v[48:51], v[92:95], v[100:103], v[48:51]
	s_add_i32 s46, s46, s37
	v_mfma_f32_16x16x32_bf16 v[40:43], v[84:87], v[112:115], v[40:43]
	v_mfma_f32_16x16x32_bf16 v[32:35], v[92:95], v[112:115], v[32:35]
	v_mfma_f32_16x16x32_bf16 v[24:27], v[84:87], v[164:167], v[24:27]
	v_mfma_f32_16x16x32_bf16 v[16:19], v[92:95], v[164:167], v[16:19]
	s_waitcnt lgkmcnt(0)
	v_mfma_f32_16x16x32_bf16 v[12:15], v[84:87], v[202:205], v[12:15]
	v_mfma_f32_16x16x32_bf16 v[8:11], v[92:95], v[202:205], v[8:11]
	s_barrier
	s_setprio 0
	s_mov_b32 m0, s46
	s_nop 0
	global_load_lds_dwordx4 v172, s[28:29]
	s_add_i32 m0, s46, 0x2000
	s_setprio 1
	global_load_lds_dwordx4 v168, s[28:29]
	s_waitcnt vmcnt(6)
	s_barrier
	v_mfma_f32_16x16x32_bf16 v[56:59], v[214:217], v[96:99], v[56:59]
	v_mfma_f32_16x16x32_bf16 v[52:55], v[222:225], v[96:99], v[52:55]
	ds_read_b128 v[80:83], v189
	v_mfma_f32_16x16x32_bf16 v[44:47], v[214:217], v[108:111], v[44:47]
	v_mfma_f32_16x16x32_bf16 v[36:39], v[222:225], v[108:111], v[36:39]
	ds_read_b128 v[84:87], v189 offset:1024
	v_mfma_f32_16x16x32_bf16 v[28:31], v[214:217], v[160:163], v[28:31]
	v_mfma_f32_16x16x32_bf16 v[20:23], v[222:225], v[160:163], v[20:23]
	ds_read_b128 v[88:91], v189 offset:2048
	v_mfma_f32_16x16x32_bf16 v[4:7], v[214:217], v[198:201], v[4:7]
	v_mfma_f32_16x16x32_bf16 v[0:3], v[222:225], v[198:201], v[0:3]
	ds_read_b128 v[92:95], v189 offset:3072
	v_mfma_f32_16x16x32_bf16 v[56:59], v[218:221], v[100:103], v[56:59]
	s_add_i32 vcc_hi, vcc_hi, 2
	v_mfma_f32_16x16x32_bf16 v[52:55], v[230:233], v[100:103], v[52:55]
	s_add_u32 s59, s59, 0x100
	s_addc_u32 vcc_lo, vcc_lo, 0
	v_mfma_f32_16x16x32_bf16 v[44:47], v[218:221], v[112:115], v[44:47]
	s_add_u32 s44, s44, 0x100
	s_addc_u32 s45, s45, 0
	v_mfma_f32_16x16x32_bf16 v[36:39], v[230:233], v[112:115], v[36:39]
	s_cmp_gt_u32 vcc_hi, 29
	v_mfma_f32_16x16x32_bf16 v[28:31], v[218:221], v[164:167], v[28:31]
	v_mfma_f32_16x16x32_bf16 v[20:23], v[230:233], v[164:167], v[20:23]
	v_mfma_f32_16x16x32_bf16 v[4:7], v[218:221], v[202:205], v[4:7]
	v_mfma_f32_16x16x32_bf16 v[0:3], v[230:233], v[202:205], v[0:3]
	s_barrier
	s_setprio 0
	s_cbranch_scc0 .LBB1_380
; DI float silu_mul(float g, float v) { return g * v * __builtin_amdgcn_rcpf(1.0f + __builtin_amdgcn_exp2f(-LOG2E * g)); }
;     DI void operator()(const f32x4 (&acc)[2][2][4][2], const Unit& u, int wr, int wc, int fr, int fq) const {
;         const int row0 = u.pm * BM + wr * 64 + fr, ch0 = u.pn * 128 + wc * 32 + 8 * fq;
;         f32x4 w0[2], w1[2], w2[2], bb[2];
; #pragma unroll
;         for (int n = 0; n < 2; ++n) { w0[n] = *(const f32x4*)(cw + ch0 + 4 * n); w1[n] = *(const f32x4*)(cw + DFF + ch0 + 4 * n); w2[n] = *(const f32x4*)(cw + 2 * DFF + ch0 + 4 * n); bb[n] = *(const f32x4*)(cb + ch0 + 4 * n); }
; #pragma unroll
;         for (int ai = 0; ai < 2; ++ai)
; #pragma unroll
;             for (int m = 0; m < 4; ++m) {
;                 const bool efirst = (m == 0) && (fr == 0), elast = (m == 3) && (fr == 15);
;                 const int row = row0 + ai * HALF + m * 16;
;                 f32x4 gc[2];
; #pragma unroll
;                 for (int n = 0; n < 2; ++n) {
;                     const f32x4 g = acc[ai][0][m][n];
;                     const f32x4 gprev = acc[ai][0][m > 0 ? m - 1 : 0][n], gnext = acc[ai][0][m < 3 ? m + 1 : 3][n];
;                     f32x4 up, dn;
; #pragma unroll
;                     for (int e = 0; e < 4; ++e) {
;                         const float pu = (m > 0 && fr == 15) ? gprev[e] : g[e];
;                         const float pd = (m < 3 && fr == 0) ? gnext[e] : g[e];
;                         up[e] = dpp_ror1(pu); dn[e] = dpp_ror15(pd);
;                     }
;                     if (efirst) up = (f32x4){0.f, 0.f, 0.f, 0.f};
;                     if (elast) dn = (f32x4){0.f, 0.f, 0.f, 0.f};
;                     gc[n] = w0[n] * up + w1[n] * g + w2[n] * dn + bb[n];
;                 }
;                 if (efirst || elast) {
;                     const size_t eo = (size_t)((row >> 6) * 2 + (elast ? 1 : 0)) * DFF + ch0;
; #pragma unroll
;                     for (int n = 0; n < 2; ++n) { *(f32x4*)(EP + eo + 4 * n) = gc[n]; *(f32x4*)(ER + eo + 4 * n) = acc[ai][0][m][n]; *(f32x4*)(EV + eo + 4 * n) = acc[ai][1][m][n]; }
;                 } else {
;                     const f32x4 v0 = acc[ai][1][m][0], v1 = acc[ai][1][m][1];
;                     u32x4 o;
;                     o[0] = pack2(silu_mul(gc[0][0], v0[0]), silu_mul(gc[0][1], v0[1])); o[1] = pack2(silu_mul(gc[0][2], v0[2]), silu_mul(gc[0][3], v0[3]));
	s_waitcnt lgkmcnt(0)
	s_lshl_b32 s23, s43, 7
	v_mov_b32_e32 v194, v186
	v_mov_b32_e32 v80, v187
	s_or_b32 s23, s23, s67
	v_lshl_add_u32 v184, v80, 3, s23
	v_ashrrev_i32_e32 v185, 31, v184
	v_lshlrev_b64 v[80:81], 2, v[184:185]
	v_lshl_add_u64 v[84:85], s[52:53], 0, v[80:81]
	v_lshl_add_u64 v[88:89], s[16:17], 0, v[80:81]
	v_lshl_add_u64 v[92:93], s[18:19], 0, v[80:81]
	v_lshl_add_u64 v[112:113], s[54:55], 0, v[80:81]
	global_load_dwordx4 v[80:83], v[84:85], off offset:16
	global_load_dwordx4 v[96:99], v[84:85], off
	s_nop 0
	global_load_dwordx4 v[84:87], v[88:89], off offset:16
	global_load_dwordx4 v[100:103], v[88:89], off
	s_nop 0
	global_load_dwordx4 v[88:91], v[92:93], off offset:16
	global_load_dwordx4 v[108:111], v[92:93], off
	s_nop 0
	global_load_dwordx4 v[92:95], v[112:113], off offset:16
	s_nop 0
	global_load_dwordx4 v[112:115], v[112:113], off
	v_cmp_eq_u32_e32 vcc, 0, v194
	s_nop 0
	s_nop 0
	v_cndmask_b32_e32 v161, v148, v136, vcc
	v_cndmask_b32_e32 v162, v149, v137, vcc
	v_cndmask_b32_e32 v163, v150, v138, vcc
	v_mov_b32_dpp v160, v161 row_ror:15 row_mask:0xf bank_mask:0xf
	s_nop 0
	s_nop 0
	v_mov_b32_dpp v161, v162 row_ror:15 row_mask:0xf bank_mask:0xf
	v_mov_b32_dpp v164, v150 row_ror:1 row_mask:0xf bank_mask:0xf
	v_cndmask_b32_e32 v165, v151, v139, vcc
	v_mov_b32_dpp v162, v163 row_ror:15 row_mask:0xf bank_mask:0xf
	v_mov_b32_dpp v195, v151 row_ror:1 row_mask:0xf bank_mask:0xf
	v_mov_b32_dpp v166, v148 row_ror:1 row_mask:0xf bank_mask:0xf
	v_mov_b32_dpp v167, v149 row_ror:1 row_mask:0xf bank_mask:0xf
	v_mov_b32_dpp v163, v165 row_ror:15 row_mask:0xf bank_mask:0xf
	v_cndmask_b32_e64 v165, v195, 0, vcc
	v_cndmask_b32_e64 v164, v164, 0, vcc
	v_cndmask_b32_e64 v167, v167, 0, vcc
	v_cndmask_b32_e64 v166, v166, 0, vcc
	s_nop 0
	s_nop 0
	v_mov_b32_dpp v195, v144 row_ror:1 row_mask:0xf bank_mask:0xf
	v_mov_b32_dpp v196, v145 row_ror:1 row_mask:0xf bank_mask:0xf
	v_mov_b32_dpp v198, v146 row_ror:1 row_mask:0xf bank_mask:0xf
	v_cndmask_b32_e32 v199, v147, v131, vcc
	v_mov_b32_dpp v200, v147 row_ror:1 row_mask:0xf bank_mask:0xf
	v_cndmask_b32_e64 v198, v198, 0, vcc
	v_cndmask_b32_e64 v201, v196, 0, vcc
	s_lshl_b32 s21, s42, 8
	s_add_i32 s21, s21, s49
	v_add_u32_e32 v193, s21, v194
	v_cmp_ne_u32_e64 s[46:47], 0, v194
	s_waitcnt vmcnt(0)
	v_pk_mul_f32 v[164:165], v[98:99], v[164:165]
	v_pk_mul_f32 v[166:167], v[96:97], v[166:167]
	v_pk_fma_f32 v[164:165], v[150:151], v[102:103], v[164:165]
	v_pk_fma_f32 v[166:167], v[148:149], v[100:101], v[166:167]
	v_pk_fma_f32 v[162:163], v[110:111], v[162:163], v[164:165]
	v_cndmask_b32_e32 v165, v144, v128, vcc
	v_pk_fma_f32 v[160:161], v[108:109], v[160:161], v[166:167]
	v_cndmask_b32_e32 v166, v145, v129, vcc
	v_mov_b32_dpp v164, v165 row_ror:15 row_mask:0xf bank_mask:0xf
	v_cndmask_b32_e32 v167, v146, v130, vcc
	v_pk_add_f32 v[162:163], v[114:115], v[162:163]
	v_mov_b32_dpp v165, v166 row_ror:15 row_mask:0xf bank_mask:0xf
	v_pk_add_f32 v[160:161], v[112:113], v[160:161]
	s_nop 0
	v_mov_b32_dpp v166, v167 row_ror:15 row_mask:0xf bank_mask:0xf
	s_nop 1
	v_mov_b32_dpp v167, v199 row_ror:15 row_mask:0xf bank_mask:0xf
	v_cndmask_b32_e64 v199, v200, 0, vcc
	v_cndmask_b32_e64 v200, v195, 0, vcc
	v_pk_mul_f32 v[200:201], v[80:81], v[200:201]
	v_pk_mul_f32 v[198:199], v[82:83], v[198:199]
	v_pk_fma_f32 v[200:201], v[144:145], v[84:85], v[200:201]
	v_pk_fma_f32 v[198:199], v[146:147], v[86:87], v[198:199]
	v_pk_fma_f32 v[164:165], v[88:89], v[164:165], v[200:201]
	v_pk_fma_f32 v[166:167], v[90:91], v[166:167], v[198:199]
	v_pk_add_f32 v[164:165], v[92:93], v[164:165]
	v_pk_add_f32 v[166:167], v[94:95], v[166:167]
	s_and_saveexec_b64 s[28:29], s[46:47]
	s_xor_b64 s[28:29], exec, s[28:29]
	s_cbranch_execz .LBB1_383
	v_mul_f32_e32 v195, 0xbfb8aa3b, v160
	v_exp_f32_e32 v195, v195
	v_mul_f32_e32 v196, 0xbfb8aa3b, v161
	v_exp_f32_e32 v196, v196
	v_pk_mul_f32 v[160:161], v[156:157], v[160:161]
	v_add_f32_e32 v195, 1.0, v195
	v_rcp_f32_e32 v198, v195
	v_add_f32_e32 v196, 1.0, v196
	v_mul_f32_e32 v195, 0xbfb8aa3b, v162
	v_rcp_f32_e32 v199, v196
	v_exp_f32_e32 v195, v195
	v_mul_f32_e32 v196, 0xbfb8aa3b, v163
	v_exp_f32_e32 v196, v196
	v_pk_mul_f32 v[160:161], v[160:161], v[198:199]
	v_add_f32_e32 v195, 1.0, v195
	v_rcp_f32_e32 v200, v195
	v_add_f32_e32 v195, 1.0, v196
	v_rcp_f32_e32 v201, v195
	v_cvt_pk_bf16_f32 v160, v160, v161
	v_mul_f32_e32 v161, 0xbfb8aa3b, v164
	v_exp_f32_e32 v195, v161
	v_mul_f32_e32 v161, 0xbfb8aa3b, v165
	v_exp_f32_e32 v196, v161
	v_pk_mul_f32 v[162:163], v[158:159], v[162:163]
	v_pk_mul_f32 v[164:165], v[152:153], v[164:165]
	v_pk_mul_f32 v[162:163], v[162:163], v[200:201]
	s_nop 0
	v_cvt_pk_bf16_f32 v161, v162, v163
	v_add_f32_e32 v162, 1.0, v195
	v_mul_f32_e32 v195, 0xbfb8aa3b, v166
	v_add_f32_e32 v163, 1.0, v196
	v_exp_f32_e32 v195, v195
	v_mul_f32_e32 v196, 0xbfb8aa3b, v167
	v_exp_f32_e32 v196, v196
	v_rcp_f32_e32 v162, v162
	v_add_f32_e32 v195, 1.0, v195
	v_rcp_f32_e32 v198, v195
	v_add_f32_e32 v195, 1.0, v196
	v_rcp_f32_e32 v163, v163
	v_rcp_f32_e32 v199, v195
	v_pk_mul_f32 v[166:167], v[154:155], v[166:167]
	v_pk_mul_f32 v[162:163], v[164:165], v[162:163]
	v_pk_mul_f32 v[164:165], v[166:167], v[198:199]
	v_cvt_pk_bf16_f32 v162, v162, v163
	v_cvt_pk_bf16_f32 v163, v164, v165
	v_mov_b64_e32 v[164:165], s[6:7]
	v_mad_i64_i32 v[164:165], s[42:43], v193, s30, v[164:165]
	v_lshl_add_u64 v[164:165], v[184:185], 1, v[164:165]
	global_store_dwordx4 v[164:165], v[160:163], off

; #define PG8_STAGE(bufoff, gbase, voff) do { _Pragma("unroll") for (int _i = 0; _i < 2; ++_i) \
;         __builtin_amdgcn_global_load_lds((const unsigned*)((const char*)(gbase) + (voff)[_i]), (LAS unsigned*)(lds + (bufoff) + ldsw + _i * 8192), 16, 0, 0); } while (0)
; #define PG8_LDA(dst, b, h) do { _Pragma("unroll") for (int m = 0; m < 4; ++m) _Pragma("unroll") for (int k = 0; k < 2; ++k) dst[m][k] = *(const LAS bf16x8*)(lds + PG8_SA(b, h) + aoff + m * 2048 + k * 1024); } while (0)
; #define PG8_LDB(dst, b, h) do { _Pragma("unroll") for (int n = 0; n < 2; ++n) _Pragma("unroll") for (int k = 0; k < 2; ++k) dst[n][k] = *(const LAS bf16x8*)(lds + PG8_SB(b, h) + boff + n * 2048 + k * 1024); } while (0)
; #define PG8_MMA(ai, bj, At, Bt) do { __builtin_amdgcn_s_setprio(1); _Pragma("unroll") for (int m = 0; m < 4; ++m) _Pragma("unroll") for (int n = 0; n < 2; ++n) _Pragma("unroll") for (int k = 0; k < 2; ++k) \
;         acc[ai][bj][m][n] = __builtin_amdgcn_mfma_f32_16x16x32_bf16(Bt[n][k], At[m][k], acc[ai][bj][m][n], 0, 0, 0); __builtin_amdgcn_s_setprio(0); } while (0)
; #define PG8_WAIT_V(n) asm volatile("s_waitcnt vmcnt(" #n ")" ::: "memory")
; #define PG8_WAIT_L(n) asm volatile("s_waitcnt lgkmcnt(" #n ")" ::: "memory")
; #define PG8_BAR __builtin_amdgcn_s_barrier()
; #define PG8_SCHED __builtin_amdgcn_sched_barrier(0)
; template <class Map, class Epi>
; DI void gemm_phase(LAS unsigned char* lds, const Map& MP, const Epi& E, const int nM, const int nN, const int K, const int lda, const int ldb) {
;     ...
;             PG8_LDB(B0, 0, 0); PG8_SCHED; PG8_LDA(At, 0, 0); PG8_STAGE(PG8_SA(1, 1), a1 + hstepA, voffA);
;             PG8_WAIT_L(8); PG8_BAR; PG8_WAIT_L(0); PG8_MMA(0, 0, At, B0); PG8_BAR; PG8_SCHED;
;             PG8_LDB(B1, 0, 1); PG8_STAGE(PG8_SB(0, 0), b2, voffB);
;             PG8_BAR; PG8_WAIT_L(0); PG8_MMA(0, 1, At, B1); PG8_BAR;
;             PG8_LDA(At, 0, 1); PG8_STAGE(PG8_SA(0, 0), a2, voffA);
;             PG8_BAR; PG8_WAIT_L(0); PG8_MMA(1, 0, At, B0); PG8_BAR; PG8_SCHED;
;             PG8_STAGE(PG8_SB(0, 1), b2 + hstepB, voffB);
;             PG8_WAIT_V(6); PG8_BAR; PG8_MMA(1, 1, At, B1); PG8_BAR;
.LBB1_550:
	s_add_u32 s10, s8, 0x100
	s_addc_u32 s11, s9, 0
	s_cmpk_eq_i32 s3, 0x54
	s_cselect_b32 s15, s43, s11
	s_cselect_b32 s14, s42, s10
	s_cselect_b32 s13, s7, s38
	s_cselect_b32 s12, s6, s5
	s_add_i32 m0, s24, 0xc000
	ds_read_b128 v[168:171], v150
	ds_read_b128 v[172:175], v150 offset:1024
	ds_read_b128 v[176:179], v150 offset:2048
	ds_read_b128 v[180:183], v150 offset:3072
	ds_read_b128 v[184:187], v150 offset:4096
	ds_read_b128 v[188:191], v150 offset:5120
	ds_read_b128 v[192:195], v150 offset:6144
	ds_read_b128 v[198:201], v150 offset:7168
	global_load_lds_dwordx4 v138, s[8:9]
	s_add_i32 m0, s24, 0xe000
	s_setprio 1
	global_load_lds_dwordx4 v136, s[8:9]
	s_waitcnt lgkmcnt(8)
	s_barrier
	s_waitcnt lgkmcnt(7)
	v_mfma_f32_16x16x32_bf16 v[124:127], v[152:155], v[168:171], v[124:127]
	v_mfma_f32_16x16x32_bf16 v[120:123], v[160:163], v[168:171], v[120:123]
	s_waitcnt lgkmcnt(5)
	v_mfma_f32_16x16x32_bf16 v[108:111], v[152:155], v[176:179], v[108:111]
	v_mfma_f32_16x16x32_bf16 v[104:107], v[160:163], v[176:179], v[104:107]
	s_waitcnt lgkmcnt(3)
	v_mfma_f32_16x16x32_bf16 v[92:95], v[152:155], v[184:187], v[92:95]
	v_mfma_f32_16x16x32_bf16 v[88:91], v[160:163], v[184:187], v[88:91]
	s_waitcnt lgkmcnt(1)
	v_mfma_f32_16x16x32_bf16 v[76:79], v[152:155], v[192:195], v[76:79]
	v_mfma_f32_16x16x32_bf16 v[72:75], v[160:163], v[192:195], v[72:75]
	v_mfma_f32_16x16x32_bf16 v[124:127], v[156:159], v[172:175], v[124:127]
	s_add_i32 s8, s35, s22
	v_mfma_f32_16x16x32_bf16 v[120:123], v[164:167], v[172:175], v[120:123]
	v_lshl_add_u64 v[144:145], s[12:13], 0, v[132:133]
	v_mfma_f32_16x16x32_bf16 v[108:111], v[156:159], v[180:183], v[108:111]
	v_lshl_add_u64 v[218:219], s[12:13], 0, v[128:129]
	v_mfma_f32_16x16x32_bf16 v[104:107], v[164:167], v[180:183], v[104:107]
	v_mfma_f32_16x16x32_bf16 v[92:95], v[156:159], v[188:191], v[92:95]
	v_mfma_f32_16x16x32_bf16 v[88:91], v[164:167], v[188:191], v[88:91]
	s_waitcnt lgkmcnt(0)
	v_mfma_f32_16x16x32_bf16 v[76:79], v[156:159], v[198:201], v[76:79]
	v_mfma_f32_16x16x32_bf16 v[72:75], v[164:167], v[198:201], v[72:75]
	s_barrier
	s_setprio 0
	s_mov_b32 m0, s8
	ds_read_b128 v[202:205], v151
	ds_read_b128 v[206:209], v151 offset:1024
	ds_read_b128 v[210:213], v151 offset:2048
	ds_read_b128 v[214:217], v151 offset:3072
	global_load_lds_dwordx4 v[144:145], off
	s_add_i32 m0, s8, 0x2000
	s_setprio 1
	global_load_lds_dwordx4 v[218:219], off
	s_barrier
	s_waitcnt lgkmcnt(3)
	v_mfma_f32_16x16x32_bf16 v[116:119], v[202:205], v[168:171], v[116:119]
	s_waitcnt lgkmcnt(1)
	v_mfma_f32_16x16x32_bf16 v[112:115], v[210:213], v[168:171], v[112:115]
	v_mfma_f32_16x16x32_bf16 v[100:103], v[202:205], v[176:179], v[100:103]
	v_mfma_f32_16x16x32_bf16 v[96:99], v[210:213], v[176:179], v[96:99]
	v_mfma_f32_16x16x32_bf16 v[84:87], v[202:205], v[184:187], v[84:87]
	v_mfma_f32_16x16x32_bf16 v[80:83], v[210:213], v[184:187], v[80:83]
	v_mfma_f32_16x16x32_bf16 v[68:71], v[202:205], v[192:195], v[68:71]
	v_mfma_f32_16x16x32_bf16 v[64:67], v[210:213], v[192:195], v[64:67]
	v_mfma_f32_16x16x32_bf16 v[116:119], v[206:209], v[172:175], v[116:119]
	v_lshl_add_u64 v[222:223], s[14:15], 0, v[130:131]
	s_mov_b32 m0, s24
	s_waitcnt lgkmcnt(0)
	v_mfma_f32_16x16x32_bf16 v[112:115], v[214:217], v[172:175], v[112:115]
	v_lshl_add_u64 v[220:221], s[14:15], 0, v[134:135]
	v_mfma_f32_16x16x32_bf16 v[100:103], v[206:209], v[180:183], v[100:103]
	v_mfma_f32_16x16x32_bf16 v[96:99], v[214:217], v[180:183], v[96:99]
	v_mfma_f32_16x16x32_bf16 v[84:87], v[206:209], v[188:191], v[84:87]
	v_mfma_f32_16x16x32_bf16 v[80:83], v[214:217], v[188:191], v[80:83]
	v_mfma_f32_16x16x32_bf16 v[68:71], v[206:209], v[198:201], v[68:71]
	v_mfma_f32_16x16x32_bf16 v[64:67], v[214:217], v[198:201], v[64:67]
	s_barrier
	s_setprio 0
	ds_read_b128 v[168:171], v150 offset:16384
	ds_read_b128 v[172:175], v150 offset:17408
	ds_read_b128 v[176:179], v150 offset:18432
	ds_read_b128 v[180:183], v150 offset:19456
	ds_read_b128 v[184:187], v150 offset:20480
	ds_read_b128 v[188:191], v150 offset:21504
	ds_read_b128 v[192:195], v150 offset:22528
	ds_read_b128 v[198:201], v150 offset:23552
	global_load_lds_dwordx4 v[220:221], off
	s_mov_b32 m0, s25
	s_setprio 1
	global_load_lds_dwordx4 v[222:223], off
	s_waitcnt vmcnt(10)
	s_barrier
	s_waitcnt lgkmcnt(7)
	v_mfma_f32_16x16x32_bf16 v[60:63], v[152:155], v[168:171], v[60:63]
	v_mfma_f32_16x16x32_bf16 v[56:59], v[160:163], v[168:171], v[56:59]
	s_waitcnt lgkmcnt(5)
	v_mfma_f32_16x16x32_bf16 v[44:47], v[152:155], v[176:179], v[44:47]
	v_mfma_f32_16x16x32_bf16 v[40:43], v[160:163], v[176:179], v[40:43]
	s_waitcnt lgkmcnt(3)
	v_mfma_f32_16x16x32_bf16 v[28:31], v[152:155], v[184:187], v[28:31]
	v_mfma_f32_16x16x32_bf16 v[24:27], v[160:163], v[184:187], v[24:27]
	s_waitcnt lgkmcnt(1)
	v_mfma_f32_16x16x32_bf16 v[12:15], v[152:155], v[192:195], v[12:15]
	v_mfma_f32_16x16x32_bf16 v[8:11], v[160:163], v[192:195], v[8:11]
	v_mfma_f32_16x16x32_bf16 v[60:63], v[156:159], v[172:175], v[60:63]
	s_add_u32 s8, s12, 0x160000
	s_addc_u32 s9, s13, 0
	v_mfma_f32_16x16x32_bf16 v[56:59], v[164:167], v[172:175], v[56:59]
	s_add_i32 s39, s36, s22
	v_mfma_f32_16x16x32_bf16 v[44:47], v[156:159], v[180:183], v[44:47]
	v_mfma_f32_16x16x32_bf16 v[40:43], v[164:167], v[180:183], v[40:43]
	v_mfma_f32_16x16x32_bf16 v[28:31], v[156:159], v[188:191], v[28:31]
	v_mfma_f32_16x16x32_bf16 v[24:27], v[164:167], v[188:191], v[24:27]
	s_waitcnt lgkmcnt(0)
	v_mfma_f32_16x16x32_bf16 v[12:15], v[156:159], v[198:201], v[12:15]
	v_mfma_f32_16x16x32_bf16 v[8:11], v[164:167], v[198:201], v[8:11]
	s_barrier
; #define PG8_STAGE(bufoff, gbase, voff) do { _Pragma("unroll") for (int _i = 0; _i < 2; ++_i) \
;         __builtin_amdgcn_global_load_lds((const unsigned*)((const char*)(gbase) + (voff)[_i]), (LAS unsigned*)(lds + (bufoff) + ldsw + _i * 8192), 16, 0, 0); } while (0)
; #define PG8_LDA(dst, b, h) do { _Pragma("unroll") for (int m = 0; m < 4; ++m) _Pragma("unroll") for (int k = 0; k < 2; ++k) dst[m][k] = *(const LAS bf16x8*)(lds + PG8_SA(b, h) + aoff + m * 2048 + k * 1024); } while (0)
; #define PG8_LDB(dst, b, h) do { _Pragma("unroll") for (int n = 0; n < 2; ++n) _Pragma("unroll") for (int k = 0; k < 2; ++k) dst[n][k] = *(const LAS bf16x8*)(lds + PG8_SB(b, h) + boff + n * 2048 + k * 1024); } while (0)
; #define PG8_MMA(ai, bj, At, Bt) do { __builtin_amdgcn_s_setprio(1); _Pragma("unroll") for (int m = 0; m < 4; ++m) _Pragma("unroll") for (int n = 0; n < 2; ++n) _Pragma("unroll") for (int k = 0; k < 2; ++k) \
;         acc[ai][bj][m][n] = __builtin_amdgcn_mfma_f32_16x16x32_bf16(Bt[n][k], At[m][k], acc[ai][bj][m][n], 0, 0, 0); __builtin_amdgcn_s_setprio(0); } while (0)
; #define PG8_WAIT_V(n) asm volatile("s_waitcnt vmcnt(" #n ")" ::: "memory")
; #define PG8_WAIT_L(n) asm volatile("s_waitcnt lgkmcnt(" #n ")" ::: "memory")
; #define PG8_BAR __builtin_amdgcn_s_barrier()
; #define PG8_SCHED __builtin_amdgcn_sched_barrier(0)
; template <class Map, class Epi>
; DI void gemm_phase(LAS unsigned char* lds, const Map& MP, const Epi& E, const int nM, const int nN, const int K, const int lda, const int ldb) {
;     ...
;             PG8_WAIT_V(6); PG8_BAR; PG8_MMA(1, 1, At, B1); PG8_BAR;
;             PG8_LDB(B0, 1, 0); PG8_SCHED; PG8_LDA(At, 1, 0); PG8_STAGE(PG8_SA(0, 1), a2 + hstepA, voffA);
;             PG8_WAIT_L(8); PG8_BAR; PG8_WAIT_L(0); PG8_MMA(0, 0, At, B0); PG8_BAR; PG8_SCHED;
;             PG8_LDB(B1, 1, 1); PG8_STAGE(PG8_SB(1, 0), b3, voffB);
;             PG8_BAR; PG8_WAIT_L(0); PG8_MMA(0, 1, At, B1); PG8_BAR;
;             PG8_LDA(At, 1, 1); PG8_STAGE(PG8_SA(1, 0), a3, voffA);
;             PG8_BAR; PG8_WAIT_L(0); PG8_MMA(1, 0, At, B0); PG8_BAR; PG8_SCHED;
;             PG8_STAGE(PG8_SB(1, 1), b3 + hstepB, voffB);
;             PG8_WAIT_V(6); PG8_BAR; PG8_MMA(1, 1, At, B1); PG8_BAR;
	s_setprio 0
	s_mov_b32 m0, s39
	s_nop 0
	global_load_lds_dwordx4 v132, s[8:9]
	s_add_i32 m0, s39, 0x2000
	s_setprio 1
	global_load_lds_dwordx4 v128, s[8:9]
	s_waitcnt vmcnt(6)
	s_barrier
	v_mfma_f32_16x16x32_bf16 v[52:55], v[202:205], v[168:171], v[52:55]
	v_mfma_f32_16x16x32_bf16 v[48:51], v[210:213], v[168:171], v[48:51]
	s_add_i32 s39, 0, 0x18000
	v_add_u32_e32 v164, s39, v148
	ds_read_b128 v[152:155], v164
	v_mfma_f32_16x16x32_bf16 v[36:39], v[202:205], v[176:179], v[36:39]
	v_mfma_f32_16x16x32_bf16 v[32:35], v[210:213], v[176:179], v[32:35]
	ds_read_b128 v[156:159], v164 offset:1024
	v_mfma_f32_16x16x32_bf16 v[20:23], v[202:205], v[184:187], v[20:23]
	v_mfma_f32_16x16x32_bf16 v[16:19], v[210:213], v[184:187], v[16:19]
	ds_read_b128 v[160:163], v164 offset:2048
	v_mfma_f32_16x16x32_bf16 v[4:7], v[202:205], v[192:195], v[4:7]
	v_mfma_f32_16x16x32_bf16 v[0:3], v[210:213], v[192:195], v[0:3]
	ds_read_b128 v[164:167], v164 offset:3072
	v_mfma_f32_16x16x32_bf16 v[52:55], v[206:209], v[172:175], v[52:55]
	s_add_u32 s8, s14, 0x160000
	s_addc_u32 s9, s15, 0
	v_mfma_f32_16x16x32_bf16 v[48:51], v[214:217], v[172:175], v[48:51]
	v_mfma_f32_16x16x32_bf16 v[36:39], v[206:209], v[180:183], v[36:39]
	v_mfma_f32_16x16x32_bf16 v[32:35], v[214:217], v[180:183], v[32:35]
	v_mfma_f32_16x16x32_bf16 v[20:23], v[206:209], v[188:191], v[20:23]
	v_mfma_f32_16x16x32_bf16 v[16:19], v[214:217], v[188:191], v[16:19]
	v_mfma_f32_16x16x32_bf16 v[4:7], v[206:209], v[198:201], v[4:7]
	v_mfma_f32_16x16x32_bf16 v[0:3], v[214:217], v[198:201], v[0:3]
	s_barrier
	s_setprio 0
	s_mov_b32 m0, s26
	ds_read_b128 v[168:171], v150 offset:32768
	ds_read_b128 v[172:175], v150 offset:33792
	ds_read_b128 v[176:179], v150 offset:34816
	ds_read_b128 v[180:183], v150 offset:35840
	ds_read_b128 v[184:187], v150 offset:36864
	ds_read_b128 v[188:191], v150 offset:37888
	ds_read_b128 v[192:195], v150 offset:38912
	ds_read_b128 v[198:201], v150 offset:39936
	global_load_lds_dwordx4 v134, s[8:9]
	s_mov_b32 m0, s27
	s_setprio 1
	global_load_lds_dwordx4 v130, s[8:9]
	s_waitcnt lgkmcnt(8)
	s_barrier
	s_waitcnt lgkmcnt(7)
	v_mfma_f32_16x16x32_bf16 v[124:127], v[152:155], v[168:171], v[124:127]
	v_mfma_f32_16x16x32_bf16 v[120:123], v[160:163], v[168:171], v[120:123]
	s_waitcnt lgkmcnt(5)
	v_mfma_f32_16x16x32_bf16 v[108:111], v[152:155], v[176:179], v[108:111]
	v_mfma_f32_16x16x32_bf16 v[104:107], v[160:163], v[176:179], v[104:107]
	s_waitcnt lgkmcnt(3)
	v_mfma_f32_16x16x32_bf16 v[92:95], v[152:155], v[184:187], v[92:95]
	v_mfma_f32_16x16x32_bf16 v[88:91], v[160:163], v[184:187], v[88:91]
	s_waitcnt lgkmcnt(1)
	v_mfma_f32_16x16x32_bf16 v[76:79], v[152:155], v[192:195], v[76:79]
	v_mfma_f32_16x16x32_bf16 v[72:75], v[160:163], v[192:195], v[72:75]
	v_mfma_f32_16x16x32_bf16 v[124:127], v[156:159], v[172:175], v[124:127]
	s_add_i32 s14, 0, 0x1c000
	v_mfma_f32_16x16x32_bf16 v[120:123], v[164:167], v[172:175], v[120:123]
	s_add_i32 s8, s39, s22
	v_mfma_f32_16x16x32_bf16 v[108:111], v[156:159], v[180:183], v[108:111]
	v_add_u32_e32 v196, s14, v148
	v_mfma_f32_16x16x32_bf16 v[104:107], v[164:167], v[180:183], v[104:107]
	v_lshl_add_u64 v[144:145], v[144:145], 0, s[52:53]
	v_mfma_f32_16x16x32_bf16 v[92:95], v[156:159], v[188:191], v[92:95]
	v_mfma_f32_16x16x32_bf16 v[88:91], v[164:167], v[188:191], v[88:91]
	s_waitcnt lgkmcnt(0)
	v_mfma_f32_16x16x32_bf16 v[76:79], v[156:159], v[198:201], v[76:79]
	v_mfma_f32_16x16x32_bf16 v[72:75], v[164:167], v[198:201], v[72:75]
	s_barrier
	s_setprio 0
	s_mov_b32 m0, s8
	ds_read_b128 v[202:205], v196
	ds_read_b128 v[206:209], v196 offset:1024
	ds_read_b128 v[210:213], v196 offset:2048
	ds_read_b128 v[214:217], v196 offset:3072
	global_load_lds_dwordx4 v[144:145], off
	v_lshl_add_u64 v[144:145], v[218:219], 0, s[52:53]
	s_add_i32 m0, s8, 0x2000
	s_setprio 1
	global_load_lds_dwordx4 v[144:145], off
	s_barrier
	s_waitcnt lgkmcnt(3)
	v_mfma_f32_16x16x32_bf16 v[116:119], v[202:205], v[168:171], v[116:119]
	s_waitcnt lgkmcnt(1)
	v_mfma_f32_16x16x32_bf16 v[112:115], v[210:213], v[168:171], v[112:115]
	v_mfma_f32_16x16x32_bf16 v[100:103], v[202:205], v[176:179], v[100:103]
	v_mfma_f32_16x16x32_bf16 v[96:99], v[210:213], v[176:179], v[96:99]
	v_mfma_f32_16x16x32_bf16 v[84:87], v[202:205], v[184:187], v[84:87]
	v_mfma_f32_16x16x32_bf16 v[80:83], v[210:213], v[184:187], v[80:83]
	v_mfma_f32_16x16x32_bf16 v[68:71], v[202:205], v[192:195], v[68:71]
	v_mfma_f32_16x16x32_bf16 v[64:67], v[210:213], v[192:195], v[64:67]
	v_mfma_f32_16x16x32_bf16 v[116:119], v[206:209], v[172:175], v[116:119]
	s_mov_b32 m0, s30
	s_waitcnt lgkmcnt(0)
	v_mfma_f32_16x16x32_bf16 v[112:115], v[214:217], v[172:175], v[112:115]
	v_lshl_add_u64 v[144:145], v[220:221], 0, s[52:53]
	v_mfma_f32_16x16x32_bf16 v[100:103], v[206:209], v[180:183], v[100:103]
	v_mfma_f32_16x16x32_bf16 v[96:99], v[214:217], v[180:183], v[96:99]
	v_mfma_f32_16x16x32_bf16 v[84:87], v[206:209], v[188:191], v[84:87]
	v_mfma_f32_16x16x32_bf16 v[80:83], v[214:217], v[188:191], v[80:83]
	v_mfma_f32_16x16x32_bf16 v[68:71], v[206:209], v[198:201], v[68:71]
	v_mfma_f32_16x16x32_bf16 v[64:67], v[214:217], v[198:201], v[64:67]
	s_barrier
	s_setprio 0
	ds_read_b128 v[168:171], v150 offset:49152
	ds_read_b128 v[172:175], v150 offset:50176
	ds_read_b128 v[176:179], v150 offset:51200
	ds_read_b128 v[180:183], v150 offset:52224
	ds_read_b128 v[184:187], v150 offset:53248
	ds_read_b128 v[188:191], v150 offset:54272
	ds_read_b128 v[192:195], v150 offset:55296
	ds_read_b128 v[198:201], v150 offset:56320
	global_load_lds_dwordx4 v[144:145], off
	v_lshl_add_u64 v[144:145], v[222:223], 0, s[52:53]
	s_mov_b32 m0, s31
	s_setprio 1
	global_load_lds_dwordx4 v[144:145], off
	s_waitcnt vmcnt(10)
	s_barrier
; DI unsigned pack2(float a, float b) { f32x2 v = {a, b}; hwbf16x2 r = __builtin_convertvector(v, hwbf16x2); return __builtin_bit_cast(unsigned, r); }
; DI float bflo(unsigned w) { return __uint_as_float(w << 16); }
; DI float bfhi(unsigned w) { return __uint_as_float(w & 0xffff0000u); }
; #define PG8_WAIT_V(n) asm volatile("s_waitcnt vmcnt(" #n ")" ::: "memory")
; #define PG8_BAR __builtin_amdgcn_s_barrier()
;     DI void operator()(const f32x4 (&acc)[2][2][4][2], const Unit& u, int wr, int wc, int fr, int fq) const {
;     ...
;         for (int ai = 0; ai < 2; ++ai)
; #pragma unroll
;             for (int m = 0; m < 4; ++m) { const size_t ro = (size_t)(row0 + ai * HALF + m * 16) * D + col0;
; #pragma unroll
;                 for (int bj = 0; bj < 2; ++bj) {
;                     f32x4 x0, x1;
;                     if constexpr (IB) { const u32x4 w = *(const u32x4*)((const bf16_t*)Xin + ro + bj * HALF);
;                         x0 = (f32x4){bflo(w[0]), bfhi(w[0]), bflo(w[1]), bfhi(w[1])}; x1 = (f32x4){bflo(w[2]), bfhi(w[2]), bflo(w[3]), bfhi(w[3])}; }
;                     else { x0 = *(const f32x4*)((const float*)Xin + ro + bj * HALF); x1 = *(const f32x4*)((const float*)Xin + ro + bj * HALF + 4); }
;                     x0 += acc[ai][bj][m][0] * sc[bj][0]; x1 += acc[ai][bj][m][1] * sc[bj][1];
;                     if constexpr (OB) { u32x4 o; o[0] = pack2(x0[0], x0[1]); o[1] = pack2(x0[2], x0[3]); o[2] = pack2(x1[0], x1[1]); o[3] = pack2(x1[2], x1[3]);
;                         *(u32x4*)((bf16_t*)Xout + ro + bj * HALF) = o; }
;                     else { *(f32x4*)((float*)Xout + ro + bj * HALF) = x0; *(f32x4*)((float*)Xout + ro + bj * HALF + 4) = x1; } } }
; template <class Map, class Epi>
; DI void gemm_phase(LAS unsigned char* lds, const Map& MP, const Epi& E, const int nM, const int nN, const int K, const int lda, const int ldb) {
;     ...
;             PG8_WAIT_L(8); PG8_BAR; PG8_WAIT_L(0); PG8_MMA(0, 0, At, B0); PG8_BAR; PG8_SCHED;
;             PG8_LDB(B1, 1, 1); PG8_STAGE(PG8_SB(1, 0), b3, voffB);
;             PG8_BAR; PG8_WAIT_L(0); PG8_MMA(0, 1, At, B1); PG8_BAR;
;             PG8_LDA(At, 1, 1); PG8_STAGE(PG8_SA(1, 0), a3, voffA);
;             PG8_BAR; PG8_WAIT_L(0); PG8_MMA(1, 0, At, B0); PG8_BAR; PG8_SCHED;
;             PG8_STAGE(PG8_SB(1, 1), b3 + hstepB, voffB);
;             PG8_WAIT_V(6); PG8_BAR; PG8_MMA(1, 1, At, B1); PG8_BAR;
	s_waitcnt lgkmcnt(7)
	v_mfma_f32_16x16x32_bf16 v[60:63], v[152:155], v[168:171], v[60:63]
	v_mfma_f32_16x16x32_bf16 v[56:59], v[160:163], v[168:171], v[56:59]
	s_waitcnt lgkmcnt(5)
	v_mfma_f32_16x16x32_bf16 v[44:47], v[152:155], v[176:179], v[44:47]
	v_mfma_f32_16x16x32_bf16 v[40:43], v[160:163], v[176:179], v[40:43]
	s_waitcnt lgkmcnt(3)
	v_mfma_f32_16x16x32_bf16 v[28:31], v[152:155], v[184:187], v[28:31]
	v_mfma_f32_16x16x32_bf16 v[24:27], v[160:163], v[184:187], v[24:27]
	s_waitcnt lgkmcnt(1)
	v_mfma_f32_16x16x32_bf16 v[12:15], v[152:155], v[192:195], v[12:15]
	v_mfma_f32_16x16x32_bf16 v[8:11], v[160:163], v[192:195], v[8:11]
	v_mfma_f32_16x16x32_bf16 v[60:63], v[156:159], v[172:175], v[60:63]
	s_add_u32 s8, s12, 0x160080
	s_addc_u32 s9, s13, 0
	v_mfma_f32_16x16x32_bf16 v[56:59], v[164:167], v[172:175], v[56:59]
	s_add_i32 s12, s14, s22
	v_mfma_f32_16x16x32_bf16 v[44:47], v[156:159], v[180:183], v[44:47]
	v_mfma_f32_16x16x32_bf16 v[40:43], v[164:167], v[180:183], v[40:43]
	v_mfma_f32_16x16x32_bf16 v[28:31], v[156:159], v[188:191], v[28:31]
	v_mfma_f32_16x16x32_bf16 v[24:27], v[164:167], v[188:191], v[24:27]
	s_waitcnt lgkmcnt(0)
	v_mfma_f32_16x16x32_bf16 v[12:15], v[156:159], v[198:201], v[12:15]
	v_mfma_f32_16x16x32_bf16 v[8:11], v[164:167], v[198:201], v[8:11]
	s_barrier
	s_setprio 0
	s_mov_b32 m0, s12
	s_nop 0
	global_load_lds_dwordx4 v132, s[8:9]
	s_add_i32 m0, s12, 0x2000
	s_setprio 1
	global_load_lds_dwordx4 v128, s[8:9]
	s_waitcnt vmcnt(6)
	s_barrier
	v_mfma_f32_16x16x32_bf16 v[52:55], v[202:205], v[168:171], v[52:55]
	v_mfma_f32_16x16x32_bf16 v[48:51], v[210:213], v[168:171], v[48:51]
	ds_read_b128 v[152:155], v149
	v_mfma_f32_16x16x32_bf16 v[36:39], v[202:205], v[176:179], v[36:39]
	v_mfma_f32_16x16x32_bf16 v[32:35], v[210:213], v[176:179], v[32:35]
	ds_read_b128 v[156:159], v149 offset:1024
	v_mfma_f32_16x16x32_bf16 v[20:23], v[202:205], v[184:187], v[20:23]
	v_mfma_f32_16x16x32_bf16 v[16:19], v[210:213], v[184:187], v[16:19]
	ds_read_b128 v[160:163], v149 offset:2048
	v_mfma_f32_16x16x32_bf16 v[4:7], v[202:205], v[192:195], v[4:7]
	v_mfma_f32_16x16x32_bf16 v[0:3], v[210:213], v[192:195], v[0:3]
	ds_read_b128 v[164:167], v149 offset:3072
	v_mfma_f32_16x16x32_bf16 v[52:55], v[206:209], v[172:175], v[52:55]
	s_add_i32 s3, s3, 2
	v_mfma_f32_16x16x32_bf16 v[48:51], v[214:217], v[172:175], v[48:51]
	s_add_u32 s5, s5, 0x100
	s_addc_u32 s38, s38, 0
	v_mfma_f32_16x16x32_bf16 v[36:39], v[206:209], v[180:183], v[36:39]
	s_cmpk_gt_u32 s3, 0x55
	v_mfma_f32_16x16x32_bf16 v[32:35], v[214:217], v[180:183], v[32:35]
	s_mov_b64 s[8:9], s[10:11]
	v_mfma_f32_16x16x32_bf16 v[20:23], v[206:209], v[188:191], v[20:23]
	v_mfma_f32_16x16x32_bf16 v[16:19], v[214:217], v[188:191], v[16:19]
	v_mfma_f32_16x16x32_bf16 v[4:7], v[206:209], v[198:201], v[4:7]
	v_mfma_f32_16x16x32_bf16 v[0:3], v[214:217], v[198:201], v[0:3]
	s_barrier
	s_setprio 0
	s_cbranch_scc0 .LBB1_550
	s_waitcnt lgkmcnt(0)
	v_mov_b32_e32 v144, v146
	v_mov_b32_e32 v152, v147
	s_lshl_b32 s2, s2, 8
	s_add_i32 s2, s2, s29
	s_lshl_b32 s3, s4, 8
	v_add_u32_e32 v152, s2, v152
	s_or_b32 s3, s3, s54
	v_ashrrev_i32_e32 v153, 31, v152
	v_lshl_add_u32 v144, v144, 3, s3
	v_lshlrev_b64 v[152:153], 12, v[152:153]
	v_ashrrev_i32_e32 v145, 31, v144
	v_lshl_add_u64 v[152:153], s[46:47], 0, v[152:153]
	v_lshl_add_u64 v[144:145], v[144:145], 1, v[152:153]
	global_load_dwordx4 v[160:163], v[144:145], off
	global_load_dwordx4 v[164:167], v[144:145], off offset:256
	s_mov_b64 s[98:99], 0x10000
	v_lshl_add_u64 v[154:155], v[144:145], 0, s[98:99]
	global_load_dwordx4 v[168:171], v[154:155], off
	global_load_dwordx4 v[172:175], v[154:155], off offset:256
	s_mov_b64 s[98:99], 0x20000
	v_lshl_add_u64 v[154:155], v[144:145], 0, s[98:99]
	global_load_dwordx4 v[176:179], v[154:155], off
	global_load_dwordx4 v[180:183], v[154:155], off offset:256
	s_mov_b64 s[98:99], 0x30000
	v_lshl_add_u64 v[154:155], v[144:145], 0, s[98:99]
	global_load_dwordx4 v[184:187], v[154:155], off
	global_load_dwordx4 v[188:191], v[154:155], off offset:256
	s_mov_b64 s[98:99], 0x80000
	v_lshl_add_u64 v[154:155], v[144:145], 0, s[98:99]
	global_load_dwordx4 v[192:195], v[154:155], off
	global_load_dwordx4 v[198:201], v[154:155], off offset:256
	s_mov_b64 s[98:99], 0x90000
	v_lshl_add_u64 v[154:155], v[144:145], 0, s[98:99]
	global_load_dwordx4 v[202:205], v[154:155], off
	global_load_dwordx4 v[206:209], v[154:155], off offset:256
	s_mov_b64 s[98:99], 0xa0000
	v_lshl_add_u64 v[154:155], v[144:145], 0, s[98:99]
	global_load_dwordx4 v[210:213], v[154:155], off
	global_load_dwordx4 v[214:217], v[154:155], off offset:256
	s_mov_b64 s[98:99], 0xb0000
	v_lshl_add_u64 v[154:155], v[144:145], 0, s[98:99]
	global_load_dwordx4 v[248:251], v[154:155], off
	global_load_dwordx4 v[252:255], v[154:155], off offset:256
	s_waitcnt vmcnt(15)
	s_nop 1
	v_mov_b32_e32 v152, v160
	v_mov_b32_e32 v153, v161
	v_mov_b32_e32 v154, v162
	v_mov_b32_e32 v155, v163
	s_mov_b64 s[2:3], 0x10000
	s_mov_b32 s4, s37
	s_mov_b64 s[10:11], s[6:7]
	s_mov_b64 s[8:9], s[42:43]
	s_waitcnt lgkmcnt(0)
	v_lshlrev_b32_e32 v156, 16, v152
	v_and_b32_e32 v157, 0xffff0000, v152
	v_lshlrev_b32_e32 v152, 16, v153
	v_and_b32_e32 v153, 0xffff0000, v153
	v_lshlrev_b32_e32 v158, 16, v154
	v_and_b32_e32 v159, 0xffff0000, v154
	v_lshlrev_b32_e32 v154, 16, v155
	v_and_b32_e32 v155, 0xffff0000, v155
	v_pk_add_f32 v[126:127], v[126:127], v[152:153]
	v_pk_add_f32 v[124:125], v[124:125], v[156:157]
	v_pk_add_f32 v[152:153], v[122:123], v[154:155]
	v_pk_add_f32 v[122:123], v[120:121], v[158:159]
	v_cvt_pk_bf16_f32 v120, v124, v125
	v_cvt_pk_bf16_f32 v121, v126, v127
	v_cvt_pk_bf16_f32 v122, v122, v123
	v_cvt_pk_bf16_f32 v123, v152, v153
	global_store_dwordx4 v[144:145], v[120:123], off
	s_waitcnt vmcnt(15)
; DI unsigned pack2(float a, float b) { f32x2 v = {a, b}; hwbf16x2 r = __builtin_convertvector(v, hwbf16x2); return __builtin_bit_cast(unsigned, r); }
; DI float bflo(unsigned w) { return __uint_as_float(w << 16); }
; DI float bfhi(unsigned w) { return __uint_as_float(w & 0xffff0000u); }
;     DI void operator()(const f32x4 (&acc)[2][2][4][2], const Unit& u, int wr, int wc, int fr, int fq) const {
;     ...
;         for (int ai = 0; ai < 2; ++ai)
; #pragma unroll
;             for (int m = 0; m < 4; ++m) { const size_t ro = (size_t)(row0 + ai * HALF + m * 16) * D + col0;
; #pragma unroll
;                 for (int bj = 0; bj < 2; ++bj) {
;                     f32x4 x0, x1;
;                     if constexpr (IB) { const u32x4 w = *(const u32x4*)((const bf16_t*)Xin + ro + bj * HALF);
;                         x0 = (f32x4){bflo(w[0]), bfhi(w[0]), bflo(w[1]), bfhi(w[1])}; x1 = (f32x4){bflo(w[2]), bfhi(w[2]), bflo(w[3]), bfhi(w[3])}; }
;                     else { x0 = *(const f32x4*)((const float*)Xin + ro + bj * HALF); x1 = *(const f32x4*)((const float*)Xin + ro + bj * HALF + 4); }
;                     x0 += acc[ai][bj][m][0] * sc[bj][0]; x1 += acc[ai][bj][m][1] * sc[bj][1];
;                     if constexpr (OB) { u32x4 o; o[0] = pack2(x0[0], x0[1]); o[1] = pack2(x0[2], x0[3]); o[2] = pack2(x1[0], x1[1]); o[3] = pack2(x1[2], x1[3]);
;                         *(u32x4*)((bf16_t*)Xout + ro + bj * HALF) = o; }
;                     else { *(f32x4*)((float*)Xout + ro + bj * HALF) = x0; *(f32x4*)((float*)Xout + ro + bj * HALF + 4) = x1; } } }
	s_nop 1
	v_mov_b32_e32 v120, v164
	v_mov_b32_e32 v121, v165
	v_mov_b32_e32 v122, v166
	v_mov_b32_e32 v123, v167
	s_waitcnt lgkmcnt(0)
	v_lshlrev_b32_e32 v124, 16, v120
	v_and_b32_e32 v125, 0xffff0000, v120
	v_lshlrev_b32_e32 v120, 16, v121
	v_and_b32_e32 v121, 0xffff0000, v121
	v_lshlrev_b32_e32 v126, 16, v122
	v_and_b32_e32 v127, 0xffff0000, v122
	v_lshlrev_b32_e32 v122, 16, v123
	v_and_b32_e32 v123, 0xffff0000, v123
	v_pk_add_f32 v[116:117], v[116:117], v[124:125]
	v_pk_add_f32 v[118:119], v[118:119], v[120:121]
	v_pk_add_f32 v[120:121], v[114:115], v[122:123]
	v_pk_add_f32 v[114:115], v[112:113], v[126:127]
	v_cvt_pk_bf16_f32 v112, v116, v117
	v_lshl_add_u64 v[116:117], v[144:145], 0, s[2:3]
	s_mov_b32 s2, 0x10000
	v_cvt_pk_bf16_f32 v113, v118, v119
	v_add_co_u32_e32 v118, vcc, s2, v144
	v_cvt_pk_bf16_f32 v114, v114, v115
	v_cvt_pk_bf16_f32 v115, v120, v121
	v_addc_co_u32_e32 v119, vcc, 0, v145, vcc
	global_store_dwordx4 v[144:145], v[112:115], off offset:256
	s_waitcnt vmcnt(15)
	s_nop 1
	v_mov_b32_e32 v112, v168
	v_mov_b32_e32 v113, v169
	v_mov_b32_e32 v114, v170
	v_mov_b32_e32 v115, v171
	s_mov_b64 s[2:3], 0x20000
	s_waitcnt lgkmcnt(0)
	v_lshlrev_b32_e32 v120, 16, v112
	v_and_b32_e32 v121, 0xffff0000, v112
	v_lshlrev_b32_e32 v112, 16, v113
	v_and_b32_e32 v113, 0xffff0000, v113
	v_lshlrev_b32_e32 v122, 16, v114
	v_and_b32_e32 v123, 0xffff0000, v114
	v_lshlrev_b32_e32 v114, 16, v115
	v_and_b32_e32 v115, 0xffff0000, v115
	v_pk_add_f32 v[110:111], v[110:111], v[112:113]
	v_pk_add_f32 v[108:109], v[108:109], v[120:121]
	v_pk_add_f32 v[112:113], v[106:107], v[114:115]
	v_pk_add_f32 v[106:107], v[104:105], v[122:123]
	v_cvt_pk_bf16_f32 v104, v108, v109
	v_cvt_pk_bf16_f32 v105, v110, v111
	v_cvt_pk_bf16_f32 v106, v106, v107
	v_cvt_pk_bf16_f32 v107, v112, v113
	global_store_dwordx4 v[118:119], v[104:107], off
	s_waitcnt vmcnt(15)
	s_nop 1
	v_mov_b32_e32 v104, v172
	v_mov_b32_e32 v105, v173
	v_mov_b32_e32 v106, v174
	v_mov_b32_e32 v107, v175
	s_waitcnt lgkmcnt(0)
	v_lshlrev_b32_e32 v108, 16, v104
	v_and_b32_e32 v109, 0xffff0000, v104
	v_lshlrev_b32_e32 v104, 16, v105
	v_and_b32_e32 v105, 0xffff0000, v105
	v_lshlrev_b32_e32 v110, 16, v106
	v_and_b32_e32 v111, 0xffff0000, v106
	v_lshlrev_b32_e32 v106, 16, v107
	v_and_b32_e32 v107, 0xffff0000, v107
	v_pk_add_f32 v[100:101], v[100:101], v[108:109]
	v_pk_add_f32 v[102:103], v[102:103], v[104:105]
	v_pk_add_f32 v[104:105], v[98:99], v[106:107]
	v_pk_add_f32 v[98:99], v[96:97], v[110:111]
	v_cvt_pk_bf16_f32 v96, v100, v101
	v_lshl_add_u64 v[100:101], v[144:145], 0, s[2:3]
	s_mov_b32 s2, 0x20000
	v_cvt_pk_bf16_f32 v97, v102, v103
	v_add_co_u32_e32 v102, vcc, s2, v144
	v_cvt_pk_bf16_f32 v98, v98, v99
	v_cvt_pk_bf16_f32 v99, v104, v105
	v_addc_co_u32_e32 v103, vcc, 0, v145, vcc
	global_store_dwordx4 v[116:117], v[96:99], off offset:256
	s_waitcnt vmcnt(15)
	s_nop 1
	v_mov_b32_e32 v96, v176
	v_mov_b32_e32 v97, v177
	v_mov_b32_e32 v98, v178
	v_mov_b32_e32 v99, v179
	s_mov_b64 s[2:3], 0x30000
	s_waitcnt lgkmcnt(0)
	v_lshlrev_b32_e32 v104, 16, v96
	v_and_b32_e32 v105, 0xffff0000, v96
	v_lshlrev_b32_e32 v96, 16, v97
	v_and_b32_e32 v97, 0xffff0000, v97
	v_lshlrev_b32_e32 v106, 16, v98
	v_and_b32_e32 v107, 0xffff0000, v98
	v_lshlrev_b32_e32 v98, 16, v99
	v_and_b32_e32 v99, 0xffff0000, v99
	v_pk_add_f32 v[94:95], v[94:95], v[96:97]
	v_pk_add_f32 v[92:93], v[92:93], v[104:105]
	v_pk_add_f32 v[96:97], v[90:91], v[98:99]
	v_pk_add_f32 v[90:91], v[88:89], v[106:107]
	v_cvt_pk_bf16_f32 v88, v92, v93
	v_cvt_pk_bf16_f32 v89, v94, v95
	v_cvt_pk_bf16_f32 v90, v90, v91
	v_cvt_pk_bf16_f32 v91, v96, v97
	global_store_dwordx4 v[102:103], v[88:91], off
	s_waitcnt vmcnt(15)
	s_nop 1
	v_mov_b32_e32 v88, v180
	v_mov_b32_e32 v89, v181
	v_mov_b32_e32 v90, v182
	v_mov_b32_e32 v91, v183
	s_waitcnt lgkmcnt(0)
	v_lshlrev_b32_e32 v92, 16, v88
	v_and_b32_e32 v93, 0xffff0000, v88
	v_lshlrev_b32_e32 v88, 16, v89
	v_and_b32_e32 v89, 0xffff0000, v89
	v_lshlrev_b32_e32 v94, 16, v90
	v_and_b32_e32 v95, 0xffff0000, v90
	v_lshlrev_b32_e32 v90, 16, v91
	v_and_b32_e32 v91, 0xffff0000, v91
	v_pk_add_f32 v[86:87], v[86:87], v[88:89]
	v_pk_add_f32 v[84:85], v[84:85], v[92:93]
	v_pk_add_f32 v[88:89], v[82:83], v[90:91]
	v_pk_add_f32 v[82:83], v[80:81], v[94:95]
	v_cvt_pk_bf16_f32 v80, v84, v85
	v_cvt_pk_bf16_f32 v81, v86, v87
	v_cvt_pk_bf16_f32 v82, v82, v83
	v_cvt_pk_bf16_f32 v83, v88, v89
	global_store_dwordx4 v[100:101], v[80:83], off offset:256
	s_nop 1
	v_lshl_add_u64 v[80:81], v[144:145], 0, s[2:3]
	s_mov_b32 s2, 0x30000
	v_add_co_u32_e32 v86, vcc, s2, v144
	s_mov_b64 s[2:3], 0x80000
	s_nop 0
	v_addc_co_u32_e32 v87, vcc, 0, v145, vcc
	s_waitcnt vmcnt(15)
	s_nop 1
	v_mov_b32_e32 v82, v184
	v_mov_b32_e32 v83, v185
	v_mov_b32_e32 v84, v186
	v_mov_b32_e32 v85, v187
	s_waitcnt lgkmcnt(0)
	v_lshlrev_b32_e32 v88, 16, v82
	v_and_b32_e32 v89, 0xffff0000, v82
	v_lshlrev_b32_e32 v82, 16, v83
	v_and_b32_e32 v83, 0xffff0000, v83
	v_lshlrev_b32_e32 v90, 16, v84
	v_and_b32_e32 v91, 0xffff0000, v84
	v_lshlrev_b32_e32 v84, 16, v85
	v_and_b32_e32 v85, 0xffff0000, v85
	v_pk_add_f32 v[78:79], v[78:79], v[82:83]
	v_pk_add_f32 v[76:77], v[76:77], v[88:89]
	v_pk_add_f32 v[82:83], v[74:75], v[84:85]
	v_pk_add_f32 v[74:75], v[72:73], v[90:91]
	v_cvt_pk_bf16_f32 v72, v76, v77
	v_cvt_pk_bf16_f32 v73, v78, v79
	v_cvt_pk_bf16_f32 v74, v74, v75
	v_cvt_pk_bf16_f32 v75, v82, v83
	global_store_dwordx4 v[86:87], v[72:75], off
	s_waitcnt vmcnt(15)
	s_nop 1
	v_mov_b32_e32 v72, v188
	v_mov_b32_e32 v73, v189
	v_mov_b32_e32 v74, v190
	v_mov_b32_e32 v75, v191
	s_waitcnt lgkmcnt(0)
; DI unsigned pack2(float a, float b) { f32x2 v = {a, b}; hwbf16x2 r = __builtin_convertvector(v, hwbf16x2); return __builtin_bit_cast(unsigned, r); }
; DI float bflo(unsigned w) { return __uint_as_float(w << 16); }
; DI float bfhi(unsigned w) { return __uint_as_float(w & 0xffff0000u); }
;     DI void operator()(const f32x4 (&acc)[2][2][4][2], const Unit& u, int wr, int wc, int fr, int fq) const {
;     ...
;         for (int ai = 0; ai < 2; ++ai)
; #pragma unroll
;             for (int m = 0; m < 4; ++m) { const size_t ro = (size_t)(row0 + ai * HALF + m * 16) * D + col0;
; #pragma unroll
;                 for (int bj = 0; bj < 2; ++bj) {
;                     f32x4 x0, x1;
;                     if constexpr (IB) { const u32x4 w = *(const u32x4*)((const bf16_t*)Xin + ro + bj * HALF);
;                         x0 = (f32x4){bflo(w[0]), bfhi(w[0]), bflo(w[1]), bfhi(w[1])}; x1 = (f32x4){bflo(w[2]), bfhi(w[2]), bflo(w[3]), bfhi(w[3])}; }
;                     else { x0 = *(const f32x4*)((const float*)Xin + ro + bj * HALF); x1 = *(const f32x4*)((const float*)Xin + ro + bj * HALF + 4); }
;                     x0 += acc[ai][bj][m][0] * sc[bj][0]; x1 += acc[ai][bj][m][1] * sc[bj][1];
;                     if constexpr (OB) { u32x4 o; o[0] = pack2(x0[0], x0[1]); o[1] = pack2(x0[2], x0[3]); o[2] = pack2(x1[0], x1[1]); o[3] = pack2(x1[2], x1[3]);
;                         *(u32x4*)((bf16_t*)Xout + ro + bj * HALF) = o; }
;                     else { *(f32x4*)((float*)Xout + ro + bj * HALF) = x0; *(f32x4*)((float*)Xout + ro + bj * HALF + 4) = x1; } } }
	v_lshlrev_b32_e32 v76, 16, v72
	v_and_b32_e32 v77, 0xffff0000, v72
	v_lshlrev_b32_e32 v72, 16, v73
	v_and_b32_e32 v73, 0xffff0000, v73
	v_lshlrev_b32_e32 v78, 16, v74
	v_and_b32_e32 v79, 0xffff0000, v74
	v_lshlrev_b32_e32 v74, 16, v75
	v_and_b32_e32 v75, 0xffff0000, v75
	v_pk_add_f32 v[70:71], v[70:71], v[72:73]
	v_pk_add_f32 v[68:69], v[68:69], v[76:77]
	v_pk_add_f32 v[72:73], v[66:67], v[74:75]
	v_pk_add_f32 v[66:67], v[64:65], v[78:79]
	v_cvt_pk_bf16_f32 v64, v68, v69
	v_cvt_pk_bf16_f32 v65, v70, v71
	v_cvt_pk_bf16_f32 v66, v66, v67
	v_cvt_pk_bf16_f32 v67, v72, v73
	global_store_dwordx4 v[80:81], v[64:67], off offset:256
	s_nop 1
	v_lshl_add_u64 v[64:65], v[144:145], 0, s[2:3]
	s_mov_b32 s2, 0x80000
	v_add_co_u32_e32 v70, vcc, s2, v144
	s_mov_b64 s[2:3], 0x90000
	s_nop 0
	v_addc_co_u32_e32 v71, vcc, 0, v145, vcc
	s_waitcnt vmcnt(15)
	s_nop 1
	v_mov_b32_e32 v66, v192
	v_mov_b32_e32 v67, v193
	v_mov_b32_e32 v68, v194
	v_mov_b32_e32 v69, v195
	s_waitcnt lgkmcnt(0)
	v_lshlrev_b32_e32 v72, 16, v66
	v_and_b32_e32 v73, 0xffff0000, v66
	v_lshlrev_b32_e32 v66, 16, v67
	v_and_b32_e32 v67, 0xffff0000, v67
	v_lshlrev_b32_e32 v74, 16, v68
	v_and_b32_e32 v75, 0xffff0000, v68
	v_lshlrev_b32_e32 v68, 16, v69
	v_and_b32_e32 v69, 0xffff0000, v69
	v_pk_add_f32 v[62:63], v[62:63], v[66:67]
	v_pk_add_f32 v[60:61], v[60:61], v[72:73]
	v_pk_add_f32 v[66:67], v[58:59], v[68:69]
	v_pk_add_f32 v[58:59], v[56:57], v[74:75]
	v_cvt_pk_bf16_f32 v56, v60, v61
	v_cvt_pk_bf16_f32 v57, v62, v63
	v_cvt_pk_bf16_f32 v58, v58, v59
	v_cvt_pk_bf16_f32 v59, v66, v67
	global_store_dwordx4 v[70:71], v[56:59], off
	s_waitcnt vmcnt(15)
	s_nop 1
	v_mov_b32_e32 v56, v198
	v_mov_b32_e32 v57, v199
	v_mov_b32_e32 v58, v200
	v_mov_b32_e32 v59, v201
	s_waitcnt lgkmcnt(0)
	v_lshlrev_b32_e32 v60, 16, v56
	v_and_b32_e32 v61, 0xffff0000, v56
	v_lshlrev_b32_e32 v56, 16, v57
	v_and_b32_e32 v57, 0xffff0000, v57
	v_lshlrev_b32_e32 v62, 16, v58
	v_and_b32_e32 v63, 0xffff0000, v58
	v_lshlrev_b32_e32 v58, 16, v59
	v_and_b32_e32 v59, 0xffff0000, v59
	v_pk_add_f32 v[54:55], v[54:55], v[56:57]
	v_pk_add_f32 v[52:53], v[52:53], v[60:61]
	v_pk_add_f32 v[56:57], v[50:51], v[58:59]
	v_pk_add_f32 v[50:51], v[48:49], v[62:63]
	v_cvt_pk_bf16_f32 v48, v52, v53
	v_cvt_pk_bf16_f32 v49, v54, v55
	v_cvt_pk_bf16_f32 v50, v50, v51
	v_cvt_pk_bf16_f32 v51, v56, v57
	global_store_dwordx4 v[64:65], v[48:51], off offset:256
	s_nop 1
	v_lshl_add_u64 v[48:49], v[144:145], 0, s[2:3]
	s_mov_b32 s2, 0x90000
	v_add_co_u32_e32 v54, vcc, s2, v144
	s_mov_b64 s[2:3], 0xa0000
	s_nop 0
	v_addc_co_u32_e32 v55, vcc, 0, v145, vcc
	s_waitcnt vmcnt(15)
	s_nop 1
	v_mov_b32_e32 v50, v202
	v_mov_b32_e32 v51, v203
	v_mov_b32_e32 v52, v204
	v_mov_b32_e32 v53, v205
	s_waitcnt lgkmcnt(0)
	v_lshlrev_b32_e32 v56, 16, v50
	v_and_b32_e32 v57, 0xffff0000, v50
	v_lshlrev_b32_e32 v50, 16, v51
	v_and_b32_e32 v51, 0xffff0000, v51
	v_lshlrev_b32_e32 v58, 16, v52
	v_and_b32_e32 v59, 0xffff0000, v52
	v_lshlrev_b32_e32 v52, 16, v53
	v_and_b32_e32 v53, 0xffff0000, v53
	v_pk_add_f32 v[46:47], v[46:47], v[50:51]
	v_pk_add_f32 v[44:45], v[44:45], v[56:57]
	v_pk_add_f32 v[50:51], v[42:43], v[52:53]
	v_pk_add_f32 v[42:43], v[40:41], v[58:59]
	v_cvt_pk_bf16_f32 v40, v44, v45
	v_cvt_pk_bf16_f32 v41, v46, v47
	v_cvt_pk_bf16_f32 v42, v42, v43
	v_cvt_pk_bf16_f32 v43, v50, v51
	global_store_dwordx4 v[54:55], v[40:43], off
	s_waitcnt vmcnt(15)
	s_nop 1
	v_mov_b32_e32 v40, v206
	v_mov_b32_e32 v41, v207
	v_mov_b32_e32 v42, v208
	v_mov_b32_e32 v43, v209
	s_waitcnt lgkmcnt(0)
; DI unsigned pack2(float a, float b) { f32x2 v = {a, b}; hwbf16x2 r = __builtin_convertvector(v, hwbf16x2); return __builtin_bit_cast(unsigned, r); }
; DI float bflo(unsigned w) { return __uint_as_float(w << 16); }
; DI float bfhi(unsigned w) { return __uint_as_float(w & 0xffff0000u); }
; #define PG8_WAIT_V(n) asm volatile("s_waitcnt vmcnt(" #n ")" ::: "memory")
; #define PG8_BAR __builtin_amdgcn_s_barrier()
;     DI void operator()(const f32x4 (&acc)[2][2][4][2], const Unit& u, int wr, int wc, int fr, int fq) const {
;     ...
;         for (int ai = 0; ai < 2; ++ai)
; #pragma unroll
;             for (int m = 0; m < 4; ++m) { const size_t ro = (size_t)(row0 + ai * HALF + m * 16) * D + col0;
; #pragma unroll
;                 for (int bj = 0; bj < 2; ++bj) {
;                     f32x4 x0, x1;
;                     if constexpr (IB) { const u32x4 w = *(const u32x4*)((const bf16_t*)Xin + ro + bj * HALF);
;                         x0 = (f32x4){bflo(w[0]), bfhi(w[0]), bflo(w[1]), bfhi(w[1])}; x1 = (f32x4){bflo(w[2]), bfhi(w[2]), bflo(w[3]), bfhi(w[3])}; }
;                     else { x0 = *(const f32x4*)((const float*)Xin + ro + bj * HALF); x1 = *(const f32x4*)((const float*)Xin + ro + bj * HALF + 4); }
;                     x0 += acc[ai][bj][m][0] * sc[bj][0]; x1 += acc[ai][bj][m][1] * sc[bj][1];
;                     if constexpr (OB) { u32x4 o; o[0] = pack2(x0[0], x0[1]); o[1] = pack2(x0[2], x0[3]); o[2] = pack2(x1[0], x1[1]); o[3] = pack2(x1[2], x1[3]);
;                         *(u32x4*)((bf16_t*)Xout + ro + bj * HALF) = o; }
;                     else { *(f32x4*)((float*)Xout + ro + bj * HALF) = x0; *(f32x4*)((float*)Xout + ro + bj * HALF + 4) = x1; } } }
; template <class Map, class Epi>
; DI void gemm_phase(LAS unsigned char* lds, const Map& MP, const Epi& E, const int nM, const int nN, const int K, const int lda, const int ldb) {
;     ...
;     PG8_WAIT_V(0);
;     if (wr == 0) PG8_BAR;
;     PG8_BAR;
	v_lshlrev_b32_e32 v44, 16, v40
	v_and_b32_e32 v45, 0xffff0000, v40
	v_lshlrev_b32_e32 v40, 16, v41
	v_and_b32_e32 v41, 0xffff0000, v41
	v_lshlrev_b32_e32 v46, 16, v42
	v_and_b32_e32 v47, 0xffff0000, v42
	v_lshlrev_b32_e32 v42, 16, v43
	v_and_b32_e32 v43, 0xffff0000, v43
	v_pk_add_f32 v[38:39], v[38:39], v[40:41]
	v_pk_add_f32 v[36:37], v[36:37], v[44:45]
	v_pk_add_f32 v[40:41], v[34:35], v[42:43]
	v_pk_add_f32 v[34:35], v[32:33], v[46:47]
	v_cvt_pk_bf16_f32 v32, v36, v37
	v_cvt_pk_bf16_f32 v33, v38, v39
	v_cvt_pk_bf16_f32 v34, v34, v35
	v_cvt_pk_bf16_f32 v35, v40, v41
	global_store_dwordx4 v[48:49], v[32:35], off offset:256
	s_nop 1
	v_lshl_add_u64 v[32:33], v[144:145], 0, s[2:3]
	s_mov_b32 s2, 0xa0000
	v_add_co_u32_e32 v38, vcc, s2, v144
	s_mov_b64 s[2:3], 0xb0000
	s_nop 0
	v_addc_co_u32_e32 v39, vcc, 0, v145, vcc
	s_waitcnt vmcnt(15)
	s_nop 1
	v_mov_b32_e32 v34, v210
	v_mov_b32_e32 v35, v211
	v_mov_b32_e32 v36, v212
	v_mov_b32_e32 v37, v213
	s_waitcnt lgkmcnt(0)
	v_lshlrev_b32_e32 v40, 16, v34
	v_and_b32_e32 v41, 0xffff0000, v34
	v_lshlrev_b32_e32 v34, 16, v35
	v_and_b32_e32 v35, 0xffff0000, v35
	v_lshlrev_b32_e32 v42, 16, v36
	v_and_b32_e32 v43, 0xffff0000, v36
	v_lshlrev_b32_e32 v36, 16, v37
	v_and_b32_e32 v37, 0xffff0000, v37
	v_pk_add_f32 v[30:31], v[30:31], v[34:35]
	v_pk_add_f32 v[28:29], v[28:29], v[40:41]
	v_pk_add_f32 v[34:35], v[26:27], v[36:37]
	v_pk_add_f32 v[26:27], v[24:25], v[42:43]
	v_cvt_pk_bf16_f32 v24, v28, v29
	v_cvt_pk_bf16_f32 v25, v30, v31
	v_cvt_pk_bf16_f32 v26, v26, v27
	v_cvt_pk_bf16_f32 v27, v34, v35
	global_store_dwordx4 v[38:39], v[24:27], off
	s_waitcnt vmcnt(15)
	s_nop 1
	v_mov_b32_e32 v24, v214
	v_mov_b32_e32 v25, v215
	v_mov_b32_e32 v26, v216
	v_mov_b32_e32 v27, v217
	s_waitcnt lgkmcnt(0)
	v_lshlrev_b32_e32 v28, 16, v24
	v_and_b32_e32 v29, 0xffff0000, v24
	v_lshlrev_b32_e32 v24, 16, v25
	v_and_b32_e32 v25, 0xffff0000, v25
	v_lshlrev_b32_e32 v30, 16, v26
	v_and_b32_e32 v31, 0xffff0000, v26
	v_lshlrev_b32_e32 v26, 16, v27
	v_and_b32_e32 v27, 0xffff0000, v27
	v_pk_add_f32 v[22:23], v[22:23], v[24:25]
	v_pk_add_f32 v[20:21], v[20:21], v[28:29]
	v_pk_add_f32 v[24:25], v[18:19], v[26:27]
	v_pk_add_f32 v[18:19], v[16:17], v[30:31]
	v_cvt_pk_bf16_f32 v16, v20, v21
	v_cvt_pk_bf16_f32 v17, v22, v23
	v_cvt_pk_bf16_f32 v18, v18, v19
	v_cvt_pk_bf16_f32 v19, v24, v25
	global_store_dwordx4 v[32:33], v[16:19], off offset:256
	s_nop 1
	v_lshl_add_u64 v[16:17], v[144:145], 0, s[2:3]
	s_mov_b32 s2, 0xb0000
	v_add_co_u32_e32 v22, vcc, s2, v144
	s_mov_b32 s2, s55
	s_nop 0
	v_addc_co_u32_e32 v23, vcc, 0, v145, vcc
	s_waitcnt vmcnt(15)
	s_nop 1
	v_mov_b32_e32 v18, v248
	v_mov_b32_e32 v19, v249
	v_mov_b32_e32 v20, v250
	v_mov_b32_e32 v21, v251
	s_and_b64 vcc, exec, s[40:41]
	s_waitcnt lgkmcnt(0)
	v_lshlrev_b32_e32 v24, 16, v18
	v_and_b32_e32 v25, 0xffff0000, v18
	v_lshlrev_b32_e32 v18, 16, v19
	v_and_b32_e32 v19, 0xffff0000, v19
	v_lshlrev_b32_e32 v26, 16, v20
	v_and_b32_e32 v27, 0xffff0000, v20
	v_lshlrev_b32_e32 v20, 16, v21
	v_and_b32_e32 v21, 0xffff0000, v21
	v_pk_add_f32 v[14:15], v[14:15], v[18:19]
	v_pk_add_f32 v[12:13], v[12:13], v[24:25]
	v_pk_add_f32 v[18:19], v[10:11], v[20:21]
	v_pk_add_f32 v[10:11], v[8:9], v[26:27]
	v_cvt_pk_bf16_f32 v8, v12, v13
	v_cvt_pk_bf16_f32 v9, v14, v15
	v_cvt_pk_bf16_f32 v10, v10, v11
	v_cvt_pk_bf16_f32 v11, v18, v19
	global_store_dwordx4 v[22:23], v[8:11], off
	s_waitcnt vmcnt(15)
	s_nop 1
	v_mov_b32_e32 v8, v252
	v_mov_b32_e32 v9, v253
	v_mov_b32_e32 v10, v254
	v_mov_b32_e32 v11, v255
	s_waitcnt lgkmcnt(0)
	v_lshlrev_b32_e32 v12, 16, v8
	v_and_b32_e32 v13, 0xffff0000, v8
	v_lshlrev_b32_e32 v8, 16, v9
	v_and_b32_e32 v9, 0xffff0000, v9
	v_lshlrev_b32_e32 v14, 16, v10
	v_and_b32_e32 v15, 0xffff0000, v10
	v_lshlrev_b32_e32 v10, 16, v11
	v_and_b32_e32 v11, 0xffff0000, v11
	v_pk_add_f32 v[6:7], v[6:7], v[8:9]
	v_pk_add_f32 v[4:5], v[4:5], v[12:13]
	v_pk_add_f32 v[8:9], v[2:3], v[10:11]
	v_pk_add_f32 v[2:3], v[0:1], v[14:15]
	v_cvt_pk_bf16_f32 v0, v4, v5
	v_cvt_pk_bf16_f32 v1, v6, v7
	v_cvt_pk_bf16_f32 v2, v2, v3
	v_cvt_pk_bf16_f32 v3, v8, v9
	global_store_dwordx4 v[16:17], v[0:3], off offset:256
	s_cbranch_vccz .LBB1_543
	s_waitcnt vmcnt(0)
	s_cmpk_gt_u32 s17, 0xff
	s_cbranch_scc1 .LBB1_554
	s_barrier

; #define PG8_STAGE(bufoff, gbase, voff) do { _Pragma("unroll") for (int _i = 0; _i < 2; ++_i) \
;         __builtin_amdgcn_global_load_lds((const unsigned*)((const char*)(gbase) + (voff)[_i]), (LAS unsigned*)(lds + (bufoff) + ldsw + _i * 8192), 16, 0, 0); } while (0)
; #define PG8_LDA(dst, b, h) do { _Pragma("unroll") for (int m = 0; m < 4; ++m) _Pragma("unroll") for (int k = 0; k < 2; ++k) dst[m][k] = *(const LAS bf16x8*)(lds + PG8_SA(b, h) + aoff + m * 2048 + k * 1024); } while (0)
; #define PG8_LDB(dst, b, h) do { _Pragma("unroll") for (int n = 0; n < 2; ++n) _Pragma("unroll") for (int k = 0; k < 2; ++k) dst[n][k] = *(const LAS bf16x8*)(lds + PG8_SB(b, h) + boff + n * 2048 + k * 1024); } while (0)
; #define PG8_MMA(ai, bj, At, Bt) do { __builtin_amdgcn_s_setprio(1); _Pragma("unroll") for (int m = 0; m < 4; ++m) _Pragma("unroll") for (int n = 0; n < 2; ++n) _Pragma("unroll") for (int k = 0; k < 2; ++k) \
;         acc[ai][bj][m][n] = __builtin_amdgcn_mfma_f32_16x16x32_bf16(Bt[n][k], At[m][k], acc[ai][bj][m][n], 0, 0, 0); __builtin_amdgcn_s_setprio(0); } while (0)
; #define PG8_WAIT_V(n) asm volatile("s_waitcnt vmcnt(" #n ")" ::: "memory")
; #define PG8_WAIT_L(n) asm volatile("s_waitcnt lgkmcnt(" #n ")" ::: "memory")
; #define PG8_BAR __builtin_amdgcn_s_barrier()
; #define PG8_SCHED __builtin_amdgcn_sched_barrier(0)
; template <class Map, class Epi>
; DI void gemm_phase(LAS unsigned char* lds, const Map& MP, const Epi& E, const int nM, const int nN, const int K, const int lda, const int ldb) {
;     ...
;             PG8_LDB(B0, 0, 0); PG8_SCHED; PG8_LDA(At, 0, 0); PG8_STAGE(PG8_SA(1, 1), a1 + hstepA, voffA);
;             PG8_WAIT_L(8); PG8_BAR; PG8_WAIT_L(0); PG8_MMA(0, 0, At, B0); PG8_BAR; PG8_SCHED;
;             PG8_LDB(B1, 0, 1); PG8_STAGE(PG8_SB(0, 0), b2, voffB);
;             PG8_BAR; PG8_WAIT_L(0); PG8_MMA(0, 1, At, B1); PG8_BAR;
;             PG8_LDA(At, 0, 1); PG8_STAGE(PG8_SA(0, 0), a2, voffA);
;             PG8_BAR; PG8_WAIT_L(0); PG8_MMA(1, 0, At, B0); PG8_BAR; PG8_SCHED;
;             PG8_STAGE(PG8_SB(0, 1), b2 + hstepB, voffB);
;             PG8_WAIT_V(6); PG8_BAR; PG8_MMA(1, 1, At, B1); PG8_BAR;
.LBB1_693:
	s_add_u32 s3, s20, 0xfff80080
	s_addc_u32 s22, s21, -1
	s_cmp_eq_u32 s54, 28
	s_cselect_b32 s25, s15, s22
	s_cselect_b32 s24, s48, s3
	s_cselect_b32 s23, s13, s53
	s_cselect_b32 s22, s49, s52
	s_add_i32 m0, s31, 0xc000
	ds_read_b128 v[166:169], v148
	ds_read_b128 v[170:173], v148 offset:1024
	ds_read_b128 v[174:177], v148 offset:2048
	ds_read_b128 v[178:181], v148 offset:3072
	ds_read_b128 v[182:185], v148 offset:4096
	ds_read_b128 v[186:189], v148 offset:5120
	ds_read_b128 v[190:193], v148 offset:6144
	ds_read_b128 v[198:201], v148 offset:7168
	global_load_lds_dwordx4 v138, s[20:21]
	s_add_i32 m0, s31, 0xe000
	s_setprio 1
	global_load_lds_dwordx4 v136, s[20:21]
	s_waitcnt lgkmcnt(8)
	s_barrier
	s_waitcnt lgkmcnt(7)
	v_mfma_f32_16x16x32_bf16 v[124:127], v[150:153], v[166:169], v[124:127]
	v_mfma_f32_16x16x32_bf16 v[120:123], v[158:161], v[166:169], v[120:123]
	s_waitcnt lgkmcnt(5)
	v_mfma_f32_16x16x32_bf16 v[116:119], v[150:153], v[174:177], v[116:119]
	v_mfma_f32_16x16x32_bf16 v[112:115], v[158:161], v[174:177], v[112:115]
	s_waitcnt lgkmcnt(3)
	v_mfma_f32_16x16x32_bf16 v[100:103], v[150:153], v[182:185], v[100:103]
	v_mfma_f32_16x16x32_bf16 v[96:99], v[158:161], v[182:185], v[96:99]
	s_waitcnt lgkmcnt(1)
	v_mfma_f32_16x16x32_bf16 v[84:87], v[150:153], v[190:193], v[84:87]
	v_mfma_f32_16x16x32_bf16 v[80:83], v[158:161], v[190:193], v[80:83]
	v_mfma_f32_16x16x32_bf16 v[124:127], v[154:157], v[170:173], v[124:127]
	s_add_i32 s3, s44, s29
	v_mfma_f32_16x16x32_bf16 v[120:123], v[162:165], v[170:173], v[120:123]
	v_lshl_add_u64 v[194:195], s[22:23], 0, v[132:133]
	v_mfma_f32_16x16x32_bf16 v[116:119], v[154:157], v[178:181], v[116:119]
	v_lshl_add_u64 v[218:219], s[22:23], 0, v[128:129]
	v_mfma_f32_16x16x32_bf16 v[112:115], v[162:165], v[178:181], v[112:115]
	v_mfma_f32_16x16x32_bf16 v[100:103], v[154:157], v[186:189], v[100:103]
	v_mfma_f32_16x16x32_bf16 v[96:99], v[162:165], v[186:189], v[96:99]
	s_waitcnt lgkmcnt(0)
	v_mfma_f32_16x16x32_bf16 v[84:87], v[154:157], v[198:201], v[84:87]
	v_mfma_f32_16x16x32_bf16 v[80:83], v[162:165], v[198:201], v[80:83]
	s_barrier
	s_setprio 0
	s_mov_b32 m0, s3
	ds_read_b128 v[202:205], v149
	ds_read_b128 v[206:209], v149 offset:1024
	ds_read_b128 v[210:213], v149 offset:2048
	ds_read_b128 v[214:217], v149 offset:3072
	global_load_lds_dwordx4 v[194:195], off
	s_add_i32 m0, s3, 0x2000
	s_setprio 1
	global_load_lds_dwordx4 v[218:219], off
	s_barrier
	s_waitcnt lgkmcnt(3)
	v_mfma_f32_16x16x32_bf16 v[108:111], v[202:205], v[166:169], v[108:111]
	s_waitcnt lgkmcnt(1)
	v_mfma_f32_16x16x32_bf16 v[104:107], v[210:213], v[166:169], v[104:107]
	v_mfma_f32_16x16x32_bf16 v[92:95], v[202:205], v[174:177], v[92:95]
	v_mfma_f32_16x16x32_bf16 v[88:91], v[210:213], v[174:177], v[88:91]
	v_mfma_f32_16x16x32_bf16 v[76:79], v[202:205], v[182:185], v[76:79]
	v_mfma_f32_16x16x32_bf16 v[72:75], v[210:213], v[182:185], v[72:75]
	v_mfma_f32_16x16x32_bf16 v[68:71], v[202:205], v[190:193], v[68:71]
	v_mfma_f32_16x16x32_bf16 v[64:67], v[210:213], v[190:193], v[64:67]
	v_mfma_f32_16x16x32_bf16 v[108:111], v[206:209], v[170:173], v[108:111]
	v_lshl_add_u64 v[222:223], s[24:25], 0, v[130:131]
	s_mov_b32 m0, s31
	s_waitcnt lgkmcnt(0)
	v_mfma_f32_16x16x32_bf16 v[104:107], v[214:217], v[170:173], v[104:107]
	v_lshl_add_u64 v[220:221], s[24:25], 0, v[134:135]
	v_mfma_f32_16x16x32_bf16 v[92:95], v[206:209], v[178:181], v[92:95]
	v_mfma_f32_16x16x32_bf16 v[88:91], v[214:217], v[178:181], v[88:91]
	v_mfma_f32_16x16x32_bf16 v[76:79], v[206:209], v[186:189], v[76:79]
	v_mfma_f32_16x16x32_bf16 v[72:75], v[214:217], v[186:189], v[72:75]
	v_mfma_f32_16x16x32_bf16 v[68:71], v[206:209], v[198:201], v[68:71]
	v_mfma_f32_16x16x32_bf16 v[64:67], v[214:217], v[198:201], v[64:67]
	s_barrier
	s_setprio 0
	ds_read_b128 v[166:169], v148 offset:16384
	ds_read_b128 v[170:173], v148 offset:17408
	ds_read_b128 v[174:177], v148 offset:18432
	ds_read_b128 v[178:181], v148 offset:19456
	ds_read_b128 v[182:185], v148 offset:20480
	ds_read_b128 v[186:189], v148 offset:21504
	ds_read_b128 v[190:193], v148 offset:22528
	ds_read_b128 v[198:201], v148 offset:23552
	global_load_lds_dwordx4 v[220:221], off
	s_mov_b32 m0, s11
	s_setprio 1
	global_load_lds_dwordx4 v[222:223], off
	s_waitcnt vmcnt(10)
	s_barrier
	s_waitcnt lgkmcnt(7)
	v_mfma_f32_16x16x32_bf16 v[60:63], v[150:153], v[166:169], v[60:63]
	v_mfma_f32_16x16x32_bf16 v[56:59], v[158:161], v[166:169], v[56:59]
	s_waitcnt lgkmcnt(5)
	v_mfma_f32_16x16x32_bf16 v[52:55], v[150:153], v[174:177], v[52:55]
	v_mfma_f32_16x16x32_bf16 v[48:51], v[158:161], v[174:177], v[48:51]
	s_waitcnt lgkmcnt(3)
	v_mfma_f32_16x16x32_bf16 v[36:39], v[150:153], v[182:185], v[36:39]
	v_mfma_f32_16x16x32_bf16 v[32:35], v[158:161], v[182:185], v[32:35]
	s_waitcnt lgkmcnt(1)
	v_mfma_f32_16x16x32_bf16 v[20:23], v[150:153], v[190:193], v[20:23]
	v_mfma_f32_16x16x32_bf16 v[16:19], v[158:161], v[190:193], v[16:19]
	v_mfma_f32_16x16x32_bf16 v[60:63], v[154:157], v[170:173], v[60:63]
	s_add_u32 s56, s22, 0x80000
	s_addc_u32 s57, s23, 0
	v_mfma_f32_16x16x32_bf16 v[56:59], v[162:165], v[170:173], v[56:59]
	s_add_i32 s3, s45, s29
	v_mfma_f32_16x16x32_bf16 v[52:55], v[154:157], v[178:181], v[52:55]
	v_mfma_f32_16x16x32_bf16 v[48:51], v[162:165], v[178:181], v[48:51]
	v_mfma_f32_16x16x32_bf16 v[36:39], v[154:157], v[186:189], v[36:39]
	v_mfma_f32_16x16x32_bf16 v[32:35], v[162:165], v[186:189], v[32:35]
	s_waitcnt lgkmcnt(0)
	v_mfma_f32_16x16x32_bf16 v[20:23], v[154:157], v[198:201], v[20:23]
	v_mfma_f32_16x16x32_bf16 v[16:19], v[162:165], v[198:201], v[16:19]
	s_barrier
; #define PG8_STAGE(bufoff, gbase, voff) do { _Pragma("unroll") for (int _i = 0; _i < 2; ++_i) \
;         __builtin_amdgcn_global_load_lds((const unsigned*)((const char*)(gbase) + (voff)[_i]), (LAS unsigned*)(lds + (bufoff) + ldsw + _i * 8192), 16, 0, 0); } while (0)
; #define PG8_LDA(dst, b, h) do { _Pragma("unroll") for (int m = 0; m < 4; ++m) _Pragma("unroll") for (int k = 0; k < 2; ++k) dst[m][k] = *(const LAS bf16x8*)(lds + PG8_SA(b, h) + aoff + m * 2048 + k * 1024); } while (0)
; #define PG8_LDB(dst, b, h) do { _Pragma("unroll") for (int n = 0; n < 2; ++n) _Pragma("unroll") for (int k = 0; k < 2; ++k) dst[n][k] = *(const LAS bf16x8*)(lds + PG8_SB(b, h) + boff + n * 2048 + k * 1024); } while (0)
; #define PG8_MMA(ai, bj, At, Bt) do { __builtin_amdgcn_s_setprio(1); _Pragma("unroll") for (int m = 0; m < 4; ++m) _Pragma("unroll") for (int n = 0; n < 2; ++n) _Pragma("unroll") for (int k = 0; k < 2; ++k) \
;         acc[ai][bj][m][n] = __builtin_amdgcn_mfma_f32_16x16x32_bf16(Bt[n][k], At[m][k], acc[ai][bj][m][n], 0, 0, 0); __builtin_amdgcn_s_setprio(0); } while (0)
; #define PG8_WAIT_V(n) asm volatile("s_waitcnt vmcnt(" #n ")" ::: "memory")
; #define PG8_WAIT_L(n) asm volatile("s_waitcnt lgkmcnt(" #n ")" ::: "memory")
; #define PG8_BAR __builtin_amdgcn_s_barrier()
; #define PG8_SCHED __builtin_amdgcn_sched_barrier(0)
; template <class Map, class Epi>
; DI void gemm_phase(LAS unsigned char* lds, const Map& MP, const Epi& E, const int nM, const int nN, const int K, const int lda, const int ldb) {
;     ...
;             PG8_WAIT_V(6); PG8_BAR; PG8_MMA(1, 1, At, B1); PG8_BAR;
;             PG8_LDB(B0, 1, 0); PG8_SCHED; PG8_LDA(At, 1, 0); PG8_STAGE(PG8_SA(0, 1), a2 + hstepA, voffA);
;             PG8_WAIT_L(8); PG8_BAR; PG8_WAIT_L(0); PG8_MMA(0, 0, At, B0); PG8_BAR; PG8_SCHED;
;             PG8_LDB(B1, 1, 1); PG8_STAGE(PG8_SB(1, 0), b3, voffB);
;             PG8_BAR; PG8_WAIT_L(0); PG8_MMA(0, 1, At, B1); PG8_BAR;
;             PG8_LDA(At, 1, 1); PG8_STAGE(PG8_SA(1, 0), a3, voffA);
;             PG8_BAR; PG8_WAIT_L(0); PG8_MMA(1, 0, At, B0); PG8_BAR; PG8_SCHED;
;             PG8_STAGE(PG8_SB(1, 1), b3 + hstepB, voffB);
;             PG8_WAIT_V(6); PG8_BAR; PG8_MMA(1, 1, At, B1); PG8_BAR;
	s_setprio 0
	s_mov_b32 m0, s3
	s_nop 0
	global_load_lds_dwordx4 v132, s[56:57]
	s_add_i32 m0, s3, 0x2000
	s_setprio 1
	global_load_lds_dwordx4 v128, s[56:57]
	s_waitcnt vmcnt(6)
	s_barrier
	v_mfma_f32_16x16x32_bf16 v[44:47], v[202:205], v[166:169], v[44:47]
	v_mfma_f32_16x16x32_bf16 v[40:43], v[210:213], v[166:169], v[40:43]
	s_add_i32 s3, 0, 0x18000
	v_add_u32_e32 v162, s3, v146
	ds_read_b128 v[150:153], v162
	v_mfma_f32_16x16x32_bf16 v[28:31], v[202:205], v[174:177], v[28:31]
	v_mfma_f32_16x16x32_bf16 v[24:27], v[210:213], v[174:177], v[24:27]
	ds_read_b128 v[154:157], v162 offset:1024
	v_mfma_f32_16x16x32_bf16 v[12:15], v[202:205], v[182:185], v[12:15]
	v_mfma_f32_16x16x32_bf16 v[8:11], v[210:213], v[182:185], v[8:11]
	ds_read_b128 v[158:161], v162 offset:2048
	v_mfma_f32_16x16x32_bf16 v[4:7], v[202:205], v[190:193], v[4:7]
	v_mfma_f32_16x16x32_bf16 v[0:3], v[210:213], v[190:193], v[0:3]
	ds_read_b128 v[162:165], v162 offset:3072
	v_mfma_f32_16x16x32_bf16 v[44:47], v[206:209], v[170:173], v[44:47]
	s_add_u32 s24, s24, 0x80000
	s_addc_u32 s25, s25, 0
	v_mfma_f32_16x16x32_bf16 v[40:43], v[214:217], v[170:173], v[40:43]
	v_mfma_f32_16x16x32_bf16 v[28:31], v[206:209], v[178:181], v[28:31]
	v_mfma_f32_16x16x32_bf16 v[24:27], v[214:217], v[178:181], v[24:27]
	v_mfma_f32_16x16x32_bf16 v[12:15], v[206:209], v[186:189], v[12:15]
	v_mfma_f32_16x16x32_bf16 v[8:11], v[214:217], v[186:189], v[8:11]
	v_mfma_f32_16x16x32_bf16 v[4:7], v[206:209], v[198:201], v[4:7]
	v_mfma_f32_16x16x32_bf16 v[0:3], v[214:217], v[198:201], v[0:3]
	s_barrier
	s_setprio 0
	s_mov_b32 m0, s34
	ds_read_b128 v[166:169], v148 offset:32768
	ds_read_b128 v[170:173], v148 offset:33792
	ds_read_b128 v[174:177], v148 offset:34816
	ds_read_b128 v[178:181], v148 offset:35840
	ds_read_b128 v[182:185], v148 offset:36864
	ds_read_b128 v[186:189], v148 offset:37888
	ds_read_b128 v[190:193], v148 offset:38912
	ds_read_b128 v[198:201], v148 offset:39936
	global_load_lds_dwordx4 v134, s[24:25]
	s_mov_b32 m0, s35
	s_setprio 1
	global_load_lds_dwordx4 v130, s[24:25]
	s_waitcnt lgkmcnt(8)
	s_barrier
	s_waitcnt lgkmcnt(7)
	v_mfma_f32_16x16x32_bf16 v[124:127], v[150:153], v[166:169], v[124:127]
	v_mfma_f32_16x16x32_bf16 v[120:123], v[158:161], v[166:169], v[120:123]
	s_waitcnt lgkmcnt(5)
	v_mfma_f32_16x16x32_bf16 v[116:119], v[150:153], v[174:177], v[116:119]
	v_mfma_f32_16x16x32_bf16 v[112:115], v[158:161], v[174:177], v[112:115]
	s_waitcnt lgkmcnt(3)
	v_mfma_f32_16x16x32_bf16 v[100:103], v[150:153], v[182:185], v[100:103]
	v_mfma_f32_16x16x32_bf16 v[96:99], v[158:161], v[182:185], v[96:99]
	s_waitcnt lgkmcnt(1)
	v_mfma_f32_16x16x32_bf16 v[84:87], v[150:153], v[190:193], v[84:87]
	v_mfma_f32_16x16x32_bf16 v[80:83], v[158:161], v[190:193], v[80:83]
	v_mfma_f32_16x16x32_bf16 v[124:127], v[154:157], v[170:173], v[124:127]
	s_add_i32 s24, 0, 0x1c000
	v_mfma_f32_16x16x32_bf16 v[120:123], v[162:165], v[170:173], v[120:123]
	s_add_i32 s3, s3, s29
	v_mfma_f32_16x16x32_bf16 v[116:119], v[154:157], v[178:181], v[116:119]
	v_add_u32_e32 v196, s24, v146
	v_mfma_f32_16x16x32_bf16 v[112:115], v[162:165], v[178:181], v[112:115]
	v_lshl_add_u64 v[194:195], v[194:195], 0, s[8:9]
	v_mfma_f32_16x16x32_bf16 v[100:103], v[154:157], v[186:189], v[100:103]
	v_mfma_f32_16x16x32_bf16 v[96:99], v[162:165], v[186:189], v[96:99]
	s_waitcnt lgkmcnt(0)
	v_mfma_f32_16x16x32_bf16 v[84:87], v[154:157], v[198:201], v[84:87]
	v_mfma_f32_16x16x32_bf16 v[80:83], v[162:165], v[198:201], v[80:83]
	s_barrier
	s_setprio 0
	s_mov_b32 m0, s3
	ds_read_b128 v[202:205], v196
	ds_read_b128 v[206:209], v196 offset:1024
	ds_read_b128 v[210:213], v196 offset:2048
	ds_read_b128 v[214:217], v196 offset:3072
	global_load_lds_dwordx4 v[194:195], off
	v_lshl_add_u64 v[194:195], v[218:219], 0, s[8:9]
	s_add_i32 m0, s3, 0x2000
	s_setprio 1
	global_load_lds_dwordx4 v[194:195], off
	s_barrier
	s_waitcnt lgkmcnt(3)
	v_mfma_f32_16x16x32_bf16 v[108:111], v[202:205], v[166:169], v[108:111]
	s_waitcnt lgkmcnt(1)
	v_mfma_f32_16x16x32_bf16 v[104:107], v[210:213], v[166:169], v[104:107]
	v_mfma_f32_16x16x32_bf16 v[92:95], v[202:205], v[174:177], v[92:95]
	v_mfma_f32_16x16x32_bf16 v[88:91], v[210:213], v[174:177], v[88:91]
	v_mfma_f32_16x16x32_bf16 v[76:79], v[202:205], v[182:185], v[76:79]
	v_mfma_f32_16x16x32_bf16 v[72:75], v[210:213], v[182:185], v[72:75]
	v_mfma_f32_16x16x32_bf16 v[68:71], v[202:205], v[190:193], v[68:71]
	v_mfma_f32_16x16x32_bf16 v[64:67], v[210:213], v[190:193], v[64:67]
	v_mfma_f32_16x16x32_bf16 v[108:111], v[206:209], v[170:173], v[108:111]
	s_mov_b32 m0, s39
	s_waitcnt lgkmcnt(0)
	v_mfma_f32_16x16x32_bf16 v[104:107], v[214:217], v[170:173], v[104:107]
	v_lshl_add_u64 v[194:195], v[220:221], 0, s[8:9]
	v_mfma_f32_16x16x32_bf16 v[92:95], v[206:209], v[178:181], v[92:95]
	v_mfma_f32_16x16x32_bf16 v[88:91], v[214:217], v[178:181], v[88:91]
	v_mfma_f32_16x16x32_bf16 v[76:79], v[206:209], v[186:189], v[76:79]
	v_mfma_f32_16x16x32_bf16 v[72:75], v[214:217], v[186:189], v[72:75]
	v_mfma_f32_16x16x32_bf16 v[68:71], v[206:209], v[198:201], v[68:71]
	v_mfma_f32_16x16x32_bf16 v[64:67], v[214:217], v[198:201], v[64:67]
	s_barrier
	s_setprio 0
	ds_read_b128 v[166:169], v148 offset:49152
	ds_read_b128 v[170:173], v148 offset:50176
	ds_read_b128 v[174:177], v148 offset:51200
	ds_read_b128 v[178:181], v148 offset:52224
	ds_read_b128 v[182:185], v148 offset:53248
	ds_read_b128 v[186:189], v148 offset:54272
	ds_read_b128 v[190:193], v148 offset:55296
	ds_read_b128 v[198:201], v148 offset:56320
	global_load_lds_dwordx4 v[194:195], off
	v_lshl_add_u64 v[194:195], v[222:223], 0, s[8:9]
	s_mov_b32 m0, s42
	s_setprio 1
	global_load_lds_dwordx4 v[194:195], off
	s_waitcnt vmcnt(10)
	s_barrier
; #define PG8_STAGE(bufoff, gbase, voff) do { _Pragma("unroll") for (int _i = 0; _i < 2; ++_i) \
;         __builtin_amdgcn_global_load_lds((const unsigned*)((const char*)(gbase) + (voff)[_i]), (LAS unsigned*)(lds + (bufoff) + ldsw + _i * 8192), 16, 0, 0); } while (0)
; #define PG8_LDA(dst, b, h) do { _Pragma("unroll") for (int m = 0; m < 4; ++m) _Pragma("unroll") for (int k = 0; k < 2; ++k) dst[m][k] = *(const LAS bf16x8*)(lds + PG8_SA(b, h) + aoff + m * 2048 + k * 1024); } while (0)
; #define PG8_LDB(dst, b, h) do { _Pragma("unroll") for (int n = 0; n < 2; ++n) _Pragma("unroll") for (int k = 0; k < 2; ++k) dst[n][k] = *(const LAS bf16x8*)(lds + PG8_SB(b, h) + boff + n * 2048 + k * 1024); } while (0)
; #define PG8_MMA(ai, bj, At, Bt) do { __builtin_amdgcn_s_setprio(1); _Pragma("unroll") for (int m = 0; m < 4; ++m) _Pragma("unroll") for (int n = 0; n < 2; ++n) _Pragma("unroll") for (int k = 0; k < 2; ++k) \
;         acc[ai][bj][m][n] = __builtin_amdgcn_mfma_f32_16x16x32_bf16(Bt[n][k], At[m][k], acc[ai][bj][m][n], 0, 0, 0); __builtin_amdgcn_s_setprio(0); } while (0)
; #define PG8_WAIT_V(n) asm volatile("s_waitcnt vmcnt(" #n ")" ::: "memory")
; #define PG8_WAIT_L(n) asm volatile("s_waitcnt lgkmcnt(" #n ")" ::: "memory")
; #define PG8_BAR __builtin_amdgcn_s_barrier()
; #define PG8_SCHED __builtin_amdgcn_sched_barrier(0)
; template <class Map, class Epi>
; DI void gemm_phase(LAS unsigned char* lds, const Map& MP, const Epi& E, const int nM, const int nN, const int K, const int lda, const int ldb) {
;     ...
;             PG8_WAIT_L(8); PG8_BAR; PG8_WAIT_L(0); PG8_MMA(0, 0, At, B0); PG8_BAR; PG8_SCHED;
;             PG8_LDB(B1, 1, 1); PG8_STAGE(PG8_SB(1, 0), b3, voffB);
;             PG8_BAR; PG8_WAIT_L(0); PG8_MMA(0, 1, At, B1); PG8_BAR;
;             PG8_LDA(At, 1, 1); PG8_STAGE(PG8_SA(1, 0), a3, voffA);
;             PG8_BAR; PG8_WAIT_L(0); PG8_MMA(1, 0, At, B0); PG8_BAR; PG8_SCHED;
;             PG8_STAGE(PG8_SB(1, 1), b3 + hstepB, voffB);
;             PG8_WAIT_V(6); PG8_BAR; PG8_MMA(1, 1, At, B1); PG8_BAR;
	s_waitcnt lgkmcnt(7)
	v_mfma_f32_16x16x32_bf16 v[60:63], v[150:153], v[166:169], v[60:63]
	v_mfma_f32_16x16x32_bf16 v[56:59], v[158:161], v[166:169], v[56:59]
	s_waitcnt lgkmcnt(5)
	v_mfma_f32_16x16x32_bf16 v[52:55], v[150:153], v[174:177], v[52:55]
	v_mfma_f32_16x16x32_bf16 v[48:51], v[158:161], v[174:177], v[48:51]
	s_waitcnt lgkmcnt(3)
	v_mfma_f32_16x16x32_bf16 v[36:39], v[150:153], v[182:185], v[36:39]
	v_mfma_f32_16x16x32_bf16 v[32:35], v[158:161], v[182:185], v[32:35]
	s_waitcnt lgkmcnt(1)
	v_mfma_f32_16x16x32_bf16 v[20:23], v[150:153], v[190:193], v[20:23]
	v_mfma_f32_16x16x32_bf16 v[16:19], v[158:161], v[190:193], v[16:19]
	v_mfma_f32_16x16x32_bf16 v[60:63], v[154:157], v[170:173], v[60:63]
	s_add_u32 s22, s22, 0x80080
	s_addc_u32 s23, s23, 0
	v_mfma_f32_16x16x32_bf16 v[56:59], v[162:165], v[170:173], v[56:59]
	s_add_i32 s3, s24, s29
	v_mfma_f32_16x16x32_bf16 v[52:55], v[154:157], v[178:181], v[52:55]
	v_mfma_f32_16x16x32_bf16 v[48:51], v[162:165], v[178:181], v[48:51]
	v_mfma_f32_16x16x32_bf16 v[36:39], v[154:157], v[186:189], v[36:39]
	v_mfma_f32_16x16x32_bf16 v[32:35], v[162:165], v[186:189], v[32:35]
	s_waitcnt lgkmcnt(0)
	v_mfma_f32_16x16x32_bf16 v[20:23], v[154:157], v[198:201], v[20:23]
	v_mfma_f32_16x16x32_bf16 v[16:19], v[162:165], v[198:201], v[16:19]
	s_barrier
	s_setprio 0
	s_mov_b32 m0, s3
	s_nop 0
	global_load_lds_dwordx4 v132, s[22:23]
	s_add_i32 m0, s3, 0x2000
	s_setprio 1
	global_load_lds_dwordx4 v128, s[22:23]
	s_waitcnt vmcnt(6)
	s_barrier
	v_mfma_f32_16x16x32_bf16 v[44:47], v[202:205], v[166:169], v[44:47]
	v_mfma_f32_16x16x32_bf16 v[40:43], v[210:213], v[166:169], v[40:43]
	ds_read_b128 v[150:153], v147
	v_mfma_f32_16x16x32_bf16 v[28:31], v[202:205], v[174:177], v[28:31]
	v_mfma_f32_16x16x32_bf16 v[24:27], v[210:213], v[174:177], v[24:27]
	ds_read_b128 v[154:157], v147 offset:1024
	v_mfma_f32_16x16x32_bf16 v[12:15], v[202:205], v[182:185], v[12:15]
	v_mfma_f32_16x16x32_bf16 v[8:11], v[210:213], v[182:185], v[8:11]
	ds_read_b128 v[158:161], v147 offset:2048
	v_mfma_f32_16x16x32_bf16 v[4:7], v[202:205], v[190:193], v[4:7]
	v_mfma_f32_16x16x32_bf16 v[0:3], v[210:213], v[190:193], v[0:3]
	ds_read_b128 v[162:165], v147 offset:3072
	v_mfma_f32_16x16x32_bf16 v[44:47], v[206:209], v[170:173], v[44:47]
	s_add_i32 s54, s54, 2
	v_mfma_f32_16x16x32_bf16 v[40:43], v[214:217], v[170:173], v[40:43]
	s_add_u32 s52, s52, 0x100
	s_addc_u32 s53, s53, 0
	v_mfma_f32_16x16x32_bf16 v[28:31], v[206:209], v[178:181], v[28:31]
	s_add_u32 s20, s20, 0x100
	s_addc_u32 s21, s21, 0
	v_mfma_f32_16x16x32_bf16 v[24:27], v[214:217], v[178:181], v[24:27]
	s_cmp_gt_u32 s54, 29
	v_mfma_f32_16x16x32_bf16 v[12:15], v[206:209], v[186:189], v[12:15]
	v_mfma_f32_16x16x32_bf16 v[8:11], v[214:217], v[186:189], v[8:11]
	v_mfma_f32_16x16x32_bf16 v[4:7], v[206:209], v[198:201], v[4:7]
	v_mfma_f32_16x16x32_bf16 v[0:3], v[214:217], v[198:201], v[0:3]
	s_barrier
	s_setprio 0
	s_cbranch_scc0 .LBB1_693
; DI unsigned pack2(float a, float b) { f32x2 v = {a, b}; hwbf16x2 r = __builtin_convertvector(v, hwbf16x2); return __builtin_bit_cast(unsigned, r); }
; #define PG8_WAIT_V(n) asm volatile("s_waitcnt vmcnt(" #n ")" ::: "memory")
; #define PG8_BAR __builtin_amdgcn_s_barrier()
;     DI void operator()(const f32x4 (&acc)[2][2][4][2], const Unit& u, int wr, int wc, int fr, int fq) const {
;         bf16_t* O = O1; int ldc = ldc1, pn = u.pn; if (pn >= split) { O = O2; ldc = ldc2; pn -= split; }
;         const int row0 = u.pm * BM + wr * 64 + fr, col0 = pn * BM + wc * 32 + 8 * fq;
; #pragma unroll
;         for (int ai = 0; ai < 2; ++ai)
; #pragma unroll
;             for (int m = 0; m < 4; ++m) { bf16_t* rowp = O + (size_t)(row0 + ai * HALF + m * 16) * ldc + col0;
; #pragma unroll
;                 for (int bj = 0; bj < 2; ++bj) { const f32x4 v0 = acc[ai][bj][m][0], v1 = acc[ai][bj][m][1];
;                     u32x4 o; o[0] = pack2(v0[0], v0[1]); o[1] = pack2(v0[2], v0[3]); o[2] = pack2(v1[0], v1[1]); o[3] = pack2(v1[2], v1[3]);
;                     *(u32x4*)(rowp + bj * HALF) = o; } }
;     }
; template <class Map, class Epi>
; DI void gemm_phase(LAS unsigned char* lds, const Map& MP, const Epi& E, const int nM, const int nN, const int K, const int lda, const int ldb) {
;     ...
;     PG8_WAIT_V(0);
;     if (wr == 0) PG8_BAR;
;     PG8_BAR;
	s_waitcnt lgkmcnt(0)
	s_lshl_b32 s3, s10, 8
	v_mov_b32_e32 v150, v144
	v_mov_b32_e32 v151, v145
	s_add_i32 s3, s3, s37
	v_cvt_pk_bf16_f32 v68, v68, v69
	v_add_u32_e32 v154, s3, v150
	s_lshl_b32 s3, s47, 8
	s_or_b32 s3, s3, s38
	v_lshl_add_u32 v150, v151, 3, s3
	v_ashrrev_i32_e32 v151, 31, v150
	v_lshl_add_u64 v[150:151], v[150:151], 1, s[6:7]
	v_cvt_pk_bf16_f32 v69, v70, v71
	v_cvt_pk_bf16_f32 v70, v64, v65
	v_add_u32_e32 v64, 0x80, v154
	v_mad_i64_i32 v[152:153], s[20:21], v154, s46, v[150:151]
	v_cvt_pk_bf16_f32 v108, v108, v109
	v_cvt_pk_bf16_f32 v109, v110, v111
	v_cvt_pk_bf16_f32 v110, v104, v105
	v_cvt_pk_bf16_f32 v111, v106, v107
	v_add_u32_e32 v104, 16, v154
	v_mad_i64_i32 v[64:65], s[20:21], v64, s46, v[150:151]
	v_cvt_pk_bf16_f32 v44, v44, v45
	v_cvt_pk_bf16_f32 v45, v46, v47
	v_cvt_pk_bf16_f32 v46, v40, v41
	v_cvt_pk_bf16_f32 v47, v42, v43
	v_add_u32_e32 v40, 0x90, v154
	global_store_dwordx4 v[152:153], v[108:111], off offset:256
	v_cvt_pk_bf16_f32 v92, v92, v93
	v_cvt_pk_bf16_f32 v93, v94, v95
	v_mad_i64_i32 v[108:109], s[20:21], v104, s46, v[150:151]
	v_cvt_pk_bf16_f32 v94, v88, v89
	v_cvt_pk_bf16_f32 v95, v90, v91
	v_add_u32_e32 v88, 32, v154
	global_store_dwordx4 v[64:65], v[44:47], off offset:256
	v_cvt_pk_bf16_f32 v28, v28, v29
	v_cvt_pk_bf16_f32 v29, v30, v31
	v_mad_i64_i32 v[44:45], s[20:21], v40, s46, v[150:151]
	v_cvt_pk_bf16_f32 v30, v24, v25
	v_cvt_pk_bf16_f32 v31, v26, v27
	v_add_u32_e32 v24, 0xa0, v154
	global_store_dwordx4 v[108:109], v[92:95], off offset:256
	v_cvt_pk_bf16_f32 v76, v76, v77
	v_cvt_pk_bf16_f32 v77, v78, v79
	v_mad_i64_i32 v[92:93], s[20:21], v88, s46, v[150:151]
	v_cvt_pk_bf16_f32 v78, v72, v73
	v_cvt_pk_bf16_f32 v79, v74, v75
	v_add_u32_e32 v72, 48, v154
	global_store_dwordx4 v[44:45], v[28:31], off offset:256
	v_cvt_pk_bf16_f32 v12, v12, v13
	v_cvt_pk_bf16_f32 v13, v14, v15
	v_mad_i64_i32 v[28:29], s[20:21], v24, s46, v[150:151]
	v_cvt_pk_bf16_f32 v14, v8, v9
	v_cvt_pk_bf16_f32 v15, v10, v11
	v_add_u32_e32 v8, 0xb0, v154
	global_store_dwordx4 v[92:93], v[76:79], off offset:256
	global_store_dwordx4 v[28:29], v[12:15], off offset:256
	v_cvt_pk_bf16_f32 v124, v124, v125
	v_mad_i64_i32 v[76:77], s[20:21], v72, s46, v[150:151]
	v_mad_i64_i32 v[12:13], s[20:21], v8, s46, v[150:151]
	v_cvt_pk_bf16_f32 v125, v126, v127
	v_cvt_pk_bf16_f32 v126, v120, v121
	v_cvt_pk_bf16_f32 v127, v122, v123
	v_cvt_pk_bf16_f32 v104, v116, v117
	v_cvt_pk_bf16_f32 v105, v118, v119
	v_cvt_pk_bf16_f32 v106, v112, v113
	v_cvt_pk_bf16_f32 v107, v114, v115
	v_cvt_pk_bf16_f32 v88, v100, v101
	v_cvt_pk_bf16_f32 v89, v102, v103
	v_cvt_pk_bf16_f32 v90, v96, v97
	v_cvt_pk_bf16_f32 v91, v98, v99
	v_cvt_pk_bf16_f32 v72, v84, v85
	v_cvt_pk_bf16_f32 v73, v86, v87
	v_cvt_pk_bf16_f32 v74, v80, v81
	v_cvt_pk_bf16_f32 v75, v82, v83
	v_cvt_pk_bf16_f32 v71, v66, v67
	v_cvt_pk_bf16_f32 v60, v60, v61
	v_cvt_pk_bf16_f32 v61, v62, v63
	v_cvt_pk_bf16_f32 v62, v56, v57
	v_cvt_pk_bf16_f32 v63, v58, v59
	v_cvt_pk_bf16_f32 v40, v52, v53
	v_cvt_pk_bf16_f32 v41, v54, v55
	v_cvt_pk_bf16_f32 v42, v48, v49
	v_cvt_pk_bf16_f32 v43, v50, v51
	v_cvt_pk_bf16_f32 v24, v36, v37
	v_cvt_pk_bf16_f32 v25, v38, v39
	v_cvt_pk_bf16_f32 v26, v32, v33
	v_cvt_pk_bf16_f32 v27, v34, v35
	v_cvt_pk_bf16_f32 v8, v20, v21
	v_cvt_pk_bf16_f32 v9, v22, v23
	v_cvt_pk_bf16_f32 v10, v16, v17
	v_cvt_pk_bf16_f32 v11, v18, v19
	v_cvt_pk_bf16_f32 v4, v4, v5
	v_cvt_pk_bf16_f32 v5, v6, v7
	v_cvt_pk_bf16_f32 v6, v0, v1
	v_cvt_pk_bf16_f32 v7, v2, v3
	s_and_b64 vcc, exec, s[40:41]
	s_mov_b32 s47, s12
	s_mov_b32 s10, s14
	s_mov_b64 s[20:21], s[18:19]
	s_mov_b64 s[22:23], s[16:17]
	global_store_dwordx4 v[152:153], v[124:127], off
	global_store_dwordx4 v[108:109], v[104:107], off
	global_store_dwordx4 v[92:93], v[88:91], off
	global_store_dwordx4 v[76:77], v[72:75], off
	global_store_dwordx4 v[76:77], v[68:71], off offset:256
	global_store_dwordx4 v[64:65], v[60:63], off
	global_store_dwordx4 v[44:45], v[40:43], off
	global_store_dwordx4 v[28:29], v[24:27], off
	global_store_dwordx4 v[12:13], v[8:11], off
	global_store_dwordx4 v[12:13], v[4:7], off offset:256
	s_cbranch_vccz .LBB1_690
	s_waitcnt vmcnt(0)
	s_cmpk_gt_u32 s4, 0xff
	s_cbranch_scc1 .LBB1_697
	s_barrier

; #define PG8_STAGE(bufoff, gbase, voff) do { _Pragma("unroll") for (int _i = 0; _i < 2; ++_i) \
;         __builtin_amdgcn_global_load_lds((const unsigned*)((const char*)(gbase) + (voff)[_i]), (LAS unsigned*)(lds + (bufoff) + ldsw + _i * 8192), 16, 0, 0); } while (0)
; #define PG8_LDA(dst, b, h) do { _Pragma("unroll") for (int m = 0; m < 4; ++m) _Pragma("unroll") for (int k = 0; k < 2; ++k) dst[m][k] = *(const LAS bf16x8*)(lds + PG8_SA(b, h) + aoff + m * 2048 + k * 1024); } while (0)
; #define PG8_LDB(dst, b, h) do { _Pragma("unroll") for (int n = 0; n < 2; ++n) _Pragma("unroll") for (int k = 0; k < 2; ++k) dst[n][k] = *(const LAS bf16x8*)(lds + PG8_SB(b, h) + boff + n * 2048 + k * 1024); } while (0)
; #define PG8_MMA(ai, bj, At, Bt) do { __builtin_amdgcn_s_setprio(1); _Pragma("unroll") for (int m = 0; m < 4; ++m) _Pragma("unroll") for (int n = 0; n < 2; ++n) _Pragma("unroll") for (int k = 0; k < 2; ++k) \
;         acc[ai][bj][m][n] = __builtin_amdgcn_mfma_f32_16x16x32_bf16(Bt[n][k], At[m][k], acc[ai][bj][m][n], 0, 0, 0); __builtin_amdgcn_s_setprio(0); } while (0)
; #define PG8_WAIT_V(n) asm volatile("s_waitcnt vmcnt(" #n ")" ::: "memory")
; #define PG8_WAIT_L(n) asm volatile("s_waitcnt lgkmcnt(" #n ")" ::: "memory")
; #define PG8_BAR __builtin_amdgcn_s_barrier()
; #define PG8_SCHED __builtin_amdgcn_sched_barrier(0)
; template <class Map, class Epi>
; DI void gemm_phase(LAS unsigned char* lds, const Map& MP, const Epi& E, const int nM, const int nN, const int K, const int lda, const int ldb) {
;     ...
;             PG8_LDB(B0, 0, 0); PG8_SCHED; PG8_LDA(At, 0, 0); PG8_STAGE(PG8_SA(1, 1), a1 + hstepA, voffA);
;             PG8_WAIT_L(8); PG8_BAR; PG8_WAIT_L(0); PG8_MMA(0, 0, At, B0); PG8_BAR; PG8_SCHED;
;             PG8_LDB(B1, 0, 1); PG8_STAGE(PG8_SB(0, 0), b2, voffB);
;             PG8_BAR; PG8_WAIT_L(0); PG8_MMA(0, 1, At, B1); PG8_BAR;
;             PG8_LDA(At, 0, 1); PG8_STAGE(PG8_SA(0, 0), a2, voffA);
;             PG8_BAR; PG8_WAIT_L(0); PG8_MMA(1, 0, At, B0); PG8_BAR; PG8_SCHED;
;             PG8_STAGE(PG8_SB(0, 1), b2 + hstepB, voffB);
;             PG8_WAIT_V(6); PG8_BAR; PG8_MMA(1, 1, At, B1); PG8_BAR;
.LBB1_925:
	s_add_u32 s3, s10, 0xfff80080
	s_addc_u32 s12, s11, -1
	s_cmp_eq_u32 s48, 28
	s_cselect_b32 s15, s4, s12
	s_cselect_b32 s14, s5, s3
	s_cselect_b32 s13, s37, s47
	s_cselect_b32 s12, s38, s39
	s_add_i32 m0, s24, 0xc000
	ds_read_b128 v[168:171], v150
	ds_read_b128 v[172:175], v150 offset:1024
	ds_read_b128 v[176:179], v150 offset:2048
	ds_read_b128 v[180:183], v150 offset:3072
	ds_read_b128 v[184:187], v150 offset:4096
	ds_read_b128 v[188:191], v150 offset:5120
	ds_read_b128 v[192:195], v150 offset:6144
	ds_read_b128 v[198:201], v150 offset:7168
	global_load_lds_dwordx4 v138, s[10:11]
	s_add_i32 m0, s24, 0xe000
	s_setprio 1
	global_load_lds_dwordx4 v136, s[10:11]
	s_waitcnt lgkmcnt(8)
	s_barrier
	s_waitcnt lgkmcnt(7)
	v_mfma_f32_16x16x32_bf16 v[124:127], v[152:155], v[168:171], v[124:127]
	v_mfma_f32_16x16x32_bf16 v[120:123], v[160:163], v[168:171], v[120:123]
	s_waitcnt lgkmcnt(5)
	v_mfma_f32_16x16x32_bf16 v[108:111], v[152:155], v[176:179], v[108:111]
	v_mfma_f32_16x16x32_bf16 v[104:107], v[160:163], v[176:179], v[104:107]
	s_waitcnt lgkmcnt(3)
	v_mfma_f32_16x16x32_bf16 v[92:95], v[152:155], v[184:187], v[92:95]
	v_mfma_f32_16x16x32_bf16 v[88:91], v[160:163], v[184:187], v[88:91]
	s_waitcnt lgkmcnt(1)
	v_mfma_f32_16x16x32_bf16 v[76:79], v[152:155], v[192:195], v[76:79]
	v_mfma_f32_16x16x32_bf16 v[72:75], v[160:163], v[192:195], v[72:75]
	v_mfma_f32_16x16x32_bf16 v[124:127], v[156:159], v[172:175], v[124:127]
	s_add_i32 s3, s35, s22
	v_mfma_f32_16x16x32_bf16 v[120:123], v[164:167], v[172:175], v[120:123]
	v_lshl_add_u64 v[144:145], s[12:13], 0, v[132:133]
	v_mfma_f32_16x16x32_bf16 v[108:111], v[156:159], v[180:183], v[108:111]
	v_lshl_add_u64 v[218:219], s[12:13], 0, v[128:129]
	v_mfma_f32_16x16x32_bf16 v[104:107], v[164:167], v[180:183], v[104:107]
	v_mfma_f32_16x16x32_bf16 v[92:95], v[156:159], v[188:191], v[92:95]
	v_mfma_f32_16x16x32_bf16 v[88:91], v[164:167], v[188:191], v[88:91]
	s_waitcnt lgkmcnt(0)
	v_mfma_f32_16x16x32_bf16 v[76:79], v[156:159], v[198:201], v[76:79]
	v_mfma_f32_16x16x32_bf16 v[72:75], v[164:167], v[198:201], v[72:75]
	s_barrier
	s_setprio 0
	s_mov_b32 m0, s3
	ds_read_b128 v[202:205], v151
	ds_read_b128 v[206:209], v151 offset:1024
	ds_read_b128 v[210:213], v151 offset:2048
	ds_read_b128 v[214:217], v151 offset:3072
	global_load_lds_dwordx4 v[144:145], off
	s_add_i32 m0, s3, 0x2000
	s_setprio 1
	global_load_lds_dwordx4 v[218:219], off
	s_barrier
	s_waitcnt lgkmcnt(3)
	v_mfma_f32_16x16x32_bf16 v[116:119], v[202:205], v[168:171], v[116:119]
	s_waitcnt lgkmcnt(1)
	v_mfma_f32_16x16x32_bf16 v[112:115], v[210:213], v[168:171], v[112:115]
	v_mfma_f32_16x16x32_bf16 v[100:103], v[202:205], v[176:179], v[100:103]
	v_mfma_f32_16x16x32_bf16 v[96:99], v[210:213], v[176:179], v[96:99]
	v_mfma_f32_16x16x32_bf16 v[84:87], v[202:205], v[184:187], v[84:87]
	v_mfma_f32_16x16x32_bf16 v[80:83], v[210:213], v[184:187], v[80:83]
	v_mfma_f32_16x16x32_bf16 v[68:71], v[202:205], v[192:195], v[68:71]
	v_mfma_f32_16x16x32_bf16 v[64:67], v[210:213], v[192:195], v[64:67]
	v_mfma_f32_16x16x32_bf16 v[116:119], v[206:209], v[172:175], v[116:119]
	v_lshl_add_u64 v[222:223], s[14:15], 0, v[130:131]
	s_mov_b32 m0, s24
	s_waitcnt lgkmcnt(0)
	v_mfma_f32_16x16x32_bf16 v[112:115], v[214:217], v[172:175], v[112:115]
	v_lshl_add_u64 v[220:221], s[14:15], 0, v[134:135]
	v_mfma_f32_16x16x32_bf16 v[100:103], v[206:209], v[180:183], v[100:103]
	v_mfma_f32_16x16x32_bf16 v[96:99], v[214:217], v[180:183], v[96:99]
	v_mfma_f32_16x16x32_bf16 v[84:87], v[206:209], v[188:191], v[84:87]
	v_mfma_f32_16x16x32_bf16 v[80:83], v[214:217], v[188:191], v[80:83]
	v_mfma_f32_16x16x32_bf16 v[68:71], v[206:209], v[198:201], v[68:71]
	v_mfma_f32_16x16x32_bf16 v[64:67], v[214:217], v[198:201], v[64:67]
	s_barrier
	s_setprio 0
	ds_read_b128 v[168:171], v150 offset:16384
	ds_read_b128 v[172:175], v150 offset:17408
	ds_read_b128 v[176:179], v150 offset:18432
	ds_read_b128 v[180:183], v150 offset:19456
	ds_read_b128 v[184:187], v150 offset:20480
	ds_read_b128 v[188:191], v150 offset:21504
	ds_read_b128 v[192:195], v150 offset:22528
	ds_read_b128 v[198:201], v150 offset:23552
	global_load_lds_dwordx4 v[220:221], off
	s_mov_b32 m0, s9
	s_setprio 1
	global_load_lds_dwordx4 v[222:223], off
	s_waitcnt vmcnt(10)
	s_barrier
	s_waitcnt lgkmcnt(7)
	v_mfma_f32_16x16x32_bf16 v[60:63], v[152:155], v[168:171], v[60:63]
	v_mfma_f32_16x16x32_bf16 v[56:59], v[160:163], v[168:171], v[56:59]
	s_waitcnt lgkmcnt(5)
	v_mfma_f32_16x16x32_bf16 v[44:47], v[152:155], v[176:179], v[44:47]
	v_mfma_f32_16x16x32_bf16 v[40:43], v[160:163], v[176:179], v[40:43]
	s_waitcnt lgkmcnt(3)
	v_mfma_f32_16x16x32_bf16 v[28:31], v[152:155], v[184:187], v[28:31]
	v_mfma_f32_16x16x32_bf16 v[24:27], v[160:163], v[184:187], v[24:27]
	s_waitcnt lgkmcnt(1)
	v_mfma_f32_16x16x32_bf16 v[12:15], v[152:155], v[192:195], v[12:15]
	v_mfma_f32_16x16x32_bf16 v[8:11], v[160:163], v[192:195], v[8:11]
	v_mfma_f32_16x16x32_bf16 v[60:63], v[156:159], v[172:175], v[60:63]
	s_add_u32 s56, s12, 0x80000
	s_addc_u32 s57, s13, 0
	v_mfma_f32_16x16x32_bf16 v[56:59], v[164:167], v[172:175], v[56:59]
	s_add_i32 s3, s36, s22
	v_mfma_f32_16x16x32_bf16 v[44:47], v[156:159], v[180:183], v[44:47]
	v_mfma_f32_16x16x32_bf16 v[40:43], v[164:167], v[180:183], v[40:43]
	v_mfma_f32_16x16x32_bf16 v[28:31], v[156:159], v[188:191], v[28:31]
	v_mfma_f32_16x16x32_bf16 v[24:27], v[164:167], v[188:191], v[24:27]
	s_waitcnt lgkmcnt(0)
	v_mfma_f32_16x16x32_bf16 v[12:15], v[156:159], v[198:201], v[12:15]
	v_mfma_f32_16x16x32_bf16 v[8:11], v[164:167], v[198:201], v[8:11]
	s_barrier
; #define PG8_STAGE(bufoff, gbase, voff) do { _Pragma("unroll") for (int _i = 0; _i < 2; ++_i) \
;         __builtin_amdgcn_global_load_lds((const unsigned*)((const char*)(gbase) + (voff)[_i]), (LAS unsigned*)(lds + (bufoff) + ldsw + _i * 8192), 16, 0, 0); } while (0)
; #define PG8_LDA(dst, b, h) do { _Pragma("unroll") for (int m = 0; m < 4; ++m) _Pragma("unroll") for (int k = 0; k < 2; ++k) dst[m][k] = *(const LAS bf16x8*)(lds + PG8_SA(b, h) + aoff + m * 2048 + k * 1024); } while (0)
; #define PG8_LDB(dst, b, h) do { _Pragma("unroll") for (int n = 0; n < 2; ++n) _Pragma("unroll") for (int k = 0; k < 2; ++k) dst[n][k] = *(const LAS bf16x8*)(lds + PG8_SB(b, h) + boff + n * 2048 + k * 1024); } while (0)
; #define PG8_MMA(ai, bj, At, Bt) do { __builtin_amdgcn_s_setprio(1); _Pragma("unroll") for (int m = 0; m < 4; ++m) _Pragma("unroll") for (int n = 0; n < 2; ++n) _Pragma("unroll") for (int k = 0; k < 2; ++k) \
;         acc[ai][bj][m][n] = __builtin_amdgcn_mfma_f32_16x16x32_bf16(Bt[n][k], At[m][k], acc[ai][bj][m][n], 0, 0, 0); __builtin_amdgcn_s_setprio(0); } while (0)
; #define PG8_WAIT_V(n) asm volatile("s_waitcnt vmcnt(" #n ")" ::: "memory")
; #define PG8_WAIT_L(n) asm volatile("s_waitcnt lgkmcnt(" #n ")" ::: "memory")
; #define PG8_BAR __builtin_amdgcn_s_barrier()
; #define PG8_SCHED __builtin_amdgcn_sched_barrier(0)
; template <class Map, class Epi>
; DI void gemm_phase(LAS unsigned char* lds, const Map& MP, const Epi& E, const int nM, const int nN, const int K, const int lda, const int ldb) {
;     ...
;             PG8_WAIT_V(6); PG8_BAR; PG8_MMA(1, 1, At, B1); PG8_BAR;
;             PG8_LDB(B0, 1, 0); PG8_SCHED; PG8_LDA(At, 1, 0); PG8_STAGE(PG8_SA(0, 1), a2 + hstepA, voffA);
;             PG8_WAIT_L(8); PG8_BAR; PG8_WAIT_L(0); PG8_MMA(0, 0, At, B0); PG8_BAR; PG8_SCHED;
;             PG8_LDB(B1, 1, 1); PG8_STAGE(PG8_SB(1, 0), b3, voffB);
;             PG8_BAR; PG8_WAIT_L(0); PG8_MMA(0, 1, At, B1); PG8_BAR;
;             PG8_LDA(At, 1, 1); PG8_STAGE(PG8_SA(1, 0), a3, voffA);
;             PG8_BAR; PG8_WAIT_L(0); PG8_MMA(1, 0, At, B0); PG8_BAR; PG8_SCHED;
;             PG8_STAGE(PG8_SB(1, 1), b3 + hstepB, voffB);
;             PG8_WAIT_V(6); PG8_BAR; PG8_MMA(1, 1, At, B1); PG8_BAR;
	s_setprio 0
	s_mov_b32 m0, s3
	s_nop 0
	global_load_lds_dwordx4 v132, s[56:57]
	s_add_i32 m0, s3, 0x2000
	s_setprio 1
	global_load_lds_dwordx4 v128, s[56:57]
	s_waitcnt vmcnt(6)
	s_barrier
	v_mfma_f32_16x16x32_bf16 v[52:55], v[202:205], v[168:171], v[52:55]
	v_mfma_f32_16x16x32_bf16 v[48:51], v[210:213], v[168:171], v[48:51]
	s_add_i32 s3, 0, 0x18000
	v_add_u32_e32 v164, s3, v148
	ds_read_b128 v[152:155], v164
	v_mfma_f32_16x16x32_bf16 v[36:39], v[202:205], v[176:179], v[36:39]
	v_mfma_f32_16x16x32_bf16 v[32:35], v[210:213], v[176:179], v[32:35]
	ds_read_b128 v[156:159], v164 offset:1024
	v_mfma_f32_16x16x32_bf16 v[20:23], v[202:205], v[184:187], v[20:23]
	v_mfma_f32_16x16x32_bf16 v[16:19], v[210:213], v[184:187], v[16:19]
	ds_read_b128 v[160:163], v164 offset:2048
	v_mfma_f32_16x16x32_bf16 v[4:7], v[202:205], v[192:195], v[4:7]
	v_mfma_f32_16x16x32_bf16 v[0:3], v[210:213], v[192:195], v[0:3]
	ds_read_b128 v[164:167], v164 offset:3072
	v_mfma_f32_16x16x32_bf16 v[52:55], v[206:209], v[172:175], v[52:55]
	s_add_u32 s14, s14, 0x80000
	s_addc_u32 s15, s15, 0
	v_mfma_f32_16x16x32_bf16 v[48:51], v[214:217], v[172:175], v[48:51]
	v_mfma_f32_16x16x32_bf16 v[36:39], v[206:209], v[180:183], v[36:39]
	v_mfma_f32_16x16x32_bf16 v[32:35], v[214:217], v[180:183], v[32:35]
	v_mfma_f32_16x16x32_bf16 v[20:23], v[206:209], v[188:191], v[20:23]
	v_mfma_f32_16x16x32_bf16 v[16:19], v[214:217], v[188:191], v[16:19]
	v_mfma_f32_16x16x32_bf16 v[4:7], v[206:209], v[198:201], v[4:7]
	v_mfma_f32_16x16x32_bf16 v[0:3], v[214:217], v[198:201], v[0:3]
	s_barrier
	s_setprio 0
	s_mov_b32 m0, s25
	ds_read_b128 v[168:171], v150 offset:32768
	ds_read_b128 v[172:175], v150 offset:33792
	ds_read_b128 v[176:179], v150 offset:34816
	ds_read_b128 v[180:183], v150 offset:35840
	ds_read_b128 v[184:187], v150 offset:36864
	ds_read_b128 v[188:191], v150 offset:37888
	ds_read_b128 v[192:195], v150 offset:38912
	ds_read_b128 v[198:201], v150 offset:39936
	global_load_lds_dwordx4 v134, s[14:15]
	s_mov_b32 m0, s26
	s_setprio 1
	global_load_lds_dwordx4 v130, s[14:15]
	s_waitcnt lgkmcnt(8)
	s_barrier
	s_waitcnt lgkmcnt(7)
	v_mfma_f32_16x16x32_bf16 v[124:127], v[152:155], v[168:171], v[124:127]
	v_mfma_f32_16x16x32_bf16 v[120:123], v[160:163], v[168:171], v[120:123]
	s_waitcnt lgkmcnt(5)
	v_mfma_f32_16x16x32_bf16 v[108:111], v[152:155], v[176:179], v[108:111]
	v_mfma_f32_16x16x32_bf16 v[104:107], v[160:163], v[176:179], v[104:107]
	s_waitcnt lgkmcnt(3)
	v_mfma_f32_16x16x32_bf16 v[92:95], v[152:155], v[184:187], v[92:95]
	v_mfma_f32_16x16x32_bf16 v[88:91], v[160:163], v[184:187], v[88:91]
	s_waitcnt lgkmcnt(1)
	v_mfma_f32_16x16x32_bf16 v[76:79], v[152:155], v[192:195], v[76:79]
	v_mfma_f32_16x16x32_bf16 v[72:75], v[160:163], v[192:195], v[72:75]
	v_mfma_f32_16x16x32_bf16 v[124:127], v[156:159], v[172:175], v[124:127]
	s_add_i32 s14, 0, 0x1c000
	v_mfma_f32_16x16x32_bf16 v[120:123], v[164:167], v[172:175], v[120:123]
	s_add_i32 s3, s3, s22
	v_mfma_f32_16x16x32_bf16 v[108:111], v[156:159], v[180:183], v[108:111]
	v_add_u32_e32 v196, s14, v148
	v_mfma_f32_16x16x32_bf16 v[104:107], v[164:167], v[180:183], v[104:107]
	v_lshl_add_u64 v[144:145], v[144:145], 0, s[44:45]
	v_mfma_f32_16x16x32_bf16 v[92:95], v[156:159], v[188:191], v[92:95]
	v_mfma_f32_16x16x32_bf16 v[88:91], v[164:167], v[188:191], v[88:91]
	s_waitcnt lgkmcnt(0)
	v_mfma_f32_16x16x32_bf16 v[76:79], v[156:159], v[198:201], v[76:79]
	v_mfma_f32_16x16x32_bf16 v[72:75], v[164:167], v[198:201], v[72:75]
	s_barrier
	s_setprio 0
	s_mov_b32 m0, s3
	ds_read_b128 v[202:205], v196
	ds_read_b128 v[206:209], v196 offset:1024
	ds_read_b128 v[210:213], v196 offset:2048
	ds_read_b128 v[214:217], v196 offset:3072
	global_load_lds_dwordx4 v[144:145], off
	v_lshl_add_u64 v[144:145], v[218:219], 0, s[44:45]
	s_add_i32 m0, s3, 0x2000
	s_setprio 1
	global_load_lds_dwordx4 v[144:145], off
	s_barrier
	s_waitcnt lgkmcnt(3)
	v_mfma_f32_16x16x32_bf16 v[116:119], v[202:205], v[168:171], v[116:119]
	s_waitcnt lgkmcnt(1)
	v_mfma_f32_16x16x32_bf16 v[112:115], v[210:213], v[168:171], v[112:115]
	v_mfma_f32_16x16x32_bf16 v[100:103], v[202:205], v[176:179], v[100:103]
	v_mfma_f32_16x16x32_bf16 v[96:99], v[210:213], v[176:179], v[96:99]
	v_mfma_f32_16x16x32_bf16 v[84:87], v[202:205], v[184:187], v[84:87]
	v_mfma_f32_16x16x32_bf16 v[80:83], v[210:213], v[184:187], v[80:83]
	v_mfma_f32_16x16x32_bf16 v[68:71], v[202:205], v[192:195], v[68:71]
	v_mfma_f32_16x16x32_bf16 v[64:67], v[210:213], v[192:195], v[64:67]
	v_mfma_f32_16x16x32_bf16 v[116:119], v[206:209], v[172:175], v[116:119]
	s_mov_b32 m0, s30
	s_waitcnt lgkmcnt(0)
	v_mfma_f32_16x16x32_bf16 v[112:115], v[214:217], v[172:175], v[112:115]
	v_lshl_add_u64 v[144:145], v[220:221], 0, s[44:45]
	v_mfma_f32_16x16x32_bf16 v[100:103], v[206:209], v[180:183], v[100:103]
	v_mfma_f32_16x16x32_bf16 v[96:99], v[214:217], v[180:183], v[96:99]
	v_mfma_f32_16x16x32_bf16 v[84:87], v[206:209], v[188:191], v[84:87]
	v_mfma_f32_16x16x32_bf16 v[80:83], v[214:217], v[188:191], v[80:83]
	v_mfma_f32_16x16x32_bf16 v[68:71], v[206:209], v[198:201], v[68:71]
	v_mfma_f32_16x16x32_bf16 v[64:67], v[214:217], v[198:201], v[64:67]
	s_barrier
	s_setprio 0
	ds_read_b128 v[168:171], v150 offset:49152
	ds_read_b128 v[172:175], v150 offset:50176
	ds_read_b128 v[176:179], v150 offset:51200
	ds_read_b128 v[180:183], v150 offset:52224
	ds_read_b128 v[184:187], v150 offset:53248
	ds_read_b128 v[188:191], v150 offset:54272
	ds_read_b128 v[192:195], v150 offset:55296
	ds_read_b128 v[198:201], v150 offset:56320
	global_load_lds_dwordx4 v[144:145], off
	v_lshl_add_u64 v[144:145], v[222:223], 0, s[44:45]
	s_mov_b32 m0, s31
	s_setprio 1
	global_load_lds_dwordx4 v[144:145], off
	s_waitcnt vmcnt(10)
	s_barrier
; DI unsigned pack2(float a, float b) { f32x2 v = {a, b}; hwbf16x2 r = __builtin_convertvector(v, hwbf16x2); return __builtin_bit_cast(unsigned, r); }
; DI float bflo(unsigned w) { return __uint_as_float(w << 16); }
; DI float bfhi(unsigned w) { return __uint_as_float(w & 0xffff0000u); }
; #define PG8_WAIT_V(n) asm volatile("s_waitcnt vmcnt(" #n ")" ::: "memory")
; #define PG8_BAR __builtin_amdgcn_s_barrier()
;     DI void operator()(const f32x4 (&acc)[2][2][4][2], const Unit& u, int wr, int wc, int fr, int fq) const {
;     ...
;         for (int ai = 0; ai < 2; ++ai)
; #pragma unroll
;             for (int m = 0; m < 4; ++m) { const size_t ro = (size_t)(row0 + ai * HALF + m * 16) * D + col0;
; #pragma unroll
;                 for (int bj = 0; bj < 2; ++bj) {
;                     f32x4 x0, x1;
;                     if constexpr (IB) { const u32x4 w = *(const u32x4*)((const bf16_t*)Xin + ro + bj * HALF);
;                         x0 = (f32x4){bflo(w[0]), bfhi(w[0]), bflo(w[1]), bfhi(w[1])}; x1 = (f32x4){bflo(w[2]), bfhi(w[2]), bflo(w[3]), bfhi(w[3])}; }
;                     else { x0 = *(const f32x4*)((const float*)Xin + ro + bj * HALF); x1 = *(const f32x4*)((const float*)Xin + ro + bj * HALF + 4); }
;                     x0 += acc[ai][bj][m][0] * sc[bj][0]; x1 += acc[ai][bj][m][1] * sc[bj][1];
;                     if constexpr (OB) { u32x4 o; o[0] = pack2(x0[0], x0[1]); o[1] = pack2(x0[2], x0[3]); o[2] = pack2(x1[0], x1[1]); o[3] = pack2(x1[2], x1[3]);
;                         *(u32x4*)((bf16_t*)Xout + ro + bj * HALF) = o; }
;                     else { *(f32x4*)((float*)Xout + ro + bj * HALF) = x0; *(f32x4*)((float*)Xout + ro + bj * HALF + 4) = x1; } } }
; template <class Map, class Epi>
; DI void gemm_phase(LAS unsigned char* lds, const Map& MP, const Epi& E, const int nM, const int nN, const int K, const int lda, const int ldb) {
;     ...
;             PG8_WAIT_L(8); PG8_BAR; PG8_WAIT_L(0); PG8_MMA(0, 0, At, B0); PG8_BAR; PG8_SCHED;
;             PG8_LDB(B1, 1, 1); PG8_STAGE(PG8_SB(1, 0), b3, voffB);
;             PG8_BAR; PG8_WAIT_L(0); PG8_MMA(0, 1, At, B1); PG8_BAR;
;             PG8_LDA(At, 1, 1); PG8_STAGE(PG8_SA(1, 0), a3, voffA);
;             PG8_BAR; PG8_WAIT_L(0); PG8_MMA(1, 0, At, B0); PG8_BAR; PG8_SCHED;
;             PG8_STAGE(PG8_SB(1, 1), b3 + hstepB, voffB);
;             PG8_WAIT_V(6); PG8_BAR; PG8_MMA(1, 1, At, B1); PG8_BAR;
	s_waitcnt lgkmcnt(7)
	v_mfma_f32_16x16x32_bf16 v[60:63], v[152:155], v[168:171], v[60:63]
	v_mfma_f32_16x16x32_bf16 v[56:59], v[160:163], v[168:171], v[56:59]
	s_waitcnt lgkmcnt(5)
	v_mfma_f32_16x16x32_bf16 v[44:47], v[152:155], v[176:179], v[44:47]
	v_mfma_f32_16x16x32_bf16 v[40:43], v[160:163], v[176:179], v[40:43]
	s_waitcnt lgkmcnt(3)
	v_mfma_f32_16x16x32_bf16 v[28:31], v[152:155], v[184:187], v[28:31]
	v_mfma_f32_16x16x32_bf16 v[24:27], v[160:163], v[184:187], v[24:27]
	s_waitcnt lgkmcnt(1)
	v_mfma_f32_16x16x32_bf16 v[12:15], v[152:155], v[192:195], v[12:15]
	v_mfma_f32_16x16x32_bf16 v[8:11], v[160:163], v[192:195], v[8:11]
	v_mfma_f32_16x16x32_bf16 v[60:63], v[156:159], v[172:175], v[60:63]
	s_add_u32 s12, s12, 0x80080
	s_addc_u32 s13, s13, 0
	v_mfma_f32_16x16x32_bf16 v[56:59], v[164:167], v[172:175], v[56:59]
	s_add_i32 s3, s14, s22
	v_mfma_f32_16x16x32_bf16 v[44:47], v[156:159], v[180:183], v[44:47]
	v_mfma_f32_16x16x32_bf16 v[40:43], v[164:167], v[180:183], v[40:43]
	v_mfma_f32_16x16x32_bf16 v[28:31], v[156:159], v[188:191], v[28:31]
	v_mfma_f32_16x16x32_bf16 v[24:27], v[164:167], v[188:191], v[24:27]
	s_waitcnt lgkmcnt(0)
	v_mfma_f32_16x16x32_bf16 v[12:15], v[156:159], v[198:201], v[12:15]
	v_mfma_f32_16x16x32_bf16 v[8:11], v[164:167], v[198:201], v[8:11]
	s_barrier
	s_setprio 0
	s_mov_b32 m0, s3
	s_nop 0
	global_load_lds_dwordx4 v132, s[12:13]
	s_add_i32 m0, s3, 0x2000
	s_setprio 1
	global_load_lds_dwordx4 v128, s[12:13]
	s_waitcnt vmcnt(6)
	s_barrier
	v_mfma_f32_16x16x32_bf16 v[52:55], v[202:205], v[168:171], v[52:55]
	v_mfma_f32_16x16x32_bf16 v[48:51], v[210:213], v[168:171], v[48:51]
	ds_read_b128 v[152:155], v149
	v_mfma_f32_16x16x32_bf16 v[36:39], v[202:205], v[176:179], v[36:39]
	v_mfma_f32_16x16x32_bf16 v[32:35], v[210:213], v[176:179], v[32:35]
	ds_read_b128 v[156:159], v149 offset:1024
	v_mfma_f32_16x16x32_bf16 v[20:23], v[202:205], v[184:187], v[20:23]
	v_mfma_f32_16x16x32_bf16 v[16:19], v[210:213], v[184:187], v[16:19]
	ds_read_b128 v[160:163], v149 offset:2048
	v_mfma_f32_16x16x32_bf16 v[4:7], v[202:205], v[192:195], v[4:7]
	v_mfma_f32_16x16x32_bf16 v[0:3], v[210:213], v[192:195], v[0:3]
	ds_read_b128 v[164:167], v149 offset:3072
	v_mfma_f32_16x16x32_bf16 v[52:55], v[206:209], v[172:175], v[52:55]
	s_add_i32 s48, s48, 2
	v_mfma_f32_16x16x32_bf16 v[48:51], v[214:217], v[172:175], v[48:51]
	s_add_u32 s39, s39, 0x100
	s_addc_u32 s47, s47, 0
	v_mfma_f32_16x16x32_bf16 v[36:39], v[206:209], v[180:183], v[36:39]
	s_add_u32 s10, s10, 0x100
	s_addc_u32 s11, s11, 0
	v_mfma_f32_16x16x32_bf16 v[32:35], v[214:217], v[180:183], v[32:35]
	s_cmp_gt_u32 s48, 29
	v_mfma_f32_16x16x32_bf16 v[20:23], v[206:209], v[188:191], v[20:23]
	v_mfma_f32_16x16x32_bf16 v[16:19], v[214:217], v[188:191], v[16:19]
	v_mfma_f32_16x16x32_bf16 v[4:7], v[206:209], v[198:201], v[4:7]
	v_mfma_f32_16x16x32_bf16 v[0:3], v[214:217], v[198:201], v[0:3]
	s_barrier
	s_setprio 0
	s_cbranch_scc0 .LBB1_925
	s_waitcnt lgkmcnt(0)
	v_mov_b32_e32 v152, v147
	v_mov_b32_e32 v144, v146
	s_lshl_b32 s2, s2, 8
	s_or_b32 s2, s2, s29
	v_lshl_add_u32 v144, v144, 3, s2
	s_lshl_b32 s2, s8, 8
	s_add_i32 s2, s2, s28
	v_add_u32_e32 v152, s2, v152
	v_ashrrev_i32_e32 v153, 31, v152
	v_lshlrev_b64 v[152:153], 12, v[152:153]
	v_ashrrev_i32_e32 v145, 31, v144
	v_lshl_add_u64 v[152:153], s[42:43], 0, v[152:153]
	v_lshl_add_u64 v[144:145], v[144:145], 1, v[152:153]
	global_load_dwordx4 v[160:163], v[144:145], off
	global_load_dwordx4 v[164:167], v[144:145], off offset:256
	s_mov_b64 s[98:99], 0x10000
	v_lshl_add_u64 v[154:155], v[144:145], 0, s[98:99]
	global_load_dwordx4 v[168:171], v[154:155], off
	global_load_dwordx4 v[172:175], v[154:155], off offset:256
	s_mov_b64 s[98:99], 0x20000
	v_lshl_add_u64 v[154:155], v[144:145], 0, s[98:99]
	global_load_dwordx4 v[176:179], v[154:155], off
	global_load_dwordx4 v[180:183], v[154:155], off offset:256
	s_mov_b64 s[98:99], 0x30000
	v_lshl_add_u64 v[154:155], v[144:145], 0, s[98:99]
	global_load_dwordx4 v[184:187], v[154:155], off
	global_load_dwordx4 v[188:191], v[154:155], off offset:256
	s_mov_b64 s[98:99], 0x80000
	v_lshl_add_u64 v[154:155], v[144:145], 0, s[98:99]
	global_load_dwordx4 v[192:195], v[154:155], off
	global_load_dwordx4 v[198:201], v[154:155], off offset:256
	s_mov_b64 s[98:99], 0x90000
	v_lshl_add_u64 v[154:155], v[144:145], 0, s[98:99]
	global_load_dwordx4 v[202:205], v[154:155], off
	global_load_dwordx4 v[206:209], v[154:155], off offset:256
	s_mov_b64 s[98:99], 0xa0000
	v_lshl_add_u64 v[154:155], v[144:145], 0, s[98:99]
	global_load_dwordx4 v[210:213], v[154:155], off
	global_load_dwordx4 v[214:217], v[154:155], off offset:256
	s_mov_b64 s[98:99], 0xb0000
	v_lshl_add_u64 v[154:155], v[144:145], 0, s[98:99]
	global_load_dwordx4 v[248:251], v[154:155], off
	global_load_dwordx4 v[252:255], v[154:155], off offset:256
	s_waitcnt vmcnt(15)
	s_nop 1
	v_mov_b32_e32 v152, v160
	v_mov_b32_e32 v153, v161
	v_mov_b32_e32 v154, v162
	v_mov_b32_e32 v155, v163
	s_mov_b64 s[2:3], 0x10000
	s_mov_b32 s8, s52
	s_mov_b64 s[10:11], s[6:7]
	s_mov_b64 s[12:13], s[54:55]
	s_waitcnt lgkmcnt(0)
	v_lshlrev_b32_e32 v156, 16, v152
	v_and_b32_e32 v157, 0xffff0000, v152
	v_lshlrev_b32_e32 v152, 16, v153
	v_and_b32_e32 v153, 0xffff0000, v153
	v_lshlrev_b32_e32 v158, 16, v154
	v_and_b32_e32 v159, 0xffff0000, v154
	v_lshlrev_b32_e32 v154, 16, v155
	v_and_b32_e32 v155, 0xffff0000, v155
	v_pk_add_f32 v[126:127], v[126:127], v[152:153]
	v_pk_add_f32 v[124:125], v[124:125], v[156:157]
	v_pk_add_f32 v[152:153], v[122:123], v[154:155]
	v_pk_add_f32 v[122:123], v[120:121], v[158:159]
	v_cvt_pk_bf16_f32 v120, v124, v125
	v_cvt_pk_bf16_f32 v121, v126, v127
	v_cvt_pk_bf16_f32 v122, v122, v123
	v_cvt_pk_bf16_f32 v123, v152, v153
	global_store_dwordx4 v[144:145], v[120:123], off
	s_waitcnt vmcnt(15)
; DI unsigned pack2(float a, float b) { f32x2 v = {a, b}; hwbf16x2 r = __builtin_convertvector(v, hwbf16x2); return __builtin_bit_cast(unsigned, r); }
; DI float bflo(unsigned w) { return __uint_as_float(w << 16); }
; DI float bfhi(unsigned w) { return __uint_as_float(w & 0xffff0000u); }
;     DI void operator()(const f32x4 (&acc)[2][2][4][2], const Unit& u, int wr, int wc, int fr, int fq) const {
;     ...
;         for (int ai = 0; ai < 2; ++ai)
; #pragma unroll
;             for (int m = 0; m < 4; ++m) { const size_t ro = (size_t)(row0 + ai * HALF + m * 16) * D + col0;
; #pragma unroll
;                 for (int bj = 0; bj < 2; ++bj) {
;                     f32x4 x0, x1;
;                     if constexpr (IB) { const u32x4 w = *(const u32x4*)((const bf16_t*)Xin + ro + bj * HALF);
;                         x0 = (f32x4){bflo(w[0]), bfhi(w[0]), bflo(w[1]), bfhi(w[1])}; x1 = (f32x4){bflo(w[2]), bfhi(w[2]), bflo(w[3]), bfhi(w[3])}; }
;                     else { x0 = *(const f32x4*)((const float*)Xin + ro + bj * HALF); x1 = *(const f32x4*)((const float*)Xin + ro + bj * HALF + 4); }
;                     x0 += acc[ai][bj][m][0] * sc[bj][0]; x1 += acc[ai][bj][m][1] * sc[bj][1];
;                     if constexpr (OB) { u32x4 o; o[0] = pack2(x0[0], x0[1]); o[1] = pack2(x0[2], x0[3]); o[2] = pack2(x1[0], x1[1]); o[3] = pack2(x1[2], x1[3]);
;                         *(u32x4*)((bf16_t*)Xout + ro + bj * HALF) = o; }
;                     else { *(f32x4*)((float*)Xout + ro + bj * HALF) = x0; *(f32x4*)((float*)Xout + ro + bj * HALF + 4) = x1; } } }
	s_nop 1
	v_mov_b32_e32 v120, v164
	v_mov_b32_e32 v121, v165
	v_mov_b32_e32 v122, v166
	v_mov_b32_e32 v123, v167
	s_waitcnt lgkmcnt(0)
	v_lshlrev_b32_e32 v124, 16, v120
	v_and_b32_e32 v125, 0xffff0000, v120
	v_lshlrev_b32_e32 v120, 16, v121
	v_and_b32_e32 v121, 0xffff0000, v121
	v_lshlrev_b32_e32 v126, 16, v122
	v_and_b32_e32 v127, 0xffff0000, v122
	v_lshlrev_b32_e32 v122, 16, v123
	v_and_b32_e32 v123, 0xffff0000, v123
	v_pk_add_f32 v[116:117], v[116:117], v[124:125]
	v_pk_add_f32 v[118:119], v[118:119], v[120:121]
	v_pk_add_f32 v[120:121], v[114:115], v[122:123]
	v_pk_add_f32 v[114:115], v[112:113], v[126:127]
	v_cvt_pk_bf16_f32 v112, v116, v117
	v_lshl_add_u64 v[116:117], v[144:145], 0, s[2:3]
	s_mov_b32 s2, 0x10000
	v_cvt_pk_bf16_f32 v113, v118, v119
	v_add_co_u32_e32 v118, vcc, s2, v144
	v_cvt_pk_bf16_f32 v114, v114, v115
	v_cvt_pk_bf16_f32 v115, v120, v121
	v_addc_co_u32_e32 v119, vcc, 0, v145, vcc
	global_store_dwordx4 v[144:145], v[112:115], off offset:256
	s_waitcnt vmcnt(15)
	s_nop 1
	v_mov_b32_e32 v112, v168
	v_mov_b32_e32 v113, v169
	v_mov_b32_e32 v114, v170
	v_mov_b32_e32 v115, v171
	s_mov_b64 s[2:3], 0x20000
	s_waitcnt lgkmcnt(0)
	v_lshlrev_b32_e32 v120, 16, v112
	v_and_b32_e32 v121, 0xffff0000, v112
	v_lshlrev_b32_e32 v112, 16, v113
	v_and_b32_e32 v113, 0xffff0000, v113
	v_lshlrev_b32_e32 v122, 16, v114
	v_and_b32_e32 v123, 0xffff0000, v114
	v_lshlrev_b32_e32 v114, 16, v115
	v_and_b32_e32 v115, 0xffff0000, v115
	v_pk_add_f32 v[110:111], v[110:111], v[112:113]
	v_pk_add_f32 v[108:109], v[108:109], v[120:121]
	v_pk_add_f32 v[112:113], v[106:107], v[114:115]
	v_pk_add_f32 v[106:107], v[104:105], v[122:123]
	v_cvt_pk_bf16_f32 v104, v108, v109
	v_cvt_pk_bf16_f32 v105, v110, v111
	v_cvt_pk_bf16_f32 v106, v106, v107
	v_cvt_pk_bf16_f32 v107, v112, v113
	global_store_dwordx4 v[118:119], v[104:107], off
	s_waitcnt vmcnt(15)
	s_nop 1
	v_mov_b32_e32 v104, v172
	v_mov_b32_e32 v105, v173
	v_mov_b32_e32 v106, v174
	v_mov_b32_e32 v107, v175
	s_waitcnt lgkmcnt(0)
	v_lshlrev_b32_e32 v108, 16, v104
	v_and_b32_e32 v109, 0xffff0000, v104
	v_lshlrev_b32_e32 v104, 16, v105
	v_and_b32_e32 v105, 0xffff0000, v105
	v_lshlrev_b32_e32 v110, 16, v106
	v_and_b32_e32 v111, 0xffff0000, v106
	v_lshlrev_b32_e32 v106, 16, v107
	v_and_b32_e32 v107, 0xffff0000, v107
	v_pk_add_f32 v[100:101], v[100:101], v[108:109]
	v_pk_add_f32 v[102:103], v[102:103], v[104:105]
	v_pk_add_f32 v[104:105], v[98:99], v[106:107]
	v_pk_add_f32 v[98:99], v[96:97], v[110:111]
	v_cvt_pk_bf16_f32 v96, v100, v101
	v_lshl_add_u64 v[100:101], v[144:145], 0, s[2:3]
	s_mov_b32 s2, 0x20000
	v_cvt_pk_bf16_f32 v97, v102, v103
	v_add_co_u32_e32 v102, vcc, s2, v144
	v_cvt_pk_bf16_f32 v98, v98, v99
	v_cvt_pk_bf16_f32 v99, v104, v105
	v_addc_co_u32_e32 v103, vcc, 0, v145, vcc
	global_store_dwordx4 v[116:117], v[96:99], off offset:256
	s_waitcnt vmcnt(15)
	s_nop 1
	v_mov_b32_e32 v96, v176
	v_mov_b32_e32 v97, v177
	v_mov_b32_e32 v98, v178
	v_mov_b32_e32 v99, v179
	s_mov_b64 s[2:3], 0x30000
	s_waitcnt lgkmcnt(0)
	v_lshlrev_b32_e32 v104, 16, v96
	v_and_b32_e32 v105, 0xffff0000, v96
	v_lshlrev_b32_e32 v96, 16, v97
	v_and_b32_e32 v97, 0xffff0000, v97
	v_lshlrev_b32_e32 v106, 16, v98
	v_and_b32_e32 v107, 0xffff0000, v98
	v_lshlrev_b32_e32 v98, 16, v99
	v_and_b32_e32 v99, 0xffff0000, v99
	v_pk_add_f32 v[94:95], v[94:95], v[96:97]
	v_pk_add_f32 v[92:93], v[92:93], v[104:105]
	v_pk_add_f32 v[96:97], v[90:91], v[98:99]
	v_pk_add_f32 v[90:91], v[88:89], v[106:107]
	v_cvt_pk_bf16_f32 v88, v92, v93
	v_cvt_pk_bf16_f32 v89, v94, v95
	v_cvt_pk_bf16_f32 v90, v90, v91
	v_cvt_pk_bf16_f32 v91, v96, v97
	global_store_dwordx4 v[102:103], v[88:91], off
	s_waitcnt vmcnt(15)
	s_nop 1
	v_mov_b32_e32 v88, v180
	v_mov_b32_e32 v89, v181
	v_mov_b32_e32 v90, v182
	v_mov_b32_e32 v91, v183
	s_waitcnt lgkmcnt(0)
	v_lshlrev_b32_e32 v92, 16, v88
	v_and_b32_e32 v93, 0xffff0000, v88
	v_lshlrev_b32_e32 v88, 16, v89
	v_and_b32_e32 v89, 0xffff0000, v89
	v_lshlrev_b32_e32 v94, 16, v90
	v_and_b32_e32 v95, 0xffff0000, v90
	v_lshlrev_b32_e32 v90, 16, v91
	v_and_b32_e32 v91, 0xffff0000, v91
	v_pk_add_f32 v[86:87], v[86:87], v[88:89]
	v_pk_add_f32 v[84:85], v[84:85], v[92:93]
	v_pk_add_f32 v[88:89], v[82:83], v[90:91]
	v_pk_add_f32 v[82:83], v[80:81], v[94:95]
	v_cvt_pk_bf16_f32 v80, v84, v85
	v_cvt_pk_bf16_f32 v81, v86, v87
	v_cvt_pk_bf16_f32 v82, v82, v83
	v_cvt_pk_bf16_f32 v83, v88, v89
	global_store_dwordx4 v[100:101], v[80:83], off offset:256
	s_nop 1
	v_lshl_add_u64 v[80:81], v[144:145], 0, s[2:3]
	s_mov_b32 s2, 0x30000
	v_add_co_u32_e32 v86, vcc, s2, v144
	s_mov_b64 s[2:3], 0x80000
	s_nop 0
	v_addc_co_u32_e32 v87, vcc, 0, v145, vcc
	s_waitcnt vmcnt(15)
	s_nop 1
	v_mov_b32_e32 v82, v184
	v_mov_b32_e32 v83, v185
	v_mov_b32_e32 v84, v186
	v_mov_b32_e32 v85, v187
	s_waitcnt lgkmcnt(0)
	v_lshlrev_b32_e32 v88, 16, v82
	v_and_b32_e32 v89, 0xffff0000, v82
	v_lshlrev_b32_e32 v82, 16, v83
	v_and_b32_e32 v83, 0xffff0000, v83
	v_lshlrev_b32_e32 v90, 16, v84
	v_and_b32_e32 v91, 0xffff0000, v84
	v_lshlrev_b32_e32 v84, 16, v85
	v_and_b32_e32 v85, 0xffff0000, v85
	v_pk_add_f32 v[78:79], v[78:79], v[82:83]
	v_pk_add_f32 v[76:77], v[76:77], v[88:89]
	v_pk_add_f32 v[82:83], v[74:75], v[84:85]
	v_pk_add_f32 v[74:75], v[72:73], v[90:91]
	v_cvt_pk_bf16_f32 v72, v76, v77
	v_cvt_pk_bf16_f32 v73, v78, v79
	v_cvt_pk_bf16_f32 v74, v74, v75
	v_cvt_pk_bf16_f32 v75, v82, v83
	global_store_dwordx4 v[86:87], v[72:75], off
	s_waitcnt vmcnt(15)
	s_nop 1
	v_mov_b32_e32 v72, v188
	v_mov_b32_e32 v73, v189
	v_mov_b32_e32 v74, v190
	v_mov_b32_e32 v75, v191
	s_waitcnt lgkmcnt(0)
; DI unsigned pack2(float a, float b) { f32x2 v = {a, b}; hwbf16x2 r = __builtin_convertvector(v, hwbf16x2); return __builtin_bit_cast(unsigned, r); }
; DI float bflo(unsigned w) { return __uint_as_float(w << 16); }
; DI float bfhi(unsigned w) { return __uint_as_float(w & 0xffff0000u); }
;     DI void operator()(const f32x4 (&acc)[2][2][4][2], const Unit& u, int wr, int wc, int fr, int fq) const {
;     ...
;         for (int ai = 0; ai < 2; ++ai)
; #pragma unroll
;             for (int m = 0; m < 4; ++m) { const size_t ro = (size_t)(row0 + ai * HALF + m * 16) * D + col0;
; #pragma unroll
;                 for (int bj = 0; bj < 2; ++bj) {
;                     f32x4 x0, x1;
;                     if constexpr (IB) { const u32x4 w = *(const u32x4*)((const bf16_t*)Xin + ro + bj * HALF);
;                         x0 = (f32x4){bflo(w[0]), bfhi(w[0]), bflo(w[1]), bfhi(w[1])}; x1 = (f32x4){bflo(w[2]), bfhi(w[2]), bflo(w[3]), bfhi(w[3])}; }
;                     else { x0 = *(const f32x4*)((const float*)Xin + ro + bj * HALF); x1 = *(const f32x4*)((const float*)Xin + ro + bj * HALF + 4); }
;                     x0 += acc[ai][bj][m][0] * sc[bj][0]; x1 += acc[ai][bj][m][1] * sc[bj][1];
;                     if constexpr (OB) { u32x4 o; o[0] = pack2(x0[0], x0[1]); o[1] = pack2(x0[2], x0[3]); o[2] = pack2(x1[0], x1[1]); o[3] = pack2(x1[2], x1[3]);
;                         *(u32x4*)((bf16_t*)Xout + ro + bj * HALF) = o; }
;                     else { *(f32x4*)((float*)Xout + ro + bj * HALF) = x0; *(f32x4*)((float*)Xout + ro + bj * HALF + 4) = x1; } } }
	v_lshlrev_b32_e32 v76, 16, v72
	v_and_b32_e32 v77, 0xffff0000, v72
	v_lshlrev_b32_e32 v72, 16, v73
	v_and_b32_e32 v73, 0xffff0000, v73
	v_lshlrev_b32_e32 v78, 16, v74
	v_and_b32_e32 v79, 0xffff0000, v74
	v_lshlrev_b32_e32 v74, 16, v75
	v_and_b32_e32 v75, 0xffff0000, v75
	v_pk_add_f32 v[70:71], v[70:71], v[72:73]
	v_pk_add_f32 v[68:69], v[68:69], v[76:77]
	v_pk_add_f32 v[72:73], v[66:67], v[74:75]
	v_pk_add_f32 v[66:67], v[64:65], v[78:79]
	v_cvt_pk_bf16_f32 v64, v68, v69
	v_cvt_pk_bf16_f32 v65, v70, v71
	v_cvt_pk_bf16_f32 v66, v66, v67
	v_cvt_pk_bf16_f32 v67, v72, v73
	global_store_dwordx4 v[80:81], v[64:67], off offset:256
	s_nop 1
	v_lshl_add_u64 v[64:65], v[144:145], 0, s[2:3]
	s_mov_b32 s2, 0x80000
	v_add_co_u32_e32 v70, vcc, s2, v144
	s_mov_b64 s[2:3], 0x90000
	s_nop 0
	v_addc_co_u32_e32 v71, vcc, 0, v145, vcc
	s_waitcnt vmcnt(15)
	s_nop 1
	v_mov_b32_e32 v66, v192
	v_mov_b32_e32 v67, v193
	v_mov_b32_e32 v68, v194
	v_mov_b32_e32 v69, v195
	s_waitcnt lgkmcnt(0)
	v_lshlrev_b32_e32 v72, 16, v66
	v_and_b32_e32 v73, 0xffff0000, v66
	v_lshlrev_b32_e32 v66, 16, v67
	v_and_b32_e32 v67, 0xffff0000, v67
	v_lshlrev_b32_e32 v74, 16, v68
	v_and_b32_e32 v75, 0xffff0000, v68
	v_lshlrev_b32_e32 v68, 16, v69
	v_and_b32_e32 v69, 0xffff0000, v69
	v_pk_add_f32 v[62:63], v[62:63], v[66:67]
	v_pk_add_f32 v[60:61], v[60:61], v[72:73]
	v_pk_add_f32 v[66:67], v[58:59], v[68:69]
	v_pk_add_f32 v[58:59], v[56:57], v[74:75]
	v_cvt_pk_bf16_f32 v56, v60, v61
	v_cvt_pk_bf16_f32 v57, v62, v63
	v_cvt_pk_bf16_f32 v58, v58, v59
	v_cvt_pk_bf16_f32 v59, v66, v67
	global_store_dwordx4 v[70:71], v[56:59], off
	s_waitcnt vmcnt(15)
	s_nop 1
	v_mov_b32_e32 v56, v198
	v_mov_b32_e32 v57, v199
	v_mov_b32_e32 v58, v200
	v_mov_b32_e32 v59, v201
	s_waitcnt lgkmcnt(0)
	v_lshlrev_b32_e32 v60, 16, v56
	v_and_b32_e32 v61, 0xffff0000, v56
	v_lshlrev_b32_e32 v56, 16, v57
	v_and_b32_e32 v57, 0xffff0000, v57
	v_lshlrev_b32_e32 v62, 16, v58
	v_and_b32_e32 v63, 0xffff0000, v58
	v_lshlrev_b32_e32 v58, 16, v59
	v_and_b32_e32 v59, 0xffff0000, v59
	v_pk_add_f32 v[54:55], v[54:55], v[56:57]
	v_pk_add_f32 v[52:53], v[52:53], v[60:61]
	v_pk_add_f32 v[56:57], v[50:51], v[58:59]
	v_pk_add_f32 v[50:51], v[48:49], v[62:63]
	v_cvt_pk_bf16_f32 v48, v52, v53
	v_cvt_pk_bf16_f32 v49, v54, v55
	v_cvt_pk_bf16_f32 v50, v50, v51
	v_cvt_pk_bf16_f32 v51, v56, v57
	global_store_dwordx4 v[64:65], v[48:51], off offset:256
	s_nop 1
	v_lshl_add_u64 v[48:49], v[144:145], 0, s[2:3]
	s_mov_b32 s2, 0x90000
	v_add_co_u32_e32 v54, vcc, s2, v144
	s_mov_b64 s[2:3], 0xa0000
	s_nop 0
	v_addc_co_u32_e32 v55, vcc, 0, v145, vcc
	s_waitcnt vmcnt(15)
	s_nop 1
	v_mov_b32_e32 v50, v202
	v_mov_b32_e32 v51, v203
	v_mov_b32_e32 v52, v204
	v_mov_b32_e32 v53, v205
	s_waitcnt lgkmcnt(0)
	v_lshlrev_b32_e32 v56, 16, v50
	v_and_b32_e32 v57, 0xffff0000, v50
	v_lshlrev_b32_e32 v50, 16, v51
	v_and_b32_e32 v51, 0xffff0000, v51
	v_lshlrev_b32_e32 v58, 16, v52
	v_and_b32_e32 v59, 0xffff0000, v52
	v_lshlrev_b32_e32 v52, 16, v53
	v_and_b32_e32 v53, 0xffff0000, v53
	v_pk_add_f32 v[46:47], v[46:47], v[50:51]
	v_pk_add_f32 v[44:45], v[44:45], v[56:57]
	v_pk_add_f32 v[50:51], v[42:43], v[52:53]
	v_pk_add_f32 v[42:43], v[40:41], v[58:59]
	v_cvt_pk_bf16_f32 v40, v44, v45
	v_cvt_pk_bf16_f32 v41, v46, v47
	v_cvt_pk_bf16_f32 v42, v42, v43
	v_cvt_pk_bf16_f32 v43, v50, v51
	global_store_dwordx4 v[54:55], v[40:43], off
	s_waitcnt vmcnt(15)
	s_nop 1
	v_mov_b32_e32 v40, v206
	v_mov_b32_e32 v41, v207
	v_mov_b32_e32 v42, v208
	v_mov_b32_e32 v43, v209
	s_waitcnt lgkmcnt(0)
; DI unsigned pack2(float a, float b) { f32x2 v = {a, b}; hwbf16x2 r = __builtin_convertvector(v, hwbf16x2); return __builtin_bit_cast(unsigned, r); }
; DI float bflo(unsigned w) { return __uint_as_float(w << 16); }
; DI float bfhi(unsigned w) { return __uint_as_float(w & 0xffff0000u); }
; #define PG8_WAIT_V(n) asm volatile("s_waitcnt vmcnt(" #n ")" ::: "memory")
; #define PG8_BAR __builtin_amdgcn_s_barrier()
;     DI void operator()(const f32x4 (&acc)[2][2][4][2], const Unit& u, int wr, int wc, int fr, int fq) const {
;     ...
;         for (int ai = 0; ai < 2; ++ai)
; #pragma unroll
;             for (int m = 0; m < 4; ++m) { const size_t ro = (size_t)(row0 + ai * HALF + m * 16) * D + col0;
; #pragma unroll
;                 for (int bj = 0; bj < 2; ++bj) {
;                     f32x4 x0, x1;
;                     if constexpr (IB) { const u32x4 w = *(const u32x4*)((const bf16_t*)Xin + ro + bj * HALF);
;                         x0 = (f32x4){bflo(w[0]), bfhi(w[0]), bflo(w[1]), bfhi(w[1])}; x1 = (f32x4){bflo(w[2]), bfhi(w[2]), bflo(w[3]), bfhi(w[3])}; }
;                     else { x0 = *(const f32x4*)((const float*)Xin + ro + bj * HALF); x1 = *(const f32x4*)((const float*)Xin + ro + bj * HALF + 4); }
;                     x0 += acc[ai][bj][m][0] * sc[bj][0]; x1 += acc[ai][bj][m][1] * sc[bj][1];
;                     if constexpr (OB) { u32x4 o; o[0] = pack2(x0[0], x0[1]); o[1] = pack2(x0[2], x0[3]); o[2] = pack2(x1[0], x1[1]); o[3] = pack2(x1[2], x1[3]);
;                         *(u32x4*)((bf16_t*)Xout + ro + bj * HALF) = o; }
;                     else { *(f32x4*)((float*)Xout + ro + bj * HALF) = x0; *(f32x4*)((float*)Xout + ro + bj * HALF + 4) = x1; } } }
; template <class Map, class Epi>
; DI void gemm_phase(LAS unsigned char* lds, const Map& MP, const Epi& E, const int nM, const int nN, const int K, const int lda, const int ldb) {
;     ...
;     PG8_WAIT_V(0);
;     if (wr == 0) PG8_BAR;
;     PG8_BAR;
	v_lshlrev_b32_e32 v44, 16, v40
	v_and_b32_e32 v45, 0xffff0000, v40
	v_lshlrev_b32_e32 v40, 16, v41
	v_and_b32_e32 v41, 0xffff0000, v41
	v_lshlrev_b32_e32 v46, 16, v42
	v_and_b32_e32 v47, 0xffff0000, v42
	v_lshlrev_b32_e32 v42, 16, v43
	v_and_b32_e32 v43, 0xffff0000, v43
	v_pk_add_f32 v[38:39], v[38:39], v[40:41]
	v_pk_add_f32 v[36:37], v[36:37], v[44:45]
	v_pk_add_f32 v[40:41], v[34:35], v[42:43]
	v_pk_add_f32 v[34:35], v[32:33], v[46:47]
	v_cvt_pk_bf16_f32 v32, v36, v37
	v_cvt_pk_bf16_f32 v33, v38, v39
	v_cvt_pk_bf16_f32 v34, v34, v35
	v_cvt_pk_bf16_f32 v35, v40, v41
	global_store_dwordx4 v[48:49], v[32:35], off offset:256
	s_nop 1
	v_lshl_add_u64 v[32:33], v[144:145], 0, s[2:3]
	s_mov_b32 s2, 0xa0000
	v_add_co_u32_e32 v38, vcc, s2, v144
	s_mov_b64 s[2:3], 0xb0000
	s_nop 0
	v_addc_co_u32_e32 v39, vcc, 0, v145, vcc
	s_waitcnt vmcnt(15)
	s_nop 1
	v_mov_b32_e32 v34, v210
	v_mov_b32_e32 v35, v211
	v_mov_b32_e32 v36, v212
	v_mov_b32_e32 v37, v213
	s_waitcnt lgkmcnt(0)
	v_lshlrev_b32_e32 v40, 16, v34
	v_and_b32_e32 v41, 0xffff0000, v34
	v_lshlrev_b32_e32 v34, 16, v35
	v_and_b32_e32 v35, 0xffff0000, v35
	v_lshlrev_b32_e32 v42, 16, v36
	v_and_b32_e32 v43, 0xffff0000, v36
	v_lshlrev_b32_e32 v36, 16, v37
	v_and_b32_e32 v37, 0xffff0000, v37
	v_pk_add_f32 v[30:31], v[30:31], v[34:35]
	v_pk_add_f32 v[28:29], v[28:29], v[40:41]
	v_pk_add_f32 v[34:35], v[26:27], v[36:37]
	v_pk_add_f32 v[26:27], v[24:25], v[42:43]
	v_cvt_pk_bf16_f32 v24, v28, v29
	v_cvt_pk_bf16_f32 v25, v30, v31
	v_cvt_pk_bf16_f32 v26, v26, v27
	v_cvt_pk_bf16_f32 v27, v34, v35
	global_store_dwordx4 v[38:39], v[24:27], off
	s_waitcnt vmcnt(15)
	s_nop 1
	v_mov_b32_e32 v24, v214
	v_mov_b32_e32 v25, v215
	v_mov_b32_e32 v26, v216
	v_mov_b32_e32 v27, v217
	s_waitcnt lgkmcnt(0)
	v_lshlrev_b32_e32 v28, 16, v24
	v_and_b32_e32 v29, 0xffff0000, v24
	v_lshlrev_b32_e32 v24, 16, v25
	v_and_b32_e32 v25, 0xffff0000, v25
	v_lshlrev_b32_e32 v30, 16, v26
	v_and_b32_e32 v31, 0xffff0000, v26
	v_lshlrev_b32_e32 v26, 16, v27
	v_and_b32_e32 v27, 0xffff0000, v27
	v_pk_add_f32 v[22:23], v[22:23], v[24:25]
	v_pk_add_f32 v[20:21], v[20:21], v[28:29]
	v_pk_add_f32 v[24:25], v[18:19], v[26:27]
	v_pk_add_f32 v[18:19], v[16:17], v[30:31]
	v_cvt_pk_bf16_f32 v16, v20, v21
	v_cvt_pk_bf16_f32 v17, v22, v23
	v_cvt_pk_bf16_f32 v18, v18, v19
	v_cvt_pk_bf16_f32 v19, v24, v25
	global_store_dwordx4 v[32:33], v[16:19], off offset:256
	s_nop 1
	v_lshl_add_u64 v[16:17], v[144:145], 0, s[2:3]
	s_mov_b32 s2, 0xb0000
	v_add_co_u32_e32 v22, vcc, s2, v144
	s_mov_b32 s2, s46
	s_nop 0
	v_addc_co_u32_e32 v23, vcc, 0, v145, vcc
	s_waitcnt vmcnt(15)
	s_nop 1
	v_mov_b32_e32 v18, v248
	v_mov_b32_e32 v19, v249
	v_mov_b32_e32 v20, v250
	v_mov_b32_e32 v21, v251
	s_and_b64 vcc, exec, s[40:41]
	s_waitcnt lgkmcnt(0)
	v_lshlrev_b32_e32 v24, 16, v18
	v_and_b32_e32 v25, 0xffff0000, v18
	v_lshlrev_b32_e32 v18, 16, v19
	v_and_b32_e32 v19, 0xffff0000, v19
	v_lshlrev_b32_e32 v26, 16, v20
	v_and_b32_e32 v27, 0xffff0000, v20
	v_lshlrev_b32_e32 v20, 16, v21
	v_and_b32_e32 v21, 0xffff0000, v21
	v_pk_add_f32 v[14:15], v[14:15], v[18:19]
	v_pk_add_f32 v[12:13], v[12:13], v[24:25]
	v_pk_add_f32 v[18:19], v[10:11], v[20:21]
	v_pk_add_f32 v[10:11], v[8:9], v[26:27]
	v_cvt_pk_bf16_f32 v8, v12, v13
	v_cvt_pk_bf16_f32 v9, v14, v15
	v_cvt_pk_bf16_f32 v10, v10, v11
	v_cvt_pk_bf16_f32 v11, v18, v19
	global_store_dwordx4 v[22:23], v[8:11], off
	s_waitcnt vmcnt(15)
	s_nop 1
	v_mov_b32_e32 v8, v252
	v_mov_b32_e32 v9, v253
	v_mov_b32_e32 v10, v254
	v_mov_b32_e32 v11, v255
	s_waitcnt lgkmcnt(0)
	v_lshlrev_b32_e32 v12, 16, v8
	v_and_b32_e32 v13, 0xffff0000, v8
	v_lshlrev_b32_e32 v8, 16, v9
	v_and_b32_e32 v9, 0xffff0000, v9
	v_lshlrev_b32_e32 v14, 16, v10
	v_and_b32_e32 v15, 0xffff0000, v10
	v_lshlrev_b32_e32 v10, 16, v11
	v_and_b32_e32 v11, 0xffff0000, v11
	v_pk_add_f32 v[6:7], v[6:7], v[8:9]
	v_pk_add_f32 v[4:5], v[4:5], v[12:13]
	v_pk_add_f32 v[8:9], v[2:3], v[10:11]
	v_pk_add_f32 v[2:3], v[0:1], v[14:15]
	v_cvt_pk_bf16_f32 v0, v4, v5
	v_cvt_pk_bf16_f32 v1, v6, v7
	v_cvt_pk_bf16_f32 v2, v2, v3
	v_cvt_pk_bf16_f32 v3, v8, v9
	global_store_dwordx4 v[16:17], v[0:3], off offset:256
	s_cbranch_vccz .LBB1_922
	s_waitcnt vmcnt(0)
	s_cmpk_gt_u32 s17, 0xff
	s_cbranch_scc1 .LBB1_929
	s_barrier

; #define PG8_STAGE(bufoff, gbase, voff) do { _Pragma("unroll") for (int _i = 0; _i < 2; ++_i) \
;         __builtin_amdgcn_global_load_lds((const unsigned*)((const char*)(gbase) + (voff)[_i]), (LAS unsigned*)(lds + (bufoff) + ldsw + _i * 8192), 16, 0, 0); } while (0)
; #define PG8_LDA(dst, b, h) do { _Pragma("unroll") for (int m = 0; m < 4; ++m) _Pragma("unroll") for (int k = 0; k < 2; ++k) dst[m][k] = *(const LAS bf16x8*)(lds + PG8_SA(b, h) + aoff + m * 2048 + k * 1024); } while (0)
; #define PG8_LDB(dst, b, h) do { _Pragma("unroll") for (int n = 0; n < 2; ++n) _Pragma("unroll") for (int k = 0; k < 2; ++k) dst[n][k] = *(const LAS bf16x8*)(lds + PG8_SB(b, h) + boff + n * 2048 + k * 1024); } while (0)
; #define PG8_MMA(ai, bj, At, Bt) do { __builtin_amdgcn_s_setprio(1); _Pragma("unroll") for (int m = 0; m < 4; ++m) _Pragma("unroll") for (int n = 0; n < 2; ++n) _Pragma("unroll") for (int k = 0; k < 2; ++k) \
;         acc[ai][bj][m][n] = __builtin_amdgcn_mfma_f32_16x16x32_bf16(Bt[n][k], At[m][k], acc[ai][bj][m][n], 0, 0, 0); __builtin_amdgcn_s_setprio(0); } while (0)
; #define PG8_WAIT_V(n) asm volatile("s_waitcnt vmcnt(" #n ")" ::: "memory")
; #define PG8_WAIT_L(n) asm volatile("s_waitcnt lgkmcnt(" #n ")" ::: "memory")
; #define PG8_BAR __builtin_amdgcn_s_barrier()
; #define PG8_SCHED __builtin_amdgcn_sched_barrier(0)
; template <class Map, class Epi>
; DI void gemm_phase(LAS unsigned char* lds, const Map& MP, const Epi& E, const int nM, const int nN, const int K, const int lda, const int ldb) {
;     ...
;             PG8_LDB(B0, 0, 0); PG8_SCHED; PG8_LDA(At, 0, 0); PG8_STAGE(PG8_SA(1, 1), a1 + hstepA, voffA);
;             PG8_WAIT_L(8); PG8_BAR; PG8_WAIT_L(0); PG8_MMA(0, 0, At, B0); PG8_BAR; PG8_SCHED;
;             PG8_LDB(B1, 0, 1); PG8_STAGE(PG8_SB(0, 0), b2, voffB);
;             PG8_BAR; PG8_WAIT_L(0); PG8_MMA(0, 1, At, B1); PG8_BAR;
;             PG8_LDA(At, 0, 1); PG8_STAGE(PG8_SA(0, 0), a2, voffA);
;             PG8_BAR; PG8_WAIT_L(0); PG8_MMA(1, 0, At, B0); PG8_BAR; PG8_SCHED;
;             PG8_STAGE(PG8_SB(0, 1), b2 + hstepB, voffB);
;             PG8_WAIT_V(6); PG8_BAR; PG8_MMA(1, 1, At, B1); PG8_BAR;
;             PG8_LDB(B0, 1, 0); PG8_SCHED; PG8_LDA(At, 1, 0); PG8_STAGE(PG8_SA(0, 1), a2 + hstepA, voffA);
;             PG8_WAIT_L(8); PG8_BAR; PG8_WAIT_L(0); PG8_MMA(0, 0, At, B0); PG8_BAR; PG8_SCHED;
.LBB1_1069:
	s_add_u32 s24, s42, 0xfff80080
	s_addc_u32 s25, s43, -1
	s_cmp_eq_u32 s3, 28
	s_cselect_b32 s47, s23, s25
	s_cselect_b32 s46, s58, s24
	s_cselect_b32 s25, s21, vcc_hi
	s_cselect_b32 s24, s59, vcc_lo
	s_add_i32 m0, s38, 0xc000
	ds_read_b128 v[96:99], v190
	ds_read_b128 v[100:103], v190 offset:1024
	ds_read_b128 v[108:111], v190 offset:2048
	ds_read_b128 v[112:115], v190 offset:3072
	ds_read_b128 v[160:163], v190 offset:4096
	ds_read_b128 v[164:167], v190 offset:5120
	ds_read_b128 v[198:201], v190 offset:6144
	ds_read_b128 v[202:205], v190 offset:7168
	global_load_lds_dwordx4 v178, s[42:43]
	s_add_i32 m0, s38, 0xe000
	s_setprio 1
	global_load_lds_dwordx4 v176, s[42:43]
	s_waitcnt lgkmcnt(8)
	s_barrier
	s_waitcnt lgkmcnt(7)
	v_mfma_f32_16x16x32_bf16 v[148:151], v[80:83], v[96:99], v[148:151]
	v_mfma_f32_16x16x32_bf16 v[144:147], v[88:91], v[96:99], v[144:147]
	s_waitcnt lgkmcnt(5)
	v_mfma_f32_16x16x32_bf16 v[136:139], v[80:83], v[108:111], v[136:139]
	v_mfma_f32_16x16x32_bf16 v[128:131], v[88:91], v[108:111], v[128:131]
	s_waitcnt lgkmcnt(3)
	v_mfma_f32_16x16x32_bf16 v[120:123], v[80:83], v[160:163], v[120:123]
	v_mfma_f32_16x16x32_bf16 v[104:107], v[88:91], v[160:163], v[104:107]
	s_waitcnt lgkmcnt(1)
	v_mfma_f32_16x16x32_bf16 v[76:79], v[80:83], v[198:201], v[76:79]
	v_mfma_f32_16x16x32_bf16 v[72:75], v[88:91], v[198:201], v[72:75]
	v_mfma_f32_16x16x32_bf16 v[148:151], v[84:87], v[100:103], v[148:151]
	s_add_i32 s68, s31, s66
	v_mfma_f32_16x16x32_bf16 v[144:147], v[92:95], v[100:103], v[144:147]
	v_lshl_add_u64 v[184:185], s[24:25], 0, v[172:173]
	v_mfma_f32_16x16x32_bf16 v[136:139], v[84:87], v[112:115], v[136:139]
	v_lshl_add_u64 v[194:195], s[24:25], 0, v[168:169]
	v_mfma_f32_16x16x32_bf16 v[128:131], v[92:95], v[112:115], v[128:131]
	v_mfma_f32_16x16x32_bf16 v[120:123], v[84:87], v[164:167], v[120:123]
	v_mfma_f32_16x16x32_bf16 v[104:107], v[92:95], v[164:167], v[104:107]
	s_waitcnt lgkmcnt(0)
	v_mfma_f32_16x16x32_bf16 v[76:79], v[84:87], v[202:205], v[76:79]
	v_mfma_f32_16x16x32_bf16 v[72:75], v[92:95], v[202:205], v[72:75]
	s_barrier
	s_setprio 0
	s_mov_b32 m0, s68
	ds_read_b128 v[206:209], v191
	ds_read_b128 v[210:213], v191 offset:1024
	ds_read_b128 v[214:217], v191 offset:2048
	ds_read_b128 v[218:221], v191 offset:3072
	global_load_lds_dwordx4 v[184:185], off
	s_add_i32 m0, s68, 0x2000
	s_setprio 1
	global_load_lds_dwordx4 v[194:195], off
	s_barrier
	s_waitcnt lgkmcnt(3)
	v_mfma_f32_16x16x32_bf16 v[156:159], v[206:209], v[96:99], v[156:159]
	s_waitcnt lgkmcnt(1)
	v_mfma_f32_16x16x32_bf16 v[96:99], v[214:217], v[96:99], v[152:155]
	v_mfma_f32_16x16x32_bf16 v[156:159], v[210:213], v[100:103], v[156:159]
	s_waitcnt lgkmcnt(0)
	v_mfma_f32_16x16x32_bf16 v[96:99], v[218:221], v[100:103], v[96:99]
	v_mfma_f32_16x16x32_bf16 v[100:103], v[206:209], v[108:111], v[140:143]
	v_mfma_f32_16x16x32_bf16 v[108:111], v[214:217], v[108:111], v[132:135]
	v_mfma_f32_16x16x32_bf16 v[116:119], v[214:217], v[160:163], v[116:119]
	v_mfma_f32_16x16x32_bf16 v[68:71], v[206:209], v[198:201], v[68:71]
	v_mfma_f32_16x16x32_bf16 v[64:67], v[214:217], v[198:201], v[64:67]
	v_lshl_add_u64 v[234:235], s[46:47], 0, v[170:171]
	s_mov_b32 m0, s38
	v_mfma_f32_16x16x32_bf16 v[100:103], v[210:213], v[112:115], v[100:103]
	v_lshl_add_u64 v[226:227], s[46:47], 0, v[174:175]
	v_mfma_f32_16x16x32_bf16 v[108:111], v[218:221], v[112:115], v[108:111]
	v_mfma_f32_16x16x32_bf16 v[112:115], v[206:209], v[160:163], v[124:127]
	v_mfma_f32_16x16x32_bf16 v[116:119], v[218:221], v[164:167], v[116:119]
	v_mfma_f32_16x16x32_bf16 v[68:71], v[210:213], v[202:205], v[68:71]
	v_mfma_f32_16x16x32_bf16 v[64:67], v[218:221], v[202:205], v[64:67]
	v_mfma_f32_16x16x32_bf16 v[112:115], v[210:213], v[164:167], v[112:115]
	s_barrier
	s_setprio 0
	ds_read_b128 v[124:127], v190 offset:16384
	ds_read_b128 v[132:135], v190 offset:17408
	ds_read_b128 v[140:143], v190 offset:18432
	ds_read_b128 v[152:155], v190 offset:19456
	ds_read_b128 v[160:163], v190 offset:20480
	ds_read_b128 v[164:167], v190 offset:21504
	ds_read_b128 v[198:201], v190 offset:22528
	ds_read_b128 v[202:205], v190 offset:23552
	global_load_lds_dwordx4 v[226:227], off
	s_mov_b32 m0, s39
	s_setprio 1
	global_load_lds_dwordx4 v[234:235], off
	s_waitcnt vmcnt(10)
	s_barrier
	s_waitcnt lgkmcnt(7)
	v_mfma_f32_16x16x32_bf16 v[60:63], v[80:83], v[124:127], v[60:63]
	v_mfma_f32_16x16x32_bf16 v[48:51], v[88:91], v[124:127], v[48:51]
	s_waitcnt lgkmcnt(5)
	v_mfma_f32_16x16x32_bf16 v[40:43], v[80:83], v[140:143], v[40:43]
	v_mfma_f32_16x16x32_bf16 v[32:35], v[88:91], v[140:143], v[32:35]
	s_waitcnt lgkmcnt(3)
	v_mfma_f32_16x16x32_bf16 v[24:27], v[80:83], v[160:163], v[24:27]
	v_mfma_f32_16x16x32_bf16 v[16:19], v[88:91], v[160:163], v[16:19]
	s_waitcnt lgkmcnt(1)
	v_mfma_f32_16x16x32_bf16 v[12:15], v[80:83], v[198:201], v[12:15]
	v_mfma_f32_16x16x32_bf16 v[8:11], v[88:91], v[198:201], v[8:11]
	v_mfma_f32_16x16x32_bf16 v[60:63], v[84:87], v[132:135], v[60:63]
	s_add_u32 s68, s24, 0x80000
	s_addc_u32 s69, s25, 0
	v_mfma_f32_16x16x32_bf16 v[48:51], v[92:95], v[132:135], v[48:51]
	s_add_i32 s70, s2, s66
	v_mfma_f32_16x16x32_bf16 v[40:43], v[84:87], v[152:155], v[40:43]
	v_mfma_f32_16x16x32_bf16 v[32:35], v[92:95], v[152:155], v[32:35]
	v_mfma_f32_16x16x32_bf16 v[24:27], v[84:87], v[164:167], v[24:27]
	v_mfma_f32_16x16x32_bf16 v[16:19], v[92:95], v[164:167], v[16:19]
	s_waitcnt lgkmcnt(0)
	v_mfma_f32_16x16x32_bf16 v[12:15], v[84:87], v[202:205], v[12:15]
	v_mfma_f32_16x16x32_bf16 v[8:11], v[92:95], v[202:205], v[8:11]
	s_barrier
	s_setprio 0
	s_mov_b32 m0, s70
	s_nop 0
	global_load_lds_dwordx4 v172, s[68:69]
	s_add_i32 m0, s70, 0x2000
	s_setprio 1
	global_load_lds_dwordx4 v168, s[68:69]
	s_waitcnt vmcnt(6)
	s_barrier
; #define PG8_STAGE(bufoff, gbase, voff) do { _Pragma("unroll") for (int _i = 0; _i < 2; ++_i) \
;         __builtin_amdgcn_global_load_lds((const unsigned*)((const char*)(gbase) + (voff)[_i]), (LAS unsigned*)(lds + (bufoff) + ldsw + _i * 8192), 16, 0, 0); } while (0)
; #define PG8_LDA(dst, b, h) do { _Pragma("unroll") for (int m = 0; m < 4; ++m) _Pragma("unroll") for (int k = 0; k < 2; ++k) dst[m][k] = *(const LAS bf16x8*)(lds + PG8_SA(b, h) + aoff + m * 2048 + k * 1024); } while (0)
; #define PG8_LDB(dst, b, h) do { _Pragma("unroll") for (int n = 0; n < 2; ++n) _Pragma("unroll") for (int k = 0; k < 2; ++k) dst[n][k] = *(const LAS bf16x8*)(lds + PG8_SB(b, h) + boff + n * 2048 + k * 1024); } while (0)
; #define PG8_MMA(ai, bj, At, Bt) do { __builtin_amdgcn_s_setprio(1); _Pragma("unroll") for (int m = 0; m < 4; ++m) _Pragma("unroll") for (int n = 0; n < 2; ++n) _Pragma("unroll") for (int k = 0; k < 2; ++k) \
;         acc[ai][bj][m][n] = __builtin_amdgcn_mfma_f32_16x16x32_bf16(Bt[n][k], At[m][k], acc[ai][bj][m][n], 0, 0, 0); __builtin_amdgcn_s_setprio(0); } while (0)
; #define PG8_WAIT_V(n) asm volatile("s_waitcnt vmcnt(" #n ")" ::: "memory")
; #define PG8_WAIT_L(n) asm volatile("s_waitcnt lgkmcnt(" #n ")" ::: "memory")
; #define PG8_BAR __builtin_amdgcn_s_barrier()
; #define PG8_SCHED __builtin_amdgcn_sched_barrier(0)
; template <class Map, class Epi>
; DI void gemm_phase(LAS unsigned char* lds, const Map& MP, const Epi& E, const int nM, const int nN, const int K, const int lda, const int ldb) {
;     ...
;             PG8_WAIT_V(6); PG8_BAR; PG8_MMA(1, 1, At, B1); PG8_BAR;
;             PG8_LDB(B0, 1, 0); PG8_SCHED; PG8_LDA(At, 1, 0); PG8_STAGE(PG8_SA(0, 1), a2 + hstepA, voffA);
;             PG8_WAIT_L(8); PG8_BAR; PG8_WAIT_L(0); PG8_MMA(0, 0, At, B0); PG8_BAR; PG8_SCHED;
;             PG8_LDB(B1, 1, 1); PG8_STAGE(PG8_SB(1, 0), b3, voffB);
;             PG8_BAR; PG8_WAIT_L(0); PG8_MMA(0, 1, At, B1); PG8_BAR;
;             PG8_LDA(At, 1, 1); PG8_STAGE(PG8_SA(1, 0), a3, voffA);
;             PG8_BAR; PG8_WAIT_L(0); PG8_MMA(1, 0, At, B0); PG8_BAR; PG8_SCHED;
;             PG8_STAGE(PG8_SB(1, 1), b3 + hstepB, voffB);
;             PG8_WAIT_V(6); PG8_BAR; PG8_MMA(1, 1, At, B1); PG8_BAR;
	v_mfma_f32_16x16x32_bf16 v[56:59], v[206:209], v[124:127], v[56:59]
	v_mfma_f32_16x16x32_bf16 v[52:55], v[214:217], v[124:127], v[52:55]
	s_add_i32 s68, 0, 0x18000
	v_add_u32_e32 v92, s68, v188
	ds_read_b128 v[80:83], v92
	v_mfma_f32_16x16x32_bf16 v[44:47], v[206:209], v[140:143], v[44:47]
	v_mfma_f32_16x16x32_bf16 v[36:39], v[214:217], v[140:143], v[36:39]
	ds_read_b128 v[84:87], v92 offset:1024
	v_mfma_f32_16x16x32_bf16 v[28:31], v[206:209], v[160:163], v[28:31]
	v_mfma_f32_16x16x32_bf16 v[20:23], v[214:217], v[160:163], v[20:23]
	ds_read_b128 v[88:91], v92 offset:2048
	v_mfma_f32_16x16x32_bf16 v[4:7], v[206:209], v[198:201], v[4:7]
	v_mfma_f32_16x16x32_bf16 v[0:3], v[214:217], v[198:201], v[0:3]
	ds_read_b128 v[92:95], v92 offset:3072
	v_mfma_f32_16x16x32_bf16 v[56:59], v[210:213], v[132:135], v[56:59]
	s_add_u32 s46, s46, 0x80000
	s_addc_u32 s47, s47, 0
	v_mfma_f32_16x16x32_bf16 v[52:55], v[218:221], v[132:135], v[52:55]
	v_mfma_f32_16x16x32_bf16 v[44:47], v[210:213], v[152:155], v[44:47]
	v_mfma_f32_16x16x32_bf16 v[36:39], v[218:221], v[152:155], v[36:39]
	v_mfma_f32_16x16x32_bf16 v[28:31], v[210:213], v[164:167], v[28:31]
	v_mfma_f32_16x16x32_bf16 v[20:23], v[218:221], v[164:167], v[20:23]
	v_mfma_f32_16x16x32_bf16 v[4:7], v[210:213], v[202:205], v[4:7]
	v_mfma_f32_16x16x32_bf16 v[0:3], v[218:221], v[202:205], v[0:3]
	s_barrier
	s_setprio 0
	s_mov_b32 m0, s56
	ds_read_b128 v[124:127], v190 offset:32768
	ds_read_b128 v[132:135], v190 offset:33792
	ds_read_b128 v[160:163], v190 offset:34816
	ds_read_b128 v[164:167], v190 offset:35840
	ds_read_b128 v[198:201], v190 offset:36864
	ds_read_b128 v[202:205], v190 offset:37888
	ds_read_b128 v[206:209], v190 offset:38912
	ds_read_b128 v[210:213], v190 offset:39936
	global_load_lds_dwordx4 v174, s[46:47]
	s_mov_b32 m0, s57
	s_setprio 1
	global_load_lds_dwordx4 v170, s[46:47]
	s_waitcnt lgkmcnt(8)
	s_barrier
	s_waitcnt lgkmcnt(7)
	v_mfma_f32_16x16x32_bf16 v[140:143], v[80:83], v[124:127], v[148:151]
	s_waitcnt lgkmcnt(6)
	v_mfma_f32_16x16x32_bf16 v[148:151], v[84:87], v[132:135], v[140:143]
	v_mfma_f32_16x16x32_bf16 v[140:143], v[88:91], v[124:127], v[144:147]
	s_waitcnt lgkmcnt(5)
	v_mfma_f32_16x16x32_bf16 v[136:139], v[80:83], v[160:163], v[136:139]
	v_mfma_f32_16x16x32_bf16 v[128:131], v[88:91], v[160:163], v[128:131]
	s_waitcnt lgkmcnt(3)
	v_mfma_f32_16x16x32_bf16 v[120:123], v[80:83], v[198:201], v[120:123]
	v_mfma_f32_16x16x32_bf16 v[104:107], v[88:91], v[198:201], v[104:107]
	s_waitcnt lgkmcnt(1)
	v_mfma_f32_16x16x32_bf16 v[76:79], v[80:83], v[206:209], v[76:79]
	v_mfma_f32_16x16x32_bf16 v[72:75], v[88:91], v[206:209], v[72:75]
	s_add_i32 s46, 0, 0x1c000
	v_mfma_f32_16x16x32_bf16 v[144:147], v[92:95], v[132:135], v[140:143]
	v_add_u32_e32 v140, s46, v188
	v_mfma_f32_16x16x32_bf16 v[136:139], v[84:87], v[164:167], v[136:139]
	s_add_i32 s47, s68, s66
	v_mfma_f32_16x16x32_bf16 v[128:131], v[92:95], v[164:167], v[128:131]
	v_mfma_f32_16x16x32_bf16 v[120:123], v[84:87], v[202:205], v[120:123]
	v_mfma_f32_16x16x32_bf16 v[104:107], v[92:95], v[202:205], v[104:107]
	s_waitcnt lgkmcnt(0)
	v_mfma_f32_16x16x32_bf16 v[76:79], v[84:87], v[210:213], v[76:79]
	v_mfma_f32_16x16x32_bf16 v[72:75], v[92:95], v[210:213], v[72:75]
	s_barrier
	s_setprio 0
	ds_read_b128 v[214:217], v140
	ds_read_b128 v[218:221], v140 offset:1024
	ds_read_b128 v[222:225], v140 offset:2048
	ds_read_b128 v[230:233], v140 offset:3072
	v_lshl_add_u64 v[140:141], v[184:185], 0, s[14:15]
	s_mov_b32 m0, s47
	s_nop 0
	global_load_lds_dwordx4 v[140:141], off
	v_lshl_add_u64 v[140:141], v[194:195], 0, s[14:15]
	s_add_i32 m0, s47, 0x2000
	s_setprio 1
	global_load_lds_dwordx4 v[140:141], off
	s_barrier
	s_waitcnt lgkmcnt(1)
	v_mfma_f32_16x16x32_bf16 v[96:99], v[222:225], v[124:127], v[96:99]
	v_mfma_f32_16x16x32_bf16 v[140:143], v[214:217], v[124:127], v[156:159]
	s_waitcnt lgkmcnt(0)
	v_mfma_f32_16x16x32_bf16 v[152:155], v[230:233], v[132:135], v[96:99]
	v_mfma_f32_16x16x32_bf16 v[96:99], v[214:217], v[160:163], v[100:103]
	v_mfma_f32_16x16x32_bf16 v[156:159], v[218:221], v[132:135], v[140:143]
	v_mfma_f32_16x16x32_bf16 v[140:143], v[218:221], v[164:167], v[96:99]
	v_mfma_f32_16x16x32_bf16 v[96:99], v[222:225], v[160:163], v[108:111]
	v_mfma_f32_16x16x32_bf16 v[132:135], v[230:233], v[164:167], v[96:99]
	v_mfma_f32_16x16x32_bf16 v[96:99], v[214:217], v[198:201], v[112:115]
	s_mov_b32 m0, s63
	v_mfma_f32_16x16x32_bf16 v[124:127], v[218:221], v[202:205], v[96:99]
	v_lshl_add_u64 v[184:185], v[226:227], 0, s[14:15]
	v_mfma_f32_16x16x32_bf16 v[96:99], v[222:225], v[198:201], v[116:119]
	v_mfma_f32_16x16x32_bf16 v[68:71], v[214:217], v[206:209], v[68:71]
	v_mfma_f32_16x16x32_bf16 v[64:67], v[222:225], v[206:209], v[64:67]
	v_mfma_f32_16x16x32_bf16 v[116:119], v[230:233], v[202:205], v[96:99]
	v_mfma_f32_16x16x32_bf16 v[68:71], v[218:221], v[210:213], v[68:71]
	v_mfma_f32_16x16x32_bf16 v[64:67], v[230:233], v[210:213], v[64:67]
	s_barrier
	s_setprio 0
	ds_read_b128 v[96:99], v190 offset:49152
	ds_read_b128 v[100:103], v190 offset:50176
	ds_read_b128 v[108:111], v190 offset:51200
	ds_read_b128 v[112:115], v190 offset:52224
	ds_read_b128 v[160:163], v190 offset:53248
	ds_read_b128 v[164:167], v190 offset:54272
	ds_read_b128 v[198:201], v190 offset:55296
	ds_read_b128 v[202:205], v190 offset:56320
	global_load_lds_dwordx4 v[184:185], off
	v_lshl_add_u64 v[184:185], v[234:235], 0, s[14:15]
	s_mov_b32 m0, s4
	s_setprio 1
	global_load_lds_dwordx4 v[184:185], off
	s_waitcnt vmcnt(10)
	s_barrier
; #define PG8_STAGE(bufoff, gbase, voff) do { _Pragma("unroll") for (int _i = 0; _i < 2; ++_i) \
;         __builtin_amdgcn_global_load_lds((const unsigned*)((const char*)(gbase) + (voff)[_i]), (LAS unsigned*)(lds + (bufoff) + ldsw + _i * 8192), 16, 0, 0); } while (0)
; #define PG8_LDA(dst, b, h) do { _Pragma("unroll") for (int m = 0; m < 4; ++m) _Pragma("unroll") for (int k = 0; k < 2; ++k) dst[m][k] = *(const LAS bf16x8*)(lds + PG8_SA(b, h) + aoff + m * 2048 + k * 1024); } while (0)
; #define PG8_LDB(dst, b, h) do { _Pragma("unroll") for (int n = 0; n < 2; ++n) _Pragma("unroll") for (int k = 0; k < 2; ++k) dst[n][k] = *(const LAS bf16x8*)(lds + PG8_SB(b, h) + boff + n * 2048 + k * 1024); } while (0)
; #define PG8_MMA(ai, bj, At, Bt) do { __builtin_amdgcn_s_setprio(1); _Pragma("unroll") for (int m = 0; m < 4; ++m) _Pragma("unroll") for (int n = 0; n < 2; ++n) _Pragma("unroll") for (int k = 0; k < 2; ++k) \
;         acc[ai][bj][m][n] = __builtin_amdgcn_mfma_f32_16x16x32_bf16(Bt[n][k], At[m][k], acc[ai][bj][m][n], 0, 0, 0); __builtin_amdgcn_s_setprio(0); } while (0)
; #define PG8_WAIT_V(n) asm volatile("s_waitcnt vmcnt(" #n ")" ::: "memory")
; #define PG8_WAIT_L(n) asm volatile("s_waitcnt lgkmcnt(" #n ")" ::: "memory")
; #define PG8_BAR __builtin_amdgcn_s_barrier()
; #define PG8_SCHED __builtin_amdgcn_sched_barrier(0)
; template <class Map, class Epi>
; DI void gemm_phase(LAS unsigned char* lds, const Map& MP, const Epi& E, const int nM, const int nN, const int K, const int lda, const int ldb) {
;     ...
;             PG8_WAIT_L(8); PG8_BAR; PG8_WAIT_L(0); PG8_MMA(0, 0, At, B0); PG8_BAR; PG8_SCHED;
;             PG8_LDB(B1, 1, 1); PG8_STAGE(PG8_SB(1, 0), b3, voffB);
;             PG8_BAR; PG8_WAIT_L(0); PG8_MMA(0, 1, At, B1); PG8_BAR;
;             PG8_LDA(At, 1, 1); PG8_STAGE(PG8_SA(1, 0), a3, voffA);
;             PG8_BAR; PG8_WAIT_L(0); PG8_MMA(1, 0, At, B0); PG8_BAR; PG8_SCHED;
;             PG8_STAGE(PG8_SB(1, 1), b3 + hstepB, voffB);
;             PG8_WAIT_V(6); PG8_BAR; PG8_MMA(1, 1, At, B1); PG8_BAR;
	s_waitcnt lgkmcnt(7)
	v_mfma_f32_16x16x32_bf16 v[60:63], v[80:83], v[96:99], v[60:63]
	v_mfma_f32_16x16x32_bf16 v[48:51], v[88:91], v[96:99], v[48:51]
	s_waitcnt lgkmcnt(5)
	v_mfma_f32_16x16x32_bf16 v[40:43], v[80:83], v[108:111], v[40:43]
	v_mfma_f32_16x16x32_bf16 v[32:35], v[88:91], v[108:111], v[32:35]
	s_waitcnt lgkmcnt(3)
	v_mfma_f32_16x16x32_bf16 v[24:27], v[80:83], v[160:163], v[24:27]
	v_mfma_f32_16x16x32_bf16 v[16:19], v[88:91], v[160:163], v[16:19]
	s_waitcnt lgkmcnt(1)
	v_mfma_f32_16x16x32_bf16 v[12:15], v[80:83], v[198:201], v[12:15]
	v_mfma_f32_16x16x32_bf16 v[8:11], v[88:91], v[198:201], v[8:11]
	v_mfma_f32_16x16x32_bf16 v[60:63], v[84:87], v[100:103], v[60:63]
	s_add_u32 s24, s24, 0x80080
	s_addc_u32 s25, s25, 0
	v_mfma_f32_16x16x32_bf16 v[48:51], v[92:95], v[100:103], v[48:51]
	s_add_i32 s46, s46, s66
	v_mfma_f32_16x16x32_bf16 v[40:43], v[84:87], v[112:115], v[40:43]
	v_mfma_f32_16x16x32_bf16 v[32:35], v[92:95], v[112:115], v[32:35]
	v_mfma_f32_16x16x32_bf16 v[24:27], v[84:87], v[164:167], v[24:27]
	v_mfma_f32_16x16x32_bf16 v[16:19], v[92:95], v[164:167], v[16:19]
	s_waitcnt lgkmcnt(0)
	v_mfma_f32_16x16x32_bf16 v[12:15], v[84:87], v[202:205], v[12:15]
	v_mfma_f32_16x16x32_bf16 v[8:11], v[92:95], v[202:205], v[8:11]
	s_barrier
	s_setprio 0
	s_mov_b32 m0, s46
	s_nop 0
	global_load_lds_dwordx4 v172, s[24:25]
	s_add_i32 m0, s46, 0x2000
	s_setprio 1
	global_load_lds_dwordx4 v168, s[24:25]
	s_waitcnt vmcnt(6)
	s_barrier
	v_mfma_f32_16x16x32_bf16 v[56:59], v[214:217], v[96:99], v[56:59]
	v_mfma_f32_16x16x32_bf16 v[52:55], v[222:225], v[96:99], v[52:55]
	ds_read_b128 v[80:83], v189
	v_mfma_f32_16x16x32_bf16 v[44:47], v[214:217], v[108:111], v[44:47]
	v_mfma_f32_16x16x32_bf16 v[36:39], v[222:225], v[108:111], v[36:39]
	ds_read_b128 v[84:87], v189 offset:1024
	v_mfma_f32_16x16x32_bf16 v[28:31], v[214:217], v[160:163], v[28:31]
	v_mfma_f32_16x16x32_bf16 v[20:23], v[222:225], v[160:163], v[20:23]
	ds_read_b128 v[88:91], v189 offset:2048
	v_mfma_f32_16x16x32_bf16 v[4:7], v[214:217], v[198:201], v[4:7]
	v_mfma_f32_16x16x32_bf16 v[0:3], v[222:225], v[198:201], v[0:3]
	ds_read_b128 v[92:95], v189 offset:3072
	v_mfma_f32_16x16x32_bf16 v[56:59], v[218:221], v[100:103], v[56:59]
	s_add_i32 s3, s3, 2
	v_mfma_f32_16x16x32_bf16 v[52:55], v[230:233], v[100:103], v[52:55]
	s_add_u32 vcc_lo, vcc_lo, 0x100
	s_addc_u32 vcc_hi, vcc_hi, 0
	v_mfma_f32_16x16x32_bf16 v[44:47], v[218:221], v[112:115], v[44:47]
	s_add_u32 s42, s42, 0x100
	s_addc_u32 s43, s43, 0
	v_mfma_f32_16x16x32_bf16 v[36:39], v[230:233], v[112:115], v[36:39]
	s_cmp_gt_u32 s3, 29
	v_mfma_f32_16x16x32_bf16 v[28:31], v[218:221], v[164:167], v[28:31]
	v_mfma_f32_16x16x32_bf16 v[20:23], v[230:233], v[164:167], v[20:23]
	v_mfma_f32_16x16x32_bf16 v[4:7], v[218:221], v[202:205], v[4:7]
	v_mfma_f32_16x16x32_bf16 v[0:3], v[230:233], v[202:205], v[0:3]
	s_barrier
	s_setprio 0
	s_cbranch_scc0 .LBB1_1069
; DI float silu_mul(float g, float v) { return g * v * __builtin_amdgcn_rcpf(1.0f + __builtin_amdgcn_exp2f(-LOG2E * g)); }
;     DI void operator()(const f32x4 (&acc)[2][2][4][2], const Unit& u, int wr, int wc, int fr, int fq) const {
;         const int row0 = u.pm * BM + wr * 64 + fr, ch0 = u.pn * 128 + wc * 32 + 8 * fq;
;         f32x4 w0[2], w1[2], w2[2], bb[2];
; #pragma unroll
;         for (int n = 0; n < 2; ++n) { w0[n] = *(const f32x4*)(cw + ch0 + 4 * n); w1[n] = *(const f32x4*)(cw + DFF + ch0 + 4 * n); w2[n] = *(const f32x4*)(cw + 2 * DFF + ch0 + 4 * n); bb[n] = *(const f32x4*)(cb + ch0 + 4 * n); }
; #pragma unroll
;         for (int ai = 0; ai < 2; ++ai)
; #pragma unroll
;             for (int m = 0; m < 4; ++m) {
;                 const bool efirst = (m == 0) && (fr == 0), elast = (m == 3) && (fr == 15);
;                 const int row = row0 + ai * HALF + m * 16;
;                 f32x4 gc[2];
; #pragma unroll
;                 for (int n = 0; n < 2; ++n) {
;                     const f32x4 g = acc[ai][0][m][n];
;                     const f32x4 gprev = acc[ai][0][m > 0 ? m - 1 : 0][n], gnext = acc[ai][0][m < 3 ? m + 1 : 3][n];
;                     f32x4 up, dn;
; #pragma unroll
;                     for (int e = 0; e < 4; ++e) {
;                         const float pu = (m > 0 && fr == 15) ? gprev[e] : g[e];
;                         const float pd = (m < 3 && fr == 0) ? gnext[e] : g[e];
;                         up[e] = dpp_ror1(pu); dn[e] = dpp_ror15(pd);
;                     }
;                     if (efirst) up = (f32x4){0.f, 0.f, 0.f, 0.f};
;                     if (elast) dn = (f32x4){0.f, 0.f, 0.f, 0.f};
;                     gc[n] = w0[n] * up + w1[n] * g + w2[n] * dn + bb[n];
;                 }
;                 if (efirst || elast) {
;                     const size_t eo = (size_t)((row >> 6) * 2 + (elast ? 1 : 0)) * DFF + ch0;
; #pragma unroll
;                     for (int n = 0; n < 2; ++n) { *(f32x4*)(EP + eo + 4 * n) = gc[n]; *(f32x4*)(ER + eo + 4 * n) = acc[ai][0][m][n]; *(f32x4*)(EV + eo + 4 * n) = acc[ai][1][m][n]; }
;                 } else {
;                     const f32x4 v0 = acc[ai][1][m][0], v1 = acc[ai][1][m][1];
;                     u32x4 o;
;                     o[0] = pack2(silu_mul(gc[0][0], v0[0]), silu_mul(gc[0][1], v0[1])); o[1] = pack2(silu_mul(gc[0][2], v0[2]), silu_mul(gc[0][3], v0[3]));
	s_waitcnt lgkmcnt(0)
	s_lshl_b32 s21, s45, 7
	v_mov_b32_e32 v194, v186
	v_mov_b32_e32 v80, v187
	s_or_b32 s21, s21, s62
	v_lshl_add_u32 v184, v80, 3, s21
	v_ashrrev_i32_e32 v185, 31, v184
	v_lshlrev_b64 v[80:81], 2, v[184:185]
	v_lshl_add_u64 v[84:85], s[6:7], 0, v[80:81]
	v_lshl_add_u64 v[88:89], s[16:17], 0, v[80:81]
	v_lshl_add_u64 v[92:93], s[18:19], 0, v[80:81]
	v_lshl_add_u64 v[112:113], s[52:53], 0, v[80:81]
	global_load_dwordx4 v[80:83], v[84:85], off offset:16
	global_load_dwordx4 v[96:99], v[84:85], off
	s_nop 0
	global_load_dwordx4 v[84:87], v[88:89], off offset:16
	global_load_dwordx4 v[100:103], v[88:89], off
	s_nop 0
	global_load_dwordx4 v[88:91], v[92:93], off offset:16
	global_load_dwordx4 v[108:111], v[92:93], off
	s_nop 0
	global_load_dwordx4 v[92:95], v[112:113], off offset:16
	s_nop 0
	global_load_dwordx4 v[112:115], v[112:113], off
	v_cmp_eq_u32_e32 vcc, 0, v194
	s_nop 0
	s_nop 0
	v_cndmask_b32_e32 v161, v148, v136, vcc
	v_cndmask_b32_e32 v162, v149, v137, vcc
	v_cndmask_b32_e32 v163, v150, v138, vcc
	v_mov_b32_dpp v160, v161 row_ror:15 row_mask:0xf bank_mask:0xf
	s_nop 0
	s_nop 0
	v_mov_b32_dpp v161, v162 row_ror:15 row_mask:0xf bank_mask:0xf
	v_mov_b32_dpp v164, v150 row_ror:1 row_mask:0xf bank_mask:0xf
	v_cndmask_b32_e32 v165, v151, v139, vcc
	v_mov_b32_dpp v162, v163 row_ror:15 row_mask:0xf bank_mask:0xf
	v_mov_b32_dpp v195, v151 row_ror:1 row_mask:0xf bank_mask:0xf
	v_mov_b32_dpp v166, v148 row_ror:1 row_mask:0xf bank_mask:0xf
	v_mov_b32_dpp v167, v149 row_ror:1 row_mask:0xf bank_mask:0xf
	v_mov_b32_dpp v163, v165 row_ror:15 row_mask:0xf bank_mask:0xf
	v_cndmask_b32_e64 v165, v195, 0, vcc
	v_cndmask_b32_e64 v164, v164, 0, vcc
	v_cndmask_b32_e64 v167, v167, 0, vcc
	v_cndmask_b32_e64 v166, v166, 0, vcc
	s_nop 0
	s_nop 0
	v_mov_b32_dpp v195, v144 row_ror:1 row_mask:0xf bank_mask:0xf
	v_mov_b32_dpp v196, v145 row_ror:1 row_mask:0xf bank_mask:0xf
	v_mov_b32_dpp v198, v146 row_ror:1 row_mask:0xf bank_mask:0xf
	v_cndmask_b32_e32 v199, v147, v131, vcc
	v_mov_b32_dpp v200, v147 row_ror:1 row_mask:0xf bank_mask:0xf
	v_cndmask_b32_e64 v198, v198, 0, vcc
	v_cndmask_b32_e64 v201, v196, 0, vcc
	s_lshl_b32 s3, s44, 8
	s_add_i32 s3, s3, s49
	v_add_u32_e32 v193, s3, v194
	v_cmp_ne_u32_e64 s[46:47], 0, v194
	s_waitcnt vmcnt(0)
	v_pk_mul_f32 v[164:165], v[98:99], v[164:165]
	v_pk_mul_f32 v[166:167], v[96:97], v[166:167]
	v_pk_fma_f32 v[164:165], v[150:151], v[102:103], v[164:165]
	v_pk_fma_f32 v[166:167], v[148:149], v[100:101], v[166:167]
	v_pk_fma_f32 v[162:163], v[110:111], v[162:163], v[164:165]
	v_cndmask_b32_e32 v165, v144, v128, vcc
	v_pk_fma_f32 v[160:161], v[108:109], v[160:161], v[166:167]
	v_cndmask_b32_e32 v166, v145, v129, vcc
	v_mov_b32_dpp v164, v165 row_ror:15 row_mask:0xf bank_mask:0xf
	v_cndmask_b32_e32 v167, v146, v130, vcc
	v_pk_add_f32 v[162:163], v[114:115], v[162:163]
	v_mov_b32_dpp v165, v166 row_ror:15 row_mask:0xf bank_mask:0xf
	v_pk_add_f32 v[160:161], v[112:113], v[160:161]
	s_nop 0
	v_mov_b32_dpp v166, v167 row_ror:15 row_mask:0xf bank_mask:0xf
	s_nop 1
	v_mov_b32_dpp v167, v199 row_ror:15 row_mask:0xf bank_mask:0xf
	v_cndmask_b32_e64 v199, v200, 0, vcc
	v_cndmask_b32_e64 v200, v195, 0, vcc
	v_pk_mul_f32 v[200:201], v[80:81], v[200:201]
	v_pk_mul_f32 v[198:199], v[82:83], v[198:199]
	v_pk_fma_f32 v[200:201], v[144:145], v[84:85], v[200:201]
	v_pk_fma_f32 v[198:199], v[146:147], v[86:87], v[198:199]
	v_pk_fma_f32 v[164:165], v[88:89], v[164:165], v[200:201]
	v_pk_fma_f32 v[166:167], v[90:91], v[166:167], v[198:199]
	v_pk_add_f32 v[164:165], v[92:93], v[164:165]
	v_pk_add_f32 v[166:167], v[94:95], v[166:167]
	s_and_saveexec_b64 s[24:25], s[46:47]
	s_xor_b64 s[24:25], exec, s[24:25]
	s_cbranch_execz .LBB1_1072
	v_mul_f32_e32 v195, 0xbfb8aa3b, v160
	v_exp_f32_e32 v195, v195
	v_mul_f32_e32 v196, 0xbfb8aa3b, v161
	v_exp_f32_e32 v196, v196
	v_pk_mul_f32 v[160:161], v[156:157], v[160:161]
	v_add_f32_e32 v195, 1.0, v195
	v_rcp_f32_e32 v198, v195
	v_add_f32_e32 v196, 1.0, v196
	v_mul_f32_e32 v195, 0xbfb8aa3b, v162
	v_rcp_f32_e32 v199, v196
	v_exp_f32_e32 v195, v195
	v_mul_f32_e32 v196, 0xbfb8aa3b, v163
	v_exp_f32_e32 v196, v196
	v_pk_mul_f32 v[160:161], v[160:161], v[198:199]
	v_add_f32_e32 v195, 1.0, v195
	v_rcp_f32_e32 v200, v195
	v_add_f32_e32 v195, 1.0, v196
	v_rcp_f32_e32 v201, v195
	v_cvt_pk_bf16_f32 v160, v160, v161
	v_mul_f32_e32 v161, 0xbfb8aa3b, v164
	v_exp_f32_e32 v195, v161
	v_mul_f32_e32 v161, 0xbfb8aa3b, v165
	v_exp_f32_e32 v196, v161
	v_pk_mul_f32 v[162:163], v[158:159], v[162:163]
	v_pk_mul_f32 v[164:165], v[152:153], v[164:165]
	v_pk_mul_f32 v[162:163], v[162:163], v[200:201]
	s_nop 0
	v_cvt_pk_bf16_f32 v161, v162, v163
	v_add_f32_e32 v162, 1.0, v195
	v_mul_f32_e32 v195, 0xbfb8aa3b, v166
	v_add_f32_e32 v163, 1.0, v196
	v_exp_f32_e32 v195, v195
	v_mul_f32_e32 v196, 0xbfb8aa3b, v167
	v_exp_f32_e32 v196, v196
	v_rcp_f32_e32 v162, v162
	v_add_f32_e32 v195, 1.0, v195
	v_rcp_f32_e32 v198, v195
	v_add_f32_e32 v195, 1.0, v196
	v_rcp_f32_e32 v163, v163
	v_rcp_f32_e32 v199, v195
	v_pk_mul_f32 v[166:167], v[154:155], v[166:167]
	v_pk_mul_f32 v[162:163], v[164:165], v[162:163]
	v_pk_mul_f32 v[164:165], v[166:167], v[198:199]
	v_cvt_pk_bf16_f32 v162, v162, v163
	v_cvt_pk_bf16_f32 v163, v164, v165
	v_mov_b64_e32 v[164:165], s[54:55]
	v_mad_i64_i32 v[164:165], s[42:43], v193, s60, v[164:165]
	v_lshl_add_u64 v[164:165], v[184:185], 1, v[164:165]
	global_store_dwordx4 v[164:165], v[160:163], off

; #define PG8_STAGE(bufoff, gbase, voff) do { _Pragma("unroll") for (int _i = 0; _i < 2; ++_i) \
;         __builtin_amdgcn_global_load_lds((const unsigned*)((const char*)(gbase) + (voff)[_i]), (LAS unsigned*)(lds + (bufoff) + ldsw + _i * 8192), 16, 0, 0); } while (0)
; #define PG8_LDA(dst, b, h) do { _Pragma("unroll") for (int m = 0; m < 4; ++m) _Pragma("unroll") for (int k = 0; k < 2; ++k) dst[m][k] = *(const LAS bf16x8*)(lds + PG8_SA(b, h) + aoff + m * 2048 + k * 1024); } while (0)
; #define PG8_LDB(dst, b, h) do { _Pragma("unroll") for (int n = 0; n < 2; ++n) _Pragma("unroll") for (int k = 0; k < 2; ++k) dst[n][k] = *(const LAS bf16x8*)(lds + PG8_SB(b, h) + boff + n * 2048 + k * 1024); } while (0)
; #define PG8_MMA(ai, bj, At, Bt) do { __builtin_amdgcn_s_setprio(1); _Pragma("unroll") for (int m = 0; m < 4; ++m) _Pragma("unroll") for (int n = 0; n < 2; ++n) _Pragma("unroll") for (int k = 0; k < 2; ++k) \
;         acc[ai][bj][m][n] = __builtin_amdgcn_mfma_f32_16x16x32_bf16(Bt[n][k], At[m][k], acc[ai][bj][m][n], 0, 0, 0); __builtin_amdgcn_s_setprio(0); } while (0)
; #define PG8_WAIT_V(n) asm volatile("s_waitcnt vmcnt(" #n ")" ::: "memory")
; #define PG8_WAIT_L(n) asm volatile("s_waitcnt lgkmcnt(" #n ")" ::: "memory")
; #define PG8_BAR __builtin_amdgcn_s_barrier()
; #define PG8_SCHED __builtin_amdgcn_sched_barrier(0)
; template <class Map, class Epi>
; DI void gemm_phase(LAS unsigned char* lds, const Map& MP, const Epi& E, const int nM, const int nN, const int K, const int lda, const int ldb) {
;     ...
;             PG8_LDB(B0, 0, 0); PG8_SCHED; PG8_LDA(At, 0, 0); PG8_STAGE(PG8_SA(1, 1), a1 + hstepA, voffA);
;             PG8_WAIT_L(8); PG8_BAR; PG8_WAIT_L(0); PG8_MMA(0, 0, At, B0); PG8_BAR; PG8_SCHED;
;             PG8_LDB(B1, 0, 1); PG8_STAGE(PG8_SB(0, 0), b2, voffB);
;             PG8_BAR; PG8_WAIT_L(0); PG8_MMA(0, 1, At, B1); PG8_BAR;
;             PG8_LDA(At, 0, 1); PG8_STAGE(PG8_SA(0, 0), a2, voffA);
;             PG8_BAR; PG8_WAIT_L(0); PG8_MMA(1, 0, At, B0); PG8_BAR; PG8_SCHED;
;             PG8_STAGE(PG8_SB(0, 1), b2 + hstepB, voffB);
;             PG8_WAIT_V(6); PG8_BAR; PG8_MMA(1, 1, At, B1); PG8_BAR;
.LBB1_1239:
	s_add_u32 s10, s8, 0x100
	s_addc_u32 s11, s9, 0
	s_cmpk_eq_i32 s3, 0x54
	s_cselect_b32 s15, s43, s11
	s_cselect_b32 s14, s42, s10
	s_cselect_b32 s13, s7, s38
	s_cselect_b32 s12, s6, s5
	s_add_i32 m0, s24, 0xc000
	ds_read_b128 v[168:171], v150
	ds_read_b128 v[172:175], v150 offset:1024
	ds_read_b128 v[176:179], v150 offset:2048
	ds_read_b128 v[180:183], v150 offset:3072
	ds_read_b128 v[184:187], v150 offset:4096
	ds_read_b128 v[188:191], v150 offset:5120
	ds_read_b128 v[192:195], v150 offset:6144
	ds_read_b128 v[198:201], v150 offset:7168
	global_load_lds_dwordx4 v138, s[8:9]
	s_add_i32 m0, s24, 0xe000
	s_setprio 1
	global_load_lds_dwordx4 v136, s[8:9]
	s_waitcnt lgkmcnt(8)
	s_barrier
	s_waitcnt lgkmcnt(7)
	v_mfma_f32_16x16x32_bf16 v[124:127], v[152:155], v[168:171], v[124:127]
	v_mfma_f32_16x16x32_bf16 v[120:123], v[160:163], v[168:171], v[120:123]
	s_waitcnt lgkmcnt(5)
	v_mfma_f32_16x16x32_bf16 v[108:111], v[152:155], v[176:179], v[108:111]
	v_mfma_f32_16x16x32_bf16 v[104:107], v[160:163], v[176:179], v[104:107]
	s_waitcnt lgkmcnt(3)
	v_mfma_f32_16x16x32_bf16 v[92:95], v[152:155], v[184:187], v[92:95]
	v_mfma_f32_16x16x32_bf16 v[88:91], v[160:163], v[184:187], v[88:91]
	s_waitcnt lgkmcnt(1)
	v_mfma_f32_16x16x32_bf16 v[76:79], v[152:155], v[192:195], v[76:79]
	v_mfma_f32_16x16x32_bf16 v[72:75], v[160:163], v[192:195], v[72:75]
	v_mfma_f32_16x16x32_bf16 v[124:127], v[156:159], v[172:175], v[124:127]
	s_add_i32 s8, s35, s22
	v_mfma_f32_16x16x32_bf16 v[120:123], v[164:167], v[172:175], v[120:123]
	v_lshl_add_u64 v[144:145], s[12:13], 0, v[132:133]
	v_mfma_f32_16x16x32_bf16 v[108:111], v[156:159], v[180:183], v[108:111]
	v_lshl_add_u64 v[218:219], s[12:13], 0, v[128:129]
	v_mfma_f32_16x16x32_bf16 v[104:107], v[164:167], v[180:183], v[104:107]
	v_mfma_f32_16x16x32_bf16 v[92:95], v[156:159], v[188:191], v[92:95]
	v_mfma_f32_16x16x32_bf16 v[88:91], v[164:167], v[188:191], v[88:91]
	s_waitcnt lgkmcnt(0)
	v_mfma_f32_16x16x32_bf16 v[76:79], v[156:159], v[198:201], v[76:79]
	v_mfma_f32_16x16x32_bf16 v[72:75], v[164:167], v[198:201], v[72:75]
	s_barrier
	s_setprio 0
	s_mov_b32 m0, s8
	ds_read_b128 v[202:205], v151
	ds_read_b128 v[206:209], v151 offset:1024
	ds_read_b128 v[210:213], v151 offset:2048
	ds_read_b128 v[214:217], v151 offset:3072
	global_load_lds_dwordx4 v[144:145], off
	s_add_i32 m0, s8, 0x2000
	s_setprio 1
	global_load_lds_dwordx4 v[218:219], off
	s_barrier
	s_waitcnt lgkmcnt(3)
	v_mfma_f32_16x16x32_bf16 v[116:119], v[202:205], v[168:171], v[116:119]
	s_waitcnt lgkmcnt(1)
	v_mfma_f32_16x16x32_bf16 v[112:115], v[210:213], v[168:171], v[112:115]
	v_mfma_f32_16x16x32_bf16 v[100:103], v[202:205], v[176:179], v[100:103]
	v_mfma_f32_16x16x32_bf16 v[96:99], v[210:213], v[176:179], v[96:99]
	v_mfma_f32_16x16x32_bf16 v[84:87], v[202:205], v[184:187], v[84:87]
	v_mfma_f32_16x16x32_bf16 v[80:83], v[210:213], v[184:187], v[80:83]
	v_mfma_f32_16x16x32_bf16 v[68:71], v[202:205], v[192:195], v[68:71]
	v_mfma_f32_16x16x32_bf16 v[64:67], v[210:213], v[192:195], v[64:67]
	v_mfma_f32_16x16x32_bf16 v[116:119], v[206:209], v[172:175], v[116:119]
	v_lshl_add_u64 v[222:223], s[14:15], 0, v[130:131]
	s_mov_b32 m0, s24
	s_waitcnt lgkmcnt(0)
	v_mfma_f32_16x16x32_bf16 v[112:115], v[214:217], v[172:175], v[112:115]
	v_lshl_add_u64 v[220:221], s[14:15], 0, v[134:135]
	v_mfma_f32_16x16x32_bf16 v[100:103], v[206:209], v[180:183], v[100:103]
	v_mfma_f32_16x16x32_bf16 v[96:99], v[214:217], v[180:183], v[96:99]
	v_mfma_f32_16x16x32_bf16 v[84:87], v[206:209], v[188:191], v[84:87]
	v_mfma_f32_16x16x32_bf16 v[80:83], v[214:217], v[188:191], v[80:83]
	v_mfma_f32_16x16x32_bf16 v[68:71], v[206:209], v[198:201], v[68:71]
	v_mfma_f32_16x16x32_bf16 v[64:67], v[214:217], v[198:201], v[64:67]
	s_barrier
	s_setprio 0
	ds_read_b128 v[168:171], v150 offset:16384
	ds_read_b128 v[172:175], v150 offset:17408
	ds_read_b128 v[176:179], v150 offset:18432
	ds_read_b128 v[180:183], v150 offset:19456
	ds_read_b128 v[184:187], v150 offset:20480
	ds_read_b128 v[188:191], v150 offset:21504
	ds_read_b128 v[192:195], v150 offset:22528
	ds_read_b128 v[198:201], v150 offset:23552
	global_load_lds_dwordx4 v[220:221], off
	s_mov_b32 m0, s25
	s_setprio 1
	global_load_lds_dwordx4 v[222:223], off
	s_waitcnt vmcnt(10)
	s_barrier
	s_waitcnt lgkmcnt(7)
	v_mfma_f32_16x16x32_bf16 v[60:63], v[152:155], v[168:171], v[60:63]
	v_mfma_f32_16x16x32_bf16 v[56:59], v[160:163], v[168:171], v[56:59]
	s_waitcnt lgkmcnt(5)
	v_mfma_f32_16x16x32_bf16 v[44:47], v[152:155], v[176:179], v[44:47]
	v_mfma_f32_16x16x32_bf16 v[40:43], v[160:163], v[176:179], v[40:43]
	s_waitcnt lgkmcnt(3)
	v_mfma_f32_16x16x32_bf16 v[28:31], v[152:155], v[184:187], v[28:31]
	v_mfma_f32_16x16x32_bf16 v[24:27], v[160:163], v[184:187], v[24:27]
	s_waitcnt lgkmcnt(1)
	v_mfma_f32_16x16x32_bf16 v[12:15], v[152:155], v[192:195], v[12:15]
	v_mfma_f32_16x16x32_bf16 v[8:11], v[160:163], v[192:195], v[8:11]
	v_mfma_f32_16x16x32_bf16 v[60:63], v[156:159], v[172:175], v[60:63]
	s_add_u32 s8, s12, 0x160000
	s_addc_u32 s9, s13, 0
	v_mfma_f32_16x16x32_bf16 v[56:59], v[164:167], v[172:175], v[56:59]
	s_add_i32 s39, s36, s22
	v_mfma_f32_16x16x32_bf16 v[44:47], v[156:159], v[180:183], v[44:47]
	v_mfma_f32_16x16x32_bf16 v[40:43], v[164:167], v[180:183], v[40:43]
	v_mfma_f32_16x16x32_bf16 v[28:31], v[156:159], v[188:191], v[28:31]
	v_mfma_f32_16x16x32_bf16 v[24:27], v[164:167], v[188:191], v[24:27]
	s_waitcnt lgkmcnt(0)
	v_mfma_f32_16x16x32_bf16 v[12:15], v[156:159], v[198:201], v[12:15]
	v_mfma_f32_16x16x32_bf16 v[8:11], v[164:167], v[198:201], v[8:11]
	s_barrier
; #define PG8_STAGE(bufoff, gbase, voff) do { _Pragma("unroll") for (int _i = 0; _i < 2; ++_i) \
;         __builtin_amdgcn_global_load_lds((const unsigned*)((const char*)(gbase) + (voff)[_i]), (LAS unsigned*)(lds + (bufoff) + ldsw + _i * 8192), 16, 0, 0); } while (0)
; #define PG8_LDA(dst, b, h) do { _Pragma("unroll") for (int m = 0; m < 4; ++m) _Pragma("unroll") for (int k = 0; k < 2; ++k) dst[m][k] = *(const LAS bf16x8*)(lds + PG8_SA(b, h) + aoff + m * 2048 + k * 1024); } while (0)
; #define PG8_LDB(dst, b, h) do { _Pragma("unroll") for (int n = 0; n < 2; ++n) _Pragma("unroll") for (int k = 0; k < 2; ++k) dst[n][k] = *(const LAS bf16x8*)(lds + PG8_SB(b, h) + boff + n * 2048 + k * 1024); } while (0)
; #define PG8_MMA(ai, bj, At, Bt) do { __builtin_amdgcn_s_setprio(1); _Pragma("unroll") for (int m = 0; m < 4; ++m) _Pragma("unroll") for (int n = 0; n < 2; ++n) _Pragma("unroll") for (int k = 0; k < 2; ++k) \
;         acc[ai][bj][m][n] = __builtin_amdgcn_mfma_f32_16x16x32_bf16(Bt[n][k], At[m][k], acc[ai][bj][m][n], 0, 0, 0); __builtin_amdgcn_s_setprio(0); } while (0)
; #define PG8_WAIT_V(n) asm volatile("s_waitcnt vmcnt(" #n ")" ::: "memory")
; #define PG8_WAIT_L(n) asm volatile("s_waitcnt lgkmcnt(" #n ")" ::: "memory")
; #define PG8_BAR __builtin_amdgcn_s_barrier()
; #define PG8_SCHED __builtin_amdgcn_sched_barrier(0)
; template <class Map, class Epi>
; DI void gemm_phase(LAS unsigned char* lds, const Map& MP, const Epi& E, const int nM, const int nN, const int K, const int lda, const int ldb) {
;     ...
;             PG8_WAIT_V(6); PG8_BAR; PG8_MMA(1, 1, At, B1); PG8_BAR;
;             PG8_LDB(B0, 1, 0); PG8_SCHED; PG8_LDA(At, 1, 0); PG8_STAGE(PG8_SA(0, 1), a2 + hstepA, voffA);
;             PG8_WAIT_L(8); PG8_BAR; PG8_WAIT_L(0); PG8_MMA(0, 0, At, B0); PG8_BAR; PG8_SCHED;
;             PG8_LDB(B1, 1, 1); PG8_STAGE(PG8_SB(1, 0), b3, voffB);
;             PG8_BAR; PG8_WAIT_L(0); PG8_MMA(0, 1, At, B1); PG8_BAR;
;             PG8_LDA(At, 1, 1); PG8_STAGE(PG8_SA(1, 0), a3, voffA);
;             PG8_BAR; PG8_WAIT_L(0); PG8_MMA(1, 0, At, B0); PG8_BAR; PG8_SCHED;
;             PG8_STAGE(PG8_SB(1, 1), b3 + hstepB, voffB);
;             PG8_WAIT_V(6); PG8_BAR; PG8_MMA(1, 1, At, B1); PG8_BAR;
	s_setprio 0
	s_mov_b32 m0, s39
	s_nop 0
	global_load_lds_dwordx4 v132, s[8:9]
	s_add_i32 m0, s39, 0x2000
	s_setprio 1
	global_load_lds_dwordx4 v128, s[8:9]
	s_waitcnt vmcnt(6)
	s_barrier
	v_mfma_f32_16x16x32_bf16 v[52:55], v[202:205], v[168:171], v[52:55]
	v_mfma_f32_16x16x32_bf16 v[48:51], v[210:213], v[168:171], v[48:51]
	s_add_i32 s39, 0, 0x18000
	v_add_u32_e32 v164, s39, v148
	ds_read_b128 v[152:155], v164
	v_mfma_f32_16x16x32_bf16 v[36:39], v[202:205], v[176:179], v[36:39]
	v_mfma_f32_16x16x32_bf16 v[32:35], v[210:213], v[176:179], v[32:35]
	ds_read_b128 v[156:159], v164 offset:1024
	v_mfma_f32_16x16x32_bf16 v[20:23], v[202:205], v[184:187], v[20:23]
	v_mfma_f32_16x16x32_bf16 v[16:19], v[210:213], v[184:187], v[16:19]
	ds_read_b128 v[160:163], v164 offset:2048
	v_mfma_f32_16x16x32_bf16 v[4:7], v[202:205], v[192:195], v[4:7]
	v_mfma_f32_16x16x32_bf16 v[0:3], v[210:213], v[192:195], v[0:3]
	ds_read_b128 v[164:167], v164 offset:3072
	v_mfma_f32_16x16x32_bf16 v[52:55], v[206:209], v[172:175], v[52:55]
	s_add_u32 s8, s14, 0x160000
	s_addc_u32 s9, s15, 0
	v_mfma_f32_16x16x32_bf16 v[48:51], v[214:217], v[172:175], v[48:51]
	v_mfma_f32_16x16x32_bf16 v[36:39], v[206:209], v[180:183], v[36:39]
	v_mfma_f32_16x16x32_bf16 v[32:35], v[214:217], v[180:183], v[32:35]
	v_mfma_f32_16x16x32_bf16 v[20:23], v[206:209], v[188:191], v[20:23]
	v_mfma_f32_16x16x32_bf16 v[16:19], v[214:217], v[188:191], v[16:19]
	v_mfma_f32_16x16x32_bf16 v[4:7], v[206:209], v[198:201], v[4:7]
	v_mfma_f32_16x16x32_bf16 v[0:3], v[214:217], v[198:201], v[0:3]
	s_barrier
	s_setprio 0
	s_mov_b32 m0, s26
	ds_read_b128 v[168:171], v150 offset:32768
	ds_read_b128 v[172:175], v150 offset:33792
	ds_read_b128 v[176:179], v150 offset:34816
	ds_read_b128 v[180:183], v150 offset:35840
	ds_read_b128 v[184:187], v150 offset:36864
	ds_read_b128 v[188:191], v150 offset:37888
	ds_read_b128 v[192:195], v150 offset:38912
	ds_read_b128 v[198:201], v150 offset:39936
	global_load_lds_dwordx4 v134, s[8:9]
	s_mov_b32 m0, s27
	s_setprio 1
	global_load_lds_dwordx4 v130, s[8:9]
	s_waitcnt lgkmcnt(8)
	s_barrier
	s_waitcnt lgkmcnt(7)
	v_mfma_f32_16x16x32_bf16 v[124:127], v[152:155], v[168:171], v[124:127]
	v_mfma_f32_16x16x32_bf16 v[120:123], v[160:163], v[168:171], v[120:123]
	s_waitcnt lgkmcnt(5)
	v_mfma_f32_16x16x32_bf16 v[108:111], v[152:155], v[176:179], v[108:111]
	v_mfma_f32_16x16x32_bf16 v[104:107], v[160:163], v[176:179], v[104:107]
	s_waitcnt lgkmcnt(3)
	v_mfma_f32_16x16x32_bf16 v[92:95], v[152:155], v[184:187], v[92:95]
	v_mfma_f32_16x16x32_bf16 v[88:91], v[160:163], v[184:187], v[88:91]
	s_waitcnt lgkmcnt(1)
	v_mfma_f32_16x16x32_bf16 v[76:79], v[152:155], v[192:195], v[76:79]
	v_mfma_f32_16x16x32_bf16 v[72:75], v[160:163], v[192:195], v[72:75]
	v_mfma_f32_16x16x32_bf16 v[124:127], v[156:159], v[172:175], v[124:127]
	s_add_i32 s14, 0, 0x1c000
	v_mfma_f32_16x16x32_bf16 v[120:123], v[164:167], v[172:175], v[120:123]
	s_add_i32 s8, s39, s22
	v_mfma_f32_16x16x32_bf16 v[108:111], v[156:159], v[180:183], v[108:111]
	v_add_u32_e32 v196, s14, v148
	v_mfma_f32_16x16x32_bf16 v[104:107], v[164:167], v[180:183], v[104:107]
	v_lshl_add_u64 v[144:145], v[144:145], 0, s[52:53]
	v_mfma_f32_16x16x32_bf16 v[92:95], v[156:159], v[188:191], v[92:95]
	v_mfma_f32_16x16x32_bf16 v[88:91], v[164:167], v[188:191], v[88:91]
	s_waitcnt lgkmcnt(0)
	v_mfma_f32_16x16x32_bf16 v[76:79], v[156:159], v[198:201], v[76:79]
	v_mfma_f32_16x16x32_bf16 v[72:75], v[164:167], v[198:201], v[72:75]
	s_barrier
	s_setprio 0
	s_mov_b32 m0, s8
	ds_read_b128 v[202:205], v196
	ds_read_b128 v[206:209], v196 offset:1024
	ds_read_b128 v[210:213], v196 offset:2048
	ds_read_b128 v[214:217], v196 offset:3072
	global_load_lds_dwordx4 v[144:145], off
	v_lshl_add_u64 v[144:145], v[218:219], 0, s[52:53]
	s_add_i32 m0, s8, 0x2000
	s_setprio 1
	global_load_lds_dwordx4 v[144:145], off
	s_barrier
	s_waitcnt lgkmcnt(3)
	v_mfma_f32_16x16x32_bf16 v[116:119], v[202:205], v[168:171], v[116:119]
	s_waitcnt lgkmcnt(1)
	v_mfma_f32_16x16x32_bf16 v[112:115], v[210:213], v[168:171], v[112:115]
	v_mfma_f32_16x16x32_bf16 v[100:103], v[202:205], v[176:179], v[100:103]
	v_mfma_f32_16x16x32_bf16 v[96:99], v[210:213], v[176:179], v[96:99]
	v_mfma_f32_16x16x32_bf16 v[84:87], v[202:205], v[184:187], v[84:87]
	v_mfma_f32_16x16x32_bf16 v[80:83], v[210:213], v[184:187], v[80:83]
	v_mfma_f32_16x16x32_bf16 v[68:71], v[202:205], v[192:195], v[68:71]
	v_mfma_f32_16x16x32_bf16 v[64:67], v[210:213], v[192:195], v[64:67]
	v_mfma_f32_16x16x32_bf16 v[116:119], v[206:209], v[172:175], v[116:119]
	s_mov_b32 m0, s30
	s_waitcnt lgkmcnt(0)
	v_mfma_f32_16x16x32_bf16 v[112:115], v[214:217], v[172:175], v[112:115]
	v_lshl_add_u64 v[144:145], v[220:221], 0, s[52:53]
	v_mfma_f32_16x16x32_bf16 v[100:103], v[206:209], v[180:183], v[100:103]
	v_mfma_f32_16x16x32_bf16 v[96:99], v[214:217], v[180:183], v[96:99]
	v_mfma_f32_16x16x32_bf16 v[84:87], v[206:209], v[188:191], v[84:87]
	v_mfma_f32_16x16x32_bf16 v[80:83], v[214:217], v[188:191], v[80:83]
	v_mfma_f32_16x16x32_bf16 v[68:71], v[206:209], v[198:201], v[68:71]
	v_mfma_f32_16x16x32_bf16 v[64:67], v[214:217], v[198:201], v[64:67]
	s_barrier
	s_setprio 0
	ds_read_b128 v[168:171], v150 offset:49152
	ds_read_b128 v[172:175], v150 offset:50176
	ds_read_b128 v[176:179], v150 offset:51200
	ds_read_b128 v[180:183], v150 offset:52224
	ds_read_b128 v[184:187], v150 offset:53248
	ds_read_b128 v[188:191], v150 offset:54272
	ds_read_b128 v[192:195], v150 offset:55296
	ds_read_b128 v[198:201], v150 offset:56320
	global_load_lds_dwordx4 v[144:145], off
	v_lshl_add_u64 v[144:145], v[222:223], 0, s[52:53]
	s_mov_b32 m0, s31
	s_setprio 1
	global_load_lds_dwordx4 v[144:145], off
	s_waitcnt vmcnt(10)
	s_barrier
; DI unsigned pack2(float a, float b) { f32x2 v = {a, b}; hwbf16x2 r = __builtin_convertvector(v, hwbf16x2); return __builtin_bit_cast(unsigned, r); }
; DI float bflo(unsigned w) { return __uint_as_float(w << 16); }
; DI float bfhi(unsigned w) { return __uint_as_float(w & 0xffff0000u); }
; #define PG8_WAIT_V(n) asm volatile("s_waitcnt vmcnt(" #n ")" ::: "memory")
; #define PG8_BAR __builtin_amdgcn_s_barrier()
;     DI void operator()(const f32x4 (&acc)[2][2][4][2], const Unit& u, int wr, int wc, int fr, int fq) const {
;     ...
;         for (int ai = 0; ai < 2; ++ai)
; #pragma unroll
;             for (int m = 0; m < 4; ++m) { const size_t ro = (size_t)(row0 + ai * HALF + m * 16) * D + col0;
; #pragma unroll
;                 for (int bj = 0; bj < 2; ++bj) {
;                     f32x4 x0, x1;
;                     if constexpr (IB) { const u32x4 w = *(const u32x4*)((const bf16_t*)Xin + ro + bj * HALF);
;                         x0 = (f32x4){bflo(w[0]), bfhi(w[0]), bflo(w[1]), bfhi(w[1])}; x1 = (f32x4){bflo(w[2]), bfhi(w[2]), bflo(w[3]), bfhi(w[3])}; }
;                     else { x0 = *(const f32x4*)((const float*)Xin + ro + bj * HALF); x1 = *(const f32x4*)((const float*)Xin + ro + bj * HALF + 4); }
;                     x0 += acc[ai][bj][m][0] * sc[bj][0]; x1 += acc[ai][bj][m][1] * sc[bj][1];
;                     if constexpr (OB) { u32x4 o; o[0] = pack2(x0[0], x0[1]); o[1] = pack2(x0[2], x0[3]); o[2] = pack2(x1[0], x1[1]); o[3] = pack2(x1[2], x1[3]);
;                         *(u32x4*)((bf16_t*)Xout + ro + bj * HALF) = o; }
;                     else { *(f32x4*)((float*)Xout + ro + bj * HALF) = x0; *(f32x4*)((float*)Xout + ro + bj * HALF + 4) = x1; } } }
; template <class Map, class Epi>
; DI void gemm_phase(LAS unsigned char* lds, const Map& MP, const Epi& E, const int nM, const int nN, const int K, const int lda, const int ldb) {
;     ...
;             PG8_WAIT_L(8); PG8_BAR; PG8_WAIT_L(0); PG8_MMA(0, 0, At, B0); PG8_BAR; PG8_SCHED;
;             PG8_LDB(B1, 1, 1); PG8_STAGE(PG8_SB(1, 0), b3, voffB);
;             PG8_BAR; PG8_WAIT_L(0); PG8_MMA(0, 1, At, B1); PG8_BAR;
;             PG8_LDA(At, 1, 1); PG8_STAGE(PG8_SA(1, 0), a3, voffA);
;             PG8_BAR; PG8_WAIT_L(0); PG8_MMA(1, 0, At, B0); PG8_BAR; PG8_SCHED;
;             PG8_STAGE(PG8_SB(1, 1), b3 + hstepB, voffB);
;             PG8_WAIT_V(6); PG8_BAR; PG8_MMA(1, 1, At, B1); PG8_BAR;
	s_waitcnt lgkmcnt(7)
	v_mfma_f32_16x16x32_bf16 v[60:63], v[152:155], v[168:171], v[60:63]
	v_mfma_f32_16x16x32_bf16 v[56:59], v[160:163], v[168:171], v[56:59]
	s_waitcnt lgkmcnt(5)
	v_mfma_f32_16x16x32_bf16 v[44:47], v[152:155], v[176:179], v[44:47]
	v_mfma_f32_16x16x32_bf16 v[40:43], v[160:163], v[176:179], v[40:43]
	s_waitcnt lgkmcnt(3)
	v_mfma_f32_16x16x32_bf16 v[28:31], v[152:155], v[184:187], v[28:31]
	v_mfma_f32_16x16x32_bf16 v[24:27], v[160:163], v[184:187], v[24:27]
	s_waitcnt lgkmcnt(1)
	v_mfma_f32_16x16x32_bf16 v[12:15], v[152:155], v[192:195], v[12:15]
	v_mfma_f32_16x16x32_bf16 v[8:11], v[160:163], v[192:195], v[8:11]
	v_mfma_f32_16x16x32_bf16 v[60:63], v[156:159], v[172:175], v[60:63]
	s_add_u32 s8, s12, 0x160080
	s_addc_u32 s9, s13, 0
	v_mfma_f32_16x16x32_bf16 v[56:59], v[164:167], v[172:175], v[56:59]
	s_add_i32 s12, s14, s22
	v_mfma_f32_16x16x32_bf16 v[44:47], v[156:159], v[180:183], v[44:47]
	v_mfma_f32_16x16x32_bf16 v[40:43], v[164:167], v[180:183], v[40:43]
	v_mfma_f32_16x16x32_bf16 v[28:31], v[156:159], v[188:191], v[28:31]
	v_mfma_f32_16x16x32_bf16 v[24:27], v[164:167], v[188:191], v[24:27]
	s_waitcnt lgkmcnt(0)
	v_mfma_f32_16x16x32_bf16 v[12:15], v[156:159], v[198:201], v[12:15]
	v_mfma_f32_16x16x32_bf16 v[8:11], v[164:167], v[198:201], v[8:11]
	s_barrier
	s_setprio 0
	s_mov_b32 m0, s12
	s_nop 0
	global_load_lds_dwordx4 v132, s[8:9]
	s_add_i32 m0, s12, 0x2000
	s_setprio 1
	global_load_lds_dwordx4 v128, s[8:9]
	s_waitcnt vmcnt(6)
	s_barrier
	v_mfma_f32_16x16x32_bf16 v[52:55], v[202:205], v[168:171], v[52:55]
	v_mfma_f32_16x16x32_bf16 v[48:51], v[210:213], v[168:171], v[48:51]
	ds_read_b128 v[152:155], v149
	v_mfma_f32_16x16x32_bf16 v[36:39], v[202:205], v[176:179], v[36:39]
	v_mfma_f32_16x16x32_bf16 v[32:35], v[210:213], v[176:179], v[32:35]
	ds_read_b128 v[156:159], v149 offset:1024
	v_mfma_f32_16x16x32_bf16 v[20:23], v[202:205], v[184:187], v[20:23]
	v_mfma_f32_16x16x32_bf16 v[16:19], v[210:213], v[184:187], v[16:19]
	ds_read_b128 v[160:163], v149 offset:2048
	v_mfma_f32_16x16x32_bf16 v[4:7], v[202:205], v[192:195], v[4:7]
	v_mfma_f32_16x16x32_bf16 v[0:3], v[210:213], v[192:195], v[0:3]
	ds_read_b128 v[164:167], v149 offset:3072
	v_mfma_f32_16x16x32_bf16 v[52:55], v[206:209], v[172:175], v[52:55]
	s_add_i32 s3, s3, 2
	v_mfma_f32_16x16x32_bf16 v[48:51], v[214:217], v[172:175], v[48:51]
	s_add_u32 s5, s5, 0x100
	s_addc_u32 s38, s38, 0
	v_mfma_f32_16x16x32_bf16 v[36:39], v[206:209], v[180:183], v[36:39]
	s_cmpk_gt_u32 s3, 0x55
	v_mfma_f32_16x16x32_bf16 v[32:35], v[214:217], v[180:183], v[32:35]
	s_mov_b64 s[8:9], s[10:11]
	v_mfma_f32_16x16x32_bf16 v[20:23], v[206:209], v[188:191], v[20:23]
	v_mfma_f32_16x16x32_bf16 v[16:19], v[214:217], v[188:191], v[16:19]
	v_mfma_f32_16x16x32_bf16 v[4:7], v[206:209], v[198:201], v[4:7]
	v_mfma_f32_16x16x32_bf16 v[0:3], v[214:217], v[198:201], v[0:3]
	s_barrier
	s_setprio 0
	s_cbranch_scc0 .LBB1_1239
	s_waitcnt lgkmcnt(0)
	v_mov_b32_e32 v152, v147
	v_mov_b32_e32 v144, v146
	s_lshl_b32 s2, s2, 8
	s_add_i32 s2, s2, s29
	s_lshl_b32 s3, s4, 8
	v_add_u32_e32 v152, s2, v152
	s_or_b32 s3, s3, s54
	v_ashrrev_i32_e32 v153, 31, v152
	v_lshl_add_u32 v144, v144, 3, s3
	v_lshlrev_b64 v[152:153], 12, v[152:153]
	v_ashrrev_i32_e32 v145, 31, v144
	v_lshl_add_u64 v[152:153], s[46:47], 0, v[152:153]
	v_lshl_add_u64 v[144:145], v[144:145], 1, v[152:153]
	global_load_dwordx4 v[160:163], v[144:145], off
	global_load_dwordx4 v[164:167], v[144:145], off offset:256
	s_mov_b64 s[98:99], 0x10000
	v_lshl_add_u64 v[154:155], v[144:145], 0, s[98:99]
	global_load_dwordx4 v[168:171], v[154:155], off
	global_load_dwordx4 v[172:175], v[154:155], off offset:256
	s_mov_b64 s[98:99], 0x20000
	v_lshl_add_u64 v[154:155], v[144:145], 0, s[98:99]
	global_load_dwordx4 v[176:179], v[154:155], off
	global_load_dwordx4 v[180:183], v[154:155], off offset:256
	s_mov_b64 s[98:99], 0x30000
	v_lshl_add_u64 v[154:155], v[144:145], 0, s[98:99]
	global_load_dwordx4 v[184:187], v[154:155], off
	global_load_dwordx4 v[188:191], v[154:155], off offset:256
	s_mov_b64 s[98:99], 0x80000
	v_lshl_add_u64 v[154:155], v[144:145], 0, s[98:99]
	global_load_dwordx4 v[192:195], v[154:155], off
	global_load_dwordx4 v[198:201], v[154:155], off offset:256
	s_mov_b64 s[98:99], 0x90000
	v_lshl_add_u64 v[154:155], v[144:145], 0, s[98:99]
	global_load_dwordx4 v[202:205], v[154:155], off
	global_load_dwordx4 v[206:209], v[154:155], off offset:256
	s_mov_b64 s[98:99], 0xa0000
	v_lshl_add_u64 v[154:155], v[144:145], 0, s[98:99]
	global_load_dwordx4 v[210:213], v[154:155], off
	global_load_dwordx4 v[214:217], v[154:155], off offset:256
	s_mov_b64 s[98:99], 0xb0000
	v_lshl_add_u64 v[154:155], v[144:145], 0, s[98:99]
	global_load_dwordx4 v[248:251], v[154:155], off
	global_load_dwordx4 v[252:255], v[154:155], off offset:256
	s_waitcnt vmcnt(15)
	s_nop 1
	v_mov_b32_e32 v152, v160
	v_mov_b32_e32 v153, v161
	v_mov_b32_e32 v154, v162
	v_mov_b32_e32 v155, v163
	s_mov_b64 s[2:3], 0x10000
	s_mov_b32 s4, s37
	s_mov_b64 s[10:11], s[6:7]
	s_mov_b64 s[8:9], s[42:43]
	s_waitcnt lgkmcnt(0)
	v_lshlrev_b32_e32 v156, 16, v152
	v_and_b32_e32 v157, 0xffff0000, v152
	v_lshlrev_b32_e32 v152, 16, v153
	v_and_b32_e32 v153, 0xffff0000, v153
	v_lshlrev_b32_e32 v158, 16, v154
	v_and_b32_e32 v159, 0xffff0000, v154
	v_lshlrev_b32_e32 v154, 16, v155
	v_and_b32_e32 v155, 0xffff0000, v155
	v_pk_add_f32 v[126:127], v[126:127], v[152:153]
	v_pk_add_f32 v[124:125], v[124:125], v[156:157]
	v_pk_add_f32 v[152:153], v[122:123], v[154:155]
	v_pk_add_f32 v[122:123], v[120:121], v[158:159]
	v_cvt_pk_bf16_f32 v120, v124, v125
	v_cvt_pk_bf16_f32 v121, v126, v127
	v_cvt_pk_bf16_f32 v122, v122, v123
	v_cvt_pk_bf16_f32 v123, v152, v153
	global_store_dwordx4 v[144:145], v[120:123], off
	s_waitcnt vmcnt(15)
; DI unsigned pack2(float a, float b) { f32x2 v = {a, b}; hwbf16x2 r = __builtin_convertvector(v, hwbf16x2); return __builtin_bit_cast(unsigned, r); }
; DI float bflo(unsigned w) { return __uint_as_float(w << 16); }
; DI float bfhi(unsigned w) { return __uint_as_float(w & 0xffff0000u); }
;     DI void operator()(const f32x4 (&acc)[2][2][4][2], const Unit& u, int wr, int wc, int fr, int fq) const {
;     ...
;             for (int m = 0; m < 4; ++m) { const size_t ro = (size_t)(row0 + ai * HALF + m * 16) * D + col0;
; #pragma unroll
;                 for (int bj = 0; bj < 2; ++bj) {
;                     f32x4 x0, x1;
;                     if constexpr (IB) { const u32x4 w = *(const u32x4*)((const bf16_t*)Xin + ro + bj * HALF);
;                         x0 = (f32x4){bflo(w[0]), bfhi(w[0]), bflo(w[1]), bfhi(w[1])}; x1 = (f32x4){bflo(w[2]), bfhi(w[2]), bflo(w[3]), bfhi(w[3])}; }
;                     else { x0 = *(const f32x4*)((const float*)Xin + ro + bj * HALF); x1 = *(const f32x4*)((const float*)Xin + ro + bj * HALF + 4); }
;                     x0 += acc[ai][bj][m][0] * sc[bj][0]; x1 += acc[ai][bj][m][1] * sc[bj][1];
;                     if constexpr (OB) { u32x4 o; o[0] = pack2(x0[0], x0[1]); o[1] = pack2(x0[2], x0[3]); o[2] = pack2(x1[0], x1[1]); o[3] = pack2(x1[2], x1[3]);
;                         *(u32x4*)((bf16_t*)Xout + ro + bj * HALF) = o; }
;                     else { *(f32x4*)((float*)Xout + ro + bj * HALF) = x0; *(f32x4*)((float*)Xout + ro + bj * HALF + 4) = x1; } } }
	s_nop 1
	v_mov_b32_e32 v120, v164
	v_mov_b32_e32 v121, v165
	v_mov_b32_e32 v122, v166
	v_mov_b32_e32 v123, v167
	s_waitcnt lgkmcnt(0)
	v_lshlrev_b32_e32 v124, 16, v120
	v_and_b32_e32 v125, 0xffff0000, v120
	v_lshlrev_b32_e32 v120, 16, v121
	v_and_b32_e32 v121, 0xffff0000, v121
	v_lshlrev_b32_e32 v126, 16, v122
	v_and_b32_e32 v127, 0xffff0000, v122
	v_lshlrev_b32_e32 v122, 16, v123
	v_and_b32_e32 v123, 0xffff0000, v123
	v_pk_add_f32 v[116:117], v[116:117], v[124:125]
	v_pk_add_f32 v[118:119], v[118:119], v[120:121]
	v_pk_add_f32 v[120:121], v[114:115], v[122:123]
	v_pk_add_f32 v[114:115], v[112:113], v[126:127]
	v_cvt_pk_bf16_f32 v112, v116, v117
	v_lshl_add_u64 v[116:117], v[144:145], 0, s[2:3]
	s_mov_b32 s2, 0x10000
	v_cvt_pk_bf16_f32 v113, v118, v119
	v_add_co_u32_e32 v118, vcc, s2, v144
	v_cvt_pk_bf16_f32 v114, v114, v115
	v_cvt_pk_bf16_f32 v115, v120, v121
	v_addc_co_u32_e32 v119, vcc, 0, v145, vcc
	global_store_dwordx4 v[144:145], v[112:115], off offset:256
	s_waitcnt vmcnt(15)
	s_nop 1
	v_mov_b32_e32 v112, v168
	v_mov_b32_e32 v113, v169
	v_mov_b32_e32 v114, v170
	v_mov_b32_e32 v115, v171
	s_mov_b64 s[2:3], 0x20000
	s_waitcnt lgkmcnt(0)
	v_lshlrev_b32_e32 v120, 16, v112
	v_and_b32_e32 v121, 0xffff0000, v112
	v_lshlrev_b32_e32 v112, 16, v113
	v_and_b32_e32 v113, 0xffff0000, v113
	v_lshlrev_b32_e32 v122, 16, v114
	v_and_b32_e32 v123, 0xffff0000, v114
	v_lshlrev_b32_e32 v114, 16, v115
	v_and_b32_e32 v115, 0xffff0000, v115
	v_pk_add_f32 v[110:111], v[110:111], v[112:113]
	v_pk_add_f32 v[108:109], v[108:109], v[120:121]
	v_pk_add_f32 v[112:113], v[106:107], v[114:115]
	v_pk_add_f32 v[106:107], v[104:105], v[122:123]
	v_cvt_pk_bf16_f32 v104, v108, v109
	v_cvt_pk_bf16_f32 v105, v110, v111
	v_cvt_pk_bf16_f32 v106, v106, v107
	v_cvt_pk_bf16_f32 v107, v112, v113
	global_store_dwordx4 v[118:119], v[104:107], off
	s_waitcnt vmcnt(15)
	s_nop 1
	v_mov_b32_e32 v104, v172
	v_mov_b32_e32 v105, v173
	v_mov_b32_e32 v106, v174
	v_mov_b32_e32 v107, v175
	s_waitcnt lgkmcnt(0)
	v_lshlrev_b32_e32 v108, 16, v104
	v_and_b32_e32 v109, 0xffff0000, v104
	v_lshlrev_b32_e32 v104, 16, v105
	v_and_b32_e32 v105, 0xffff0000, v105
	v_lshlrev_b32_e32 v110, 16, v106
	v_and_b32_e32 v111, 0xffff0000, v106
	v_lshlrev_b32_e32 v106, 16, v107
	v_and_b32_e32 v107, 0xffff0000, v107
	v_pk_add_f32 v[100:101], v[100:101], v[108:109]
	v_pk_add_f32 v[102:103], v[102:103], v[104:105]
	v_pk_add_f32 v[104:105], v[98:99], v[106:107]
	v_pk_add_f32 v[98:99], v[96:97], v[110:111]
	v_cvt_pk_bf16_f32 v96, v100, v101
	v_lshl_add_u64 v[100:101], v[144:145], 0, s[2:3]
	s_mov_b32 s2, 0x20000
	v_cvt_pk_bf16_f32 v97, v102, v103
	v_add_co_u32_e32 v102, vcc, s2, v144
	v_cvt_pk_bf16_f32 v98, v98, v99
	v_cvt_pk_bf16_f32 v99, v104, v105
	v_addc_co_u32_e32 v103, vcc, 0, v145, vcc
	global_store_dwordx4 v[116:117], v[96:99], off offset:256
	s_waitcnt vmcnt(15)
	s_nop 1
	v_mov_b32_e32 v96, v176
	v_mov_b32_e32 v97, v177
	v_mov_b32_e32 v98, v178
	v_mov_b32_e32 v99, v179
	s_mov_b64 s[2:3], 0x30000
	s_waitcnt lgkmcnt(0)
	v_lshlrev_b32_e32 v104, 16, v96
	v_and_b32_e32 v105, 0xffff0000, v96
	v_lshlrev_b32_e32 v96, 16, v97
	v_and_b32_e32 v97, 0xffff0000, v97
	v_lshlrev_b32_e32 v106, 16, v98
	v_and_b32_e32 v107, 0xffff0000, v98
	v_lshlrev_b32_e32 v98, 16, v99
	v_and_b32_e32 v99, 0xffff0000, v99
	v_pk_add_f32 v[94:95], v[94:95], v[96:97]
	v_pk_add_f32 v[92:93], v[92:93], v[104:105]
	v_pk_add_f32 v[96:97], v[90:91], v[98:99]
	v_pk_add_f32 v[90:91], v[88:89], v[106:107]
	v_cvt_pk_bf16_f32 v88, v92, v93
	v_cvt_pk_bf16_f32 v89, v94, v95
	v_cvt_pk_bf16_f32 v90, v90, v91
	v_cvt_pk_bf16_f32 v91, v96, v97
	global_store_dwordx4 v[102:103], v[88:91], off
	s_waitcnt vmcnt(15)
	s_nop 1
	v_mov_b32_e32 v88, v180
	v_mov_b32_e32 v89, v181
	v_mov_b32_e32 v90, v182
	v_mov_b32_e32 v91, v183
	s_waitcnt lgkmcnt(0)
	v_lshlrev_b32_e32 v92, 16, v88
	v_and_b32_e32 v93, 0xffff0000, v88
	v_lshlrev_b32_e32 v88, 16, v89
	v_and_b32_e32 v89, 0xffff0000, v89
	v_lshlrev_b32_e32 v94, 16, v90
	v_and_b32_e32 v95, 0xffff0000, v90
	v_lshlrev_b32_e32 v90, 16, v91
	v_and_b32_e32 v91, 0xffff0000, v91
	v_pk_add_f32 v[86:87], v[86:87], v[88:89]
	v_pk_add_f32 v[84:85], v[84:85], v[92:93]
	v_pk_add_f32 v[88:89], v[82:83], v[90:91]
	v_pk_add_f32 v[82:83], v[80:81], v[94:95]
	v_cvt_pk_bf16_f32 v80, v84, v85
	v_cvt_pk_bf16_f32 v81, v86, v87
	v_cvt_pk_bf16_f32 v82, v82, v83
	v_cvt_pk_bf16_f32 v83, v88, v89
	global_store_dwordx4 v[100:101], v[80:83], off offset:256
	s_nop 1
	v_lshl_add_u64 v[80:81], v[144:145], 0, s[2:3]
	s_mov_b32 s2, 0x30000
	v_add_co_u32_e32 v86, vcc, s2, v144
	s_mov_b64 s[2:3], 0x80000
	s_nop 0
	v_addc_co_u32_e32 v87, vcc, 0, v145, vcc
	s_waitcnt vmcnt(15)
	s_nop 1
	v_mov_b32_e32 v82, v184
	v_mov_b32_e32 v83, v185
	v_mov_b32_e32 v84, v186
	v_mov_b32_e32 v85, v187
	s_waitcnt lgkmcnt(0)
	v_lshlrev_b32_e32 v88, 16, v82
	v_and_b32_e32 v89, 0xffff0000, v82
	v_lshlrev_b32_e32 v82, 16, v83
	v_and_b32_e32 v83, 0xffff0000, v83
	v_lshlrev_b32_e32 v90, 16, v84
	v_and_b32_e32 v91, 0xffff0000, v84
	v_lshlrev_b32_e32 v84, 16, v85
	v_and_b32_e32 v85, 0xffff0000, v85
	v_pk_add_f32 v[78:79], v[78:79], v[82:83]
	v_pk_add_f32 v[76:77], v[76:77], v[88:89]
	v_pk_add_f32 v[82:83], v[74:75], v[84:85]
	v_pk_add_f32 v[74:75], v[72:73], v[90:91]
	v_cvt_pk_bf16_f32 v72, v76, v77
	v_cvt_pk_bf16_f32 v73, v78, v79
	v_cvt_pk_bf16_f32 v74, v74, v75
	v_cvt_pk_bf16_f32 v75, v82, v83
	global_store_dwordx4 v[86:87], v[72:75], off
	s_waitcnt vmcnt(15)
	s_nop 1
	v_mov_b32_e32 v72, v188
	v_mov_b32_e32 v73, v189
	v_mov_b32_e32 v74, v190
	v_mov_b32_e32 v75, v191
	s_waitcnt lgkmcnt(0)
; DI unsigned pack2(float a, float b) { f32x2 v = {a, b}; hwbf16x2 r = __builtin_convertvector(v, hwbf16x2); return __builtin_bit_cast(unsigned, r); }
; DI float bflo(unsigned w) { return __uint_as_float(w << 16); }
; DI float bfhi(unsigned w) { return __uint_as_float(w & 0xffff0000u); }
;     DI void operator()(const f32x4 (&acc)[2][2][4][2], const Unit& u, int wr, int wc, int fr, int fq) const {
;     ...
;             for (int m = 0; m < 4; ++m) { const size_t ro = (size_t)(row0 + ai * HALF + m * 16) * D + col0;
; #pragma unroll
;                 for (int bj = 0; bj < 2; ++bj) {
;                     f32x4 x0, x1;
;                     if constexpr (IB) { const u32x4 w = *(const u32x4*)((const bf16_t*)Xin + ro + bj * HALF);
;                         x0 = (f32x4){bflo(w[0]), bfhi(w[0]), bflo(w[1]), bfhi(w[1])}; x1 = (f32x4){bflo(w[2]), bfhi(w[2]), bflo(w[3]), bfhi(w[3])}; }
;                     else { x0 = *(const f32x4*)((const float*)Xin + ro + bj * HALF); x1 = *(const f32x4*)((const float*)Xin + ro + bj * HALF + 4); }
;                     x0 += acc[ai][bj][m][0] * sc[bj][0]; x1 += acc[ai][bj][m][1] * sc[bj][1];
;                     if constexpr (OB) { u32x4 o; o[0] = pack2(x0[0], x0[1]); o[1] = pack2(x0[2], x0[3]); o[2] = pack2(x1[0], x1[1]); o[3] = pack2(x1[2], x1[3]);
;                         *(u32x4*)((bf16_t*)Xout + ro + bj * HALF) = o; }
;                     else { *(f32x4*)((float*)Xout + ro + bj * HALF) = x0; *(f32x4*)((float*)Xout + ro + bj * HALF + 4) = x1; } } }
	v_lshlrev_b32_e32 v76, 16, v72
	v_and_b32_e32 v77, 0xffff0000, v72
	v_lshlrev_b32_e32 v72, 16, v73
	v_and_b32_e32 v73, 0xffff0000, v73
	v_lshlrev_b32_e32 v78, 16, v74
	v_and_b32_e32 v79, 0xffff0000, v74
	v_lshlrev_b32_e32 v74, 16, v75
	v_and_b32_e32 v75, 0xffff0000, v75
	v_pk_add_f32 v[70:71], v[70:71], v[72:73]
	v_pk_add_f32 v[68:69], v[68:69], v[76:77]
	v_pk_add_f32 v[72:73], v[66:67], v[74:75]
	v_pk_add_f32 v[66:67], v[64:65], v[78:79]
	v_cvt_pk_bf16_f32 v64, v68, v69
	v_cvt_pk_bf16_f32 v65, v70, v71
	v_cvt_pk_bf16_f32 v66, v66, v67
	v_cvt_pk_bf16_f32 v67, v72, v73
	global_store_dwordx4 v[80:81], v[64:67], off offset:256
	s_nop 1
	v_lshl_add_u64 v[64:65], v[144:145], 0, s[2:3]
	s_mov_b32 s2, 0x80000
	v_add_co_u32_e32 v70, vcc, s2, v144
	s_mov_b64 s[2:3], 0x90000
	s_nop 0
	v_addc_co_u32_e32 v71, vcc, 0, v145, vcc
	s_waitcnt vmcnt(15)
	s_nop 1
	v_mov_b32_e32 v66, v192
	v_mov_b32_e32 v67, v193
	v_mov_b32_e32 v68, v194
	v_mov_b32_e32 v69, v195
	s_waitcnt lgkmcnt(0)
	v_lshlrev_b32_e32 v72, 16, v66
	v_and_b32_e32 v73, 0xffff0000, v66
	v_lshlrev_b32_e32 v66, 16, v67
	v_and_b32_e32 v67, 0xffff0000, v67
	v_lshlrev_b32_e32 v74, 16, v68
	v_and_b32_e32 v75, 0xffff0000, v68
	v_lshlrev_b32_e32 v68, 16, v69
	v_and_b32_e32 v69, 0xffff0000, v69
	v_pk_add_f32 v[62:63], v[62:63], v[66:67]
	v_pk_add_f32 v[60:61], v[60:61], v[72:73]
	v_pk_add_f32 v[66:67], v[58:59], v[68:69]
	v_pk_add_f32 v[58:59], v[56:57], v[74:75]
	v_cvt_pk_bf16_f32 v56, v60, v61
	v_cvt_pk_bf16_f32 v57, v62, v63
	v_cvt_pk_bf16_f32 v58, v58, v59
	v_cvt_pk_bf16_f32 v59, v66, v67
	global_store_dwordx4 v[70:71], v[56:59], off
	s_waitcnt vmcnt(15)
	s_nop 1
	v_mov_b32_e32 v56, v198
	v_mov_b32_e32 v57, v199
	v_mov_b32_e32 v58, v200
	v_mov_b32_e32 v59, v201
	s_waitcnt lgkmcnt(0)
	v_lshlrev_b32_e32 v60, 16, v56
	v_and_b32_e32 v61, 0xffff0000, v56
	v_lshlrev_b32_e32 v56, 16, v57
	v_and_b32_e32 v57, 0xffff0000, v57
	v_lshlrev_b32_e32 v62, 16, v58
	v_and_b32_e32 v63, 0xffff0000, v58
	v_lshlrev_b32_e32 v58, 16, v59
	v_and_b32_e32 v59, 0xffff0000, v59
	v_pk_add_f32 v[54:55], v[54:55], v[56:57]
	v_pk_add_f32 v[52:53], v[52:53], v[60:61]
	v_pk_add_f32 v[56:57], v[50:51], v[58:59]
	v_pk_add_f32 v[50:51], v[48:49], v[62:63]
	v_cvt_pk_bf16_f32 v48, v52, v53
	v_cvt_pk_bf16_f32 v49, v54, v55
	v_cvt_pk_bf16_f32 v50, v50, v51
	v_cvt_pk_bf16_f32 v51, v56, v57
	global_store_dwordx4 v[64:65], v[48:51], off offset:256
	s_nop 1
	v_lshl_add_u64 v[48:49], v[144:145], 0, s[2:3]
	s_mov_b32 s2, 0x90000
	v_add_co_u32_e32 v54, vcc, s2, v144
	s_mov_b64 s[2:3], 0xa0000
	s_nop 0
	v_addc_co_u32_e32 v55, vcc, 0, v145, vcc
	s_waitcnt vmcnt(15)
	s_nop 1
	v_mov_b32_e32 v50, v202
	v_mov_b32_e32 v51, v203
	v_mov_b32_e32 v52, v204
	v_mov_b32_e32 v53, v205
	s_waitcnt lgkmcnt(0)
	v_lshlrev_b32_e32 v56, 16, v50
	v_and_b32_e32 v57, 0xffff0000, v50
	v_lshlrev_b32_e32 v50, 16, v51
	v_and_b32_e32 v51, 0xffff0000, v51
	v_lshlrev_b32_e32 v58, 16, v52
	v_and_b32_e32 v59, 0xffff0000, v52
	v_lshlrev_b32_e32 v52, 16, v53
	v_and_b32_e32 v53, 0xffff0000, v53
	v_pk_add_f32 v[46:47], v[46:47], v[50:51]
	v_pk_add_f32 v[44:45], v[44:45], v[56:57]
	v_pk_add_f32 v[50:51], v[42:43], v[52:53]
	v_pk_add_f32 v[42:43], v[40:41], v[58:59]
	v_cvt_pk_bf16_f32 v40, v44, v45
	v_cvt_pk_bf16_f32 v41, v46, v47
	v_cvt_pk_bf16_f32 v42, v42, v43
	v_cvt_pk_bf16_f32 v43, v50, v51
	global_store_dwordx4 v[54:55], v[40:43], off
	s_waitcnt vmcnt(15)
	s_nop 1
	v_mov_b32_e32 v40, v206
	v_mov_b32_e32 v41, v207
	v_mov_b32_e32 v42, v208
	v_mov_b32_e32 v43, v209
	s_waitcnt lgkmcnt(0)
; DI unsigned pack2(float a, float b) { f32x2 v = {a, b}; hwbf16x2 r = __builtin_convertvector(v, hwbf16x2); return __builtin_bit_cast(unsigned, r); }
; DI float bflo(unsigned w) { return __uint_as_float(w << 16); }
; DI float bfhi(unsigned w) { return __uint_as_float(w & 0xffff0000u); }
;     DI const char* a(const Unit& u) const { return (const char*)(A + (size_t)u.pm * BM * lda); }
;     DI const char* a(const Unit& u) const { return (const char*)(A + (size_t)u.pm * BM * 2048 + (u.pn >> 1) * 512); }
; #define PG8_BAR __builtin_amdgcn_s_barrier()
;     DI void operator()(const f32x4 (&acc)[2][2][4][2], const Unit& u, int wr, int wc, int fr, int fq) const {
;     ...
;             for (int m = 0; m < 4; ++m) { const size_t ro = (size_t)(row0 + ai * HALF + m * 16) * D + col0;
; #pragma unroll
;                 for (int bj = 0; bj < 2; ++bj) {
;                     f32x4 x0, x1;
;                     if constexpr (IB) { const u32x4 w = *(const u32x4*)((const bf16_t*)Xin + ro + bj * HALF);
;                         x0 = (f32x4){bflo(w[0]), bfhi(w[0]), bflo(w[1]), bfhi(w[1])}; x1 = (f32x4){bflo(w[2]), bfhi(w[2]), bflo(w[3]), bfhi(w[3])}; }
;                     else { x0 = *(const f32x4*)((const float*)Xin + ro + bj * HALF); x1 = *(const f32x4*)((const float*)Xin + ro + bj * HALF + 4); }
;                     x0 += acc[ai][bj][m][0] * sc[bj][0]; x1 += acc[ai][bj][m][1] * sc[bj][1];
;                     if constexpr (OB) { u32x4 o; o[0] = pack2(x0[0], x0[1]); o[1] = pack2(x0[2], x0[3]); o[2] = pack2(x1[0], x1[1]); o[3] = pack2(x1[2], x1[3]);
;                         *(u32x4*)((bf16_t*)Xout + ro + bj * HALF) = o; }
;                     else { *(f32x4*)((float*)Xout + ro + bj * HALF) = x0; *(f32x4*)((float*)Xout + ro + bj * HALF + 4) = x1; } } }
; template <class Map, class Epi>
; DI void gemm_phase(LAS unsigned char* lds, const Map& MP, const Epi& E, const int nM, const int nN, const int K, const int lda, const int ldb) {
;     ...
;         if (!has_next) break;
; #pragma unroll
;         for (int a = 0; a < 2; ++a)
; #pragma unroll
;             for (int b = 0; b < 2; ++b)
; #pragma unroll
;                 for (int m = 0; m < 4; ++m)
; #pragma unroll
;                     for (int n = 0; n < 2; ++n) acc[a][b][m][n] = (f32x4){0.f, 0.f, 0.f, 0.f};
;         cur = nxt; cA = nA; cB = nB; ++ui;
;     }
;     PG8_WAIT_V(0);
;     if (wr == 0) PG8_BAR;
;     PG8_BAR;
	v_lshlrev_b32_e32 v44, 16, v40
	v_and_b32_e32 v45, 0xffff0000, v40
	v_lshlrev_b32_e32 v40, 16, v41
	v_and_b32_e32 v41, 0xffff0000, v41
	v_lshlrev_b32_e32 v46, 16, v42
	v_and_b32_e32 v47, 0xffff0000, v42
	v_lshlrev_b32_e32 v42, 16, v43
	v_and_b32_e32 v43, 0xffff0000, v43
	v_pk_add_f32 v[38:39], v[38:39], v[40:41]
	v_pk_add_f32 v[36:37], v[36:37], v[44:45]
	v_pk_add_f32 v[40:41], v[34:35], v[42:43]
	v_pk_add_f32 v[34:35], v[32:33], v[46:47]
	v_cvt_pk_bf16_f32 v32, v36, v37
	v_cvt_pk_bf16_f32 v33, v38, v39
	v_cvt_pk_bf16_f32 v34, v34, v35
	v_cvt_pk_bf16_f32 v35, v40, v41
	global_store_dwordx4 v[48:49], v[32:35], off offset:256
	s_nop 1
	v_lshl_add_u64 v[32:33], v[144:145], 0, s[2:3]
	s_mov_b32 s2, 0xa0000
	v_add_co_u32_e32 v38, vcc, s2, v144
	s_mov_b64 s[2:3], 0xb0000
	s_nop 0
	v_addc_co_u32_e32 v39, vcc, 0, v145, vcc
	s_waitcnt vmcnt(15)
	s_nop 1
	v_mov_b32_e32 v34, v210
	v_mov_b32_e32 v35, v211
	v_mov_b32_e32 v36, v212
	v_mov_b32_e32 v37, v213
	s_waitcnt lgkmcnt(0)
	v_lshlrev_b32_e32 v40, 16, v34
	v_and_b32_e32 v41, 0xffff0000, v34
	v_lshlrev_b32_e32 v34, 16, v35
	v_and_b32_e32 v35, 0xffff0000, v35
	v_lshlrev_b32_e32 v42, 16, v36
	v_and_b32_e32 v43, 0xffff0000, v36
	v_lshlrev_b32_e32 v36, 16, v37
	v_and_b32_e32 v37, 0xffff0000, v37
	v_pk_add_f32 v[30:31], v[30:31], v[34:35]
	v_pk_add_f32 v[28:29], v[28:29], v[40:41]
	v_pk_add_f32 v[34:35], v[26:27], v[36:37]
	v_pk_add_f32 v[26:27], v[24:25], v[42:43]
	v_cvt_pk_bf16_f32 v24, v28, v29
	v_cvt_pk_bf16_f32 v25, v30, v31
	v_cvt_pk_bf16_f32 v26, v26, v27
	v_cvt_pk_bf16_f32 v27, v34, v35
	global_store_dwordx4 v[38:39], v[24:27], off
	s_waitcnt vmcnt(15)
	s_nop 1
	v_mov_b32_e32 v24, v214
	v_mov_b32_e32 v25, v215
	v_mov_b32_e32 v26, v216
	v_mov_b32_e32 v27, v217
	s_waitcnt lgkmcnt(0)
	v_lshlrev_b32_e32 v28, 16, v24
	v_and_b32_e32 v29, 0xffff0000, v24
	v_lshlrev_b32_e32 v24, 16, v25
	v_and_b32_e32 v25, 0xffff0000, v25
	v_lshlrev_b32_e32 v30, 16, v26
	v_and_b32_e32 v31, 0xffff0000, v26
	v_lshlrev_b32_e32 v26, 16, v27
	v_and_b32_e32 v27, 0xffff0000, v27
	v_pk_add_f32 v[22:23], v[22:23], v[24:25]
	v_pk_add_f32 v[20:21], v[20:21], v[28:29]
	v_pk_add_f32 v[24:25], v[18:19], v[26:27]
	v_pk_add_f32 v[18:19], v[16:17], v[30:31]
	v_cvt_pk_bf16_f32 v16, v20, v21
	v_cvt_pk_bf16_f32 v17, v22, v23
	v_cvt_pk_bf16_f32 v18, v18, v19
	v_cvt_pk_bf16_f32 v19, v24, v25
	global_store_dwordx4 v[32:33], v[16:19], off offset:256
	s_nop 1
	v_lshl_add_u64 v[16:17], v[144:145], 0, s[2:3]
	s_mov_b32 s2, 0xb0000
	v_add_co_u32_e32 v22, vcc, s2, v144
	s_mov_b32 s2, s55
	s_nop 0
	v_addc_co_u32_e32 v23, vcc, 0, v145, vcc
	s_waitcnt vmcnt(15)
	s_nop 1
	v_mov_b32_e32 v18, v248
	v_mov_b32_e32 v19, v249
	v_mov_b32_e32 v20, v250
	v_mov_b32_e32 v21, v251
	s_and_b64 vcc, exec, s[40:41]
	s_waitcnt lgkmcnt(0)
	v_lshlrev_b32_e32 v24, 16, v18
	v_and_b32_e32 v25, 0xffff0000, v18
	v_lshlrev_b32_e32 v18, 16, v19
	v_and_b32_e32 v19, 0xffff0000, v19
	v_lshlrev_b32_e32 v26, 16, v20
	v_and_b32_e32 v27, 0xffff0000, v20
	v_lshlrev_b32_e32 v20, 16, v21
	v_and_b32_e32 v21, 0xffff0000, v21
	v_pk_add_f32 v[14:15], v[14:15], v[18:19]
	v_pk_add_f32 v[12:13], v[12:13], v[24:25]
	v_pk_add_f32 v[18:19], v[10:11], v[20:21]
	v_pk_add_f32 v[10:11], v[8:9], v[26:27]
	v_cvt_pk_bf16_f32 v8, v12, v13
	v_cvt_pk_bf16_f32 v9, v14, v15
	v_cvt_pk_bf16_f32 v10, v10, v11
	v_cvt_pk_bf16_f32 v11, v18, v19
	global_store_dwordx4 v[22:23], v[8:11], off
	s_waitcnt vmcnt(15)
	s_nop 1
	v_mov_b32_e32 v8, v252
	v_mov_b32_e32 v9, v253
	v_mov_b32_e32 v10, v254
	v_mov_b32_e32 v11, v255
	s_waitcnt lgkmcnt(0)
	v_lshlrev_b32_e32 v12, 16, v8
	v_and_b32_e32 v13, 0xffff0000, v8
	v_lshlrev_b32_e32 v8, 16, v9
	v_and_b32_e32 v9, 0xffff0000, v9
	v_lshlrev_b32_e32 v14, 16, v10
	v_and_b32_e32 v15, 0xffff0000, v10
	v_lshlrev_b32_e32 v10, 16, v11
	v_and_b32_e32 v11, 0xffff0000, v11
	v_pk_add_f32 v[6:7], v[6:7], v[8:9]
	v_pk_add_f32 v[4:5], v[4:5], v[12:13]
	v_pk_add_f32 v[8:9], v[2:3], v[10:11]
	v_pk_add_f32 v[2:3], v[0:1], v[14:15]
	v_cvt_pk_bf16_f32 v0, v4, v5
	v_cvt_pk_bf16_f32 v1, v6, v7
	v_cvt_pk_bf16_f32 v2, v2, v3
	v_cvt_pk_bf16_f32 v3, v8, v9
	global_store_dwordx4 v[16:17], v[0:3], off offset:256
	s_cbranch_vccz .LBB1_1232
	s_waitcnt vmcnt(0)
	s_cmpk_gt_u32 s17, 0xff
	s_cbranch_scc1 .LBB1_1243
	s_barrier

; #define PG8_STAGE(bufoff, gbase, voff) do { _Pragma("unroll") for (int _i = 0; _i < 2; ++_i) \
;         __builtin_amdgcn_global_load_lds((const unsigned*)((const char*)(gbase) + (voff)[_i]), (LAS unsigned*)(lds + (bufoff) + ldsw + _i * 8192), 16, 0, 0); } while (0)
; #define PG8_LDA(dst, b, h) do { _Pragma("unroll") for (int m = 0; m < 4; ++m) _Pragma("unroll") for (int k = 0; k < 2; ++k) dst[m][k] = *(const LAS bf16x8*)(lds + PG8_SA(b, h) + aoff + m * 2048 + k * 1024); } while (0)
; #define PG8_LDB(dst, b, h) do { _Pragma("unroll") for (int n = 0; n < 2; ++n) _Pragma("unroll") for (int k = 0; k < 2; ++k) dst[n][k] = *(const LAS bf16x8*)(lds + PG8_SB(b, h) + boff + n * 2048 + k * 1024); } while (0)
; #define PG8_MMA(ai, bj, At, Bt) do { __builtin_amdgcn_s_setprio(1); _Pragma("unroll") for (int m = 0; m < 4; ++m) _Pragma("unroll") for (int n = 0; n < 2; ++n) _Pragma("unroll") for (int k = 0; k < 2; ++k) \
;         acc[ai][bj][m][n] = __builtin_amdgcn_mfma_f32_16x16x32_bf16(Bt[n][k], At[m][k], acc[ai][bj][m][n], 0, 0, 0); __builtin_amdgcn_s_setprio(0); } while (0)
; #define PG8_WAIT_L(n) asm volatile("s_waitcnt lgkmcnt(" #n ")" ::: "memory")
; #define PG8_BAR __builtin_amdgcn_s_barrier()
; #define PG8_SCHED __builtin_amdgcn_sched_barrier(0)
; template <class Map, class Epi>
; DI void gemm_phase(LAS unsigned char* lds, const Map& MP, const Epi& E, const int nM, const int nN, const int K, const int lda, const int ldb) {
;     ...
;         for (int t = 0; t < nt; t += 2) {
;             const bool last = (t == nt - 2);
;             const char* a1 = cA + (size_t)(t + 1) * kstep;
;             const char* a2 = last ? nA : cA + (size_t)(t + 2) * kstep; const char* b2 = last ? nB : cB + (size_t)(t + 2) * kstep;
;             const char* a3 = a2 + kstep; const char* b3 = b2 + kstep;
;             PG8_LDB(B0, 0, 0); PG8_SCHED; PG8_LDA(At, 0, 0); PG8_STAGE(PG8_SA(1, 1), a1 + hstepA, voffA);
;             PG8_WAIT_L(8); PG8_BAR; PG8_WAIT_L(0); PG8_MMA(0, 0, At, B0); PG8_BAR; PG8_SCHED;
;             PG8_LDB(B1, 0, 1); PG8_STAGE(PG8_SB(0, 0), b2, voffB);
;             PG8_BAR; PG8_WAIT_L(0); PG8_MMA(0, 1, At, B1); PG8_BAR;
;             PG8_LDA(At, 0, 1); PG8_STAGE(PG8_SA(0, 0), a2, voffA);
;             PG8_BAR; PG8_WAIT_L(0); PG8_MMA(1, 0, At, B0); PG8_BAR; PG8_SCHED;
.LBB1_1382:
	s_add_u32 s22, s20, 0xfff80080
	s_addc_u32 s23, s21, -1
	s_cmp_eq_u32 s3, 28
	s_cselect_b32 s25, s15, s23
	s_cselect_b32 s24, s48, s22
	s_cselect_b32 s23, s13, s53
	s_cselect_b32 s22, s49, s52
	s_add_i32 m0, s31, 0xc000
	ds_read_b128 v[166:169], v148
	ds_read_b128 v[170:173], v148 offset:1024
	ds_read_b128 v[174:177], v148 offset:2048
	ds_read_b128 v[178:181], v148 offset:3072
	ds_read_b128 v[182:185], v148 offset:4096
	ds_read_b128 v[186:189], v148 offset:5120
	ds_read_b128 v[190:193], v148 offset:6144
	ds_read_b128 v[198:201], v148 offset:7168
	global_load_lds_dwordx4 v138, s[20:21]
	s_add_i32 m0, s31, 0xe000
	s_setprio 1
	global_load_lds_dwordx4 v136, s[20:21]
	s_waitcnt lgkmcnt(8)
	s_barrier
	s_waitcnt lgkmcnt(7)
	v_mfma_f32_16x16x32_bf16 v[124:127], v[150:153], v[166:169], v[124:127]
	v_mfma_f32_16x16x32_bf16 v[120:123], v[158:161], v[166:169], v[120:123]
	s_waitcnt lgkmcnt(5)
	v_mfma_f32_16x16x32_bf16 v[116:119], v[150:153], v[174:177], v[116:119]
	v_mfma_f32_16x16x32_bf16 v[112:115], v[158:161], v[174:177], v[112:115]
	s_waitcnt lgkmcnt(3)
	v_mfma_f32_16x16x32_bf16 v[100:103], v[150:153], v[182:185], v[100:103]
	v_mfma_f32_16x16x32_bf16 v[96:99], v[158:161], v[182:185], v[96:99]
	s_waitcnt lgkmcnt(1)
	v_mfma_f32_16x16x32_bf16 v[84:87], v[150:153], v[190:193], v[84:87]
	v_mfma_f32_16x16x32_bf16 v[80:83], v[158:161], v[190:193], v[80:83]
	v_mfma_f32_16x16x32_bf16 v[124:127], v[154:157], v[170:173], v[124:127]
	s_add_i32 s54, s44, s29
	v_mfma_f32_16x16x32_bf16 v[120:123], v[162:165], v[170:173], v[120:123]
	v_lshl_add_u64 v[194:195], s[22:23], 0, v[132:133]
	v_mfma_f32_16x16x32_bf16 v[116:119], v[154:157], v[178:181], v[116:119]
	v_lshl_add_u64 v[218:219], s[22:23], 0, v[128:129]
	v_mfma_f32_16x16x32_bf16 v[112:115], v[162:165], v[178:181], v[112:115]
	v_mfma_f32_16x16x32_bf16 v[100:103], v[154:157], v[186:189], v[100:103]
	v_mfma_f32_16x16x32_bf16 v[96:99], v[162:165], v[186:189], v[96:99]
	s_waitcnt lgkmcnt(0)
	v_mfma_f32_16x16x32_bf16 v[84:87], v[154:157], v[198:201], v[84:87]
	v_mfma_f32_16x16x32_bf16 v[80:83], v[162:165], v[198:201], v[80:83]
	s_barrier
	s_setprio 0
	s_mov_b32 m0, s54
	ds_read_b128 v[202:205], v149
	ds_read_b128 v[206:209], v149 offset:1024
	ds_read_b128 v[210:213], v149 offset:2048
	ds_read_b128 v[214:217], v149 offset:3072
	global_load_lds_dwordx4 v[194:195], off
	s_add_i32 m0, s54, 0x2000
	s_setprio 1
	global_load_lds_dwordx4 v[218:219], off
	s_barrier
	s_waitcnt lgkmcnt(3)
	v_mfma_f32_16x16x32_bf16 v[108:111], v[202:205], v[166:169], v[108:111]
	s_waitcnt lgkmcnt(1)
	v_mfma_f32_16x16x32_bf16 v[104:107], v[210:213], v[166:169], v[104:107]
	v_mfma_f32_16x16x32_bf16 v[92:95], v[202:205], v[174:177], v[92:95]
	v_mfma_f32_16x16x32_bf16 v[88:91], v[210:213], v[174:177], v[88:91]
	v_mfma_f32_16x16x32_bf16 v[76:79], v[202:205], v[182:185], v[76:79]
	v_mfma_f32_16x16x32_bf16 v[72:75], v[210:213], v[182:185], v[72:75]
	v_mfma_f32_16x16x32_bf16 v[68:71], v[202:205], v[190:193], v[68:71]
	v_mfma_f32_16x16x32_bf16 v[64:67], v[210:213], v[190:193], v[64:67]
	v_mfma_f32_16x16x32_bf16 v[108:111], v[206:209], v[170:173], v[108:111]
	v_lshl_add_u64 v[222:223], s[24:25], 0, v[130:131]
	s_mov_b32 m0, s31
	s_waitcnt lgkmcnt(0)
	v_mfma_f32_16x16x32_bf16 v[104:107], v[214:217], v[170:173], v[104:107]
	v_lshl_add_u64 v[220:221], s[24:25], 0, v[134:135]
	v_mfma_f32_16x16x32_bf16 v[92:95], v[206:209], v[178:181], v[92:95]
	v_mfma_f32_16x16x32_bf16 v[88:91], v[214:217], v[178:181], v[88:91]
	v_mfma_f32_16x16x32_bf16 v[76:79], v[206:209], v[186:189], v[76:79]
	v_mfma_f32_16x16x32_bf16 v[72:75], v[214:217], v[186:189], v[72:75]
	v_mfma_f32_16x16x32_bf16 v[68:71], v[206:209], v[198:201], v[68:71]
	v_mfma_f32_16x16x32_bf16 v[64:67], v[214:217], v[198:201], v[64:67]
	s_barrier
	s_setprio 0
	ds_read_b128 v[166:169], v148 offset:16384
	ds_read_b128 v[170:173], v148 offset:17408
	ds_read_b128 v[174:177], v148 offset:18432
	ds_read_b128 v[178:181], v148 offset:19456
	ds_read_b128 v[182:185], v148 offset:20480
	ds_read_b128 v[186:189], v148 offset:21504
	ds_read_b128 v[190:193], v148 offset:22528
	ds_read_b128 v[198:201], v148 offset:23552
	global_load_lds_dwordx4 v[220:221], off
	s_mov_b32 m0, s11
	s_setprio 1
	global_load_lds_dwordx4 v[222:223], off
	s_waitcnt vmcnt(10)
	s_barrier
	s_waitcnt lgkmcnt(7)
	v_mfma_f32_16x16x32_bf16 v[60:63], v[150:153], v[166:169], v[60:63]
	v_mfma_f32_16x16x32_bf16 v[56:59], v[158:161], v[166:169], v[56:59]
	s_waitcnt lgkmcnt(5)
	v_mfma_f32_16x16x32_bf16 v[52:55], v[150:153], v[174:177], v[52:55]
	v_mfma_f32_16x16x32_bf16 v[48:51], v[158:161], v[174:177], v[48:51]
	s_waitcnt lgkmcnt(3)
	v_mfma_f32_16x16x32_bf16 v[36:39], v[150:153], v[182:185], v[36:39]
	v_mfma_f32_16x16x32_bf16 v[32:35], v[158:161], v[182:185], v[32:35]
	s_waitcnt lgkmcnt(1)
	v_mfma_f32_16x16x32_bf16 v[20:23], v[150:153], v[190:193], v[20:23]
	v_mfma_f32_16x16x32_bf16 v[16:19], v[158:161], v[190:193], v[16:19]
	v_mfma_f32_16x16x32_bf16 v[60:63], v[154:157], v[170:173], v[60:63]
	s_add_u32 s54, s22, 0x80000
	s_addc_u32 s55, s23, 0
	v_mfma_f32_16x16x32_bf16 v[56:59], v[162:165], v[170:173], v[56:59]
	s_add_i32 s56, s45, s29
	v_mfma_f32_16x16x32_bf16 v[52:55], v[154:157], v[178:181], v[52:55]
	v_mfma_f32_16x16x32_bf16 v[48:51], v[162:165], v[178:181], v[48:51]
	v_mfma_f32_16x16x32_bf16 v[36:39], v[154:157], v[186:189], v[36:39]
	v_mfma_f32_16x16x32_bf16 v[32:35], v[162:165], v[186:189], v[32:35]
	s_waitcnt lgkmcnt(0)
	v_mfma_f32_16x16x32_bf16 v[20:23], v[154:157], v[198:201], v[20:23]
	v_mfma_f32_16x16x32_bf16 v[16:19], v[162:165], v[198:201], v[16:19]
	s_barrier
; #define PG8_STAGE(bufoff, gbase, voff) do { _Pragma("unroll") for (int _i = 0; _i < 2; ++_i) \
;         __builtin_amdgcn_global_load_lds((const unsigned*)((const char*)(gbase) + (voff)[_i]), (LAS unsigned*)(lds + (bufoff) + ldsw + _i * 8192), 16, 0, 0); } while (0)
; #define PG8_LDA(dst, b, h) do { _Pragma("unroll") for (int m = 0; m < 4; ++m) _Pragma("unroll") for (int k = 0; k < 2; ++k) dst[m][k] = *(const LAS bf16x8*)(lds + PG8_SA(b, h) + aoff + m * 2048 + k * 1024); } while (0)
; #define PG8_LDB(dst, b, h) do { _Pragma("unroll") for (int n = 0; n < 2; ++n) _Pragma("unroll") for (int k = 0; k < 2; ++k) dst[n][k] = *(const LAS bf16x8*)(lds + PG8_SB(b, h) + boff + n * 2048 + k * 1024); } while (0)
; #define PG8_MMA(ai, bj, At, Bt) do { __builtin_amdgcn_s_setprio(1); _Pragma("unroll") for (int m = 0; m < 4; ++m) _Pragma("unroll") for (int n = 0; n < 2; ++n) _Pragma("unroll") for (int k = 0; k < 2; ++k) \
;         acc[ai][bj][m][n] = __builtin_amdgcn_mfma_f32_16x16x32_bf16(Bt[n][k], At[m][k], acc[ai][bj][m][n], 0, 0, 0); __builtin_amdgcn_s_setprio(0); } while (0)
; #define PG8_WAIT_V(n) asm volatile("s_waitcnt vmcnt(" #n ")" ::: "memory")
; #define PG8_WAIT_L(n) asm volatile("s_waitcnt lgkmcnt(" #n ")" ::: "memory")
; #define PG8_BAR __builtin_amdgcn_s_barrier()
; #define PG8_SCHED __builtin_amdgcn_sched_barrier(0)
; template <class Map, class Epi>
; DI void gemm_phase(LAS unsigned char* lds, const Map& MP, const Epi& E, const int nM, const int nN, const int K, const int lda, const int ldb) {
;     ...
;             PG8_STAGE(PG8_SB(0, 1), b2 + hstepB, voffB);
;             PG8_WAIT_V(6); PG8_BAR; PG8_MMA(1, 1, At, B1); PG8_BAR;
;             PG8_LDB(B0, 1, 0); PG8_SCHED; PG8_LDA(At, 1, 0); PG8_STAGE(PG8_SA(0, 1), a2 + hstepA, voffA);
;             PG8_WAIT_L(8); PG8_BAR; PG8_WAIT_L(0); PG8_MMA(0, 0, At, B0); PG8_BAR; PG8_SCHED;
;             PG8_LDB(B1, 1, 1); PG8_STAGE(PG8_SB(1, 0), b3, voffB);
;             PG8_BAR; PG8_WAIT_L(0); PG8_MMA(0, 1, At, B1); PG8_BAR;
;             PG8_LDA(At, 1, 1); PG8_STAGE(PG8_SA(1, 0), a3, voffA);
	s_setprio 0
	s_mov_b32 m0, s56
	s_nop 0
	global_load_lds_dwordx4 v132, s[54:55]
	s_add_i32 m0, s56, 0x2000
	s_setprio 1
	global_load_lds_dwordx4 v128, s[54:55]
	s_waitcnt vmcnt(6)
	s_barrier
	v_mfma_f32_16x16x32_bf16 v[44:47], v[202:205], v[166:169], v[44:47]
	v_mfma_f32_16x16x32_bf16 v[40:43], v[210:213], v[166:169], v[40:43]
	s_add_i32 s54, 0, 0x18000
	v_add_u32_e32 v162, s54, v146
	ds_read_b128 v[150:153], v162
	v_mfma_f32_16x16x32_bf16 v[28:31], v[202:205], v[174:177], v[28:31]
	v_mfma_f32_16x16x32_bf16 v[24:27], v[210:213], v[174:177], v[24:27]
	ds_read_b128 v[154:157], v162 offset:1024
	v_mfma_f32_16x16x32_bf16 v[12:15], v[202:205], v[182:185], v[12:15]
	v_mfma_f32_16x16x32_bf16 v[8:11], v[210:213], v[182:185], v[8:11]
	ds_read_b128 v[158:161], v162 offset:2048
	v_mfma_f32_16x16x32_bf16 v[4:7], v[202:205], v[190:193], v[4:7]
	v_mfma_f32_16x16x32_bf16 v[0:3], v[210:213], v[190:193], v[0:3]
	ds_read_b128 v[162:165], v162 offset:3072
	v_mfma_f32_16x16x32_bf16 v[44:47], v[206:209], v[170:173], v[44:47]
	s_add_u32 s24, s24, 0x80000
	s_addc_u32 s25, s25, 0
	v_mfma_f32_16x16x32_bf16 v[40:43], v[214:217], v[170:173], v[40:43]
	v_mfma_f32_16x16x32_bf16 v[28:31], v[206:209], v[178:181], v[28:31]
	v_mfma_f32_16x16x32_bf16 v[24:27], v[214:217], v[178:181], v[24:27]
	v_mfma_f32_16x16x32_bf16 v[12:15], v[206:209], v[186:189], v[12:15]
	v_mfma_f32_16x16x32_bf16 v[8:11], v[214:217], v[186:189], v[8:11]
	v_mfma_f32_16x16x32_bf16 v[4:7], v[206:209], v[198:201], v[4:7]
	v_mfma_f32_16x16x32_bf16 v[0:3], v[214:217], v[198:201], v[0:3]
	s_barrier
	s_setprio 0
	s_mov_b32 m0, s34
	ds_read_b128 v[166:169], v148 offset:32768
	ds_read_b128 v[170:173], v148 offset:33792
	ds_read_b128 v[174:177], v148 offset:34816
	ds_read_b128 v[178:181], v148 offset:35840
	ds_read_b128 v[182:185], v148 offset:36864
	ds_read_b128 v[186:189], v148 offset:37888
	ds_read_b128 v[190:193], v148 offset:38912
	ds_read_b128 v[198:201], v148 offset:39936
	global_load_lds_dwordx4 v134, s[24:25]
	s_mov_b32 m0, s35
	s_setprio 1
	global_load_lds_dwordx4 v130, s[24:25]
	s_waitcnt lgkmcnt(8)
	s_barrier
	s_waitcnt lgkmcnt(7)
	v_mfma_f32_16x16x32_bf16 v[124:127], v[150:153], v[166:169], v[124:127]
	v_mfma_f32_16x16x32_bf16 v[120:123], v[158:161], v[166:169], v[120:123]
	s_waitcnt lgkmcnt(5)
	v_mfma_f32_16x16x32_bf16 v[116:119], v[150:153], v[174:177], v[116:119]
	v_mfma_f32_16x16x32_bf16 v[112:115], v[158:161], v[174:177], v[112:115]
	s_waitcnt lgkmcnt(3)
	v_mfma_f32_16x16x32_bf16 v[100:103], v[150:153], v[182:185], v[100:103]
	v_mfma_f32_16x16x32_bf16 v[96:99], v[158:161], v[182:185], v[96:99]
	s_waitcnt lgkmcnt(1)
	v_mfma_f32_16x16x32_bf16 v[84:87], v[150:153], v[190:193], v[84:87]
	v_mfma_f32_16x16x32_bf16 v[80:83], v[158:161], v[190:193], v[80:83]
	v_mfma_f32_16x16x32_bf16 v[124:127], v[154:157], v[170:173], v[124:127]
	s_add_i32 s24, 0, 0x1c000
	v_mfma_f32_16x16x32_bf16 v[120:123], v[162:165], v[170:173], v[120:123]
	s_add_i32 s25, s54, s29
	v_mfma_f32_16x16x32_bf16 v[116:119], v[154:157], v[178:181], v[116:119]
	v_add_u32_e32 v196, s24, v146
	v_mfma_f32_16x16x32_bf16 v[112:115], v[162:165], v[178:181], v[112:115]
	v_lshl_add_u64 v[194:195], v[194:195], 0, s[8:9]
	v_mfma_f32_16x16x32_bf16 v[100:103], v[154:157], v[186:189], v[100:103]
	v_mfma_f32_16x16x32_bf16 v[96:99], v[162:165], v[186:189], v[96:99]
	s_waitcnt lgkmcnt(0)
	v_mfma_f32_16x16x32_bf16 v[84:87], v[154:157], v[198:201], v[84:87]
	v_mfma_f32_16x16x32_bf16 v[80:83], v[162:165], v[198:201], v[80:83]
	s_barrier
	s_setprio 0
	s_mov_b32 m0, s25
	ds_read_b128 v[202:205], v196
	ds_read_b128 v[206:209], v196 offset:1024
	ds_read_b128 v[210:213], v196 offset:2048
	ds_read_b128 v[214:217], v196 offset:3072
	global_load_lds_dwordx4 v[194:195], off
	v_lshl_add_u64 v[194:195], v[218:219], 0, s[8:9]
	s_add_i32 m0, s25, 0x2000
	s_setprio 1
	global_load_lds_dwordx4 v[194:195], off
	s_barrier
	s_waitcnt lgkmcnt(3)
	v_mfma_f32_16x16x32_bf16 v[108:111], v[202:205], v[166:169], v[108:111]
	s_waitcnt lgkmcnt(1)
	v_mfma_f32_16x16x32_bf16 v[104:107], v[210:213], v[166:169], v[104:107]
	v_mfma_f32_16x16x32_bf16 v[92:95], v[202:205], v[174:177], v[92:95]
	v_mfma_f32_16x16x32_bf16 v[88:91], v[210:213], v[174:177], v[88:91]
	v_mfma_f32_16x16x32_bf16 v[76:79], v[202:205], v[182:185], v[76:79]
	v_mfma_f32_16x16x32_bf16 v[72:75], v[210:213], v[182:185], v[72:75]
	v_mfma_f32_16x16x32_bf16 v[68:71], v[202:205], v[190:193], v[68:71]
	v_mfma_f32_16x16x32_bf16 v[64:67], v[210:213], v[190:193], v[64:67]
	v_mfma_f32_16x16x32_bf16 v[108:111], v[206:209], v[170:173], v[108:111]
	s_mov_b32 m0, s39
	s_waitcnt lgkmcnt(0)
	v_mfma_f32_16x16x32_bf16 v[104:107], v[214:217], v[170:173], v[104:107]
	v_lshl_add_u64 v[194:195], v[220:221], 0, s[8:9]
	v_mfma_f32_16x16x32_bf16 v[92:95], v[206:209], v[178:181], v[92:95]
	v_mfma_f32_16x16x32_bf16 v[88:91], v[214:217], v[178:181], v[88:91]
	v_mfma_f32_16x16x32_bf16 v[76:79], v[206:209], v[186:189], v[76:79]
	v_mfma_f32_16x16x32_bf16 v[72:75], v[214:217], v[186:189], v[72:75]
	v_mfma_f32_16x16x32_bf16 v[68:71], v[206:209], v[198:201], v[68:71]
	v_mfma_f32_16x16x32_bf16 v[64:67], v[214:217], v[198:201], v[64:67]
	s_barrier
	s_setprio 0
	ds_read_b128 v[166:169], v148 offset:49152
	ds_read_b128 v[170:173], v148 offset:50176
	ds_read_b128 v[174:177], v148 offset:51200
	ds_read_b128 v[178:181], v148 offset:52224
	ds_read_b128 v[182:185], v148 offset:53248
	ds_read_b128 v[186:189], v148 offset:54272
	ds_read_b128 v[190:193], v148 offset:55296
	ds_read_b128 v[198:201], v148 offset:56320
	global_load_lds_dwordx4 v[194:195], off
	v_lshl_add_u64 v[194:195], v[222:223], 0, s[8:9]
	s_mov_b32 m0, s42
	s_setprio 1
	global_load_lds_dwordx4 v[194:195], off
	s_waitcnt vmcnt(10)
	s_barrier
; #define PG8_STAGE(bufoff, gbase, voff) do { _Pragma("unroll") for (int _i = 0; _i < 2; ++_i) \
;         __builtin_amdgcn_global_load_lds((const unsigned*)((const char*)(gbase) + (voff)[_i]), (LAS unsigned*)(lds + (bufoff) + ldsw + _i * 8192), 16, 0, 0); } while (0)
; #define PG8_LDA(dst, b, h) do { _Pragma("unroll") for (int m = 0; m < 4; ++m) _Pragma("unroll") for (int k = 0; k < 2; ++k) dst[m][k] = *(const LAS bf16x8*)(lds + PG8_SA(b, h) + aoff + m * 2048 + k * 1024); } while (0)
; #define PG8_MMA(ai, bj, At, Bt) do { __builtin_amdgcn_s_setprio(1); _Pragma("unroll") for (int m = 0; m < 4; ++m) _Pragma("unroll") for (int n = 0; n < 2; ++n) _Pragma("unroll") for (int k = 0; k < 2; ++k) \
;         acc[ai][bj][m][n] = __builtin_amdgcn_mfma_f32_16x16x32_bf16(Bt[n][k], At[m][k], acc[ai][bj][m][n], 0, 0, 0); __builtin_amdgcn_s_setprio(0); } while (0)
; #define PG8_WAIT_V(n) asm volatile("s_waitcnt vmcnt(" #n ")" ::: "memory")
; #define PG8_WAIT_L(n) asm volatile("s_waitcnt lgkmcnt(" #n ")" ::: "memory")
; #define PG8_BAR __builtin_amdgcn_s_barrier()
; #define PG8_SCHED __builtin_amdgcn_sched_barrier(0)
; template <class Map, class Epi>
; DI void gemm_phase(LAS unsigned char* lds, const Map& MP, const Epi& E, const int nM, const int nN, const int K, const int lda, const int ldb) {
;     ...
;             PG8_LDA(At, 1, 1); PG8_STAGE(PG8_SA(1, 0), a3, voffA);
;             PG8_BAR; PG8_WAIT_L(0); PG8_MMA(1, 0, At, B0); PG8_BAR; PG8_SCHED;
;             PG8_STAGE(PG8_SB(1, 1), b3 + hstepB, voffB);
;             PG8_WAIT_V(6); PG8_BAR; PG8_MMA(1, 1, At, B1); PG8_BAR;
;         }
	s_waitcnt lgkmcnt(7)
	v_mfma_f32_16x16x32_bf16 v[60:63], v[150:153], v[166:169], v[60:63]
	v_mfma_f32_16x16x32_bf16 v[56:59], v[158:161], v[166:169], v[56:59]
	s_waitcnt lgkmcnt(5)
	v_mfma_f32_16x16x32_bf16 v[52:55], v[150:153], v[174:177], v[52:55]
	v_mfma_f32_16x16x32_bf16 v[48:51], v[158:161], v[174:177], v[48:51]
	s_waitcnt lgkmcnt(3)
	v_mfma_f32_16x16x32_bf16 v[36:39], v[150:153], v[182:185], v[36:39]
	v_mfma_f32_16x16x32_bf16 v[32:35], v[158:161], v[182:185], v[32:35]
	s_waitcnt lgkmcnt(1)
	v_mfma_f32_16x16x32_bf16 v[20:23], v[150:153], v[190:193], v[20:23]
	v_mfma_f32_16x16x32_bf16 v[16:19], v[158:161], v[190:193], v[16:19]
	v_mfma_f32_16x16x32_bf16 v[60:63], v[154:157], v[170:173], v[60:63]
	s_add_u32 s22, s22, 0x80080
	s_addc_u32 s23, s23, 0
	v_mfma_f32_16x16x32_bf16 v[56:59], v[162:165], v[170:173], v[56:59]
	s_add_i32 s24, s24, s29
	v_mfma_f32_16x16x32_bf16 v[52:55], v[154:157], v[178:181], v[52:55]
	v_mfma_f32_16x16x32_bf16 v[48:51], v[162:165], v[178:181], v[48:51]
	v_mfma_f32_16x16x32_bf16 v[36:39], v[154:157], v[186:189], v[36:39]
	v_mfma_f32_16x16x32_bf16 v[32:35], v[162:165], v[186:189], v[32:35]
	s_waitcnt lgkmcnt(0)
	v_mfma_f32_16x16x32_bf16 v[20:23], v[154:157], v[198:201], v[20:23]
	v_mfma_f32_16x16x32_bf16 v[16:19], v[162:165], v[198:201], v[16:19]
	s_barrier
	s_setprio 0
	s_mov_b32 m0, s24
	s_nop 0
	global_load_lds_dwordx4 v132, s[22:23]
	s_add_i32 m0, s24, 0x2000
	s_setprio 1
	global_load_lds_dwordx4 v128, s[22:23]
	s_waitcnt vmcnt(6)
	s_barrier
	v_mfma_f32_16x16x32_bf16 v[44:47], v[202:205], v[166:169], v[44:47]
	v_mfma_f32_16x16x32_bf16 v[40:43], v[210:213], v[166:169], v[40:43]
	ds_read_b128 v[150:153], v147
	v_mfma_f32_16x16x32_bf16 v[28:31], v[202:205], v[174:177], v[28:31]
	v_mfma_f32_16x16x32_bf16 v[24:27], v[210:213], v[174:177], v[24:27]
	ds_read_b128 v[154:157], v147 offset:1024
	v_mfma_f32_16x16x32_bf16 v[12:15], v[202:205], v[182:185], v[12:15]
	v_mfma_f32_16x16x32_bf16 v[8:11], v[210:213], v[182:185], v[8:11]
	ds_read_b128 v[158:161], v147 offset:2048
	v_mfma_f32_16x16x32_bf16 v[4:7], v[202:205], v[190:193], v[4:7]
	v_mfma_f32_16x16x32_bf16 v[0:3], v[210:213], v[190:193], v[0:3]
	ds_read_b128 v[162:165], v147 offset:3072
	v_mfma_f32_16x16x32_bf16 v[44:47], v[206:209], v[170:173], v[44:47]
	s_add_i32 s3, s3, 2
	v_mfma_f32_16x16x32_bf16 v[40:43], v[214:217], v[170:173], v[40:43]
	s_add_u32 s52, s52, 0x100
	s_addc_u32 s53, s53, 0
	v_mfma_f32_16x16x32_bf16 v[28:31], v[206:209], v[178:181], v[28:31]
	s_add_u32 s20, s20, 0x100
	s_addc_u32 s21, s21, 0
	v_mfma_f32_16x16x32_bf16 v[24:27], v[214:217], v[178:181], v[24:27]
	s_cmp_gt_u32 s3, 29
	v_mfma_f32_16x16x32_bf16 v[12:15], v[206:209], v[186:189], v[12:15]
	v_mfma_f32_16x16x32_bf16 v[8:11], v[214:217], v[186:189], v[8:11]
	v_mfma_f32_16x16x32_bf16 v[4:7], v[206:209], v[198:201], v[4:7]
	v_mfma_f32_16x16x32_bf16 v[0:3], v[214:217], v[198:201], v[0:3]
	s_barrier
	s_setprio 0
	s_cbranch_scc0 .LBB1_1382
; DI unsigned pack2(float a, float b) { f32x2 v = {a, b}; hwbf16x2 r = __builtin_convertvector(v, hwbf16x2); return __builtin_bit_cast(unsigned, r); }
;     DI const char* a(const Unit& u) const { return (const char*)(A + (size_t)u.pm * BM * lda); }
;     DI const char* a(const Unit& u) const { return (const char*)(A + (size_t)u.pm * BM * 2048 + (u.pn >> 1) * 512); }
;     DI const char* a(const Unit& u) const { return (const char*)((u.pn < 12 ? A1 : A2) + (size_t)u.pm * BM * 512); }
; #define PG8_WAIT_V(n) asm volatile("s_waitcnt vmcnt(" #n ")" ::: "memory")
; #define PG8_BAR __builtin_amdgcn_s_barrier()
;     DI void operator()(const f32x4 (&acc)[2][2][4][2], const Unit& u, int wr, int wc, int fr, int fq) const {
;         bf16_t* O = O1; int ldc = ldc1, pn = u.pn; if (pn >= split) { O = O2; ldc = ldc2; pn -= split; }
;         const int row0 = u.pm * BM + wr * 64 + fr, col0 = pn * BM + wc * 32 + 8 * fq;
; #pragma unroll
;         for (int ai = 0; ai < 2; ++ai)
; #pragma unroll
;             for (int m = 0; m < 4; ++m) { bf16_t* rowp = O + (size_t)(row0 + ai * HALF + m * 16) * ldc + col0;
; #pragma unroll
;                 for (int bj = 0; bj < 2; ++bj) { const f32x4 v0 = acc[ai][bj][m][0], v1 = acc[ai][bj][m][1];
;                     u32x4 o; o[0] = pack2(v0[0], v0[1]); o[1] = pack2(v0[2], v0[3]); o[2] = pack2(v1[0], v1[1]); o[3] = pack2(v1[2], v1[3]);
;                     *(u32x4*)(rowp + bj * HALF) = o; } }
; template <class Map, class Epi>
; DI void gemm_phase(LAS unsigned char* lds, const Map& MP, const Epi& E, const int nM, const int nN, const int K, const int lda, const int ldb) {
;     ...
;         { int frr = fr, fqq = fq; asm volatile("" : "+v"(frr), "+v"(fqq)); E(acc, cur, wr, wc, frr, fqq); }
;         if (!has_next) break;
; #pragma unroll
;         for (int a = 0; a < 2; ++a)
; #pragma unroll
;             for (int b = 0; b < 2; ++b)
; #pragma unroll
;                 for (int m = 0; m < 4; ++m)
; #pragma unroll
;                     for (int n = 0; n < 2; ++n) acc[a][b][m][n] = (f32x4){0.f, 0.f, 0.f, 0.f};
;         cur = nxt; cA = nA; cB = nB; ++ui;
;     }
;     PG8_WAIT_V(0);
;     if (wr == 0) PG8_BAR;
	s_waitcnt lgkmcnt(0)
	s_lshl_b32 s3, s10, 8
	v_mov_b32_e32 v150, v144
	v_mov_b32_e32 v151, v145
	s_add_i32 s3, s3, s37
	v_cvt_pk_bf16_f32 v68, v68, v69
	v_add_u32_e32 v154, s3, v150
	s_lshl_b32 s3, s47, 8
	s_or_b32 s3, s3, s38
	v_lshl_add_u32 v150, v151, 3, s3
	v_ashrrev_i32_e32 v151, 31, v150
	v_lshl_add_u64 v[150:151], v[150:151], 1, s[6:7]
	v_cvt_pk_bf16_f32 v69, v70, v71
	v_cvt_pk_bf16_f32 v70, v64, v65
	v_add_u32_e32 v64, 0x80, v154
	v_mad_i64_i32 v[152:153], s[20:21], v154, s46, v[150:151]
	v_cvt_pk_bf16_f32 v108, v108, v109
	v_cvt_pk_bf16_f32 v109, v110, v111
	v_cvt_pk_bf16_f32 v110, v104, v105
	v_cvt_pk_bf16_f32 v111, v106, v107
	v_add_u32_e32 v104, 16, v154
	v_mad_i64_i32 v[64:65], s[20:21], v64, s46, v[150:151]
	v_cvt_pk_bf16_f32 v44, v44, v45
	v_cvt_pk_bf16_f32 v45, v46, v47
	v_cvt_pk_bf16_f32 v46, v40, v41
	v_cvt_pk_bf16_f32 v47, v42, v43
	v_add_u32_e32 v40, 0x90, v154
	global_store_dwordx4 v[152:153], v[108:111], off offset:256
	v_cvt_pk_bf16_f32 v92, v92, v93
	v_cvt_pk_bf16_f32 v93, v94, v95
	v_mad_i64_i32 v[108:109], s[20:21], v104, s46, v[150:151]
	v_cvt_pk_bf16_f32 v94, v88, v89
	v_cvt_pk_bf16_f32 v95, v90, v91
	v_add_u32_e32 v88, 32, v154
	global_store_dwordx4 v[64:65], v[44:47], off offset:256
	v_cvt_pk_bf16_f32 v28, v28, v29
	v_cvt_pk_bf16_f32 v29, v30, v31
	v_mad_i64_i32 v[44:45], s[20:21], v40, s46, v[150:151]
	v_cvt_pk_bf16_f32 v30, v24, v25
	v_cvt_pk_bf16_f32 v31, v26, v27
	v_add_u32_e32 v24, 0xa0, v154
	global_store_dwordx4 v[108:109], v[92:95], off offset:256
	v_cvt_pk_bf16_f32 v76, v76, v77
	v_cvt_pk_bf16_f32 v77, v78, v79
	v_mad_i64_i32 v[92:93], s[20:21], v88, s46, v[150:151]
	v_cvt_pk_bf16_f32 v78, v72, v73
	v_cvt_pk_bf16_f32 v79, v74, v75
	v_add_u32_e32 v72, 48, v154
	global_store_dwordx4 v[44:45], v[28:31], off offset:256
	v_cvt_pk_bf16_f32 v12, v12, v13
	v_cvt_pk_bf16_f32 v13, v14, v15
	v_mad_i64_i32 v[28:29], s[20:21], v24, s46, v[150:151]
	v_cvt_pk_bf16_f32 v14, v8, v9
	v_cvt_pk_bf16_f32 v15, v10, v11
	v_add_u32_e32 v8, 0xb0, v154
	global_store_dwordx4 v[92:93], v[76:79], off offset:256
	global_store_dwordx4 v[28:29], v[12:15], off offset:256
	v_cvt_pk_bf16_f32 v124, v124, v125
	v_mad_i64_i32 v[76:77], s[20:21], v72, s46, v[150:151]
	v_mad_i64_i32 v[12:13], s[20:21], v8, s46, v[150:151]
	v_cvt_pk_bf16_f32 v125, v126, v127
	v_cvt_pk_bf16_f32 v126, v120, v121
	v_cvt_pk_bf16_f32 v127, v122, v123
	v_cvt_pk_bf16_f32 v104, v116, v117
	v_cvt_pk_bf16_f32 v105, v118, v119
	v_cvt_pk_bf16_f32 v106, v112, v113
	v_cvt_pk_bf16_f32 v107, v114, v115
	v_cvt_pk_bf16_f32 v88, v100, v101
	v_cvt_pk_bf16_f32 v89, v102, v103
	v_cvt_pk_bf16_f32 v90, v96, v97
	v_cvt_pk_bf16_f32 v91, v98, v99
	v_cvt_pk_bf16_f32 v72, v84, v85
	v_cvt_pk_bf16_f32 v73, v86, v87
	v_cvt_pk_bf16_f32 v74, v80, v81
	v_cvt_pk_bf16_f32 v75, v82, v83
	v_cvt_pk_bf16_f32 v71, v66, v67
	v_cvt_pk_bf16_f32 v60, v60, v61
	v_cvt_pk_bf16_f32 v61, v62, v63
	v_cvt_pk_bf16_f32 v62, v56, v57
	v_cvt_pk_bf16_f32 v63, v58, v59
	v_cvt_pk_bf16_f32 v40, v52, v53
	v_cvt_pk_bf16_f32 v41, v54, v55
	v_cvt_pk_bf16_f32 v42, v48, v49
	v_cvt_pk_bf16_f32 v43, v50, v51
	v_cvt_pk_bf16_f32 v24, v36, v37
	v_cvt_pk_bf16_f32 v25, v38, v39
	v_cvt_pk_bf16_f32 v26, v32, v33
	v_cvt_pk_bf16_f32 v27, v34, v35
	v_cvt_pk_bf16_f32 v8, v20, v21
	v_cvt_pk_bf16_f32 v9, v22, v23
	v_cvt_pk_bf16_f32 v10, v16, v17
	v_cvt_pk_bf16_f32 v11, v18, v19
	v_cvt_pk_bf16_f32 v4, v4, v5
	v_cvt_pk_bf16_f32 v5, v6, v7
	v_cvt_pk_bf16_f32 v6, v0, v1
	v_cvt_pk_bf16_f32 v7, v2, v3
	s_and_b64 vcc, exec, s[40:41]
	s_mov_b32 s47, s12
	s_mov_b32 s10, s14
	s_mov_b64 s[20:21], s[18:19]
	s_mov_b64 s[22:23], s[16:17]
	global_store_dwordx4 v[152:153], v[124:127], off
	global_store_dwordx4 v[108:109], v[104:107], off
	global_store_dwordx4 v[92:93], v[88:91], off
	global_store_dwordx4 v[76:77], v[72:75], off
	global_store_dwordx4 v[76:77], v[68:71], off offset:256
	global_store_dwordx4 v[64:65], v[60:63], off
	global_store_dwordx4 v[44:45], v[40:43], off
	global_store_dwordx4 v[28:29], v[24:27], off
	global_store_dwordx4 v[12:13], v[8:11], off
	global_store_dwordx4 v[12:13], v[4:7], off offset:256
	s_cbranch_vccz .LBB1_1379
	s_waitcnt vmcnt(0)
	s_cmpk_gt_u32 s4, 0xff
	s_cbranch_scc1 .LBB1_1386
	s_barrier

; #define PG8_STAGE(bufoff, gbase, voff) do { _Pragma("unroll") for (int _i = 0; _i < 2; ++_i) \
;         __builtin_amdgcn_global_load_lds((const unsigned*)((const char*)(gbase) + (voff)[_i]), (LAS unsigned*)(lds + (bufoff) + ldsw + _i * 8192), 16, 0, 0); } while (0)
; #define PG8_LDA(dst, b, h) do { _Pragma("unroll") for (int m = 0; m < 4; ++m) _Pragma("unroll") for (int k = 0; k < 2; ++k) dst[m][k] = *(const LAS bf16x8*)(lds + PG8_SA(b, h) + aoff + m * 2048 + k * 1024); } while (0)
; #define PG8_LDB(dst, b, h) do { _Pragma("unroll") for (int n = 0; n < 2; ++n) _Pragma("unroll") for (int k = 0; k < 2; ++k) dst[n][k] = *(const LAS bf16x8*)(lds + PG8_SB(b, h) + boff + n * 2048 + k * 1024); } while (0)
; #define PG8_MMA(ai, bj, At, Bt) do { __builtin_amdgcn_s_setprio(1); _Pragma("unroll") for (int m = 0; m < 4; ++m) _Pragma("unroll") for (int n = 0; n < 2; ++n) _Pragma("unroll") for (int k = 0; k < 2; ++k) \
;         acc[ai][bj][m][n] = __builtin_amdgcn_mfma_f32_16x16x32_bf16(Bt[n][k], At[m][k], acc[ai][bj][m][n], 0, 0, 0); __builtin_amdgcn_s_setprio(0); } while (0)
; #define PG8_WAIT_L(n) asm volatile("s_waitcnt lgkmcnt(" #n ")" ::: "memory")
; #define PG8_BAR __builtin_amdgcn_s_barrier()
; #define PG8_SCHED __builtin_amdgcn_sched_barrier(0)
; template <class Map, class Epi>
; DI void gemm_phase(LAS unsigned char* lds, const Map& MP, const Epi& E, const int nM, const int nN, const int K, const int lda, const int ldb) {
;     ...
;         for (int t = 0; t < nt; t += 2) {
;             const bool last = (t == nt - 2);
;             const char* a1 = cA + (size_t)(t + 1) * kstep;
;             const char* a2 = last ? nA : cA + (size_t)(t + 2) * kstep; const char* b2 = last ? nB : cB + (size_t)(t + 2) * kstep;
;             const char* a3 = a2 + kstep; const char* b3 = b2 + kstep;
;             PG8_LDB(B0, 0, 0); PG8_SCHED; PG8_LDA(At, 0, 0); PG8_STAGE(PG8_SA(1, 1), a1 + hstepA, voffA);
;             PG8_WAIT_L(8); PG8_BAR; PG8_WAIT_L(0); PG8_MMA(0, 0, At, B0); PG8_BAR; PG8_SCHED;
;             PG8_LDB(B1, 0, 1); PG8_STAGE(PG8_SB(0, 0), b2, voffB);
;             PG8_BAR; PG8_WAIT_L(0); PG8_MMA(0, 1, At, B1); PG8_BAR;
;             PG8_LDA(At, 0, 1); PG8_STAGE(PG8_SA(0, 0), a2, voffA);
;             PG8_BAR; PG8_WAIT_L(0); PG8_MMA(1, 0, At, B0); PG8_BAR; PG8_SCHED;
.LBB1_1529:
	s_add_u32 s20, s18, 0xfffe0080
	s_addc_u32 s21, s19, -1
	s_cmp_eq_u32 s3, 4
	s_cselect_b32 s23, s13, s21
	s_cselect_b32 s22, s52, s20
	s_cselect_b32 s21, s53, s56
	s_cselect_b32 s20, s54, s55
	s_add_i32 m0, s11, 0xc000
	ds_read_b128 v[166:169], v148
	ds_read_b128 v[170:173], v148 offset:1024
	ds_read_b128 v[174:177], v148 offset:2048
	ds_read_b128 v[178:181], v148 offset:3072
	ds_read_b128 v[182:185], v148 offset:4096
	ds_read_b128 v[186:189], v148 offset:5120
	ds_read_b128 v[190:193], v148 offset:6144
	ds_read_b128 v[198:201], v148 offset:7168
	global_load_lds_dwordx4 v138, s[18:19]
	s_add_i32 m0, s11, 0xe000
	s_setprio 1
	global_load_lds_dwordx4 v136, s[18:19]
	s_waitcnt lgkmcnt(8)
	s_barrier
	s_waitcnt lgkmcnt(7)
	v_mfma_f32_16x16x32_bf16 v[124:127], v[150:153], v[166:169], v[124:127]
	v_mfma_f32_16x16x32_bf16 v[120:123], v[158:161], v[166:169], v[120:123]
	s_waitcnt lgkmcnt(5)
	v_mfma_f32_16x16x32_bf16 v[116:119], v[150:153], v[174:177], v[116:119]
	v_mfma_f32_16x16x32_bf16 v[112:115], v[158:161], v[174:177], v[112:115]
	s_waitcnt lgkmcnt(3)
	v_mfma_f32_16x16x32_bf16 v[100:103], v[150:153], v[182:185], v[100:103]
	v_mfma_f32_16x16x32_bf16 v[96:99], v[158:161], v[182:185], v[96:99]
	s_waitcnt lgkmcnt(1)
	v_mfma_f32_16x16x32_bf16 v[84:87], v[150:153], v[190:193], v[84:87]
	v_mfma_f32_16x16x32_bf16 v[80:83], v[158:161], v[190:193], v[80:83]
	v_mfma_f32_16x16x32_bf16 v[124:127], v[154:157], v[170:173], v[124:127]
	s_add_i32 s57, s47, s31
	v_mfma_f32_16x16x32_bf16 v[120:123], v[162:165], v[170:173], v[120:123]
	v_lshl_add_u64 v[194:195], s[20:21], 0, v[132:133]
	v_mfma_f32_16x16x32_bf16 v[116:119], v[154:157], v[178:181], v[116:119]
	v_lshl_add_u64 v[218:219], s[20:21], 0, v[128:129]
	v_mfma_f32_16x16x32_bf16 v[112:115], v[162:165], v[178:181], v[112:115]
	v_mfma_f32_16x16x32_bf16 v[100:103], v[154:157], v[186:189], v[100:103]
	v_mfma_f32_16x16x32_bf16 v[96:99], v[162:165], v[186:189], v[96:99]
	s_waitcnt lgkmcnt(0)
	v_mfma_f32_16x16x32_bf16 v[84:87], v[154:157], v[198:201], v[84:87]
	v_mfma_f32_16x16x32_bf16 v[80:83], v[162:165], v[198:201], v[80:83]
	s_barrier
	s_setprio 0
	s_mov_b32 m0, s57
	ds_read_b128 v[202:205], v149
	ds_read_b128 v[206:209], v149 offset:1024
	ds_read_b128 v[210:213], v149 offset:2048
	ds_read_b128 v[214:217], v149 offset:3072
	global_load_lds_dwordx4 v[194:195], off
	s_add_i32 m0, s57, 0x2000
	s_setprio 1
	global_load_lds_dwordx4 v[218:219], off
	s_barrier
	s_waitcnt lgkmcnt(3)
	v_mfma_f32_16x16x32_bf16 v[108:111], v[202:205], v[166:169], v[108:111]
	s_waitcnt lgkmcnt(1)
	v_mfma_f32_16x16x32_bf16 v[104:107], v[210:213], v[166:169], v[104:107]
	v_mfma_f32_16x16x32_bf16 v[92:95], v[202:205], v[174:177], v[92:95]
	v_mfma_f32_16x16x32_bf16 v[88:91], v[210:213], v[174:177], v[88:91]
	v_mfma_f32_16x16x32_bf16 v[76:79], v[202:205], v[182:185], v[76:79]
	v_mfma_f32_16x16x32_bf16 v[72:75], v[210:213], v[182:185], v[72:75]
	v_mfma_f32_16x16x32_bf16 v[68:71], v[202:205], v[190:193], v[68:71]
	v_mfma_f32_16x16x32_bf16 v[64:67], v[210:213], v[190:193], v[64:67]
	v_mfma_f32_16x16x32_bf16 v[108:111], v[206:209], v[170:173], v[108:111]
	v_lshl_add_u64 v[222:223], s[22:23], 0, v[130:131]
	s_mov_b32 m0, s11
	s_waitcnt lgkmcnt(0)
	v_mfma_f32_16x16x32_bf16 v[104:107], v[214:217], v[170:173], v[104:107]
	v_lshl_add_u64 v[220:221], s[22:23], 0, v[134:135]
	v_mfma_f32_16x16x32_bf16 v[92:95], v[206:209], v[178:181], v[92:95]
	v_mfma_f32_16x16x32_bf16 v[88:91], v[214:217], v[178:181], v[88:91]
	v_mfma_f32_16x16x32_bf16 v[76:79], v[206:209], v[186:189], v[76:79]
	v_mfma_f32_16x16x32_bf16 v[72:75], v[214:217], v[186:189], v[72:75]
	v_mfma_f32_16x16x32_bf16 v[68:71], v[206:209], v[198:201], v[68:71]
	v_mfma_f32_16x16x32_bf16 v[64:67], v[214:217], v[198:201], v[64:67]
	s_barrier
	s_setprio 0
	ds_read_b128 v[166:169], v148 offset:16384
	ds_read_b128 v[170:173], v148 offset:17408
	ds_read_b128 v[174:177], v148 offset:18432
	ds_read_b128 v[178:181], v148 offset:19456
	ds_read_b128 v[182:185], v148 offset:20480
	ds_read_b128 v[186:189], v148 offset:21504
	ds_read_b128 v[190:193], v148 offset:22528
	ds_read_b128 v[198:201], v148 offset:23552
	global_load_lds_dwordx4 v[220:221], off
	s_mov_b32 m0, s35
	s_setprio 1
	global_load_lds_dwordx4 v[222:223], off
	s_waitcnt vmcnt(10)
	s_barrier
	s_waitcnt lgkmcnt(7)
	v_mfma_f32_16x16x32_bf16 v[60:63], v[150:153], v[166:169], v[60:63]
	v_mfma_f32_16x16x32_bf16 v[56:59], v[158:161], v[166:169], v[56:59]
	s_waitcnt lgkmcnt(5)
	v_mfma_f32_16x16x32_bf16 v[52:55], v[150:153], v[174:177], v[52:55]
	v_mfma_f32_16x16x32_bf16 v[48:51], v[158:161], v[174:177], v[48:51]
	s_waitcnt lgkmcnt(3)
	v_mfma_f32_16x16x32_bf16 v[36:39], v[150:153], v[182:185], v[36:39]
	v_mfma_f32_16x16x32_bf16 v[32:35], v[158:161], v[182:185], v[32:35]
	s_waitcnt lgkmcnt(1)
	v_mfma_f32_16x16x32_bf16 v[20:23], v[150:153], v[190:193], v[20:23]
	v_mfma_f32_16x16x32_bf16 v[16:19], v[158:161], v[190:193], v[16:19]
	v_mfma_f32_16x16x32_bf16 v[60:63], v[154:157], v[170:173], v[60:63]
	s_add_u32 s58, s20, 0x20000
	s_addc_u32 s59, s21, 0
	v_mfma_f32_16x16x32_bf16 v[56:59], v[162:165], v[170:173], v[56:59]
	s_add_i32 s57, s48, s31
	v_mfma_f32_16x16x32_bf16 v[52:55], v[154:157], v[178:181], v[52:55]
	v_mfma_f32_16x16x32_bf16 v[48:51], v[162:165], v[178:181], v[48:51]
	v_mfma_f32_16x16x32_bf16 v[36:39], v[154:157], v[186:189], v[36:39]
	v_mfma_f32_16x16x32_bf16 v[32:35], v[162:165], v[186:189], v[32:35]
	s_waitcnt lgkmcnt(0)
	v_mfma_f32_16x16x32_bf16 v[20:23], v[154:157], v[198:201], v[20:23]
	v_mfma_f32_16x16x32_bf16 v[16:19], v[162:165], v[198:201], v[16:19]
	s_barrier
; #define PG8_STAGE(bufoff, gbase, voff) do { _Pragma("unroll") for (int _i = 0; _i < 2; ++_i) \
;         __builtin_amdgcn_global_load_lds((const unsigned*)((const char*)(gbase) + (voff)[_i]), (LAS unsigned*)(lds + (bufoff) + ldsw + _i * 8192), 16, 0, 0); } while (0)
; #define PG8_LDA(dst, b, h) do { _Pragma("unroll") for (int m = 0; m < 4; ++m) _Pragma("unroll") for (int k = 0; k < 2; ++k) dst[m][k] = *(const LAS bf16x8*)(lds + PG8_SA(b, h) + aoff + m * 2048 + k * 1024); } while (0)
; #define PG8_LDB(dst, b, h) do { _Pragma("unroll") for (int n = 0; n < 2; ++n) _Pragma("unroll") for (int k = 0; k < 2; ++k) dst[n][k] = *(const LAS bf16x8*)(lds + PG8_SB(b, h) + boff + n * 2048 + k * 1024); } while (0)
; #define PG8_MMA(ai, bj, At, Bt) do { __builtin_amdgcn_s_setprio(1); _Pragma("unroll") for (int m = 0; m < 4; ++m) _Pragma("unroll") for (int n = 0; n < 2; ++n) _Pragma("unroll") for (int k = 0; k < 2; ++k) \
;         acc[ai][bj][m][n] = __builtin_amdgcn_mfma_f32_16x16x32_bf16(Bt[n][k], At[m][k], acc[ai][bj][m][n], 0, 0, 0); __builtin_amdgcn_s_setprio(0); } while (0)
; #define PG8_WAIT_V(n) asm volatile("s_waitcnt vmcnt(" #n ")" ::: "memory")
; #define PG8_WAIT_L(n) asm volatile("s_waitcnt lgkmcnt(" #n ")" ::: "memory")
; #define PG8_BAR __builtin_amdgcn_s_barrier()
; #define PG8_SCHED __builtin_amdgcn_sched_barrier(0)
; template <class Map, class Epi>
; DI void gemm_phase(LAS unsigned char* lds, const Map& MP, const Epi& E, const int nM, const int nN, const int K, const int lda, const int ldb) {
;     ...
;             PG8_STAGE(PG8_SB(0, 1), b2 + hstepB, voffB);
;             PG8_WAIT_V(6); PG8_BAR; PG8_MMA(1, 1, At, B1); PG8_BAR;
;             PG8_LDB(B0, 1, 0); PG8_SCHED; PG8_LDA(At, 1, 0); PG8_STAGE(PG8_SA(0, 1), a2 + hstepA, voffA);
;             PG8_WAIT_L(8); PG8_BAR; PG8_WAIT_L(0); PG8_MMA(0, 0, At, B0); PG8_BAR; PG8_SCHED;
;             PG8_LDB(B1, 1, 1); PG8_STAGE(PG8_SB(1, 0), b3, voffB);
;             PG8_BAR; PG8_WAIT_L(0); PG8_MMA(0, 1, At, B1); PG8_BAR;
;             PG8_LDA(At, 1, 1); PG8_STAGE(PG8_SA(1, 0), a3, voffA);
	s_setprio 0
	s_mov_b32 m0, s57
	s_nop 0
	global_load_lds_dwordx4 v132, s[58:59]
	s_add_i32 m0, s57, 0x2000
	s_setprio 1
	global_load_lds_dwordx4 v128, s[58:59]
	s_waitcnt vmcnt(6)
	s_barrier
	v_mfma_f32_16x16x32_bf16 v[44:47], v[202:205], v[166:169], v[44:47]
	v_mfma_f32_16x16x32_bf16 v[40:43], v[210:213], v[166:169], v[40:43]
	s_add_i32 s57, 0, 0x18000
	v_add_u32_e32 v162, s57, v146
	ds_read_b128 v[150:153], v162
	v_mfma_f32_16x16x32_bf16 v[28:31], v[202:205], v[174:177], v[28:31]
	v_mfma_f32_16x16x32_bf16 v[24:27], v[210:213], v[174:177], v[24:27]
	ds_read_b128 v[154:157], v162 offset:1024
	v_mfma_f32_16x16x32_bf16 v[12:15], v[202:205], v[182:185], v[12:15]
	v_mfma_f32_16x16x32_bf16 v[8:11], v[210:213], v[182:185], v[8:11]
	ds_read_b128 v[158:161], v162 offset:2048
	v_mfma_f32_16x16x32_bf16 v[4:7], v[202:205], v[190:193], v[4:7]
	v_mfma_f32_16x16x32_bf16 v[0:3], v[210:213], v[190:193], v[0:3]
	ds_read_b128 v[162:165], v162 offset:3072
	v_mfma_f32_16x16x32_bf16 v[44:47], v[206:209], v[170:173], v[44:47]
	s_add_u32 s22, s22, 0x20000
	s_addc_u32 s23, s23, 0
	v_mfma_f32_16x16x32_bf16 v[40:43], v[214:217], v[170:173], v[40:43]
	v_mfma_f32_16x16x32_bf16 v[28:31], v[206:209], v[178:181], v[28:31]
	v_mfma_f32_16x16x32_bf16 v[24:27], v[214:217], v[178:181], v[24:27]
	v_mfma_f32_16x16x32_bf16 v[12:15], v[206:209], v[186:189], v[12:15]
	v_mfma_f32_16x16x32_bf16 v[8:11], v[214:217], v[186:189], v[8:11]
	v_mfma_f32_16x16x32_bf16 v[4:7], v[206:209], v[198:201], v[4:7]
	v_mfma_f32_16x16x32_bf16 v[0:3], v[214:217], v[198:201], v[0:3]
	s_barrier
	s_setprio 0
	s_mov_b32 m0, s36
	ds_read_b128 v[166:169], v148 offset:32768
	ds_read_b128 v[170:173], v148 offset:33792
	ds_read_b128 v[174:177], v148 offset:34816
	ds_read_b128 v[178:181], v148 offset:35840
	ds_read_b128 v[182:185], v148 offset:36864
	ds_read_b128 v[186:189], v148 offset:37888
	ds_read_b128 v[190:193], v148 offset:38912
	ds_read_b128 v[198:201], v148 offset:39936
	global_load_lds_dwordx4 v134, s[22:23]
	s_mov_b32 m0, s37
	s_setprio 1
	global_load_lds_dwordx4 v130, s[22:23]
	s_waitcnt lgkmcnt(8)
	s_barrier
	s_waitcnt lgkmcnt(7)
	v_mfma_f32_16x16x32_bf16 v[124:127], v[150:153], v[166:169], v[124:127]
	v_mfma_f32_16x16x32_bf16 v[120:123], v[158:161], v[166:169], v[120:123]
	s_waitcnt lgkmcnt(5)
	v_mfma_f32_16x16x32_bf16 v[116:119], v[150:153], v[174:177], v[116:119]
	v_mfma_f32_16x16x32_bf16 v[112:115], v[158:161], v[174:177], v[112:115]
	s_waitcnt lgkmcnt(3)
	v_mfma_f32_16x16x32_bf16 v[100:103], v[150:153], v[182:185], v[100:103]
	v_mfma_f32_16x16x32_bf16 v[96:99], v[158:161], v[182:185], v[96:99]
	s_waitcnt lgkmcnt(1)
	v_mfma_f32_16x16x32_bf16 v[84:87], v[150:153], v[190:193], v[84:87]
	v_mfma_f32_16x16x32_bf16 v[80:83], v[158:161], v[190:193], v[80:83]
	v_mfma_f32_16x16x32_bf16 v[124:127], v[154:157], v[170:173], v[124:127]
	s_add_i32 s22, 0, 0x1c000
	v_mfma_f32_16x16x32_bf16 v[120:123], v[162:165], v[170:173], v[120:123]
	s_add_i32 s23, s57, s31
	v_mfma_f32_16x16x32_bf16 v[116:119], v[154:157], v[178:181], v[116:119]
	v_add_u32_e32 v196, s22, v146
	v_mfma_f32_16x16x32_bf16 v[112:115], v[162:165], v[178:181], v[112:115]
	v_lshl_add_u64 v[194:195], v[194:195], 0, s[8:9]
	v_mfma_f32_16x16x32_bf16 v[100:103], v[154:157], v[186:189], v[100:103]
	v_mfma_f32_16x16x32_bf16 v[96:99], v[162:165], v[186:189], v[96:99]
	s_waitcnt lgkmcnt(0)
	v_mfma_f32_16x16x32_bf16 v[84:87], v[154:157], v[198:201], v[84:87]
	v_mfma_f32_16x16x32_bf16 v[80:83], v[162:165], v[198:201], v[80:83]
	s_barrier
	s_setprio 0
	s_mov_b32 m0, s23
	ds_read_b128 v[202:205], v196
	ds_read_b128 v[206:209], v196 offset:1024
	ds_read_b128 v[210:213], v196 offset:2048
	ds_read_b128 v[214:217], v196 offset:3072
	global_load_lds_dwordx4 v[194:195], off
	v_lshl_add_u64 v[194:195], v[218:219], 0, s[8:9]
	s_add_i32 m0, s23, 0x2000
	s_setprio 1
	global_load_lds_dwordx4 v[194:195], off
	s_barrier
	s_waitcnt lgkmcnt(3)
	v_mfma_f32_16x16x32_bf16 v[108:111], v[202:205], v[166:169], v[108:111]
	s_waitcnt lgkmcnt(1)
	v_mfma_f32_16x16x32_bf16 v[104:107], v[210:213], v[166:169], v[104:107]
	v_mfma_f32_16x16x32_bf16 v[92:95], v[202:205], v[174:177], v[92:95]
	v_mfma_f32_16x16x32_bf16 v[88:91], v[210:213], v[174:177], v[88:91]
	v_mfma_f32_16x16x32_bf16 v[76:79], v[202:205], v[182:185], v[76:79]
	v_mfma_f32_16x16x32_bf16 v[72:75], v[210:213], v[182:185], v[72:75]
	v_mfma_f32_16x16x32_bf16 v[68:71], v[202:205], v[190:193], v[68:71]
	v_mfma_f32_16x16x32_bf16 v[64:67], v[210:213], v[190:193], v[64:67]
	v_mfma_f32_16x16x32_bf16 v[108:111], v[206:209], v[170:173], v[108:111]
	s_mov_b32 m0, s43
	s_waitcnt lgkmcnt(0)
	v_mfma_f32_16x16x32_bf16 v[104:107], v[214:217], v[170:173], v[104:107]
	v_lshl_add_u64 v[194:195], v[220:221], 0, s[8:9]
	v_mfma_f32_16x16x32_bf16 v[92:95], v[206:209], v[178:181], v[92:95]
	v_mfma_f32_16x16x32_bf16 v[88:91], v[214:217], v[178:181], v[88:91]
	v_mfma_f32_16x16x32_bf16 v[76:79], v[206:209], v[186:189], v[76:79]
	v_mfma_f32_16x16x32_bf16 v[72:75], v[214:217], v[186:189], v[72:75]
	v_mfma_f32_16x16x32_bf16 v[68:71], v[206:209], v[198:201], v[68:71]
	v_mfma_f32_16x16x32_bf16 v[64:67], v[214:217], v[198:201], v[64:67]
	s_barrier
	s_setprio 0
	ds_read_b128 v[166:169], v148 offset:49152
	ds_read_b128 v[170:173], v148 offset:50176
	ds_read_b128 v[174:177], v148 offset:51200
	ds_read_b128 v[178:181], v148 offset:52224
	ds_read_b128 v[182:185], v148 offset:53248
	ds_read_b128 v[186:189], v148 offset:54272
	ds_read_b128 v[190:193], v148 offset:55296
	ds_read_b128 v[198:201], v148 offset:56320
	global_load_lds_dwordx4 v[194:195], off
	v_lshl_add_u64 v[194:195], v[222:223], 0, s[8:9]
	s_mov_b32 m0, s44
	s_setprio 1
	global_load_lds_dwordx4 v[194:195], off
	s_waitcnt vmcnt(10)
	s_barrier
; #define PG8_STAGE(bufoff, gbase, voff) do { _Pragma("unroll") for (int _i = 0; _i < 2; ++_i) \
;         __builtin_amdgcn_global_load_lds((const unsigned*)((const char*)(gbase) + (voff)[_i]), (LAS unsigned*)(lds + (bufoff) + ldsw + _i * 8192), 16, 0, 0); } while (0)
; #define PG8_LDA(dst, b, h) do { _Pragma("unroll") for (int m = 0; m < 4; ++m) _Pragma("unroll") for (int k = 0; k < 2; ++k) dst[m][k] = *(const LAS bf16x8*)(lds + PG8_SA(b, h) + aoff + m * 2048 + k * 1024); } while (0)
; #define PG8_MMA(ai, bj, At, Bt) do { __builtin_amdgcn_s_setprio(1); _Pragma("unroll") for (int m = 0; m < 4; ++m) _Pragma("unroll") for (int n = 0; n < 2; ++n) _Pragma("unroll") for (int k = 0; k < 2; ++k) \
;         acc[ai][bj][m][n] = __builtin_amdgcn_mfma_f32_16x16x32_bf16(Bt[n][k], At[m][k], acc[ai][bj][m][n], 0, 0, 0); __builtin_amdgcn_s_setprio(0); } while (0)
; #define PG8_WAIT_V(n) asm volatile("s_waitcnt vmcnt(" #n ")" ::: "memory")
; #define PG8_WAIT_L(n) asm volatile("s_waitcnt lgkmcnt(" #n ")" ::: "memory")
; #define PG8_BAR __builtin_amdgcn_s_barrier()
; #define PG8_SCHED __builtin_amdgcn_sched_barrier(0)
; template <class Map, class Epi>
; DI void gemm_phase(LAS unsigned char* lds, const Map& MP, const Epi& E, const int nM, const int nN, const int K, const int lda, const int ldb) {
;     ...
;             PG8_LDA(At, 1, 1); PG8_STAGE(PG8_SA(1, 0), a3, voffA);
;             PG8_BAR; PG8_WAIT_L(0); PG8_MMA(1, 0, At, B0); PG8_BAR; PG8_SCHED;
;             PG8_STAGE(PG8_SB(1, 1), b3 + hstepB, voffB);
;             PG8_WAIT_V(6); PG8_BAR; PG8_MMA(1, 1, At, B1); PG8_BAR;
;         }
	s_waitcnt lgkmcnt(7)
	v_mfma_f32_16x16x32_bf16 v[60:63], v[150:153], v[166:169], v[60:63]
	v_mfma_f32_16x16x32_bf16 v[56:59], v[158:161], v[166:169], v[56:59]
	s_waitcnt lgkmcnt(5)
	v_mfma_f32_16x16x32_bf16 v[52:55], v[150:153], v[174:177], v[52:55]
	v_mfma_f32_16x16x32_bf16 v[48:51], v[158:161], v[174:177], v[48:51]
	s_waitcnt lgkmcnt(3)
	v_mfma_f32_16x16x32_bf16 v[36:39], v[150:153], v[182:185], v[36:39]
	v_mfma_f32_16x16x32_bf16 v[32:35], v[158:161], v[182:185], v[32:35]
	s_waitcnt lgkmcnt(1)
	v_mfma_f32_16x16x32_bf16 v[20:23], v[150:153], v[190:193], v[20:23]
	v_mfma_f32_16x16x32_bf16 v[16:19], v[158:161], v[190:193], v[16:19]
	v_mfma_f32_16x16x32_bf16 v[60:63], v[154:157], v[170:173], v[60:63]
	s_add_u32 s20, s20, 0x20080
	s_addc_u32 s21, s21, 0
	v_mfma_f32_16x16x32_bf16 v[56:59], v[162:165], v[170:173], v[56:59]
	s_add_i32 s22, s22, s31
	v_mfma_f32_16x16x32_bf16 v[52:55], v[154:157], v[178:181], v[52:55]
	v_mfma_f32_16x16x32_bf16 v[48:51], v[162:165], v[178:181], v[48:51]
	v_mfma_f32_16x16x32_bf16 v[36:39], v[154:157], v[186:189], v[36:39]
	v_mfma_f32_16x16x32_bf16 v[32:35], v[162:165], v[186:189], v[32:35]
	s_waitcnt lgkmcnt(0)
	v_mfma_f32_16x16x32_bf16 v[20:23], v[154:157], v[198:201], v[20:23]
	v_mfma_f32_16x16x32_bf16 v[16:19], v[162:165], v[198:201], v[16:19]
	s_barrier
	s_setprio 0
	s_mov_b32 m0, s22
	s_nop 0
	global_load_lds_dwordx4 v132, s[20:21]
	s_add_i32 m0, s22, 0x2000
	s_setprio 1
	global_load_lds_dwordx4 v128, s[20:21]
	s_waitcnt vmcnt(6)
	s_barrier
	v_mfma_f32_16x16x32_bf16 v[44:47], v[202:205], v[166:169], v[44:47]
	v_mfma_f32_16x16x32_bf16 v[40:43], v[210:213], v[166:169], v[40:43]
	ds_read_b128 v[150:153], v147
	v_mfma_f32_16x16x32_bf16 v[28:31], v[202:205], v[174:177], v[28:31]
	v_mfma_f32_16x16x32_bf16 v[24:27], v[210:213], v[174:177], v[24:27]
	ds_read_b128 v[154:157], v147 offset:1024
	v_mfma_f32_16x16x32_bf16 v[12:15], v[202:205], v[182:185], v[12:15]
	v_mfma_f32_16x16x32_bf16 v[8:11], v[210:213], v[182:185], v[8:11]
	ds_read_b128 v[158:161], v147 offset:2048
	v_mfma_f32_16x16x32_bf16 v[4:7], v[202:205], v[190:193], v[4:7]
	v_mfma_f32_16x16x32_bf16 v[0:3], v[210:213], v[190:193], v[0:3]
	ds_read_b128 v[162:165], v147 offset:3072
	v_mfma_f32_16x16x32_bf16 v[44:47], v[206:209], v[170:173], v[44:47]
	s_add_i32 s3, s3, 2
	v_mfma_f32_16x16x32_bf16 v[40:43], v[214:217], v[170:173], v[40:43]
	s_add_u32 s55, s55, 0x100
	s_addc_u32 s56, s56, 0
	v_mfma_f32_16x16x32_bf16 v[28:31], v[206:209], v[178:181], v[28:31]
	s_add_u32 s18, s18, 0x100
	s_addc_u32 s19, s19, 0
	v_mfma_f32_16x16x32_bf16 v[24:27], v[214:217], v[178:181], v[24:27]
	s_cmp_gt_u32 s3, 5
	v_mfma_f32_16x16x32_bf16 v[12:15], v[206:209], v[186:189], v[12:15]
	v_mfma_f32_16x16x32_bf16 v[8:11], v[214:217], v[186:189], v[8:11]
	v_mfma_f32_16x16x32_bf16 v[4:7], v[206:209], v[198:201], v[4:7]
	v_mfma_f32_16x16x32_bf16 v[0:3], v[214:217], v[198:201], v[0:3]
	s_barrier
	s_setprio 0
	s_cbranch_scc0 .LBB1_1529
; DI unsigned pack2(float a, float b) { f32x2 v = {a, b}; hwbf16x2 r = __builtin_convertvector(v, hwbf16x2); return __builtin_bit_cast(unsigned, r); }
;     DI const char* a(const Unit& u) const { return (const char*)(A + (size_t)u.pm * BM * lda); }
;     DI const char* a(const Unit& u) const { return (const char*)(A + (size_t)u.pm * BM * 2048 + (u.pn >> 1) * 512); }
;     DI const char* a(const Unit& u) const { return (const char*)((u.pn < 12 ? A1 : A2) + (size_t)u.pm * BM * 512); }
; #define PG8_WAIT_V(n) asm volatile("s_waitcnt vmcnt(" #n ")" ::: "memory")
; #define PG8_BAR __builtin_amdgcn_s_barrier()
;     DI void operator()(const f32x4 (&acc)[2][2][4][2], const Unit& u, int wr, int wc, int fr, int fq) const {
;         bf16_t* O = O1; int ldc = ldc1, pn = u.pn; if (pn >= split) { O = O2; ldc = ldc2; pn -= split; }
;         const int row0 = u.pm * BM + wr * 64 + fr, col0 = pn * BM + wc * 32 + 8 * fq;
; #pragma unroll
;         for (int ai = 0; ai < 2; ++ai)
; #pragma unroll
;             for (int m = 0; m < 4; ++m) { bf16_t* rowp = O + (size_t)(row0 + ai * HALF + m * 16) * ldc + col0;
; #pragma unroll
;                 for (int bj = 0; bj < 2; ++bj) { const f32x4 v0 = acc[ai][bj][m][0], v1 = acc[ai][bj][m][1];
;                     u32x4 o; o[0] = pack2(v0[0], v0[1]); o[1] = pack2(v0[2], v0[3]); o[2] = pack2(v1[0], v1[1]); o[3] = pack2(v1[2], v1[3]);
;                     *(u32x4*)(rowp + bj * HALF) = o; } }
; template <class Map, class Epi>
; DI void gemm_phase(LAS unsigned char* lds, const Map& MP, const Epi& E, const int nM, const int nN, const int K, const int lda, const int ldb) {
;     ...
;         { int frr = fr, fqq = fq; asm volatile("" : "+v"(frr), "+v"(fqq)); E(acc, cur, wr, wc, frr, fqq); }
;         if (!has_next) break;
; #pragma unroll
;         for (int a = 0; a < 2; ++a)
; #pragma unroll
;             for (int b = 0; b < 2; ++b)
; #pragma unroll
;                 for (int m = 0; m < 4; ++m)
; #pragma unroll
;                     for (int n = 0; n < 2; ++n) acc[a][b][m][n] = (f32x4){0.f, 0.f, 0.f, 0.f};
;         cur = nxt; cA = nA; cB = nB; ++ui;
;     }
;     PG8_WAIT_V(0);
;     if (wr == 0) PG8_BAR;
	s_waitcnt lgkmcnt(0)
	s_cmp_lt_i32 s45, 12
	s_cselect_b32 s3, 0, -12
	s_mov_b32 s13, 0x1e510000
	s_movk_i32 s18, 0xc00
	s_cselect_b32 s13, s13, 0x2a510000
	s_cselect_b32 s20, s18, 0x1000
	s_add_i32 s3, s3, s45
	s_add_u32 s18, s6, s13
	v_mov_b32_e32 v150, v144
	v_mov_b32_e32 v151, v145
	s_addc_u32 s19, s7, 0
	s_lshl_b32 s10, s10, 8
	s_lshl_b32 s3, s3, 8
	s_add_i32 s10, s10, s39
	s_or_b32 s3, s3, s42
	v_add_u32_e32 v154, s10, v150
	v_lshl_add_u32 v150, v151, 3, s3
	v_ashrrev_i32_e32 v151, 31, v150
	v_lshl_add_u64 v[150:151], v[150:151], 1, s[18:19]
	v_mad_i64_i32 v[152:153], s[18:19], s20, v154, 0
	v_cvt_pk_bf16_f32 v108, v108, v109
	v_cvt_pk_bf16_f32 v109, v110, v111
	v_cvt_pk_bf16_f32 v110, v104, v105
	v_add_u32_e32 v104, 16, v154
	v_lshl_add_u64 v[152:153], v[152:153], 1, v[150:151]
	v_cvt_pk_bf16_f32 v111, v106, v107
	v_mad_i64_i32 v[104:105], s[18:19], s20, v104, 0
	v_cvt_pk_bf16_f32 v92, v92, v93
	v_cvt_pk_bf16_f32 v93, v94, v95
	v_cvt_pk_bf16_f32 v94, v88, v89
	v_add_u32_e32 v88, 32, v154
	v_cvt_pk_bf16_f32 v124, v124, v125
	v_cvt_pk_bf16_f32 v125, v126, v127
	v_cvt_pk_bf16_f32 v126, v120, v121
	v_cvt_pk_bf16_f32 v127, v122, v123
	global_store_dwordx4 v[152:153], v[108:111], off offset:256
	v_cvt_pk_bf16_f32 v95, v90, v91
	v_mad_i64_i32 v[88:89], s[18:19], s20, v88, 0
	v_lshl_add_u64 v[108:109], v[104:105], 1, v[150:151]
	v_cvt_pk_bf16_f32 v76, v76, v77
	v_cvt_pk_bf16_f32 v77, v78, v79
	v_cvt_pk_bf16_f32 v78, v72, v73
	v_add_u32_e32 v72, 48, v154
	v_cvt_pk_bf16_f32 v68, v68, v69
	v_cvt_pk_bf16_f32 v69, v70, v71
	v_cvt_pk_bf16_f32 v70, v64, v65
	v_add_u32_e32 v64, 0x80, v154
	global_store_dwordx4 v[152:153], v[124:127], off
	v_cvt_pk_bf16_f32 v104, v116, v117
	v_cvt_pk_bf16_f32 v105, v118, v119
	v_cvt_pk_bf16_f32 v106, v112, v113
	v_cvt_pk_bf16_f32 v107, v114, v115
	global_store_dwordx4 v[108:109], v[92:95], off offset:256
	v_cvt_pk_bf16_f32 v79, v74, v75
	v_mad_i64_i32 v[72:73], s[18:19], s20, v72, 0
	v_lshl_add_u64 v[92:93], v[88:89], 1, v[150:151]
	v_mad_i64_i32 v[64:65], s[18:19], s20, v64, 0
	v_cvt_pk_bf16_f32 v44, v44, v45
	v_cvt_pk_bf16_f32 v45, v46, v47
	v_cvt_pk_bf16_f32 v46, v40, v41
	v_add_u32_e32 v40, 0x90, v154
	global_store_dwordx4 v[108:109], v[104:107], off
	v_cvt_pk_bf16_f32 v88, v100, v101
	v_cvt_pk_bf16_f32 v89, v102, v103
	v_cvt_pk_bf16_f32 v90, v96, v97
	v_cvt_pk_bf16_f32 v91, v98, v99
	global_store_dwordx4 v[92:93], v[76:79], off offset:256
	v_cvt_pk_bf16_f32 v74, v80, v81
	v_cvt_pk_bf16_f32 v75, v82, v83
	v_lshl_add_u64 v[76:77], v[72:73], 1, v[150:151]
	v_cvt_pk_bf16_f32 v72, v84, v85
	v_cvt_pk_bf16_f32 v73, v86, v87
	v_cvt_pk_bf16_f32 v71, v66, v67
	v_lshl_add_u64 v[64:65], v[64:65], 1, v[150:151]
	v_cvt_pk_bf16_f32 v47, v42, v43
	v_mad_i64_i32 v[40:41], s[18:19], s20, v40, 0
	v_cvt_pk_bf16_f32 v28, v28, v29
	v_cvt_pk_bf16_f32 v29, v30, v31
	v_cvt_pk_bf16_f32 v30, v24, v25
	v_add_u32_e32 v24, 0xa0, v154
	global_store_dwordx4 v[92:93], v[88:91], off
	global_store_dwordx4 v[76:77], v[72:75], off
	global_store_dwordx4 v[76:77], v[68:71], off offset:256
	v_cvt_pk_bf16_f32 v60, v60, v61
	v_cvt_pk_bf16_f32 v61, v62, v63
	v_cvt_pk_bf16_f32 v62, v56, v57
	v_cvt_pk_bf16_f32 v63, v58, v59
	global_store_dwordx4 v[64:65], v[44:47], off offset:256
	v_cvt_pk_bf16_f32 v31, v26, v27
	v_mad_i64_i32 v[24:25], s[18:19], s20, v24, 0
	v_lshl_add_u64 v[44:45], v[40:41], 1, v[150:151]
	v_cvt_pk_bf16_f32 v12, v12, v13
	v_cvt_pk_bf16_f32 v13, v14, v15
	v_cvt_pk_bf16_f32 v14, v8, v9
	v_add_u32_e32 v8, 0xb0, v154
	global_store_dwordx4 v[64:65], v[60:63], off
	v_cvt_pk_bf16_f32 v40, v52, v53
	v_cvt_pk_bf16_f32 v41, v54, v55
	v_cvt_pk_bf16_f32 v42, v48, v49
	v_cvt_pk_bf16_f32 v43, v50, v51
	global_store_dwordx4 v[44:45], v[28:31], off offset:256
	v_cvt_pk_bf16_f32 v15, v10, v11
	v_mad_i64_i32 v[8:9], s[18:19], s20, v8, 0
	v_lshl_add_u64 v[28:29], v[24:25], 1, v[150:151]
	global_store_dwordx4 v[44:45], v[40:43], off
	v_cvt_pk_bf16_f32 v24, v36, v37
	v_cvt_pk_bf16_f32 v25, v38, v39
	v_cvt_pk_bf16_f32 v26, v32, v33
	v_cvt_pk_bf16_f32 v27, v34, v35
	global_store_dwordx4 v[28:29], v[12:15], off offset:256
	v_cvt_pk_bf16_f32 v10, v16, v17
	v_cvt_pk_bf16_f32 v11, v18, v19
	v_lshl_add_u64 v[12:13], v[8:9], 1, v[150:151]
	v_cvt_pk_bf16_f32 v8, v20, v21
	v_cvt_pk_bf16_f32 v9, v22, v23
	v_cvt_pk_bf16_f32 v4, v4, v5
	v_cvt_pk_bf16_f32 v5, v6, v7
	v_cvt_pk_bf16_f32 v6, v0, v1
	v_cvt_pk_bf16_f32 v7, v2, v3
	s_and_b64 vcc, exec, s[40:41]
	s_mov_b32 s45, s49
	s_mov_b32 s10, s12
	s_mov_b64 s[18:19], s[16:17]
	s_mov_b64 s[20:21], s[14:15]
	global_store_dwordx4 v[28:29], v[24:27], off
	global_store_dwordx4 v[12:13], v[8:11], off
	global_store_dwordx4 v[12:13], v[4:7], off offset:256
	s_cbranch_vccz .LBB1_1526
	s_waitcnt vmcnt(0)
	s_cmpk_gt_u32 s4, 0xff
	s_cbranch_scc1 .LBB1_1533
	s_barrier

; #define PG8_STAGE(bufoff, gbase, voff) do { _Pragma("unroll") for (int _i = 0; _i < 2; ++_i) \
;         __builtin_amdgcn_global_load_lds((const unsigned*)((const char*)(gbase) + (voff)[_i]), (LAS unsigned*)(lds + (bufoff) + ldsw + _i * 8192), 16, 0, 0); } while (0)
; #define PG8_LDA(dst, b, h) do { _Pragma("unroll") for (int m = 0; m < 4; ++m) _Pragma("unroll") for (int k = 0; k < 2; ++k) dst[m][k] = *(const LAS bf16x8*)(lds + PG8_SA(b, h) + aoff + m * 2048 + k * 1024); } while (0)
; #define PG8_LDB(dst, b, h) do { _Pragma("unroll") for (int n = 0; n < 2; ++n) _Pragma("unroll") for (int k = 0; k < 2; ++k) dst[n][k] = *(const LAS bf16x8*)(lds + PG8_SB(b, h) + boff + n * 2048 + k * 1024); } while (0)
; #define PG8_MMA(ai, bj, At, Bt) do { __builtin_amdgcn_s_setprio(1); _Pragma("unroll") for (int m = 0; m < 4; ++m) _Pragma("unroll") for (int n = 0; n < 2; ++n) _Pragma("unroll") for (int k = 0; k < 2; ++k) \
;         acc[ai][bj][m][n] = __builtin_amdgcn_mfma_f32_16x16x32_bf16(Bt[n][k], At[m][k], acc[ai][bj][m][n], 0, 0, 0); __builtin_amdgcn_s_setprio(0); } while (0)
; #define PG8_WAIT_L(n) asm volatile("s_waitcnt lgkmcnt(" #n ")" ::: "memory")
; #define PG8_BAR __builtin_amdgcn_s_barrier()
; #define PG8_SCHED __builtin_amdgcn_sched_barrier(0)
; template <class Map, class Epi>
; DI void gemm_phase(LAS unsigned char* lds, const Map& MP, const Epi& E, const int nM, const int nN, const int K, const int lda, const int ldb) {
;     ...
;         for (int t = 0; t < nt; t += 2) {
;             const bool last = (t == nt - 2);
;             const char* a1 = cA + (size_t)(t + 1) * kstep;
;             const char* a2 = last ? nA : cA + (size_t)(t + 2) * kstep; const char* b2 = last ? nB : cB + (size_t)(t + 2) * kstep;
;             const char* a3 = a2 + kstep; const char* b3 = b2 + kstep;
;             PG8_LDB(B0, 0, 0); PG8_SCHED; PG8_LDA(At, 0, 0); PG8_STAGE(PG8_SA(1, 1), a1 + hstepA, voffA);
;             PG8_WAIT_L(8); PG8_BAR; PG8_WAIT_L(0); PG8_MMA(0, 0, At, B0); PG8_BAR; PG8_SCHED;
;             PG8_LDB(B1, 0, 1); PG8_STAGE(PG8_SB(0, 0), b2, voffB);
;             PG8_BAR; PG8_WAIT_L(0); PG8_MMA(0, 1, At, B1); PG8_BAR;
;             PG8_LDA(At, 0, 1); PG8_STAGE(PG8_SA(0, 0), a2, voffA);
;             PG8_BAR; PG8_WAIT_L(0); PG8_MMA(1, 0, At, B0); PG8_BAR; PG8_SCHED;
.LBB1_1764:
	s_add_u32 s12, s10, 0xfff80080
	s_addc_u32 s13, s11, -1
	s_cmp_eq_u32 s3, 28
	s_cselect_b32 s15, s37, s13
	s_cselect_b32 s14, s38, s12
	s_cselect_b32 s13, s39, s48
	s_cselect_b32 s12, s45, s47
	s_add_i32 m0, s24, 0xc000
	ds_read_b128 v[168:171], v150
	ds_read_b128 v[172:175], v150 offset:1024
	ds_read_b128 v[176:179], v150 offset:2048
	ds_read_b128 v[180:183], v150 offset:3072
	ds_read_b128 v[184:187], v150 offset:4096
	ds_read_b128 v[188:191], v150 offset:5120
	ds_read_b128 v[192:195], v150 offset:6144
	ds_read_b128 v[198:201], v150 offset:7168
	global_load_lds_dwordx4 v138, s[10:11]
	s_add_i32 m0, s24, 0xe000
	s_setprio 1
	global_load_lds_dwordx4 v136, s[10:11]
	s_waitcnt lgkmcnt(8)
	s_barrier
	s_waitcnt lgkmcnt(7)
	v_mfma_f32_16x16x32_bf16 v[124:127], v[152:155], v[168:171], v[124:127]
	v_mfma_f32_16x16x32_bf16 v[120:123], v[160:163], v[168:171], v[120:123]
	s_waitcnt lgkmcnt(5)
	v_mfma_f32_16x16x32_bf16 v[108:111], v[152:155], v[176:179], v[108:111]
	v_mfma_f32_16x16x32_bf16 v[104:107], v[160:163], v[176:179], v[104:107]
	s_waitcnt lgkmcnt(3)
	v_mfma_f32_16x16x32_bf16 v[92:95], v[152:155], v[184:187], v[92:95]
	v_mfma_f32_16x16x32_bf16 v[88:91], v[160:163], v[184:187], v[88:91]
	s_waitcnt lgkmcnt(1)
	v_mfma_f32_16x16x32_bf16 v[76:79], v[152:155], v[192:195], v[76:79]
	v_mfma_f32_16x16x32_bf16 v[72:75], v[160:163], v[192:195], v[72:75]
	v_mfma_f32_16x16x32_bf16 v[124:127], v[156:159], v[172:175], v[124:127]
	s_add_i32 s49, s35, s22
	v_mfma_f32_16x16x32_bf16 v[120:123], v[164:167], v[172:175], v[120:123]
	v_lshl_add_u64 v[144:145], s[12:13], 0, v[132:133]
	v_mfma_f32_16x16x32_bf16 v[108:111], v[156:159], v[180:183], v[108:111]
	v_lshl_add_u64 v[218:219], s[12:13], 0, v[128:129]
	v_mfma_f32_16x16x32_bf16 v[104:107], v[164:167], v[180:183], v[104:107]
	v_mfma_f32_16x16x32_bf16 v[92:95], v[156:159], v[188:191], v[92:95]
	v_mfma_f32_16x16x32_bf16 v[88:91], v[164:167], v[188:191], v[88:91]
	s_waitcnt lgkmcnt(0)
	v_mfma_f32_16x16x32_bf16 v[76:79], v[156:159], v[198:201], v[76:79]
	v_mfma_f32_16x16x32_bf16 v[72:75], v[164:167], v[198:201], v[72:75]
	s_barrier
	s_setprio 0
	s_mov_b32 m0, s49
	ds_read_b128 v[202:205], v151
	ds_read_b128 v[206:209], v151 offset:1024
	ds_read_b128 v[210:213], v151 offset:2048
	ds_read_b128 v[214:217], v151 offset:3072
	global_load_lds_dwordx4 v[144:145], off
	s_add_i32 m0, s49, 0x2000
	s_setprio 1
	global_load_lds_dwordx4 v[218:219], off
	s_barrier
	s_waitcnt lgkmcnt(3)
	v_mfma_f32_16x16x32_bf16 v[116:119], v[202:205], v[168:171], v[116:119]
	s_waitcnt lgkmcnt(1)
	v_mfma_f32_16x16x32_bf16 v[112:115], v[210:213], v[168:171], v[112:115]
	v_mfma_f32_16x16x32_bf16 v[100:103], v[202:205], v[176:179], v[100:103]
	v_mfma_f32_16x16x32_bf16 v[96:99], v[210:213], v[176:179], v[96:99]
	v_mfma_f32_16x16x32_bf16 v[84:87], v[202:205], v[184:187], v[84:87]
	v_mfma_f32_16x16x32_bf16 v[80:83], v[210:213], v[184:187], v[80:83]
	v_mfma_f32_16x16x32_bf16 v[68:71], v[202:205], v[192:195], v[68:71]
	v_mfma_f32_16x16x32_bf16 v[64:67], v[210:213], v[192:195], v[64:67]
	v_mfma_f32_16x16x32_bf16 v[116:119], v[206:209], v[172:175], v[116:119]
	v_lshl_add_u64 v[222:223], s[14:15], 0, v[130:131]
	s_mov_b32 m0, s24
	s_waitcnt lgkmcnt(0)
	v_mfma_f32_16x16x32_bf16 v[112:115], v[214:217], v[172:175], v[112:115]
	v_lshl_add_u64 v[220:221], s[14:15], 0, v[134:135]
	v_mfma_f32_16x16x32_bf16 v[100:103], v[206:209], v[180:183], v[100:103]
	v_mfma_f32_16x16x32_bf16 v[96:99], v[214:217], v[180:183], v[96:99]
	v_mfma_f32_16x16x32_bf16 v[84:87], v[206:209], v[188:191], v[84:87]
	v_mfma_f32_16x16x32_bf16 v[80:83], v[214:217], v[188:191], v[80:83]
	v_mfma_f32_16x16x32_bf16 v[68:71], v[206:209], v[198:201], v[68:71]
	v_mfma_f32_16x16x32_bf16 v[64:67], v[214:217], v[198:201], v[64:67]
	s_barrier
	s_setprio 0
	ds_read_b128 v[168:171], v150 offset:16384
	ds_read_b128 v[172:175], v150 offset:17408
	ds_read_b128 v[176:179], v150 offset:18432
	ds_read_b128 v[180:183], v150 offset:19456
	ds_read_b128 v[184:187], v150 offset:20480
	ds_read_b128 v[188:191], v150 offset:21504
	ds_read_b128 v[192:195], v150 offset:22528
	ds_read_b128 v[198:201], v150 offset:23552
	global_load_lds_dwordx4 v[220:221], off
	s_mov_b32 m0, s9
	s_setprio 1
	global_load_lds_dwordx4 v[222:223], off
	s_waitcnt vmcnt(10)
	s_barrier
	s_waitcnt lgkmcnt(7)
	v_mfma_f32_16x16x32_bf16 v[60:63], v[152:155], v[168:171], v[60:63]
	v_mfma_f32_16x16x32_bf16 v[56:59], v[160:163], v[168:171], v[56:59]
	s_waitcnt lgkmcnt(5)
	v_mfma_f32_16x16x32_bf16 v[44:47], v[152:155], v[176:179], v[44:47]
	v_mfma_f32_16x16x32_bf16 v[40:43], v[160:163], v[176:179], v[40:43]
	s_waitcnt lgkmcnt(3)
	v_mfma_f32_16x16x32_bf16 v[28:31], v[152:155], v[184:187], v[28:31]
	v_mfma_f32_16x16x32_bf16 v[24:27], v[160:163], v[184:187], v[24:27]
	s_waitcnt lgkmcnt(1)
	v_mfma_f32_16x16x32_bf16 v[12:15], v[152:155], v[192:195], v[12:15]
	v_mfma_f32_16x16x32_bf16 v[8:11], v[160:163], v[192:195], v[8:11]
	v_mfma_f32_16x16x32_bf16 v[60:63], v[156:159], v[172:175], v[60:63]
	s_add_u32 s54, s12, 0x80000
	s_addc_u32 s55, s13, 0
	v_mfma_f32_16x16x32_bf16 v[56:59], v[164:167], v[172:175], v[56:59]
	s_add_i32 s49, s36, s22
	v_mfma_f32_16x16x32_bf16 v[44:47], v[156:159], v[180:183], v[44:47]
	v_mfma_f32_16x16x32_bf16 v[40:43], v[164:167], v[180:183], v[40:43]
	v_mfma_f32_16x16x32_bf16 v[28:31], v[156:159], v[188:191], v[28:31]
	v_mfma_f32_16x16x32_bf16 v[24:27], v[164:167], v[188:191], v[24:27]
	s_waitcnt lgkmcnt(0)
	v_mfma_f32_16x16x32_bf16 v[12:15], v[156:159], v[198:201], v[12:15]
	v_mfma_f32_16x16x32_bf16 v[8:11], v[164:167], v[198:201], v[8:11]
	s_barrier
; #define PG8_STAGE(bufoff, gbase, voff) do { _Pragma("unroll") for (int _i = 0; _i < 2; ++_i) \
;         __builtin_amdgcn_global_load_lds((const unsigned*)((const char*)(gbase) + (voff)[_i]), (LAS unsigned*)(lds + (bufoff) + ldsw + _i * 8192), 16, 0, 0); } while (0)
; #define PG8_LDA(dst, b, h) do { _Pragma("unroll") for (int m = 0; m < 4; ++m) _Pragma("unroll") for (int k = 0; k < 2; ++k) dst[m][k] = *(const LAS bf16x8*)(lds + PG8_SA(b, h) + aoff + m * 2048 + k * 1024); } while (0)
; #define PG8_LDB(dst, b, h) do { _Pragma("unroll") for (int n = 0; n < 2; ++n) _Pragma("unroll") for (int k = 0; k < 2; ++k) dst[n][k] = *(const LAS bf16x8*)(lds + PG8_SB(b, h) + boff + n * 2048 + k * 1024); } while (0)
; #define PG8_MMA(ai, bj, At, Bt) do { __builtin_amdgcn_s_setprio(1); _Pragma("unroll") for (int m = 0; m < 4; ++m) _Pragma("unroll") for (int n = 0; n < 2; ++n) _Pragma("unroll") for (int k = 0; k < 2; ++k) \
;         acc[ai][bj][m][n] = __builtin_amdgcn_mfma_f32_16x16x32_bf16(Bt[n][k], At[m][k], acc[ai][bj][m][n], 0, 0, 0); __builtin_amdgcn_s_setprio(0); } while (0)
; #define PG8_WAIT_V(n) asm volatile("s_waitcnt vmcnt(" #n ")" ::: "memory")
; #define PG8_WAIT_L(n) asm volatile("s_waitcnt lgkmcnt(" #n ")" ::: "memory")
; #define PG8_BAR __builtin_amdgcn_s_barrier()
; #define PG8_SCHED __builtin_amdgcn_sched_barrier(0)
; template <class Map, class Epi>
; DI void gemm_phase(LAS unsigned char* lds, const Map& MP, const Epi& E, const int nM, const int nN, const int K, const int lda, const int ldb) {
;     ...
;             PG8_STAGE(PG8_SB(0, 1), b2 + hstepB, voffB);
;             PG8_WAIT_V(6); PG8_BAR; PG8_MMA(1, 1, At, B1); PG8_BAR;
;             PG8_LDB(B0, 1, 0); PG8_SCHED; PG8_LDA(At, 1, 0); PG8_STAGE(PG8_SA(0, 1), a2 + hstepA, voffA);
;             PG8_WAIT_L(8); PG8_BAR; PG8_WAIT_L(0); PG8_MMA(0, 0, At, B0); PG8_BAR; PG8_SCHED;
;             PG8_LDB(B1, 1, 1); PG8_STAGE(PG8_SB(1, 0), b3, voffB);
;             PG8_BAR; PG8_WAIT_L(0); PG8_MMA(0, 1, At, B1); PG8_BAR;
;             PG8_LDA(At, 1, 1); PG8_STAGE(PG8_SA(1, 0), a3, voffA);
	s_setprio 0
	s_mov_b32 m0, s49
	s_nop 0
	global_load_lds_dwordx4 v132, s[54:55]
	s_add_i32 m0, s49, 0x2000
	s_setprio 1
	global_load_lds_dwordx4 v128, s[54:55]
	s_waitcnt vmcnt(6)
	s_barrier
	v_mfma_f32_16x16x32_bf16 v[52:55], v[202:205], v[168:171], v[52:55]
	v_mfma_f32_16x16x32_bf16 v[48:51], v[210:213], v[168:171], v[48:51]
	s_add_i32 s49, 0, 0x18000
	v_add_u32_e32 v164, s49, v148
	ds_read_b128 v[152:155], v164
	v_mfma_f32_16x16x32_bf16 v[36:39], v[202:205], v[176:179], v[36:39]
	v_mfma_f32_16x16x32_bf16 v[32:35], v[210:213], v[176:179], v[32:35]
	ds_read_b128 v[156:159], v164 offset:1024
	v_mfma_f32_16x16x32_bf16 v[20:23], v[202:205], v[184:187], v[20:23]
	v_mfma_f32_16x16x32_bf16 v[16:19], v[210:213], v[184:187], v[16:19]
	ds_read_b128 v[160:163], v164 offset:2048
	v_mfma_f32_16x16x32_bf16 v[4:7], v[202:205], v[192:195], v[4:7]
	v_mfma_f32_16x16x32_bf16 v[0:3], v[210:213], v[192:195], v[0:3]
	ds_read_b128 v[164:167], v164 offset:3072
	v_mfma_f32_16x16x32_bf16 v[52:55], v[206:209], v[172:175], v[52:55]
	s_add_u32 s14, s14, 0x80000
	s_addc_u32 s15, s15, 0
	v_mfma_f32_16x16x32_bf16 v[48:51], v[214:217], v[172:175], v[48:51]
	v_mfma_f32_16x16x32_bf16 v[36:39], v[206:209], v[180:183], v[36:39]
	v_mfma_f32_16x16x32_bf16 v[32:35], v[214:217], v[180:183], v[32:35]
	v_mfma_f32_16x16x32_bf16 v[20:23], v[206:209], v[188:191], v[20:23]
	v_mfma_f32_16x16x32_bf16 v[16:19], v[214:217], v[188:191], v[16:19]
	v_mfma_f32_16x16x32_bf16 v[4:7], v[206:209], v[198:201], v[4:7]
	v_mfma_f32_16x16x32_bf16 v[0:3], v[214:217], v[198:201], v[0:3]
	s_barrier
	s_setprio 0
	s_mov_b32 m0, s25
	ds_read_b128 v[168:171], v150 offset:32768
	ds_read_b128 v[172:175], v150 offset:33792
	ds_read_b128 v[176:179], v150 offset:34816
	ds_read_b128 v[180:183], v150 offset:35840
	ds_read_b128 v[184:187], v150 offset:36864
	ds_read_b128 v[188:191], v150 offset:37888
	ds_read_b128 v[192:195], v150 offset:38912
	ds_read_b128 v[198:201], v150 offset:39936
	global_load_lds_dwordx4 v134, s[14:15]
	s_mov_b32 m0, s26
	s_setprio 1
	global_load_lds_dwordx4 v130, s[14:15]
	s_waitcnt lgkmcnt(8)
	s_barrier
	s_waitcnt lgkmcnt(7)
	v_mfma_f32_16x16x32_bf16 v[124:127], v[152:155], v[168:171], v[124:127]
	v_mfma_f32_16x16x32_bf16 v[120:123], v[160:163], v[168:171], v[120:123]
	s_waitcnt lgkmcnt(5)
	v_mfma_f32_16x16x32_bf16 v[108:111], v[152:155], v[176:179], v[108:111]
	v_mfma_f32_16x16x32_bf16 v[104:107], v[160:163], v[176:179], v[104:107]
	s_waitcnt lgkmcnt(3)
	v_mfma_f32_16x16x32_bf16 v[92:95], v[152:155], v[184:187], v[92:95]
	v_mfma_f32_16x16x32_bf16 v[88:91], v[160:163], v[184:187], v[88:91]
	s_waitcnt lgkmcnt(1)
	v_mfma_f32_16x16x32_bf16 v[76:79], v[152:155], v[192:195], v[76:79]
	v_mfma_f32_16x16x32_bf16 v[72:75], v[160:163], v[192:195], v[72:75]
	v_mfma_f32_16x16x32_bf16 v[124:127], v[156:159], v[172:175], v[124:127]
	s_add_i32 s14, 0, 0x1c000
	v_mfma_f32_16x16x32_bf16 v[120:123], v[164:167], v[172:175], v[120:123]
	s_add_i32 s15, s49, s22
	v_mfma_f32_16x16x32_bf16 v[108:111], v[156:159], v[180:183], v[108:111]
	v_add_u32_e32 v196, s14, v148
	v_mfma_f32_16x16x32_bf16 v[104:107], v[164:167], v[180:183], v[104:107]
	v_lshl_add_u64 v[144:145], v[144:145], 0, s[42:43]
	v_mfma_f32_16x16x32_bf16 v[92:95], v[156:159], v[188:191], v[92:95]
	v_mfma_f32_16x16x32_bf16 v[88:91], v[164:167], v[188:191], v[88:91]
	s_waitcnt lgkmcnt(0)
	v_mfma_f32_16x16x32_bf16 v[76:79], v[156:159], v[198:201], v[76:79]
	v_mfma_f32_16x16x32_bf16 v[72:75], v[164:167], v[198:201], v[72:75]
	s_barrier
	s_setprio 0
	s_mov_b32 m0, s15
	ds_read_b128 v[202:205], v196
	ds_read_b128 v[206:209], v196 offset:1024
	ds_read_b128 v[210:213], v196 offset:2048
	ds_read_b128 v[214:217], v196 offset:3072
	global_load_lds_dwordx4 v[144:145], off
	v_lshl_add_u64 v[144:145], v[218:219], 0, s[42:43]
	s_add_i32 m0, s15, 0x2000
	s_setprio 1
	global_load_lds_dwordx4 v[144:145], off
	s_barrier
	s_waitcnt lgkmcnt(3)
	v_mfma_f32_16x16x32_bf16 v[116:119], v[202:205], v[168:171], v[116:119]
	s_waitcnt lgkmcnt(1)
	v_mfma_f32_16x16x32_bf16 v[112:115], v[210:213], v[168:171], v[112:115]
	v_mfma_f32_16x16x32_bf16 v[100:103], v[202:205], v[176:179], v[100:103]
	v_mfma_f32_16x16x32_bf16 v[96:99], v[210:213], v[176:179], v[96:99]
	v_mfma_f32_16x16x32_bf16 v[84:87], v[202:205], v[184:187], v[84:87]
	v_mfma_f32_16x16x32_bf16 v[80:83], v[210:213], v[184:187], v[80:83]
	v_mfma_f32_16x16x32_bf16 v[68:71], v[202:205], v[192:195], v[68:71]
	v_mfma_f32_16x16x32_bf16 v[64:67], v[210:213], v[192:195], v[64:67]
	v_mfma_f32_16x16x32_bf16 v[116:119], v[206:209], v[172:175], v[116:119]
	s_mov_b32 m0, s30
	s_waitcnt lgkmcnt(0)
	v_mfma_f32_16x16x32_bf16 v[112:115], v[214:217], v[172:175], v[112:115]
	v_lshl_add_u64 v[144:145], v[220:221], 0, s[42:43]
	v_mfma_f32_16x16x32_bf16 v[100:103], v[206:209], v[180:183], v[100:103]
	v_mfma_f32_16x16x32_bf16 v[96:99], v[214:217], v[180:183], v[96:99]
	v_mfma_f32_16x16x32_bf16 v[84:87], v[206:209], v[188:191], v[84:87]
	v_mfma_f32_16x16x32_bf16 v[80:83], v[214:217], v[188:191], v[80:83]
	v_mfma_f32_16x16x32_bf16 v[68:71], v[206:209], v[198:201], v[68:71]
	v_mfma_f32_16x16x32_bf16 v[64:67], v[214:217], v[198:201], v[64:67]
	s_barrier
	s_setprio 0
	ds_read_b128 v[168:171], v150 offset:49152
	ds_read_b128 v[172:175], v150 offset:50176
	ds_read_b128 v[176:179], v150 offset:51200
	ds_read_b128 v[180:183], v150 offset:52224
	ds_read_b128 v[184:187], v150 offset:53248
	ds_read_b128 v[188:191], v150 offset:54272
	ds_read_b128 v[192:195], v150 offset:55296
	ds_read_b128 v[198:201], v150 offset:56320
	global_load_lds_dwordx4 v[144:145], off
	v_lshl_add_u64 v[144:145], v[222:223], 0, s[42:43]
	s_mov_b32 m0, s31
	s_setprio 1
	global_load_lds_dwordx4 v[144:145], off
	s_waitcnt vmcnt(10)
	s_barrier
; DI unsigned pack2(float a, float b) { f32x2 v = {a, b}; hwbf16x2 r = __builtin_convertvector(v, hwbf16x2); return __builtin_bit_cast(unsigned, r); }
; DI float bflo(unsigned w) { return __uint_as_float(w << 16); }
; DI float bfhi(unsigned w) { return __uint_as_float(w & 0xffff0000u); }
; #define PG8_STAGE(bufoff, gbase, voff) do { _Pragma("unroll") for (int _i = 0; _i < 2; ++_i) \
;         __builtin_amdgcn_global_load_lds((const unsigned*)((const char*)(gbase) + (voff)[_i]), (LAS unsigned*)(lds + (bufoff) + ldsw + _i * 8192), 16, 0, 0); } while (0)
; #define PG8_WAIT_V(n) asm volatile("s_waitcnt vmcnt(" #n ")" ::: "memory")
; #define PG8_WAIT_L(n) asm volatile("s_waitcnt lgkmcnt(" #n ")" ::: "memory")
;     DI void operator()(const f32x4 (&acc)[2][2][4][2], const Unit& u, int wr, int wc, int fr, int fq) const {
;     ...
;             for (int m = 0; m < 4; ++m) { const size_t ro = (size_t)(row0 + ai * HALF + m * 16) * D + col0;
; #pragma unroll
;                 for (int bj = 0; bj < 2; ++bj) {
;                     f32x4 x0, x1;
;                     if constexpr (IB) { const u32x4 w = *(const u32x4*)((const bf16_t*)Xin + ro + bj * HALF);
;                         x0 = (f32x4){bflo(w[0]), bfhi(w[0]), bflo(w[1]), bfhi(w[1])}; x1 = (f32x4){bflo(w[2]), bfhi(w[2]), bflo(w[3]), bfhi(w[3])}; }
;                     else { x0 = *(const f32x4*)((const float*)Xin + ro + bj * HALF); x1 = *(const f32x4*)((const float*)Xin + ro + bj * HALF + 4); }
;                     x0 += acc[ai][bj][m][0] * sc[bj][0]; x1 += acc[ai][bj][m][1] * sc[bj][1];
;                     if constexpr (OB) { u32x4 o; o[0] = pack2(x0[0], x0[1]); o[1] = pack2(x0[2], x0[3]); o[2] = pack2(x1[0], x1[1]); o[3] = pack2(x1[2], x1[3]);
;                         *(u32x4*)((bf16_t*)Xout + ro + bj * HALF) = o; }
;                     else { *(f32x4*)((float*)Xout + ro + bj * HALF) = x0; *(f32x4*)((float*)Xout + ro + bj * HALF + 4) = x1; } } }
; template <class Map, class Epi>
; DI void gemm_phase(LAS unsigned char* lds, const Map& MP, const Epi& E, const int nM, const int nN, const int K, const int lda, const int ldb) {
;     ...
;             PG8_LDA(At, 1, 1); PG8_STAGE(PG8_SA(1, 0), a3, voffA);
;             PG8_BAR; PG8_WAIT_L(0); PG8_MMA(1, 0, At, B0); PG8_BAR; PG8_SCHED;
;             PG8_STAGE(PG8_SB(1, 1), b3 + hstepB, voffB);
;             PG8_WAIT_V(6); PG8_BAR; PG8_MMA(1, 1, At, B1); PG8_BAR;
;         }
	s_waitcnt lgkmcnt(7)
	v_mfma_f32_16x16x32_bf16 v[60:63], v[152:155], v[168:171], v[60:63]
	v_mfma_f32_16x16x32_bf16 v[56:59], v[160:163], v[168:171], v[56:59]
	s_waitcnt lgkmcnt(5)
	v_mfma_f32_16x16x32_bf16 v[44:47], v[152:155], v[176:179], v[44:47]
	v_mfma_f32_16x16x32_bf16 v[40:43], v[160:163], v[176:179], v[40:43]
	s_waitcnt lgkmcnt(3)
	v_mfma_f32_16x16x32_bf16 v[28:31], v[152:155], v[184:187], v[28:31]
	v_mfma_f32_16x16x32_bf16 v[24:27], v[160:163], v[184:187], v[24:27]
	s_waitcnt lgkmcnt(1)
	v_mfma_f32_16x16x32_bf16 v[12:15], v[152:155], v[192:195], v[12:15]
	v_mfma_f32_16x16x32_bf16 v[8:11], v[160:163], v[192:195], v[8:11]
	v_mfma_f32_16x16x32_bf16 v[60:63], v[156:159], v[172:175], v[60:63]
	s_add_u32 s12, s12, 0x80080
	s_addc_u32 s13, s13, 0
	v_mfma_f32_16x16x32_bf16 v[56:59], v[164:167], v[172:175], v[56:59]
	s_add_i32 s14, s14, s22
	v_mfma_f32_16x16x32_bf16 v[44:47], v[156:159], v[180:183], v[44:47]
	v_mfma_f32_16x16x32_bf16 v[40:43], v[164:167], v[180:183], v[40:43]
	v_mfma_f32_16x16x32_bf16 v[28:31], v[156:159], v[188:191], v[28:31]
	v_mfma_f32_16x16x32_bf16 v[24:27], v[164:167], v[188:191], v[24:27]
	s_waitcnt lgkmcnt(0)
	v_mfma_f32_16x16x32_bf16 v[12:15], v[156:159], v[198:201], v[12:15]
	v_mfma_f32_16x16x32_bf16 v[8:11], v[164:167], v[198:201], v[8:11]
	s_barrier
	s_setprio 0
	s_mov_b32 m0, s14
	s_nop 0
	global_load_lds_dwordx4 v132, s[12:13]
	s_add_i32 m0, s14, 0x2000
	s_setprio 1
	global_load_lds_dwordx4 v128, s[12:13]
	s_waitcnt vmcnt(6)
	s_barrier
	v_mfma_f32_16x16x32_bf16 v[52:55], v[202:205], v[168:171], v[52:55]
	v_mfma_f32_16x16x32_bf16 v[48:51], v[210:213], v[168:171], v[48:51]
	ds_read_b128 v[152:155], v149
	v_mfma_f32_16x16x32_bf16 v[36:39], v[202:205], v[176:179], v[36:39]
	v_mfma_f32_16x16x32_bf16 v[32:35], v[210:213], v[176:179], v[32:35]
	ds_read_b128 v[156:159], v149 offset:1024
	v_mfma_f32_16x16x32_bf16 v[20:23], v[202:205], v[184:187], v[20:23]
	v_mfma_f32_16x16x32_bf16 v[16:19], v[210:213], v[184:187], v[16:19]
	ds_read_b128 v[160:163], v149 offset:2048
	v_mfma_f32_16x16x32_bf16 v[4:7], v[202:205], v[192:195], v[4:7]
	v_mfma_f32_16x16x32_bf16 v[0:3], v[210:213], v[192:195], v[0:3]
	ds_read_b128 v[164:167], v149 offset:3072
	v_mfma_f32_16x16x32_bf16 v[52:55], v[206:209], v[172:175], v[52:55]
	s_add_i32 s3, s3, 2
	v_mfma_f32_16x16x32_bf16 v[48:51], v[214:217], v[172:175], v[48:51]
	s_add_u32 s47, s47, 0x100
	s_addc_u32 s48, s48, 0
	v_mfma_f32_16x16x32_bf16 v[36:39], v[206:209], v[180:183], v[36:39]
	s_add_u32 s10, s10, 0x100
	s_addc_u32 s11, s11, 0
	v_mfma_f32_16x16x32_bf16 v[32:35], v[214:217], v[180:183], v[32:35]
	s_cmp_gt_u32 s3, 29
	v_mfma_f32_16x16x32_bf16 v[20:23], v[206:209], v[188:191], v[20:23]
	v_mfma_f32_16x16x32_bf16 v[16:19], v[214:217], v[188:191], v[16:19]
	v_mfma_f32_16x16x32_bf16 v[4:7], v[206:209], v[198:201], v[4:7]
	v_mfma_f32_16x16x32_bf16 v[0:3], v[214:217], v[198:201], v[0:3]
	s_barrier
	s_setprio 0
	s_cbranch_scc0 .LBB1_1764
	s_waitcnt lgkmcnt(0)
	v_mov_b32_e32 v152, v147
	v_mov_b32_e32 v144, v146
	s_lshl_b32 s2, s2, 8
	s_or_b32 s2, s2, s29
	v_lshl_add_u32 v144, v144, 3, s2
	s_lshl_b32 s2, s8, 8
	s_add_i32 s2, s2, s28
	v_add_u32_e32 v152, s2, v152
	v_ashrrev_i32_e32 v153, 31, v152
	v_lshlrev_b64 v[152:153], 12, v[152:153]
	v_ashrrev_i32_e32 v145, 31, v144
	v_lshl_add_u64 v[152:153], s[4:5], 0, v[152:153]
	v_lshl_add_u64 v[144:145], v[144:145], 1, v[152:153]
	global_load_dwordx4 v[160:163], v[144:145], off
	global_load_dwordx4 v[164:167], v[144:145], off offset:256
	s_mov_b64 s[98:99], 0x10000
	v_lshl_add_u64 v[154:155], v[144:145], 0, s[98:99]
	global_load_dwordx4 v[168:171], v[154:155], off
	global_load_dwordx4 v[172:175], v[154:155], off offset:256
	s_mov_b64 s[98:99], 0x20000
	v_lshl_add_u64 v[154:155], v[144:145], 0, s[98:99]
	global_load_dwordx4 v[176:179], v[154:155], off
	global_load_dwordx4 v[180:183], v[154:155], off offset:256
	s_mov_b64 s[98:99], 0x30000
	v_lshl_add_u64 v[154:155], v[144:145], 0, s[98:99]
	global_load_dwordx4 v[184:187], v[154:155], off
	global_load_dwordx4 v[188:191], v[154:155], off offset:256
	s_mov_b64 s[98:99], 0x80000
	v_lshl_add_u64 v[154:155], v[144:145], 0, s[98:99]
	global_load_dwordx4 v[192:195], v[154:155], off
	global_load_dwordx4 v[198:201], v[154:155], off offset:256
	s_mov_b64 s[98:99], 0x90000
	v_lshl_add_u64 v[154:155], v[144:145], 0, s[98:99]
	global_load_dwordx4 v[202:205], v[154:155], off
	global_load_dwordx4 v[206:209], v[154:155], off offset:256
	s_mov_b64 s[98:99], 0xa0000
	v_lshl_add_u64 v[154:155], v[144:145], 0, s[98:99]
	global_load_dwordx4 v[210:213], v[154:155], off
	global_load_dwordx4 v[214:217], v[154:155], off offset:256
	s_mov_b64 s[98:99], 0xb0000
	v_lshl_add_u64 v[154:155], v[144:145], 0, s[98:99]
	global_load_dwordx4 v[248:251], v[154:155], off
	global_load_dwordx4 v[252:255], v[154:155], off offset:256
	s_waitcnt vmcnt(15)
	s_nop 1
	v_mov_b32_e32 v152, v160
	v_mov_b32_e32 v153, v161
	v_mov_b32_e32 v154, v162
	v_mov_b32_e32 v155, v163
	s_mov_b64 s[2:3], 0x10000
	s_mov_b32 s8, s46
	s_mov_b64 s[10:11], s[6:7]
	s_mov_b64 s[12:13], s[52:53]
	s_waitcnt lgkmcnt(0)
	v_lshlrev_b32_e32 v156, 16, v152
	v_and_b32_e32 v157, 0xffff0000, v152
	v_lshlrev_b32_e32 v152, 16, v153
	v_and_b32_e32 v153, 0xffff0000, v153
	v_lshlrev_b32_e32 v158, 16, v154
	v_and_b32_e32 v159, 0xffff0000, v154
	v_lshlrev_b32_e32 v154, 16, v155
	v_and_b32_e32 v155, 0xffff0000, v155
	v_pk_add_f32 v[126:127], v[126:127], v[152:153]
	v_pk_add_f32 v[124:125], v[124:125], v[156:157]
	v_pk_add_f32 v[152:153], v[122:123], v[154:155]
	v_pk_add_f32 v[122:123], v[120:121], v[158:159]
	v_cvt_pk_bf16_f32 v120, v124, v125
	v_cvt_pk_bf16_f32 v121, v126, v127
	v_cvt_pk_bf16_f32 v122, v122, v123
	v_cvt_pk_bf16_f32 v123, v152, v153
	global_store_dwordx4 v[144:145], v[120:123], off
	s_waitcnt vmcnt(15)
; DI unsigned pack2(float a, float b) { f32x2 v = {a, b}; hwbf16x2 r = __builtin_convertvector(v, hwbf16x2); return __builtin_bit_cast(unsigned, r); }
; DI float bflo(unsigned w) { return __uint_as_float(w << 16); }
; DI float bfhi(unsigned w) { return __uint_as_float(w & 0xffff0000u); }
;     DI void operator()(const f32x4 (&acc)[2][2][4][2], const Unit& u, int wr, int wc, int fr, int fq) const {
;     ...
;             for (int m = 0; m < 4; ++m) { const size_t ro = (size_t)(row0 + ai * HALF + m * 16) * D + col0;
; #pragma unroll
;                 for (int bj = 0; bj < 2; ++bj) {
;                     f32x4 x0, x1;
;                     if constexpr (IB) { const u32x4 w = *(const u32x4*)((const bf16_t*)Xin + ro + bj * HALF);
;                         x0 = (f32x4){bflo(w[0]), bfhi(w[0]), bflo(w[1]), bfhi(w[1])}; x1 = (f32x4){bflo(w[2]), bfhi(w[2]), bflo(w[3]), bfhi(w[3])}; }
;                     else { x0 = *(const f32x4*)((const float*)Xin + ro + bj * HALF); x1 = *(const f32x4*)((const float*)Xin + ro + bj * HALF + 4); }
;                     x0 += acc[ai][bj][m][0] * sc[bj][0]; x1 += acc[ai][bj][m][1] * sc[bj][1];
;                     if constexpr (OB) { u32x4 o; o[0] = pack2(x0[0], x0[1]); o[1] = pack2(x0[2], x0[3]); o[2] = pack2(x1[0], x1[1]); o[3] = pack2(x1[2], x1[3]);
;                         *(u32x4*)((bf16_t*)Xout + ro + bj * HALF) = o; }
;                     else { *(f32x4*)((float*)Xout + ro + bj * HALF) = x0; *(f32x4*)((float*)Xout + ro + bj * HALF + 4) = x1; } } }
	s_nop 1
	v_mov_b32_e32 v120, v164
	v_mov_b32_e32 v121, v165
	v_mov_b32_e32 v122, v166
	v_mov_b32_e32 v123, v167
	s_waitcnt lgkmcnt(0)
	v_lshlrev_b32_e32 v124, 16, v120
	v_and_b32_e32 v125, 0xffff0000, v120
	v_lshlrev_b32_e32 v120, 16, v121
	v_and_b32_e32 v121, 0xffff0000, v121
	v_lshlrev_b32_e32 v126, 16, v122
	v_and_b32_e32 v127, 0xffff0000, v122
	v_lshlrev_b32_e32 v122, 16, v123
	v_and_b32_e32 v123, 0xffff0000, v123
	v_pk_add_f32 v[116:117], v[116:117], v[124:125]
	v_pk_add_f32 v[118:119], v[118:119], v[120:121]
	v_pk_add_f32 v[120:121], v[114:115], v[122:123]
	v_pk_add_f32 v[114:115], v[112:113], v[126:127]
	v_cvt_pk_bf16_f32 v112, v116, v117
	v_lshl_add_u64 v[116:117], v[144:145], 0, s[2:3]
	s_mov_b32 s2, 0x10000
	v_cvt_pk_bf16_f32 v113, v118, v119
	v_add_co_u32_e32 v118, vcc, s2, v144
	v_cvt_pk_bf16_f32 v114, v114, v115
	v_cvt_pk_bf16_f32 v115, v120, v121
	v_addc_co_u32_e32 v119, vcc, 0, v145, vcc
	global_store_dwordx4 v[144:145], v[112:115], off offset:256
	s_waitcnt vmcnt(15)
	s_nop 1
	v_mov_b32_e32 v112, v168
	v_mov_b32_e32 v113, v169
	v_mov_b32_e32 v114, v170
	v_mov_b32_e32 v115, v171
	s_mov_b64 s[2:3], 0x20000
	s_waitcnt lgkmcnt(0)
	v_lshlrev_b32_e32 v120, 16, v112
	v_and_b32_e32 v121, 0xffff0000, v112
	v_lshlrev_b32_e32 v112, 16, v113
	v_and_b32_e32 v113, 0xffff0000, v113
	v_lshlrev_b32_e32 v122, 16, v114
	v_and_b32_e32 v123, 0xffff0000, v114
	v_lshlrev_b32_e32 v114, 16, v115
	v_and_b32_e32 v115, 0xffff0000, v115
	v_pk_add_f32 v[110:111], v[110:111], v[112:113]
	v_pk_add_f32 v[108:109], v[108:109], v[120:121]
	v_pk_add_f32 v[112:113], v[106:107], v[114:115]
	v_pk_add_f32 v[106:107], v[104:105], v[122:123]
	v_cvt_pk_bf16_f32 v104, v108, v109
	v_cvt_pk_bf16_f32 v105, v110, v111
	v_cvt_pk_bf16_f32 v106, v106, v107
	v_cvt_pk_bf16_f32 v107, v112, v113
	global_store_dwordx4 v[118:119], v[104:107], off
	s_waitcnt vmcnt(15)
	s_nop 1
	v_mov_b32_e32 v104, v172
	v_mov_b32_e32 v105, v173
	v_mov_b32_e32 v106, v174
	v_mov_b32_e32 v107, v175
	s_waitcnt lgkmcnt(0)
	v_lshlrev_b32_e32 v108, 16, v104
	v_and_b32_e32 v109, 0xffff0000, v104
	v_lshlrev_b32_e32 v104, 16, v105
	v_and_b32_e32 v105, 0xffff0000, v105
	v_lshlrev_b32_e32 v110, 16, v106
	v_and_b32_e32 v111, 0xffff0000, v106
	v_lshlrev_b32_e32 v106, 16, v107
	v_and_b32_e32 v107, 0xffff0000, v107
	v_pk_add_f32 v[100:101], v[100:101], v[108:109]
	v_pk_add_f32 v[102:103], v[102:103], v[104:105]
	v_pk_add_f32 v[104:105], v[98:99], v[106:107]
	v_pk_add_f32 v[98:99], v[96:97], v[110:111]
	v_cvt_pk_bf16_f32 v96, v100, v101
	v_lshl_add_u64 v[100:101], v[144:145], 0, s[2:3]
	s_mov_b32 s2, 0x20000
	v_cvt_pk_bf16_f32 v97, v102, v103
	v_add_co_u32_e32 v102, vcc, s2, v144
	v_cvt_pk_bf16_f32 v98, v98, v99
	v_cvt_pk_bf16_f32 v99, v104, v105
	v_addc_co_u32_e32 v103, vcc, 0, v145, vcc
	global_store_dwordx4 v[116:117], v[96:99], off offset:256
	s_waitcnt vmcnt(15)
	s_nop 1
	v_mov_b32_e32 v96, v176
	v_mov_b32_e32 v97, v177
	v_mov_b32_e32 v98, v178
	v_mov_b32_e32 v99, v179
	s_mov_b64 s[2:3], 0x30000
	s_waitcnt lgkmcnt(0)
	v_lshlrev_b32_e32 v104, 16, v96
	v_and_b32_e32 v105, 0xffff0000, v96
	v_lshlrev_b32_e32 v96, 16, v97
	v_and_b32_e32 v97, 0xffff0000, v97
	v_lshlrev_b32_e32 v106, 16, v98
	v_and_b32_e32 v107, 0xffff0000, v98
	v_lshlrev_b32_e32 v98, 16, v99
	v_and_b32_e32 v99, 0xffff0000, v99
	v_pk_add_f32 v[94:95], v[94:95], v[96:97]
	v_pk_add_f32 v[92:93], v[92:93], v[104:105]
	v_pk_add_f32 v[96:97], v[90:91], v[98:99]
	v_pk_add_f32 v[90:91], v[88:89], v[106:107]
	v_cvt_pk_bf16_f32 v88, v92, v93
	v_cvt_pk_bf16_f32 v89, v94, v95
	v_cvt_pk_bf16_f32 v90, v90, v91
	v_cvt_pk_bf16_f32 v91, v96, v97
	global_store_dwordx4 v[102:103], v[88:91], off
	s_waitcnt vmcnt(15)
	s_nop 1
	v_mov_b32_e32 v88, v180
	v_mov_b32_e32 v89, v181
	v_mov_b32_e32 v90, v182
	v_mov_b32_e32 v91, v183
	s_waitcnt lgkmcnt(0)
	v_lshlrev_b32_e32 v92, 16, v88
	v_and_b32_e32 v93, 0xffff0000, v88
	v_lshlrev_b32_e32 v88, 16, v89
	v_and_b32_e32 v89, 0xffff0000, v89
	v_lshlrev_b32_e32 v94, 16, v90
	v_and_b32_e32 v95, 0xffff0000, v90
	v_lshlrev_b32_e32 v90, 16, v91
	v_and_b32_e32 v91, 0xffff0000, v91
	v_pk_add_f32 v[86:87], v[86:87], v[88:89]
	v_pk_add_f32 v[84:85], v[84:85], v[92:93]
	v_pk_add_f32 v[88:89], v[82:83], v[90:91]
	v_pk_add_f32 v[82:83], v[80:81], v[94:95]
	v_cvt_pk_bf16_f32 v80, v84, v85
	v_cvt_pk_bf16_f32 v81, v86, v87
	v_cvt_pk_bf16_f32 v82, v82, v83
	v_cvt_pk_bf16_f32 v83, v88, v89
	global_store_dwordx4 v[100:101], v[80:83], off offset:256
	s_nop 1
	v_lshl_add_u64 v[80:81], v[144:145], 0, s[2:3]
	s_mov_b32 s2, 0x30000
	v_add_co_u32_e32 v86, vcc, s2, v144
	s_mov_b64 s[2:3], 0x80000
	s_nop 0
	v_addc_co_u32_e32 v87, vcc, 0, v145, vcc
	s_waitcnt vmcnt(15)
	s_nop 1
	v_mov_b32_e32 v82, v184
	v_mov_b32_e32 v83, v185
	v_mov_b32_e32 v84, v186
	v_mov_b32_e32 v85, v187
	s_waitcnt lgkmcnt(0)
	v_lshlrev_b32_e32 v88, 16, v82
	v_and_b32_e32 v89, 0xffff0000, v82
	v_lshlrev_b32_e32 v82, 16, v83
	v_and_b32_e32 v83, 0xffff0000, v83
	v_lshlrev_b32_e32 v90, 16, v84
	v_and_b32_e32 v91, 0xffff0000, v84
	v_lshlrev_b32_e32 v84, 16, v85
	v_and_b32_e32 v85, 0xffff0000, v85
	v_pk_add_f32 v[78:79], v[78:79], v[82:83]
	v_pk_add_f32 v[76:77], v[76:77], v[88:89]
	v_pk_add_f32 v[82:83], v[74:75], v[84:85]
	v_pk_add_f32 v[74:75], v[72:73], v[90:91]
	v_cvt_pk_bf16_f32 v72, v76, v77
	v_cvt_pk_bf16_f32 v73, v78, v79
	v_cvt_pk_bf16_f32 v74, v74, v75
	v_cvt_pk_bf16_f32 v75, v82, v83
	global_store_dwordx4 v[86:87], v[72:75], off
	s_waitcnt vmcnt(15)
	s_nop 1
	v_mov_b32_e32 v72, v188
	v_mov_b32_e32 v73, v189
	v_mov_b32_e32 v74, v190
	v_mov_b32_e32 v75, v191
	s_waitcnt lgkmcnt(0)
; DI unsigned pack2(float a, float b) { f32x2 v = {a, b}; hwbf16x2 r = __builtin_convertvector(v, hwbf16x2); return __builtin_bit_cast(unsigned, r); }
; DI float bflo(unsigned w) { return __uint_as_float(w << 16); }
; DI float bfhi(unsigned w) { return __uint_as_float(w & 0xffff0000u); }
;     DI void operator()(const f32x4 (&acc)[2][2][4][2], const Unit& u, int wr, int wc, int fr, int fq) const {
;     ...
;             for (int m = 0; m < 4; ++m) { const size_t ro = (size_t)(row0 + ai * HALF + m * 16) * D + col0;
; #pragma unroll
;                 for (int bj = 0; bj < 2; ++bj) {
;                     f32x4 x0, x1;
;                     if constexpr (IB) { const u32x4 w = *(const u32x4*)((const bf16_t*)Xin + ro + bj * HALF);
;                         x0 = (f32x4){bflo(w[0]), bfhi(w[0]), bflo(w[1]), bfhi(w[1])}; x1 = (f32x4){bflo(w[2]), bfhi(w[2]), bflo(w[3]), bfhi(w[3])}; }
;                     else { x0 = *(const f32x4*)((const float*)Xin + ro + bj * HALF); x1 = *(const f32x4*)((const float*)Xin + ro + bj * HALF + 4); }
;                     x0 += acc[ai][bj][m][0] * sc[bj][0]; x1 += acc[ai][bj][m][1] * sc[bj][1];
;                     if constexpr (OB) { u32x4 o; o[0] = pack2(x0[0], x0[1]); o[1] = pack2(x0[2], x0[3]); o[2] = pack2(x1[0], x1[1]); o[3] = pack2(x1[2], x1[3]);
;                         *(u32x4*)((bf16_t*)Xout + ro + bj * HALF) = o; }
;                     else { *(f32x4*)((float*)Xout + ro + bj * HALF) = x0; *(f32x4*)((float*)Xout + ro + bj * HALF + 4) = x1; } } }
	v_lshlrev_b32_e32 v76, 16, v72
	v_and_b32_e32 v77, 0xffff0000, v72
	v_lshlrev_b32_e32 v72, 16, v73
	v_and_b32_e32 v73, 0xffff0000, v73
	v_lshlrev_b32_e32 v78, 16, v74
	v_and_b32_e32 v79, 0xffff0000, v74
	v_lshlrev_b32_e32 v74, 16, v75
	v_and_b32_e32 v75, 0xffff0000, v75
	v_pk_add_f32 v[70:71], v[70:71], v[72:73]
	v_pk_add_f32 v[68:69], v[68:69], v[76:77]
	v_pk_add_f32 v[72:73], v[66:67], v[74:75]
	v_pk_add_f32 v[66:67], v[64:65], v[78:79]
	v_cvt_pk_bf16_f32 v64, v68, v69
	v_cvt_pk_bf16_f32 v65, v70, v71
	v_cvt_pk_bf16_f32 v66, v66, v67
	v_cvt_pk_bf16_f32 v67, v72, v73
	global_store_dwordx4 v[80:81], v[64:67], off offset:256
	s_nop 1
	v_lshl_add_u64 v[64:65], v[144:145], 0, s[2:3]
	s_mov_b32 s2, 0x80000
	v_add_co_u32_e32 v70, vcc, s2, v144
	s_mov_b64 s[2:3], 0x90000
	s_nop 0
	v_addc_co_u32_e32 v71, vcc, 0, v145, vcc
	s_waitcnt vmcnt(15)
	s_nop 1
	v_mov_b32_e32 v66, v192
	v_mov_b32_e32 v67, v193
	v_mov_b32_e32 v68, v194
	v_mov_b32_e32 v69, v195
	s_waitcnt lgkmcnt(0)
	v_lshlrev_b32_e32 v72, 16, v66
	v_and_b32_e32 v73, 0xffff0000, v66
	v_lshlrev_b32_e32 v66, 16, v67
	v_and_b32_e32 v67, 0xffff0000, v67
	v_lshlrev_b32_e32 v74, 16, v68
	v_and_b32_e32 v75, 0xffff0000, v68
	v_lshlrev_b32_e32 v68, 16, v69
	v_and_b32_e32 v69, 0xffff0000, v69
	v_pk_add_f32 v[62:63], v[62:63], v[66:67]
	v_pk_add_f32 v[60:61], v[60:61], v[72:73]
	v_pk_add_f32 v[66:67], v[58:59], v[68:69]
	v_pk_add_f32 v[58:59], v[56:57], v[74:75]
	v_cvt_pk_bf16_f32 v56, v60, v61
	v_cvt_pk_bf16_f32 v57, v62, v63
	v_cvt_pk_bf16_f32 v58, v58, v59
	v_cvt_pk_bf16_f32 v59, v66, v67
	global_store_dwordx4 v[70:71], v[56:59], off
	s_waitcnt vmcnt(15)
	s_nop 1
	v_mov_b32_e32 v56, v198
	v_mov_b32_e32 v57, v199
	v_mov_b32_e32 v58, v200
	v_mov_b32_e32 v59, v201
	s_waitcnt lgkmcnt(0)
	v_lshlrev_b32_e32 v60, 16, v56
	v_and_b32_e32 v61, 0xffff0000, v56
	v_lshlrev_b32_e32 v56, 16, v57
	v_and_b32_e32 v57, 0xffff0000, v57
	v_lshlrev_b32_e32 v62, 16, v58
	v_and_b32_e32 v63, 0xffff0000, v58
	v_lshlrev_b32_e32 v58, 16, v59
	v_and_b32_e32 v59, 0xffff0000, v59
	v_pk_add_f32 v[54:55], v[54:55], v[56:57]
	v_pk_add_f32 v[52:53], v[52:53], v[60:61]
	v_pk_add_f32 v[56:57], v[50:51], v[58:59]
	v_pk_add_f32 v[50:51], v[48:49], v[62:63]
	v_cvt_pk_bf16_f32 v48, v52, v53
	v_cvt_pk_bf16_f32 v49, v54, v55
	v_cvt_pk_bf16_f32 v50, v50, v51
	v_cvt_pk_bf16_f32 v51, v56, v57
	global_store_dwordx4 v[64:65], v[48:51], off offset:256
	s_nop 1
	v_lshl_add_u64 v[48:49], v[144:145], 0, s[2:3]
	s_mov_b32 s2, 0x90000
	v_add_co_u32_e32 v54, vcc, s2, v144
	s_mov_b64 s[2:3], 0xa0000
	s_nop 0
	v_addc_co_u32_e32 v55, vcc, 0, v145, vcc
	s_waitcnt vmcnt(15)
	s_nop 1
	v_mov_b32_e32 v50, v202
	v_mov_b32_e32 v51, v203
	v_mov_b32_e32 v52, v204
	v_mov_b32_e32 v53, v205
	s_waitcnt lgkmcnt(0)
	v_lshlrev_b32_e32 v56, 16, v50
	v_and_b32_e32 v57, 0xffff0000, v50
	v_lshlrev_b32_e32 v50, 16, v51
	v_and_b32_e32 v51, 0xffff0000, v51
	v_lshlrev_b32_e32 v58, 16, v52
	v_and_b32_e32 v59, 0xffff0000, v52
	v_lshlrev_b32_e32 v52, 16, v53
	v_and_b32_e32 v53, 0xffff0000, v53
	v_pk_add_f32 v[46:47], v[46:47], v[50:51]
	v_pk_add_f32 v[44:45], v[44:45], v[56:57]
	v_pk_add_f32 v[50:51], v[42:43], v[52:53]
	v_pk_add_f32 v[42:43], v[40:41], v[58:59]
	v_cvt_pk_bf16_f32 v40, v44, v45
	v_cvt_pk_bf16_f32 v41, v46, v47
	v_cvt_pk_bf16_f32 v42, v42, v43
	v_cvt_pk_bf16_f32 v43, v50, v51
	global_store_dwordx4 v[54:55], v[40:43], off
	s_waitcnt vmcnt(15)
	s_nop 1
	v_mov_b32_e32 v40, v206
	v_mov_b32_e32 v41, v207
	v_mov_b32_e32 v42, v208
	v_mov_b32_e32 v43, v209
	s_waitcnt lgkmcnt(0)
; DI unsigned pack2(float a, float b) { f32x2 v = {a, b}; hwbf16x2 r = __builtin_convertvector(v, hwbf16x2); return __builtin_bit_cast(unsigned, r); }
; DI float bflo(unsigned w) { return __uint_as_float(w << 16); }
; DI float bfhi(unsigned w) { return __uint_as_float(w & 0xffff0000u); }
;     DI const char* a(const Unit& u) const { return (const char*)(A + (size_t)u.pm * BM * lda); }
;     DI const char* a(const Unit& u) const { return (const char*)(A + (size_t)u.pm * BM * 2048 + (u.pn >> 1) * 512); }
; #define PG8_BAR __builtin_amdgcn_s_barrier()
;     DI void operator()(const f32x4 (&acc)[2][2][4][2], const Unit& u, int wr, int wc, int fr, int fq) const {
;     ...
;             for (int m = 0; m < 4; ++m) { const size_t ro = (size_t)(row0 + ai * HALF + m * 16) * D + col0;
; #pragma unroll
;                 for (int bj = 0; bj < 2; ++bj) {
;                     f32x4 x0, x1;
;                     if constexpr (IB) { const u32x4 w = *(const u32x4*)((const bf16_t*)Xin + ro + bj * HALF);
;                         x0 = (f32x4){bflo(w[0]), bfhi(w[0]), bflo(w[1]), bfhi(w[1])}; x1 = (f32x4){bflo(w[2]), bfhi(w[2]), bflo(w[3]), bfhi(w[3])}; }
;                     else { x0 = *(const f32x4*)((const float*)Xin + ro + bj * HALF); x1 = *(const f32x4*)((const float*)Xin + ro + bj * HALF + 4); }
;                     x0 += acc[ai][bj][m][0] * sc[bj][0]; x1 += acc[ai][bj][m][1] * sc[bj][1];
;                     if constexpr (OB) { u32x4 o; o[0] = pack2(x0[0], x0[1]); o[1] = pack2(x0[2], x0[3]); o[2] = pack2(x1[0], x1[1]); o[3] = pack2(x1[2], x1[3]);
;                         *(u32x4*)((bf16_t*)Xout + ro + bj * HALF) = o; }
;                     else { *(f32x4*)((float*)Xout + ro + bj * HALF) = x0; *(f32x4*)((float*)Xout + ro + bj * HALF + 4) = x1; } } }
; template <class Map, class Epi>
; DI void gemm_phase(LAS unsigned char* lds, const Map& MP, const Epi& E, const int nM, const int nN, const int K, const int lda, const int ldb) {
;     ...
;         if (!has_next) break;
; #pragma unroll
;         for (int a = 0; a < 2; ++a)
; #pragma unroll
;             for (int b = 0; b < 2; ++b)
; #pragma unroll
;                 for (int m = 0; m < 4; ++m)
; #pragma unroll
;                     for (int n = 0; n < 2; ++n) acc[a][b][m][n] = (f32x4){0.f, 0.f, 0.f, 0.f};
;         cur = nxt; cA = nA; cB = nB; ++ui;
;     }
;     PG8_WAIT_V(0);
;     if (wr == 0) PG8_BAR;
;     PG8_BAR;
	v_lshlrev_b32_e32 v44, 16, v40
	v_and_b32_e32 v45, 0xffff0000, v40
	v_lshlrev_b32_e32 v40, 16, v41
	v_and_b32_e32 v41, 0xffff0000, v41
	v_lshlrev_b32_e32 v46, 16, v42
	v_and_b32_e32 v47, 0xffff0000, v42
	v_lshlrev_b32_e32 v42, 16, v43
	v_and_b32_e32 v43, 0xffff0000, v43
	v_pk_add_f32 v[38:39], v[38:39], v[40:41]
	v_pk_add_f32 v[36:37], v[36:37], v[44:45]
	v_pk_add_f32 v[40:41], v[34:35], v[42:43]
	v_pk_add_f32 v[34:35], v[32:33], v[46:47]
	v_cvt_pk_bf16_f32 v32, v36, v37
	v_cvt_pk_bf16_f32 v33, v38, v39
	v_cvt_pk_bf16_f32 v34, v34, v35
	v_cvt_pk_bf16_f32 v35, v40, v41
	global_store_dwordx4 v[48:49], v[32:35], off offset:256
	s_nop 1
	v_lshl_add_u64 v[32:33], v[144:145], 0, s[2:3]
	s_mov_b32 s2, 0xa0000
	v_add_co_u32_e32 v38, vcc, s2, v144
	s_mov_b64 s[2:3], 0xb0000
	s_nop 0
	v_addc_co_u32_e32 v39, vcc, 0, v145, vcc
	s_waitcnt vmcnt(15)
	s_nop 1
	v_mov_b32_e32 v34, v210
	v_mov_b32_e32 v35, v211
	v_mov_b32_e32 v36, v212
	v_mov_b32_e32 v37, v213
	s_waitcnt lgkmcnt(0)
	v_lshlrev_b32_e32 v40, 16, v34
	v_and_b32_e32 v41, 0xffff0000, v34
	v_lshlrev_b32_e32 v34, 16, v35
	v_and_b32_e32 v35, 0xffff0000, v35
	v_lshlrev_b32_e32 v42, 16, v36
	v_and_b32_e32 v43, 0xffff0000, v36
	v_lshlrev_b32_e32 v36, 16, v37
	v_and_b32_e32 v37, 0xffff0000, v37
	v_pk_add_f32 v[30:31], v[30:31], v[34:35]
	v_pk_add_f32 v[28:29], v[28:29], v[40:41]
	v_pk_add_f32 v[34:35], v[26:27], v[36:37]
	v_pk_add_f32 v[26:27], v[24:25], v[42:43]
	v_cvt_pk_bf16_f32 v24, v28, v29
	v_cvt_pk_bf16_f32 v25, v30, v31
	v_cvt_pk_bf16_f32 v26, v26, v27
	v_cvt_pk_bf16_f32 v27, v34, v35
	global_store_dwordx4 v[38:39], v[24:27], off
	s_waitcnt vmcnt(15)
	s_nop 1
	v_mov_b32_e32 v24, v214
	v_mov_b32_e32 v25, v215
	v_mov_b32_e32 v26, v216
	v_mov_b32_e32 v27, v217
	s_waitcnt lgkmcnt(0)
	v_lshlrev_b32_e32 v28, 16, v24
	v_and_b32_e32 v29, 0xffff0000, v24
	v_lshlrev_b32_e32 v24, 16, v25
	v_and_b32_e32 v25, 0xffff0000, v25
	v_lshlrev_b32_e32 v30, 16, v26
	v_and_b32_e32 v31, 0xffff0000, v26
	v_lshlrev_b32_e32 v26, 16, v27
	v_and_b32_e32 v27, 0xffff0000, v27
	v_pk_add_f32 v[22:23], v[22:23], v[24:25]
	v_pk_add_f32 v[20:21], v[20:21], v[28:29]
	v_pk_add_f32 v[24:25], v[18:19], v[26:27]
	v_pk_add_f32 v[18:19], v[16:17], v[30:31]
	v_cvt_pk_bf16_f32 v16, v20, v21
	v_cvt_pk_bf16_f32 v17, v22, v23
	v_cvt_pk_bf16_f32 v18, v18, v19
	v_cvt_pk_bf16_f32 v19, v24, v25
	global_store_dwordx4 v[32:33], v[16:19], off offset:256
	s_nop 1
	v_lshl_add_u64 v[16:17], v[144:145], 0, s[2:3]
	s_mov_b32 s2, 0xb0000
	v_add_co_u32_e32 v22, vcc, s2, v144
	s_mov_b32 s2, s44
	s_nop 0
	v_addc_co_u32_e32 v23, vcc, 0, v145, vcc
	s_waitcnt vmcnt(15)
	s_nop 1
	v_mov_b32_e32 v18, v248
	v_mov_b32_e32 v19, v249
	v_mov_b32_e32 v20, v250
	v_mov_b32_e32 v21, v251
	s_and_b64 vcc, exec, s[40:41]
	s_waitcnt lgkmcnt(0)
	v_lshlrev_b32_e32 v24, 16, v18
	v_and_b32_e32 v25, 0xffff0000, v18
	v_lshlrev_b32_e32 v18, 16, v19
	v_and_b32_e32 v19, 0xffff0000, v19
	v_lshlrev_b32_e32 v26, 16, v20
	v_and_b32_e32 v27, 0xffff0000, v20
	v_lshlrev_b32_e32 v20, 16, v21
	v_and_b32_e32 v21, 0xffff0000, v21
	v_pk_add_f32 v[14:15], v[14:15], v[18:19]
	v_pk_add_f32 v[12:13], v[12:13], v[24:25]
	v_pk_add_f32 v[18:19], v[10:11], v[20:21]
	v_pk_add_f32 v[10:11], v[8:9], v[26:27]
	v_cvt_pk_bf16_f32 v8, v12, v13
	v_cvt_pk_bf16_f32 v9, v14, v15
	v_cvt_pk_bf16_f32 v10, v10, v11
	v_cvt_pk_bf16_f32 v11, v18, v19
	global_store_dwordx4 v[22:23], v[8:11], off
	s_waitcnt vmcnt(15)
	s_nop 1
	v_mov_b32_e32 v8, v252
	v_mov_b32_e32 v9, v253
	v_mov_b32_e32 v10, v254
	v_mov_b32_e32 v11, v255
	s_waitcnt lgkmcnt(0)
	v_lshlrev_b32_e32 v12, 16, v8
	v_and_b32_e32 v13, 0xffff0000, v8
	v_lshlrev_b32_e32 v8, 16, v9
	v_and_b32_e32 v9, 0xffff0000, v9
	v_lshlrev_b32_e32 v14, 16, v10
	v_and_b32_e32 v15, 0xffff0000, v10
	v_lshlrev_b32_e32 v10, 16, v11
	v_and_b32_e32 v11, 0xffff0000, v11
	v_pk_add_f32 v[6:7], v[6:7], v[8:9]
	v_pk_add_f32 v[4:5], v[4:5], v[12:13]
	v_pk_add_f32 v[8:9], v[2:3], v[10:11]
	v_pk_add_f32 v[2:3], v[0:1], v[14:15]
	v_cvt_pk_bf16_f32 v0, v4, v5
	v_cvt_pk_bf16_f32 v1, v6, v7
	v_cvt_pk_bf16_f32 v2, v2, v3
	v_cvt_pk_bf16_f32 v3, v8, v9
	global_store_dwordx4 v[16:17], v[0:3], off offset:256
	s_cbranch_vccz .LBB1_1761
	s_waitcnt vmcnt(0)
	s_cmpk_gt_u32 s17, 0xff
	s_cbranch_scc1 .LBB1_1768
	s_barrier

; #define PG8_STAGE(bufoff, gbase, voff) do { _Pragma("unroll") for (int _i = 0; _i < 2; ++_i) \
;         __builtin_amdgcn_global_load_lds((const unsigned*)((const char*)(gbase) + (voff)[_i]), (LAS unsigned*)(lds + (bufoff) + ldsw + _i * 8192), 16, 0, 0); } while (0)
; #define PG8_LDA(dst, b, h) do { _Pragma("unroll") for (int m = 0; m < 4; ++m) _Pragma("unroll") for (int k = 0; k < 2; ++k) dst[m][k] = *(const LAS bf16x8*)(lds + PG8_SA(b, h) + aoff + m * 2048 + k * 1024); } while (0)
; #define PG8_LDB(dst, b, h) do { _Pragma("unroll") for (int n = 0; n < 2; ++n) _Pragma("unroll") for (int k = 0; k < 2; ++k) dst[n][k] = *(const LAS bf16x8*)(lds + PG8_SB(b, h) + boff + n * 2048 + k * 1024); } while (0)
; #define PG8_MMA(ai, bj, At, Bt) do { __builtin_amdgcn_s_setprio(1); _Pragma("unroll") for (int m = 0; m < 4; ++m) _Pragma("unroll") for (int n = 0; n < 2; ++n) _Pragma("unroll") for (int k = 0; k < 2; ++k) \
;         acc[ai][bj][m][n] = __builtin_amdgcn_mfma_f32_16x16x32_bf16(Bt[n][k], At[m][k], acc[ai][bj][m][n], 0, 0, 0); __builtin_amdgcn_s_setprio(0); } while (0)
; #define PG8_WAIT_L(n) asm volatile("s_waitcnt lgkmcnt(" #n ")" ::: "memory")
; #define PG8_BAR __builtin_amdgcn_s_barrier()
; #define PG8_SCHED __builtin_amdgcn_sched_barrier(0)
; template <class Map, class Epi>
; DI void gemm_phase(LAS unsigned char* lds, const Map& MP, const Epi& E, const int nM, const int nN, const int K, const int lda, const int ldb) {
;     ...
;         for (int t = 0; t < nt; t += 2) {
;             const bool last = (t == nt - 2);
;             const char* a1 = cA + (size_t)(t + 1) * kstep;
;             const char* a2 = last ? nA : cA + (size_t)(t + 2) * kstep; const char* b2 = last ? nB : cB + (size_t)(t + 2) * kstep;
;             const char* a3 = a2 + kstep; const char* b3 = b2 + kstep;
;             PG8_LDB(B0, 0, 0); PG8_SCHED; PG8_LDA(At, 0, 0); PG8_STAGE(PG8_SA(1, 1), a1 + hstepA, voffA);
;             PG8_WAIT_L(8); PG8_BAR; PG8_WAIT_L(0); PG8_MMA(0, 0, At, B0); PG8_BAR; PG8_SCHED;
;             PG8_LDB(B1, 0, 1); PG8_STAGE(PG8_SB(0, 0), b2, voffB);
;             PG8_BAR; PG8_WAIT_L(0); PG8_MMA(0, 1, At, B1); PG8_BAR;
;             PG8_LDA(At, 0, 1); PG8_STAGE(PG8_SA(0, 0), a2, voffA);
;             PG8_BAR; PG8_WAIT_L(0); PG8_MMA(1, 0, At, B0); PG8_BAR; PG8_SCHED;
.LBB1_1908:
	s_add_u32 s28, s42, 0xfff80080
	s_addc_u32 s29, s43, -1
	s_cmp_eq_u32 s3, 28
	s_cselect_b32 s47, s23, s29
	s_cselect_b32 s46, s58, s28
	s_cselect_b32 s29, s21, vcc_hi
	s_cselect_b32 s28, s59, vcc_lo
	s_add_i32 m0, s38, 0xc000
	ds_read_b128 v[96:99], v190
	ds_read_b128 v[100:103], v190 offset:1024
	ds_read_b128 v[108:111], v190 offset:2048
	ds_read_b128 v[112:115], v190 offset:3072
	ds_read_b128 v[160:163], v190 offset:4096
	ds_read_b128 v[164:167], v190 offset:5120
	ds_read_b128 v[198:201], v190 offset:6144
	ds_read_b128 v[202:205], v190 offset:7168
	global_load_lds_dwordx4 v178, s[42:43]
	s_add_i32 m0, s38, 0xe000
	s_setprio 1
	global_load_lds_dwordx4 v176, s[42:43]
	s_waitcnt lgkmcnt(8)
	s_barrier
	s_waitcnt lgkmcnt(7)
	v_mfma_f32_16x16x32_bf16 v[148:151], v[80:83], v[96:99], v[148:151]
	v_mfma_f32_16x16x32_bf16 v[144:147], v[88:91], v[96:99], v[144:147]
	s_waitcnt lgkmcnt(5)
	v_mfma_f32_16x16x32_bf16 v[136:139], v[80:83], v[108:111], v[136:139]
	v_mfma_f32_16x16x32_bf16 v[128:131], v[88:91], v[108:111], v[128:131]
	s_waitcnt lgkmcnt(3)
	v_mfma_f32_16x16x32_bf16 v[120:123], v[80:83], v[160:163], v[120:123]
	v_mfma_f32_16x16x32_bf16 v[104:107], v[88:91], v[160:163], v[104:107]
	s_waitcnt lgkmcnt(1)
	v_mfma_f32_16x16x32_bf16 v[76:79], v[80:83], v[198:201], v[76:79]
	v_mfma_f32_16x16x32_bf16 v[72:75], v[88:91], v[198:201], v[72:75]
	v_mfma_f32_16x16x32_bf16 v[148:151], v[84:87], v[100:103], v[148:151]
	s_add_i32 s68, s2, s54
	v_mfma_f32_16x16x32_bf16 v[144:147], v[92:95], v[100:103], v[144:147]
	v_lshl_add_u64 v[184:185], s[28:29], 0, v[172:173]
	v_mfma_f32_16x16x32_bf16 v[136:139], v[84:87], v[112:115], v[136:139]
	v_lshl_add_u64 v[194:195], s[28:29], 0, v[168:169]
	v_mfma_f32_16x16x32_bf16 v[128:131], v[92:95], v[112:115], v[128:131]
	v_mfma_f32_16x16x32_bf16 v[120:123], v[84:87], v[164:167], v[120:123]
	v_mfma_f32_16x16x32_bf16 v[104:107], v[92:95], v[164:167], v[104:107]
	s_waitcnt lgkmcnt(0)
	v_mfma_f32_16x16x32_bf16 v[76:79], v[84:87], v[202:205], v[76:79]
	v_mfma_f32_16x16x32_bf16 v[72:75], v[92:95], v[202:205], v[72:75]
	s_barrier
	s_setprio 0
	s_mov_b32 m0, s68
	ds_read_b128 v[206:209], v191
	ds_read_b128 v[210:213], v191 offset:1024
	ds_read_b128 v[214:217], v191 offset:2048
	ds_read_b128 v[218:221], v191 offset:3072
	global_load_lds_dwordx4 v[184:185], off
	s_add_i32 m0, s68, 0x2000
	s_setprio 1
	global_load_lds_dwordx4 v[194:195], off
	s_barrier
	s_waitcnt lgkmcnt(3)
	v_mfma_f32_16x16x32_bf16 v[156:159], v[206:209], v[96:99], v[156:159]
	s_waitcnt lgkmcnt(1)
	v_mfma_f32_16x16x32_bf16 v[96:99], v[214:217], v[96:99], v[152:155]
	v_mfma_f32_16x16x32_bf16 v[156:159], v[210:213], v[100:103], v[156:159]
	s_waitcnt lgkmcnt(0)
	v_mfma_f32_16x16x32_bf16 v[96:99], v[218:221], v[100:103], v[96:99]
	v_mfma_f32_16x16x32_bf16 v[100:103], v[206:209], v[108:111], v[140:143]
	v_mfma_f32_16x16x32_bf16 v[108:111], v[214:217], v[108:111], v[132:135]
	v_mfma_f32_16x16x32_bf16 v[116:119], v[214:217], v[160:163], v[116:119]
	v_mfma_f32_16x16x32_bf16 v[68:71], v[206:209], v[198:201], v[68:71]
	v_mfma_f32_16x16x32_bf16 v[64:67], v[214:217], v[198:201], v[64:67]
	v_lshl_add_u64 v[234:235], s[46:47], 0, v[170:171]
	s_mov_b32 m0, s38
	v_mfma_f32_16x16x32_bf16 v[100:103], v[210:213], v[112:115], v[100:103]
	v_lshl_add_u64 v[226:227], s[46:47], 0, v[174:175]
	v_mfma_f32_16x16x32_bf16 v[108:111], v[218:221], v[112:115], v[108:111]
	v_mfma_f32_16x16x32_bf16 v[112:115], v[206:209], v[160:163], v[124:127]
	v_mfma_f32_16x16x32_bf16 v[116:119], v[218:221], v[164:167], v[116:119]
	v_mfma_f32_16x16x32_bf16 v[68:71], v[210:213], v[202:205], v[68:71]
	v_mfma_f32_16x16x32_bf16 v[64:67], v[218:221], v[202:205], v[64:67]
	v_mfma_f32_16x16x32_bf16 v[112:115], v[210:213], v[164:167], v[112:115]
	s_barrier
	s_setprio 0
	ds_read_b128 v[124:127], v190 offset:16384
	ds_read_b128 v[132:135], v190 offset:17408
	ds_read_b128 v[140:143], v190 offset:18432
	ds_read_b128 v[152:155], v190 offset:19456
	ds_read_b128 v[160:163], v190 offset:20480
	ds_read_b128 v[164:167], v190 offset:21504
	ds_read_b128 v[198:201], v190 offset:22528
	ds_read_b128 v[202:205], v190 offset:23552
	global_load_lds_dwordx4 v[226:227], off
	s_mov_b32 m0, s39
	s_setprio 1
	global_load_lds_dwordx4 v[234:235], off
	s_waitcnt vmcnt(10)
	s_barrier
	s_waitcnt lgkmcnt(7)
	v_mfma_f32_16x16x32_bf16 v[60:63], v[80:83], v[124:127], v[60:63]
	v_mfma_f32_16x16x32_bf16 v[48:51], v[88:91], v[124:127], v[48:51]
	s_waitcnt lgkmcnt(5)
	v_mfma_f32_16x16x32_bf16 v[40:43], v[80:83], v[140:143], v[40:43]
	v_mfma_f32_16x16x32_bf16 v[32:35], v[88:91], v[140:143], v[32:35]
	s_waitcnt lgkmcnt(3)
	v_mfma_f32_16x16x32_bf16 v[24:27], v[80:83], v[160:163], v[24:27]
	v_mfma_f32_16x16x32_bf16 v[16:19], v[88:91], v[160:163], v[16:19]
	s_waitcnt lgkmcnt(1)
	v_mfma_f32_16x16x32_bf16 v[12:15], v[80:83], v[198:201], v[12:15]
	v_mfma_f32_16x16x32_bf16 v[8:11], v[88:91], v[198:201], v[8:11]
	v_mfma_f32_16x16x32_bf16 v[60:63], v[84:87], v[132:135], v[60:63]
	s_add_u32 s68, s28, 0x80000
	s_addc_u32 s69, s29, 0
	v_mfma_f32_16x16x32_bf16 v[48:51], v[92:95], v[132:135], v[48:51]
	s_add_i32 s70, s31, s54
	v_mfma_f32_16x16x32_bf16 v[40:43], v[84:87], v[152:155], v[40:43]
	v_mfma_f32_16x16x32_bf16 v[32:35], v[92:95], v[152:155], v[32:35]
	v_mfma_f32_16x16x32_bf16 v[24:27], v[84:87], v[164:167], v[24:27]
	v_mfma_f32_16x16x32_bf16 v[16:19], v[92:95], v[164:167], v[16:19]
	s_waitcnt lgkmcnt(0)
	v_mfma_f32_16x16x32_bf16 v[12:15], v[84:87], v[202:205], v[12:15]
	v_mfma_f32_16x16x32_bf16 v[8:11], v[92:95], v[202:205], v[8:11]
	s_barrier
	s_setprio 0
	s_mov_b32 m0, s70
	s_nop 0
	global_load_lds_dwordx4 v172, s[68:69]
	s_add_i32 m0, s70, 0x2000
	s_setprio 1
	global_load_lds_dwordx4 v168, s[68:69]
	s_waitcnt vmcnt(6)
	s_barrier
; #define PG8_STAGE(bufoff, gbase, voff) do { _Pragma("unroll") for (int _i = 0; _i < 2; ++_i) \
;         __builtin_amdgcn_global_load_lds((const unsigned*)((const char*)(gbase) + (voff)[_i]), (LAS unsigned*)(lds + (bufoff) + ldsw + _i * 8192), 16, 0, 0); } while (0)
; #define PG8_LDA(dst, b, h) do { _Pragma("unroll") for (int m = 0; m < 4; ++m) _Pragma("unroll") for (int k = 0; k < 2; ++k) dst[m][k] = *(const LAS bf16x8*)(lds + PG8_SA(b, h) + aoff + m * 2048 + k * 1024); } while (0)
; #define PG8_LDB(dst, b, h) do { _Pragma("unroll") for (int n = 0; n < 2; ++n) _Pragma("unroll") for (int k = 0; k < 2; ++k) dst[n][k] = *(const LAS bf16x8*)(lds + PG8_SB(b, h) + boff + n * 2048 + k * 1024); } while (0)
; #define PG8_MMA(ai, bj, At, Bt) do { __builtin_amdgcn_s_setprio(1); _Pragma("unroll") for (int m = 0; m < 4; ++m) _Pragma("unroll") for (int n = 0; n < 2; ++n) _Pragma("unroll") for (int k = 0; k < 2; ++k) \
;         acc[ai][bj][m][n] = __builtin_amdgcn_mfma_f32_16x16x32_bf16(Bt[n][k], At[m][k], acc[ai][bj][m][n], 0, 0, 0); __builtin_amdgcn_s_setprio(0); } while (0)
; #define PG8_WAIT_V(n) asm volatile("s_waitcnt vmcnt(" #n ")" ::: "memory")
; #define PG8_WAIT_L(n) asm volatile("s_waitcnt lgkmcnt(" #n ")" ::: "memory")
; #define PG8_BAR __builtin_amdgcn_s_barrier()
; #define PG8_SCHED __builtin_amdgcn_sched_barrier(0)
; template <class Map, class Epi>
; DI void gemm_phase(LAS unsigned char* lds, const Map& MP, const Epi& E, const int nM, const int nN, const int K, const int lda, const int ldb) {
;     ...
;             PG8_BAR; PG8_WAIT_L(0); PG8_MMA(1, 0, At, B0); PG8_BAR; PG8_SCHED;
;             PG8_STAGE(PG8_SB(0, 1), b2 + hstepB, voffB);
;             PG8_WAIT_V(6); PG8_BAR; PG8_MMA(1, 1, At, B1); PG8_BAR;
;             PG8_LDB(B0, 1, 0); PG8_SCHED; PG8_LDA(At, 1, 0); PG8_STAGE(PG8_SA(0, 1), a2 + hstepA, voffA);
;             PG8_WAIT_L(8); PG8_BAR; PG8_WAIT_L(0); PG8_MMA(0, 0, At, B0); PG8_BAR; PG8_SCHED;
;             PG8_LDB(B1, 1, 1); PG8_STAGE(PG8_SB(1, 0), b3, voffB);
;             PG8_BAR; PG8_WAIT_L(0); PG8_MMA(0, 1, At, B1); PG8_BAR;
;             PG8_LDA(At, 1, 1); PG8_STAGE(PG8_SA(1, 0), a3, voffA);
	v_mfma_f32_16x16x32_bf16 v[56:59], v[206:209], v[124:127], v[56:59]
	v_mfma_f32_16x16x32_bf16 v[52:55], v[214:217], v[124:127], v[52:55]
	s_add_i32 s68, 0, 0x18000
	v_add_u32_e32 v92, s68, v188
	ds_read_b128 v[80:83], v92
	v_mfma_f32_16x16x32_bf16 v[44:47], v[206:209], v[140:143], v[44:47]
	v_mfma_f32_16x16x32_bf16 v[36:39], v[214:217], v[140:143], v[36:39]
	ds_read_b128 v[84:87], v92 offset:1024
	v_mfma_f32_16x16x32_bf16 v[28:31], v[206:209], v[160:163], v[28:31]
	v_mfma_f32_16x16x32_bf16 v[20:23], v[214:217], v[160:163], v[20:23]
	ds_read_b128 v[88:91], v92 offset:2048
	v_mfma_f32_16x16x32_bf16 v[4:7], v[206:209], v[198:201], v[4:7]
	v_mfma_f32_16x16x32_bf16 v[0:3], v[214:217], v[198:201], v[0:3]
	ds_read_b128 v[92:95], v92 offset:3072
	v_mfma_f32_16x16x32_bf16 v[56:59], v[210:213], v[132:135], v[56:59]
	s_add_u32 s46, s46, 0x80000
	s_addc_u32 s47, s47, 0
	v_mfma_f32_16x16x32_bf16 v[52:55], v[218:221], v[132:135], v[52:55]
	v_mfma_f32_16x16x32_bf16 v[44:47], v[210:213], v[152:155], v[44:47]
	v_mfma_f32_16x16x32_bf16 v[36:39], v[218:221], v[152:155], v[36:39]
	v_mfma_f32_16x16x32_bf16 v[28:31], v[210:213], v[164:167], v[28:31]
	v_mfma_f32_16x16x32_bf16 v[20:23], v[218:221], v[164:167], v[20:23]
	v_mfma_f32_16x16x32_bf16 v[4:7], v[210:213], v[202:205], v[4:7]
	v_mfma_f32_16x16x32_bf16 v[0:3], v[218:221], v[202:205], v[0:3]
	s_barrier
	s_setprio 0
	s_mov_b32 m0, s56
	ds_read_b128 v[124:127], v190 offset:32768
	ds_read_b128 v[132:135], v190 offset:33792
	ds_read_b128 v[160:163], v190 offset:34816
	ds_read_b128 v[164:167], v190 offset:35840
	ds_read_b128 v[198:201], v190 offset:36864
	ds_read_b128 v[202:205], v190 offset:37888
	ds_read_b128 v[206:209], v190 offset:38912
	ds_read_b128 v[210:213], v190 offset:39936
	global_load_lds_dwordx4 v174, s[46:47]
	s_mov_b32 m0, s57
	s_setprio 1
	global_load_lds_dwordx4 v170, s[46:47]
	s_waitcnt lgkmcnt(8)
	s_barrier
	s_waitcnt lgkmcnt(7)
	v_mfma_f32_16x16x32_bf16 v[140:143], v[80:83], v[124:127], v[148:151]
	s_waitcnt lgkmcnt(6)
	v_mfma_f32_16x16x32_bf16 v[148:151], v[84:87], v[132:135], v[140:143]
	v_mfma_f32_16x16x32_bf16 v[140:143], v[88:91], v[124:127], v[144:147]
	s_waitcnt lgkmcnt(5)
	v_mfma_f32_16x16x32_bf16 v[136:139], v[80:83], v[160:163], v[136:139]
	v_mfma_f32_16x16x32_bf16 v[128:131], v[88:91], v[160:163], v[128:131]
	s_waitcnt lgkmcnt(3)
	v_mfma_f32_16x16x32_bf16 v[120:123], v[80:83], v[198:201], v[120:123]
	v_mfma_f32_16x16x32_bf16 v[104:107], v[88:91], v[198:201], v[104:107]
	s_waitcnt lgkmcnt(1)
	v_mfma_f32_16x16x32_bf16 v[76:79], v[80:83], v[206:209], v[76:79]
	v_mfma_f32_16x16x32_bf16 v[72:75], v[88:91], v[206:209], v[72:75]
	s_add_i32 s46, 0, 0x1c000
	v_mfma_f32_16x16x32_bf16 v[144:147], v[92:95], v[132:135], v[140:143]
	v_add_u32_e32 v140, s46, v188
	v_mfma_f32_16x16x32_bf16 v[136:139], v[84:87], v[164:167], v[136:139]
	s_add_i32 s47, s68, s54
	v_mfma_f32_16x16x32_bf16 v[128:131], v[92:95], v[164:167], v[128:131]
	v_mfma_f32_16x16x32_bf16 v[120:123], v[84:87], v[202:205], v[120:123]
	v_mfma_f32_16x16x32_bf16 v[104:107], v[92:95], v[202:205], v[104:107]
	s_waitcnt lgkmcnt(0)
	v_mfma_f32_16x16x32_bf16 v[76:79], v[84:87], v[210:213], v[76:79]
	v_mfma_f32_16x16x32_bf16 v[72:75], v[92:95], v[210:213], v[72:75]
	s_barrier
	s_setprio 0
	ds_read_b128 v[214:217], v140
	ds_read_b128 v[218:221], v140 offset:1024
	ds_read_b128 v[222:225], v140 offset:2048
	ds_read_b128 v[230:233], v140 offset:3072
	v_lshl_add_u64 v[140:141], v[184:185], 0, s[14:15]
	s_mov_b32 m0, s47
	s_nop 0
	global_load_lds_dwordx4 v[140:141], off
	v_lshl_add_u64 v[140:141], v[194:195], 0, s[14:15]
	s_add_i32 m0, s47, 0x2000
	s_setprio 1
	global_load_lds_dwordx4 v[140:141], off
	s_barrier
	s_waitcnt lgkmcnt(1)
	v_mfma_f32_16x16x32_bf16 v[96:99], v[222:225], v[124:127], v[96:99]
	v_mfma_f32_16x16x32_bf16 v[140:143], v[214:217], v[124:127], v[156:159]
	s_waitcnt lgkmcnt(0)
	v_mfma_f32_16x16x32_bf16 v[152:155], v[230:233], v[132:135], v[96:99]
	v_mfma_f32_16x16x32_bf16 v[96:99], v[214:217], v[160:163], v[100:103]
	v_mfma_f32_16x16x32_bf16 v[156:159], v[218:221], v[132:135], v[140:143]
	v_mfma_f32_16x16x32_bf16 v[140:143], v[218:221], v[164:167], v[96:99]
	v_mfma_f32_16x16x32_bf16 v[96:99], v[222:225], v[160:163], v[108:111]
	v_mfma_f32_16x16x32_bf16 v[132:135], v[230:233], v[164:167], v[96:99]
	v_mfma_f32_16x16x32_bf16 v[96:99], v[214:217], v[198:201], v[112:115]
	s_mov_b32 m0, s63
	v_mfma_f32_16x16x32_bf16 v[124:127], v[218:221], v[202:205], v[96:99]
	v_lshl_add_u64 v[184:185], v[226:227], 0, s[14:15]
	v_mfma_f32_16x16x32_bf16 v[96:99], v[222:225], v[198:201], v[116:119]
	v_mfma_f32_16x16x32_bf16 v[68:71], v[214:217], v[206:209], v[68:71]
	v_mfma_f32_16x16x32_bf16 v[64:67], v[222:225], v[206:209], v[64:67]
	v_mfma_f32_16x16x32_bf16 v[116:119], v[230:233], v[202:205], v[96:99]
	v_mfma_f32_16x16x32_bf16 v[68:71], v[218:221], v[210:213], v[68:71]
	v_mfma_f32_16x16x32_bf16 v[64:67], v[230:233], v[210:213], v[64:67]
	s_barrier
	s_setprio 0
	ds_read_b128 v[96:99], v190 offset:49152
	ds_read_b128 v[100:103], v190 offset:50176
	ds_read_b128 v[108:111], v190 offset:51200
	ds_read_b128 v[112:115], v190 offset:52224
	ds_read_b128 v[160:163], v190 offset:53248
	ds_read_b128 v[164:167], v190 offset:54272
	ds_read_b128 v[198:201], v190 offset:55296
	ds_read_b128 v[202:205], v190 offset:56320
	global_load_lds_dwordx4 v[184:185], off
	v_lshl_add_u64 v[184:185], v[234:235], 0, s[14:15]
	s_mov_b32 m0, s66
	s_setprio 1
	global_load_lds_dwordx4 v[184:185], off
	s_waitcnt vmcnt(10)
	s_barrier
; #define PG8_STAGE(bufoff, gbase, voff) do { _Pragma("unroll") for (int _i = 0; _i < 2; ++_i) \
;         __builtin_amdgcn_global_load_lds((const unsigned*)((const char*)(gbase) + (voff)[_i]), (LAS unsigned*)(lds + (bufoff) + ldsw + _i * 8192), 16, 0, 0); } while (0)
; #define PG8_LDA(dst, b, h) do { _Pragma("unroll") for (int m = 0; m < 4; ++m) _Pragma("unroll") for (int k = 0; k < 2; ++k) dst[m][k] = *(const LAS bf16x8*)(lds + PG8_SA(b, h) + aoff + m * 2048 + k * 1024); } while (0)
; #define PG8_MMA(ai, bj, At, Bt) do { __builtin_amdgcn_s_setprio(1); _Pragma("unroll") for (int m = 0; m < 4; ++m) _Pragma("unroll") for (int n = 0; n < 2; ++n) _Pragma("unroll") for (int k = 0; k < 2; ++k) \
;         acc[ai][bj][m][n] = __builtin_amdgcn_mfma_f32_16x16x32_bf16(Bt[n][k], At[m][k], acc[ai][bj][m][n], 0, 0, 0); __builtin_amdgcn_s_setprio(0); } while (0)
; #define PG8_WAIT_V(n) asm volatile("s_waitcnt vmcnt(" #n ")" ::: "memory")
; #define PG8_WAIT_L(n) asm volatile("s_waitcnt lgkmcnt(" #n ")" ::: "memory")
; #define PG8_BAR __builtin_amdgcn_s_barrier()
; #define PG8_SCHED __builtin_amdgcn_sched_barrier(0)
; template <class Map, class Epi>
; DI void gemm_phase(LAS unsigned char* lds, const Map& MP, const Epi& E, const int nM, const int nN, const int K, const int lda, const int ldb) {
;     ...
;             PG8_LDA(At, 1, 1); PG8_STAGE(PG8_SA(1, 0), a3, voffA);
;             PG8_BAR; PG8_WAIT_L(0); PG8_MMA(1, 0, At, B0); PG8_BAR; PG8_SCHED;
;             PG8_STAGE(PG8_SB(1, 1), b3 + hstepB, voffB);
;             PG8_WAIT_V(6); PG8_BAR; PG8_MMA(1, 1, At, B1); PG8_BAR;
;         }
	s_waitcnt lgkmcnt(7)
	v_mfma_f32_16x16x32_bf16 v[60:63], v[80:83], v[96:99], v[60:63]
	v_mfma_f32_16x16x32_bf16 v[48:51], v[88:91], v[96:99], v[48:51]
	s_waitcnt lgkmcnt(5)
	v_mfma_f32_16x16x32_bf16 v[40:43], v[80:83], v[108:111], v[40:43]
	v_mfma_f32_16x16x32_bf16 v[32:35], v[88:91], v[108:111], v[32:35]
	s_waitcnt lgkmcnt(3)
	v_mfma_f32_16x16x32_bf16 v[24:27], v[80:83], v[160:163], v[24:27]
	v_mfma_f32_16x16x32_bf16 v[16:19], v[88:91], v[160:163], v[16:19]
	s_waitcnt lgkmcnt(1)
	v_mfma_f32_16x16x32_bf16 v[12:15], v[80:83], v[198:201], v[12:15]
	v_mfma_f32_16x16x32_bf16 v[8:11], v[88:91], v[198:201], v[8:11]
	v_mfma_f32_16x16x32_bf16 v[60:63], v[84:87], v[100:103], v[60:63]
	s_add_u32 s28, s28, 0x80080
	s_addc_u32 s29, s29, 0
	v_mfma_f32_16x16x32_bf16 v[48:51], v[92:95], v[100:103], v[48:51]
	s_add_i32 s46, s46, s54
	v_mfma_f32_16x16x32_bf16 v[40:43], v[84:87], v[112:115], v[40:43]
	v_mfma_f32_16x16x32_bf16 v[32:35], v[92:95], v[112:115], v[32:35]
	v_mfma_f32_16x16x32_bf16 v[24:27], v[84:87], v[164:167], v[24:27]
	v_mfma_f32_16x16x32_bf16 v[16:19], v[92:95], v[164:167], v[16:19]
	s_waitcnt lgkmcnt(0)
	v_mfma_f32_16x16x32_bf16 v[12:15], v[84:87], v[202:205], v[12:15]
	v_mfma_f32_16x16x32_bf16 v[8:11], v[92:95], v[202:205], v[8:11]
	s_barrier
	s_setprio 0
	s_mov_b32 m0, s46
	s_nop 0
	global_load_lds_dwordx4 v172, s[28:29]
	s_add_i32 m0, s46, 0x2000
	s_setprio 1
	global_load_lds_dwordx4 v168, s[28:29]
	s_waitcnt vmcnt(6)
	s_barrier
	v_mfma_f32_16x16x32_bf16 v[56:59], v[214:217], v[96:99], v[56:59]
	v_mfma_f32_16x16x32_bf16 v[52:55], v[222:225], v[96:99], v[52:55]
	ds_read_b128 v[80:83], v189
	v_mfma_f32_16x16x32_bf16 v[44:47], v[214:217], v[108:111], v[44:47]
	v_mfma_f32_16x16x32_bf16 v[36:39], v[222:225], v[108:111], v[36:39]
	ds_read_b128 v[84:87], v189 offset:1024
	v_mfma_f32_16x16x32_bf16 v[28:31], v[214:217], v[160:163], v[28:31]
	v_mfma_f32_16x16x32_bf16 v[20:23], v[222:225], v[160:163], v[20:23]
	ds_read_b128 v[88:91], v189 offset:2048
	v_mfma_f32_16x16x32_bf16 v[4:7], v[214:217], v[198:201], v[4:7]
	v_mfma_f32_16x16x32_bf16 v[0:3], v[222:225], v[198:201], v[0:3]
	ds_read_b128 v[92:95], v189 offset:3072
	v_mfma_f32_16x16x32_bf16 v[56:59], v[218:221], v[100:103], v[56:59]
	s_add_i32 s3, s3, 2
	v_mfma_f32_16x16x32_bf16 v[52:55], v[230:233], v[100:103], v[52:55]
	s_add_u32 vcc_lo, vcc_lo, 0x100
	s_addc_u32 vcc_hi, vcc_hi, 0
	v_mfma_f32_16x16x32_bf16 v[44:47], v[218:221], v[112:115], v[44:47]
	s_add_u32 s42, s42, 0x100
	s_addc_u32 s43, s43, 0
	v_mfma_f32_16x16x32_bf16 v[36:39], v[230:233], v[112:115], v[36:39]
	s_cmp_gt_u32 s3, 29
	v_mfma_f32_16x16x32_bf16 v[28:31], v[218:221], v[164:167], v[28:31]
	v_mfma_f32_16x16x32_bf16 v[20:23], v[230:233], v[164:167], v[20:23]
	v_mfma_f32_16x16x32_bf16 v[4:7], v[218:221], v[202:205], v[4:7]
	v_mfma_f32_16x16x32_bf16 v[0:3], v[230:233], v[202:205], v[0:3]
	s_barrier
	s_setprio 0
	s_cbranch_scc0 .LBB1_1908
; DI float silu_mul(float g, float v) { return g * v * __builtin_amdgcn_rcpf(1.0f + __builtin_amdgcn_exp2f(-LOG2E * g)); }
;     DI void operator()(const f32x4 (&acc)[2][2][4][2], const Unit& u, int wr, int wc, int fr, int fq) const {
;         const int row0 = u.pm * BM + wr * 64 + fr, ch0 = u.pn * 128 + wc * 32 + 8 * fq;
;         f32x4 w0[2], w1[2], w2[2], bb[2];
; #pragma unroll
;         for (int n = 0; n < 2; ++n) { w0[n] = *(const f32x4*)(cw + ch0 + 4 * n); w1[n] = *(const f32x4*)(cw + DFF + ch0 + 4 * n); w2[n] = *(const f32x4*)(cw + 2 * DFF + ch0 + 4 * n); bb[n] = *(const f32x4*)(cb + ch0 + 4 * n); }
; #pragma unroll
;         for (int ai = 0; ai < 2; ++ai)
; #pragma unroll
;             for (int m = 0; m < 4; ++m) {
;                 const bool efirst = (m == 0) && (fr == 0), elast = (m == 3) && (fr == 15);
;                 const int row = row0 + ai * HALF + m * 16;
;                 f32x4 gc[2];
; #pragma unroll
;                 for (int n = 0; n < 2; ++n) {
;                     const f32x4 g = acc[ai][0][m][n];
;                     const f32x4 gprev = acc[ai][0][m > 0 ? m - 1 : 0][n], gnext = acc[ai][0][m < 3 ? m + 1 : 3][n];
;                     f32x4 up, dn;
; #pragma unroll
;                     for (int e = 0; e < 4; ++e) {
;                         const float pu = (m > 0 && fr == 15) ? gprev[e] : g[e];
;                         const float pd = (m < 3 && fr == 0) ? gnext[e] : g[e];
;                         up[e] = dpp_ror1(pu); dn[e] = dpp_ror15(pd);
;                     }
;                     if (efirst) up = (f32x4){0.f, 0.f, 0.f, 0.f};
;                     if (elast) dn = (f32x4){0.f, 0.f, 0.f, 0.f};
;                     gc[n] = w0[n] * up + w1[n] * g + w2[n] * dn + bb[n];
;                 }
;                 if (efirst || elast) {
;                     const size_t eo = (size_t)((row >> 6) * 2 + (elast ? 1 : 0)) * DFF + ch0;
; #pragma unroll
;                     for (int n = 0; n < 2; ++n) { *(f32x4*)(EP + eo + 4 * n) = gc[n]; *(f32x4*)(ER + eo + 4 * n) = acc[ai][0][m][n]; *(f32x4*)(EV + eo + 4 * n) = acc[ai][1][m][n]; }
;                 } else {
;                     const f32x4 v0 = acc[ai][1][m][0], v1 = acc[ai][1][m][1];
;                     u32x4 o;
;                     o[0] = pack2(silu_mul(gc[0][0], v0[0]), silu_mul(gc[0][1], v0[1])); o[1] = pack2(silu_mul(gc[0][2], v0[2]), silu_mul(gc[0][3], v0[3]));
	s_waitcnt lgkmcnt(0)
	s_lshl_b32 s21, s45, 7
	v_mov_b32_e32 v194, v186
	v_mov_b32_e32 v80, v187
	s_or_b32 s21, s21, s62
	v_lshl_add_u32 v184, v80, 3, s21
	v_ashrrev_i32_e32 v185, 31, v184
	v_lshlrev_b64 v[80:81], 2, v[184:185]
	v_lshl_add_u64 v[84:85], s[4:5], 0, v[80:81]
	v_lshl_add_u64 v[88:89], s[16:17], 0, v[80:81]
	v_lshl_add_u64 v[92:93], s[18:19], 0, v[80:81]
	v_lshl_add_u64 v[112:113], s[6:7], 0, v[80:81]
	global_load_dwordx4 v[80:83], v[84:85], off offset:16
	global_load_dwordx4 v[96:99], v[84:85], off
	s_nop 0
	global_load_dwordx4 v[84:87], v[88:89], off offset:16
	global_load_dwordx4 v[100:103], v[88:89], off
	s_nop 0
	global_load_dwordx4 v[88:91], v[92:93], off offset:16
	global_load_dwordx4 v[108:111], v[92:93], off
	s_nop 0
	global_load_dwordx4 v[92:95], v[112:113], off offset:16
	s_nop 0
	global_load_dwordx4 v[112:115], v[112:113], off
	v_cmp_eq_u32_e32 vcc, 0, v194
	s_nop 0
	s_nop 0
	v_cndmask_b32_e32 v161, v148, v136, vcc
	v_cndmask_b32_e32 v162, v149, v137, vcc
	v_cndmask_b32_e32 v163, v150, v138, vcc
	v_mov_b32_dpp v160, v161 row_ror:15 row_mask:0xf bank_mask:0xf
	s_nop 0
	s_nop 0
	v_mov_b32_dpp v161, v162 row_ror:15 row_mask:0xf bank_mask:0xf
	v_mov_b32_dpp v164, v150 row_ror:1 row_mask:0xf bank_mask:0xf
	v_cndmask_b32_e32 v165, v151, v139, vcc
	v_mov_b32_dpp v162, v163 row_ror:15 row_mask:0xf bank_mask:0xf
	v_mov_b32_dpp v195, v151 row_ror:1 row_mask:0xf bank_mask:0xf
	v_mov_b32_dpp v166, v148 row_ror:1 row_mask:0xf bank_mask:0xf
	v_mov_b32_dpp v167, v149 row_ror:1 row_mask:0xf bank_mask:0xf
	v_mov_b32_dpp v163, v165 row_ror:15 row_mask:0xf bank_mask:0xf
	v_cndmask_b32_e64 v165, v195, 0, vcc
	v_cndmask_b32_e64 v164, v164, 0, vcc
	v_cndmask_b32_e64 v167, v167, 0, vcc
	v_cndmask_b32_e64 v166, v166, 0, vcc
	s_nop 0
	s_nop 0
	v_mov_b32_dpp v195, v144 row_ror:1 row_mask:0xf bank_mask:0xf
	v_mov_b32_dpp v196, v145 row_ror:1 row_mask:0xf bank_mask:0xf
	v_mov_b32_dpp v198, v146 row_ror:1 row_mask:0xf bank_mask:0xf
	v_cndmask_b32_e32 v199, v147, v131, vcc
	v_mov_b32_dpp v200, v147 row_ror:1 row_mask:0xf bank_mask:0xf
	v_cndmask_b32_e64 v198, v198, 0, vcc
	v_cndmask_b32_e64 v201, v196, 0, vcc
	s_lshl_b32 s3, s44, 8
	s_add_i32 s3, s3, s49
	v_add_u32_e32 v193, s3, v194
	v_cmp_ne_u32_e64 s[46:47], 0, v194
	s_waitcnt vmcnt(0)
	v_pk_mul_f32 v[164:165], v[98:99], v[164:165]
	v_pk_mul_f32 v[166:167], v[96:97], v[166:167]
	v_pk_fma_f32 v[164:165], v[150:151], v[102:103], v[164:165]
	v_pk_fma_f32 v[166:167], v[148:149], v[100:101], v[166:167]
	v_pk_fma_f32 v[162:163], v[110:111], v[162:163], v[164:165]
	v_cndmask_b32_e32 v165, v144, v128, vcc
	v_pk_fma_f32 v[160:161], v[108:109], v[160:161], v[166:167]
	v_cndmask_b32_e32 v166, v145, v129, vcc
	v_mov_b32_dpp v164, v165 row_ror:15 row_mask:0xf bank_mask:0xf
	v_cndmask_b32_e32 v167, v146, v130, vcc
	v_pk_add_f32 v[162:163], v[114:115], v[162:163]
	v_mov_b32_dpp v165, v166 row_ror:15 row_mask:0xf bank_mask:0xf
	v_pk_add_f32 v[160:161], v[112:113], v[160:161]
	s_nop 0
	v_mov_b32_dpp v166, v167 row_ror:15 row_mask:0xf bank_mask:0xf
	s_nop 1
	v_mov_b32_dpp v167, v199 row_ror:15 row_mask:0xf bank_mask:0xf
	v_cndmask_b32_e64 v199, v200, 0, vcc
	v_cndmask_b32_e64 v200, v195, 0, vcc
	v_pk_mul_f32 v[200:201], v[80:81], v[200:201]
	v_pk_mul_f32 v[198:199], v[82:83], v[198:199]
	v_pk_fma_f32 v[200:201], v[144:145], v[84:85], v[200:201]
	v_pk_fma_f32 v[198:199], v[146:147], v[86:87], v[198:199]
	v_pk_fma_f32 v[164:165], v[88:89], v[164:165], v[200:201]
	v_pk_fma_f32 v[166:167], v[90:91], v[166:167], v[198:199]
	v_pk_add_f32 v[164:165], v[92:93], v[164:165]
	v_pk_add_f32 v[166:167], v[94:95], v[166:167]
	s_and_saveexec_b64 s[28:29], s[46:47]
	s_xor_b64 s[28:29], exec, s[28:29]
	s_cbranch_execz .LBB1_1911
	v_mul_f32_e32 v195, 0xbfb8aa3b, v160
	v_exp_f32_e32 v195, v195
	v_mul_f32_e32 v196, 0xbfb8aa3b, v161
	v_exp_f32_e32 v196, v196
	v_pk_mul_f32 v[160:161], v[156:157], v[160:161]
	v_add_f32_e32 v195, 1.0, v195
	v_rcp_f32_e32 v198, v195
	v_add_f32_e32 v196, 1.0, v196
	v_mul_f32_e32 v195, 0xbfb8aa3b, v162
	v_rcp_f32_e32 v199, v196
	v_exp_f32_e32 v195, v195
	v_mul_f32_e32 v196, 0xbfb8aa3b, v163
	v_exp_f32_e32 v196, v196
	v_pk_mul_f32 v[160:161], v[160:161], v[198:199]
	v_add_f32_e32 v195, 1.0, v195
	v_rcp_f32_e32 v200, v195
	v_add_f32_e32 v195, 1.0, v196
	v_rcp_f32_e32 v201, v195
	v_cvt_pk_bf16_f32 v160, v160, v161
	v_mul_f32_e32 v161, 0xbfb8aa3b, v164
	v_exp_f32_e32 v195, v161
	v_mul_f32_e32 v161, 0xbfb8aa3b, v165
	v_exp_f32_e32 v196, v161
	v_pk_mul_f32 v[162:163], v[158:159], v[162:163]
	v_pk_mul_f32 v[164:165], v[152:153], v[164:165]
	v_pk_mul_f32 v[162:163], v[162:163], v[200:201]
	s_nop 0
	v_cvt_pk_bf16_f32 v161, v162, v163
	v_add_f32_e32 v162, 1.0, v195
	v_mul_f32_e32 v195, 0xbfb8aa3b, v166
	v_add_f32_e32 v163, 1.0, v196
	v_exp_f32_e32 v195, v195
	v_mul_f32_e32 v196, 0xbfb8aa3b, v167
	v_exp_f32_e32 v196, v196
	v_rcp_f32_e32 v162, v162
	v_add_f32_e32 v195, 1.0, v195
	v_rcp_f32_e32 v198, v195
	v_add_f32_e32 v195, 1.0, v196
	v_rcp_f32_e32 v163, v163
	v_rcp_f32_e32 v199, v195
	v_pk_mul_f32 v[166:167], v[154:155], v[166:167]
	v_pk_mul_f32 v[162:163], v[164:165], v[162:163]
	v_pk_mul_f32 v[164:165], v[166:167], v[198:199]
	v_cvt_pk_bf16_f32 v162, v162, v163
	v_cvt_pk_bf16_f32 v163, v164, v165
	v_mov_b64_e32 v[164:165], s[52:53]
	v_mad_i64_i32 v[164:165], s[42:43], v193, s60, v[164:165]
	v_lshl_add_u64 v[164:165], v[184:185], 1, v[164:165]
	global_store_dwordx4 v[164:165], v[160:163], off

; #define PG8_STAGE(bufoff, gbase, voff) do { _Pragma("unroll") for (int _i = 0; _i < 2; ++_i) \
;         __builtin_amdgcn_global_load_lds((const unsigned*)((const char*)(gbase) + (voff)[_i]), (LAS unsigned*)(lds + (bufoff) + ldsw + _i * 8192), 16, 0, 0); } while (0)
; #define PG8_LDA(dst, b, h) do { _Pragma("unroll") for (int m = 0; m < 4; ++m) _Pragma("unroll") for (int k = 0; k < 2; ++k) dst[m][k] = *(const LAS bf16x8*)(lds + PG8_SA(b, h) + aoff + m * 2048 + k * 1024); } while (0)
; #define PG8_LDB(dst, b, h) do { _Pragma("unroll") for (int n = 0; n < 2; ++n) _Pragma("unroll") for (int k = 0; k < 2; ++k) dst[n][k] = *(const LAS bf16x8*)(lds + PG8_SB(b, h) + boff + n * 2048 + k * 1024); } while (0)
; #define PG8_MMA(ai, bj, At, Bt) do { __builtin_amdgcn_s_setprio(1); _Pragma("unroll") for (int m = 0; m < 4; ++m) _Pragma("unroll") for (int n = 0; n < 2; ++n) _Pragma("unroll") for (int k = 0; k < 2; ++k) \
;         acc[ai][bj][m][n] = __builtin_amdgcn_mfma_f32_16x16x32_bf16(Bt[n][k], At[m][k], acc[ai][bj][m][n], 0, 0, 0); __builtin_amdgcn_s_setprio(0); } while (0)
; #define PG8_WAIT_L(n) asm volatile("s_waitcnt lgkmcnt(" #n ")" ::: "memory")
; #define PG8_BAR __builtin_amdgcn_s_barrier()
; #define PG8_SCHED __builtin_amdgcn_sched_barrier(0)
; template <class Map, class Epi>
; DI void gemm_phase(LAS unsigned char* lds, const Map& MP, const Epi& E, const int nM, const int nN, const int K, const int lda, const int ldb) {
;     ...
;         for (int t = 0; t < nt; t += 2) {
;             const bool last = (t == nt - 2);
;             const char* a1 = cA + (size_t)(t + 1) * kstep;
;             const char* a2 = last ? nA : cA + (size_t)(t + 2) * kstep; const char* b2 = last ? nB : cB + (size_t)(t + 2) * kstep;
;             const char* a3 = a2 + kstep; const char* b3 = b2 + kstep;
;             PG8_LDB(B0, 0, 0); PG8_SCHED; PG8_LDA(At, 0, 0); PG8_STAGE(PG8_SA(1, 1), a1 + hstepA, voffA);
;             PG8_WAIT_L(8); PG8_BAR; PG8_WAIT_L(0); PG8_MMA(0, 0, At, B0); PG8_BAR; PG8_SCHED;
;             PG8_LDB(B1, 0, 1); PG8_STAGE(PG8_SB(0, 0), b2, voffB);
;             PG8_BAR; PG8_WAIT_L(0); PG8_MMA(0, 1, At, B1); PG8_BAR;
;             PG8_LDA(At, 0, 1); PG8_STAGE(PG8_SA(0, 0), a2, voffA);
;             PG8_BAR; PG8_WAIT_L(0); PG8_MMA(1, 0, At, B0); PG8_BAR; PG8_SCHED;
.LBB1_2078:
	s_add_u32 s10, s8, 0x100
	s_addc_u32 s11, s9, 0
	s_cmpk_eq_i32 s3, 0x54
	s_cselect_b32 s15, s43, s11
	s_cselect_b32 s14, s42, s10
	s_cselect_b32 s13, s7, s44
	s_cselect_b32 s12, s6, s39
	s_add_i32 m0, s24, 0xc000
	ds_read_b128 v[168:171], v150
	ds_read_b128 v[172:175], v150 offset:1024
	ds_read_b128 v[176:179], v150 offset:2048
	ds_read_b128 v[180:183], v150 offset:3072
	ds_read_b128 v[184:187], v150 offset:4096
	ds_read_b128 v[188:191], v150 offset:5120
	ds_read_b128 v[192:195], v150 offset:6144
	ds_read_b128 v[198:201], v150 offset:7168
	global_load_lds_dwordx4 v138, s[8:9]
	s_add_i32 m0, s24, 0xe000
	s_setprio 1
	global_load_lds_dwordx4 v136, s[8:9]
	s_waitcnt lgkmcnt(8)
	s_barrier
	s_waitcnt lgkmcnt(7)
	v_mfma_f32_16x16x32_bf16 v[124:127], v[152:155], v[168:171], v[124:127]
	v_mfma_f32_16x16x32_bf16 v[120:123], v[160:163], v[168:171], v[120:123]
	s_waitcnt lgkmcnt(5)
	v_mfma_f32_16x16x32_bf16 v[108:111], v[152:155], v[176:179], v[108:111]
	v_mfma_f32_16x16x32_bf16 v[104:107], v[160:163], v[176:179], v[104:107]
	s_waitcnt lgkmcnt(3)
	v_mfma_f32_16x16x32_bf16 v[92:95], v[152:155], v[184:187], v[92:95]
	v_mfma_f32_16x16x32_bf16 v[88:91], v[160:163], v[184:187], v[88:91]
	s_waitcnt lgkmcnt(1)
	v_mfma_f32_16x16x32_bf16 v[76:79], v[152:155], v[192:195], v[76:79]
	v_mfma_f32_16x16x32_bf16 v[72:75], v[160:163], v[192:195], v[72:75]
	v_mfma_f32_16x16x32_bf16 v[124:127], v[156:159], v[172:175], v[124:127]
	s_add_i32 s8, s35, s22
	v_mfma_f32_16x16x32_bf16 v[120:123], v[164:167], v[172:175], v[120:123]
	v_lshl_add_u64 v[144:145], s[12:13], 0, v[132:133]
	v_mfma_f32_16x16x32_bf16 v[108:111], v[156:159], v[180:183], v[108:111]
	v_lshl_add_u64 v[218:219], s[12:13], 0, v[128:129]
	v_mfma_f32_16x16x32_bf16 v[104:107], v[164:167], v[180:183], v[104:107]
	v_mfma_f32_16x16x32_bf16 v[92:95], v[156:159], v[188:191], v[92:95]
	v_mfma_f32_16x16x32_bf16 v[88:91], v[164:167], v[188:191], v[88:91]
	s_waitcnt lgkmcnt(0)
	v_mfma_f32_16x16x32_bf16 v[76:79], v[156:159], v[198:201], v[76:79]
	v_mfma_f32_16x16x32_bf16 v[72:75], v[164:167], v[198:201], v[72:75]
	s_barrier
	s_setprio 0
	s_mov_b32 m0, s8
	ds_read_b128 v[202:205], v151
	ds_read_b128 v[206:209], v151 offset:1024
	ds_read_b128 v[210:213], v151 offset:2048
	ds_read_b128 v[214:217], v151 offset:3072
	global_load_lds_dwordx4 v[144:145], off
	s_add_i32 m0, s8, 0x2000
	s_setprio 1
	global_load_lds_dwordx4 v[218:219], off
	s_barrier
	s_waitcnt lgkmcnt(3)
	v_mfma_f32_16x16x32_bf16 v[116:119], v[202:205], v[168:171], v[116:119]
	s_waitcnt lgkmcnt(1)
	v_mfma_f32_16x16x32_bf16 v[112:115], v[210:213], v[168:171], v[112:115]
	v_mfma_f32_16x16x32_bf16 v[100:103], v[202:205], v[176:179], v[100:103]
	v_mfma_f32_16x16x32_bf16 v[96:99], v[210:213], v[176:179], v[96:99]
	v_mfma_f32_16x16x32_bf16 v[84:87], v[202:205], v[184:187], v[84:87]
	v_mfma_f32_16x16x32_bf16 v[80:83], v[210:213], v[184:187], v[80:83]
	v_mfma_f32_16x16x32_bf16 v[68:71], v[202:205], v[192:195], v[68:71]
	v_mfma_f32_16x16x32_bf16 v[64:67], v[210:213], v[192:195], v[64:67]
	v_mfma_f32_16x16x32_bf16 v[116:119], v[206:209], v[172:175], v[116:119]
	v_lshl_add_u64 v[222:223], s[14:15], 0, v[130:131]
	s_mov_b32 m0, s24
	s_waitcnt lgkmcnt(0)
	v_mfma_f32_16x16x32_bf16 v[112:115], v[214:217], v[172:175], v[112:115]
	v_lshl_add_u64 v[220:221], s[14:15], 0, v[134:135]
	v_mfma_f32_16x16x32_bf16 v[100:103], v[206:209], v[180:183], v[100:103]
	v_mfma_f32_16x16x32_bf16 v[96:99], v[214:217], v[180:183], v[96:99]
	v_mfma_f32_16x16x32_bf16 v[84:87], v[206:209], v[188:191], v[84:87]
	v_mfma_f32_16x16x32_bf16 v[80:83], v[214:217], v[188:191], v[80:83]
	v_mfma_f32_16x16x32_bf16 v[68:71], v[206:209], v[198:201], v[68:71]
	v_mfma_f32_16x16x32_bf16 v[64:67], v[214:217], v[198:201], v[64:67]
	s_barrier
	s_setprio 0
	ds_read_b128 v[168:171], v150 offset:16384
	ds_read_b128 v[172:175], v150 offset:17408
	ds_read_b128 v[176:179], v150 offset:18432
	ds_read_b128 v[180:183], v150 offset:19456
	ds_read_b128 v[184:187], v150 offset:20480
	ds_read_b128 v[188:191], v150 offset:21504
	ds_read_b128 v[192:195], v150 offset:22528
	ds_read_b128 v[198:201], v150 offset:23552
	global_load_lds_dwordx4 v[220:221], off
	s_mov_b32 m0, s25
	s_setprio 1
	global_load_lds_dwordx4 v[222:223], off
	s_waitcnt vmcnt(10)
	s_barrier
	s_waitcnt lgkmcnt(7)
	v_mfma_f32_16x16x32_bf16 v[60:63], v[152:155], v[168:171], v[60:63]
	v_mfma_f32_16x16x32_bf16 v[56:59], v[160:163], v[168:171], v[56:59]
	s_waitcnt lgkmcnt(5)
	v_mfma_f32_16x16x32_bf16 v[44:47], v[152:155], v[176:179], v[44:47]
	v_mfma_f32_16x16x32_bf16 v[40:43], v[160:163], v[176:179], v[40:43]
	s_waitcnt lgkmcnt(3)
	v_mfma_f32_16x16x32_bf16 v[28:31], v[152:155], v[184:187], v[28:31]
	v_mfma_f32_16x16x32_bf16 v[24:27], v[160:163], v[184:187], v[24:27]
	s_waitcnt lgkmcnt(1)
	v_mfma_f32_16x16x32_bf16 v[12:15], v[152:155], v[192:195], v[12:15]
	v_mfma_f32_16x16x32_bf16 v[8:11], v[160:163], v[192:195], v[8:11]
	v_mfma_f32_16x16x32_bf16 v[60:63], v[156:159], v[172:175], v[60:63]
	s_add_u32 s8, s12, 0x160000
	s_addc_u32 s9, s13, 0
	v_mfma_f32_16x16x32_bf16 v[56:59], v[164:167], v[172:175], v[56:59]
	s_add_i32 s45, s36, s22
	v_mfma_f32_16x16x32_bf16 v[44:47], v[156:159], v[180:183], v[44:47]
	v_mfma_f32_16x16x32_bf16 v[40:43], v[164:167], v[180:183], v[40:43]
	v_mfma_f32_16x16x32_bf16 v[28:31], v[156:159], v[188:191], v[28:31]
	v_mfma_f32_16x16x32_bf16 v[24:27], v[164:167], v[188:191], v[24:27]
	s_waitcnt lgkmcnt(0)
	v_mfma_f32_16x16x32_bf16 v[12:15], v[156:159], v[198:201], v[12:15]
	v_mfma_f32_16x16x32_bf16 v[8:11], v[164:167], v[198:201], v[8:11]
	s_barrier
; #define PG8_STAGE(bufoff, gbase, voff) do { _Pragma("unroll") for (int _i = 0; _i < 2; ++_i) \
;         __builtin_amdgcn_global_load_lds((const unsigned*)((const char*)(gbase) + (voff)[_i]), (LAS unsigned*)(lds + (bufoff) + ldsw + _i * 8192), 16, 0, 0); } while (0)
; #define PG8_LDA(dst, b, h) do { _Pragma("unroll") for (int m = 0; m < 4; ++m) _Pragma("unroll") for (int k = 0; k < 2; ++k) dst[m][k] = *(const LAS bf16x8*)(lds + PG8_SA(b, h) + aoff + m * 2048 + k * 1024); } while (0)
; #define PG8_LDB(dst, b, h) do { _Pragma("unroll") for (int n = 0; n < 2; ++n) _Pragma("unroll") for (int k = 0; k < 2; ++k) dst[n][k] = *(const LAS bf16x8*)(lds + PG8_SB(b, h) + boff + n * 2048 + k * 1024); } while (0)
; #define PG8_MMA(ai, bj, At, Bt) do { __builtin_amdgcn_s_setprio(1); _Pragma("unroll") for (int m = 0; m < 4; ++m) _Pragma("unroll") for (int n = 0; n < 2; ++n) _Pragma("unroll") for (int k = 0; k < 2; ++k) \
;         acc[ai][bj][m][n] = __builtin_amdgcn_mfma_f32_16x16x32_bf16(Bt[n][k], At[m][k], acc[ai][bj][m][n], 0, 0, 0); __builtin_amdgcn_s_setprio(0); } while (0)
; #define PG8_WAIT_V(n) asm volatile("s_waitcnt vmcnt(" #n ")" ::: "memory")
; #define PG8_WAIT_L(n) asm volatile("s_waitcnt lgkmcnt(" #n ")" ::: "memory")
; #define PG8_BAR __builtin_amdgcn_s_barrier()
; #define PG8_SCHED __builtin_amdgcn_sched_barrier(0)
; template <class Map, class Epi>
; DI void gemm_phase(LAS unsigned char* lds, const Map& MP, const Epi& E, const int nM, const int nN, const int K, const int lda, const int ldb) {
;     ...
;             PG8_STAGE(PG8_SB(0, 1), b2 + hstepB, voffB);
;             PG8_WAIT_V(6); PG8_BAR; PG8_MMA(1, 1, At, B1); PG8_BAR;
;             PG8_LDB(B0, 1, 0); PG8_SCHED; PG8_LDA(At, 1, 0); PG8_STAGE(PG8_SA(0, 1), a2 + hstepA, voffA);
;             PG8_WAIT_L(8); PG8_BAR; PG8_WAIT_L(0); PG8_MMA(0, 0, At, B0); PG8_BAR; PG8_SCHED;
;             PG8_LDB(B1, 1, 1); PG8_STAGE(PG8_SB(1, 0), b3, voffB);
;             PG8_BAR; PG8_WAIT_L(0); PG8_MMA(0, 1, At, B1); PG8_BAR;
;             PG8_LDA(At, 1, 1); PG8_STAGE(PG8_SA(1, 0), a3, voffA);
	s_setprio 0
	s_mov_b32 m0, s45
	s_nop 0
	global_load_lds_dwordx4 v132, s[8:9]
	s_add_i32 m0, s45, 0x2000
	s_setprio 1
	global_load_lds_dwordx4 v128, s[8:9]
	s_waitcnt vmcnt(6)
	s_barrier
	v_mfma_f32_16x16x32_bf16 v[52:55], v[202:205], v[168:171], v[52:55]
	v_mfma_f32_16x16x32_bf16 v[48:51], v[210:213], v[168:171], v[48:51]
	s_add_i32 s45, 0, 0x18000
	v_add_u32_e32 v164, s45, v148
	ds_read_b128 v[152:155], v164
	v_mfma_f32_16x16x32_bf16 v[36:39], v[202:205], v[176:179], v[36:39]
	v_mfma_f32_16x16x32_bf16 v[32:35], v[210:213], v[176:179], v[32:35]
	ds_read_b128 v[156:159], v164 offset:1024
	v_mfma_f32_16x16x32_bf16 v[20:23], v[202:205], v[184:187], v[20:23]
	v_mfma_f32_16x16x32_bf16 v[16:19], v[210:213], v[184:187], v[16:19]
	ds_read_b128 v[160:163], v164 offset:2048
	v_mfma_f32_16x16x32_bf16 v[4:7], v[202:205], v[192:195], v[4:7]
	v_mfma_f32_16x16x32_bf16 v[0:3], v[210:213], v[192:195], v[0:3]
	ds_read_b128 v[164:167], v164 offset:3072
	v_mfma_f32_16x16x32_bf16 v[52:55], v[206:209], v[172:175], v[52:55]
	s_add_u32 s8, s14, 0x160000
	s_addc_u32 s9, s15, 0
	v_mfma_f32_16x16x32_bf16 v[48:51], v[214:217], v[172:175], v[48:51]
	v_mfma_f32_16x16x32_bf16 v[36:39], v[206:209], v[180:183], v[36:39]
	v_mfma_f32_16x16x32_bf16 v[32:35], v[214:217], v[180:183], v[32:35]
	v_mfma_f32_16x16x32_bf16 v[20:23], v[206:209], v[188:191], v[20:23]
	v_mfma_f32_16x16x32_bf16 v[16:19], v[214:217], v[188:191], v[16:19]
	v_mfma_f32_16x16x32_bf16 v[4:7], v[206:209], v[198:201], v[4:7]
	v_mfma_f32_16x16x32_bf16 v[0:3], v[214:217], v[198:201], v[0:3]
	s_barrier
	s_setprio 0
	s_mov_b32 m0, s26
	ds_read_b128 v[168:171], v150 offset:32768
	ds_read_b128 v[172:175], v150 offset:33792
	ds_read_b128 v[176:179], v150 offset:34816
	ds_read_b128 v[180:183], v150 offset:35840
	ds_read_b128 v[184:187], v150 offset:36864
	ds_read_b128 v[188:191], v150 offset:37888
	ds_read_b128 v[192:195], v150 offset:38912
	ds_read_b128 v[198:201], v150 offset:39936
	global_load_lds_dwordx4 v134, s[8:9]
	s_mov_b32 m0, s27
	s_setprio 1
	global_load_lds_dwordx4 v130, s[8:9]
	s_waitcnt lgkmcnt(8)
	s_barrier
	s_waitcnt lgkmcnt(7)
	v_mfma_f32_16x16x32_bf16 v[124:127], v[152:155], v[168:171], v[124:127]
	v_mfma_f32_16x16x32_bf16 v[120:123], v[160:163], v[168:171], v[120:123]
	s_waitcnt lgkmcnt(5)
	v_mfma_f32_16x16x32_bf16 v[108:111], v[152:155], v[176:179], v[108:111]
	v_mfma_f32_16x16x32_bf16 v[104:107], v[160:163], v[176:179], v[104:107]
	s_waitcnt lgkmcnt(3)
	v_mfma_f32_16x16x32_bf16 v[92:95], v[152:155], v[184:187], v[92:95]
	v_mfma_f32_16x16x32_bf16 v[88:91], v[160:163], v[184:187], v[88:91]
	s_waitcnt lgkmcnt(1)
	v_mfma_f32_16x16x32_bf16 v[76:79], v[152:155], v[192:195], v[76:79]
	v_mfma_f32_16x16x32_bf16 v[72:75], v[160:163], v[192:195], v[72:75]
	v_mfma_f32_16x16x32_bf16 v[124:127], v[156:159], v[172:175], v[124:127]
	s_add_i32 s14, 0, 0x1c000
	v_mfma_f32_16x16x32_bf16 v[120:123], v[164:167], v[172:175], v[120:123]
	s_add_i32 s8, s45, s22
	v_mfma_f32_16x16x32_bf16 v[108:111], v[156:159], v[180:183], v[108:111]
	v_add_u32_e32 v196, s14, v148
	v_mfma_f32_16x16x32_bf16 v[104:107], v[164:167], v[180:183], v[104:107]
	v_lshl_add_u64 v[144:145], v[144:145], 0, s[46:47]
	v_mfma_f32_16x16x32_bf16 v[92:95], v[156:159], v[188:191], v[92:95]
	v_mfma_f32_16x16x32_bf16 v[88:91], v[164:167], v[188:191], v[88:91]
	s_waitcnt lgkmcnt(0)
	v_mfma_f32_16x16x32_bf16 v[76:79], v[156:159], v[198:201], v[76:79]
	v_mfma_f32_16x16x32_bf16 v[72:75], v[164:167], v[198:201], v[72:75]
	s_barrier
	s_setprio 0
	s_mov_b32 m0, s8
	ds_read_b128 v[202:205], v196
	ds_read_b128 v[206:209], v196 offset:1024
	ds_read_b128 v[210:213], v196 offset:2048
	ds_read_b128 v[214:217], v196 offset:3072
	global_load_lds_dwordx4 v[144:145], off
	v_lshl_add_u64 v[144:145], v[218:219], 0, s[46:47]
	s_add_i32 m0, s8, 0x2000
	s_setprio 1
	global_load_lds_dwordx4 v[144:145], off
	s_barrier
	s_waitcnt lgkmcnt(3)
	v_mfma_f32_16x16x32_bf16 v[116:119], v[202:205], v[168:171], v[116:119]
	s_waitcnt lgkmcnt(1)
	v_mfma_f32_16x16x32_bf16 v[112:115], v[210:213], v[168:171], v[112:115]
	v_mfma_f32_16x16x32_bf16 v[100:103], v[202:205], v[176:179], v[100:103]
	v_mfma_f32_16x16x32_bf16 v[96:99], v[210:213], v[176:179], v[96:99]
	v_mfma_f32_16x16x32_bf16 v[84:87], v[202:205], v[184:187], v[84:87]
	v_mfma_f32_16x16x32_bf16 v[80:83], v[210:213], v[184:187], v[80:83]
	v_mfma_f32_16x16x32_bf16 v[68:71], v[202:205], v[192:195], v[68:71]
	v_mfma_f32_16x16x32_bf16 v[64:67], v[210:213], v[192:195], v[64:67]
	v_mfma_f32_16x16x32_bf16 v[116:119], v[206:209], v[172:175], v[116:119]
	s_mov_b32 m0, s30
	s_waitcnt lgkmcnt(0)
	v_mfma_f32_16x16x32_bf16 v[112:115], v[214:217], v[172:175], v[112:115]
	v_lshl_add_u64 v[144:145], v[220:221], 0, s[46:47]
	v_mfma_f32_16x16x32_bf16 v[100:103], v[206:209], v[180:183], v[100:103]
	v_mfma_f32_16x16x32_bf16 v[96:99], v[214:217], v[180:183], v[96:99]
	v_mfma_f32_16x16x32_bf16 v[84:87], v[206:209], v[188:191], v[84:87]
	v_mfma_f32_16x16x32_bf16 v[80:83], v[214:217], v[188:191], v[80:83]
	v_mfma_f32_16x16x32_bf16 v[68:71], v[206:209], v[198:201], v[68:71]
	v_mfma_f32_16x16x32_bf16 v[64:67], v[214:217], v[198:201], v[64:67]
	s_barrier
	s_setprio 0
	ds_read_b128 v[168:171], v150 offset:49152
	ds_read_b128 v[172:175], v150 offset:50176
	ds_read_b128 v[176:179], v150 offset:51200
	ds_read_b128 v[180:183], v150 offset:52224
	ds_read_b128 v[184:187], v150 offset:53248
	ds_read_b128 v[188:191], v150 offset:54272
	ds_read_b128 v[192:195], v150 offset:55296
	ds_read_b128 v[198:201], v150 offset:56320
	global_load_lds_dwordx4 v[144:145], off
	v_lshl_add_u64 v[144:145], v[222:223], 0, s[46:47]
	s_mov_b32 m0, s31
	s_setprio 1
	global_load_lds_dwordx4 v[144:145], off
	s_waitcnt vmcnt(10)
	s_barrier
; DI unsigned pack2(float a, float b) { f32x2 v = {a, b}; hwbf16x2 r = __builtin_convertvector(v, hwbf16x2); return __builtin_bit_cast(unsigned, r); }
; DI float bflo(unsigned w) { return __uint_as_float(w << 16); }
; DI float bfhi(unsigned w) { return __uint_as_float(w & 0xffff0000u); }
; #define PG8_STAGE(bufoff, gbase, voff) do { _Pragma("unroll") for (int _i = 0; _i < 2; ++_i) \
;         __builtin_amdgcn_global_load_lds((const unsigned*)((const char*)(gbase) + (voff)[_i]), (LAS unsigned*)(lds + (bufoff) + ldsw + _i * 8192), 16, 0, 0); } while (0)
; #define PG8_WAIT_V(n) asm volatile("s_waitcnt vmcnt(" #n ")" ::: "memory")
; #define PG8_WAIT_L(n) asm volatile("s_waitcnt lgkmcnt(" #n ")" ::: "memory")
;     DI void operator()(const f32x4 (&acc)[2][2][4][2], const Unit& u, int wr, int wc, int fr, int fq) const {
;     ...
;             for (int m = 0; m < 4; ++m) { const size_t ro = (size_t)(row0 + ai * HALF + m * 16) * D + col0;
; #pragma unroll
;                 for (int bj = 0; bj < 2; ++bj) {
;                     f32x4 x0, x1;
;                     if constexpr (IB) { const u32x4 w = *(const u32x4*)((const bf16_t*)Xin + ro + bj * HALF);
;                         x0 = (f32x4){bflo(w[0]), bfhi(w[0]), bflo(w[1]), bfhi(w[1])}; x1 = (f32x4){bflo(w[2]), bfhi(w[2]), bflo(w[3]), bfhi(w[3])}; }
;                     else { x0 = *(const f32x4*)((const float*)Xin + ro + bj * HALF); x1 = *(const f32x4*)((const float*)Xin + ro + bj * HALF + 4); }
;                     x0 += acc[ai][bj][m][0] * sc[bj][0]; x1 += acc[ai][bj][m][1] * sc[bj][1];
;                     if constexpr (OB) { u32x4 o; o[0] = pack2(x0[0], x0[1]); o[1] = pack2(x0[2], x0[3]); o[2] = pack2(x1[0], x1[1]); o[3] = pack2(x1[2], x1[3]);
;                         *(u32x4*)((bf16_t*)Xout + ro + bj * HALF) = o; }
;                     else { *(f32x4*)((float*)Xout + ro + bj * HALF) = x0; *(f32x4*)((float*)Xout + ro + bj * HALF + 4) = x1; } } }
; template <class Map, class Epi>
; DI void gemm_phase(LAS unsigned char* lds, const Map& MP, const Epi& E, const int nM, const int nN, const int K, const int lda, const int ldb) {
;     ...
;             PG8_LDA(At, 1, 1); PG8_STAGE(PG8_SA(1, 0), a3, voffA);
;             PG8_BAR; PG8_WAIT_L(0); PG8_MMA(1, 0, At, B0); PG8_BAR; PG8_SCHED;
;             PG8_STAGE(PG8_SB(1, 1), b3 + hstepB, voffB);
;             PG8_WAIT_V(6); PG8_BAR; PG8_MMA(1, 1, At, B1); PG8_BAR;
;         }
	s_waitcnt lgkmcnt(7)
	v_mfma_f32_16x16x32_bf16 v[60:63], v[152:155], v[168:171], v[60:63]
	v_mfma_f32_16x16x32_bf16 v[56:59], v[160:163], v[168:171], v[56:59]
	s_waitcnt lgkmcnt(5)
	v_mfma_f32_16x16x32_bf16 v[44:47], v[152:155], v[176:179], v[44:47]
	v_mfma_f32_16x16x32_bf16 v[40:43], v[160:163], v[176:179], v[40:43]
	s_waitcnt lgkmcnt(3)
	v_mfma_f32_16x16x32_bf16 v[28:31], v[152:155], v[184:187], v[28:31]
	v_mfma_f32_16x16x32_bf16 v[24:27], v[160:163], v[184:187], v[24:27]
	s_waitcnt lgkmcnt(1)
	v_mfma_f32_16x16x32_bf16 v[12:15], v[152:155], v[192:195], v[12:15]
	v_mfma_f32_16x16x32_bf16 v[8:11], v[160:163], v[192:195], v[8:11]
	v_mfma_f32_16x16x32_bf16 v[60:63], v[156:159], v[172:175], v[60:63]
	s_add_u32 s8, s12, 0x160080
	s_addc_u32 s9, s13, 0
	v_mfma_f32_16x16x32_bf16 v[56:59], v[164:167], v[172:175], v[56:59]
	s_add_i32 s12, s14, s22
	v_mfma_f32_16x16x32_bf16 v[44:47], v[156:159], v[180:183], v[44:47]
	v_mfma_f32_16x16x32_bf16 v[40:43], v[164:167], v[180:183], v[40:43]
	v_mfma_f32_16x16x32_bf16 v[28:31], v[156:159], v[188:191], v[28:31]
	v_mfma_f32_16x16x32_bf16 v[24:27], v[164:167], v[188:191], v[24:27]
	s_waitcnt lgkmcnt(0)
	v_mfma_f32_16x16x32_bf16 v[12:15], v[156:159], v[198:201], v[12:15]
	v_mfma_f32_16x16x32_bf16 v[8:11], v[164:167], v[198:201], v[8:11]
	s_barrier
	s_setprio 0
	s_mov_b32 m0, s12
	s_nop 0
	global_load_lds_dwordx4 v132, s[8:9]
	s_add_i32 m0, s12, 0x2000
	s_setprio 1
	global_load_lds_dwordx4 v128, s[8:9]
	s_waitcnt vmcnt(6)
	s_barrier
	v_mfma_f32_16x16x32_bf16 v[52:55], v[202:205], v[168:171], v[52:55]
	v_mfma_f32_16x16x32_bf16 v[48:51], v[210:213], v[168:171], v[48:51]
	ds_read_b128 v[152:155], v149
	v_mfma_f32_16x16x32_bf16 v[36:39], v[202:205], v[176:179], v[36:39]
	v_mfma_f32_16x16x32_bf16 v[32:35], v[210:213], v[176:179], v[32:35]
	ds_read_b128 v[156:159], v149 offset:1024
	v_mfma_f32_16x16x32_bf16 v[20:23], v[202:205], v[184:187], v[20:23]
	v_mfma_f32_16x16x32_bf16 v[16:19], v[210:213], v[184:187], v[16:19]
	ds_read_b128 v[160:163], v149 offset:2048
	v_mfma_f32_16x16x32_bf16 v[4:7], v[202:205], v[192:195], v[4:7]
	v_mfma_f32_16x16x32_bf16 v[0:3], v[210:213], v[192:195], v[0:3]
	ds_read_b128 v[164:167], v149 offset:3072
	v_mfma_f32_16x16x32_bf16 v[52:55], v[206:209], v[172:175], v[52:55]
	s_add_i32 s3, s3, 2
	v_mfma_f32_16x16x32_bf16 v[48:51], v[214:217], v[172:175], v[48:51]
	s_add_u32 s39, s39, 0x100
	s_addc_u32 s44, s44, 0
	v_mfma_f32_16x16x32_bf16 v[36:39], v[206:209], v[180:183], v[36:39]
	s_cmpk_gt_u32 s3, 0x55
	v_mfma_f32_16x16x32_bf16 v[32:35], v[214:217], v[180:183], v[32:35]
	s_mov_b64 s[8:9], s[10:11]
	v_mfma_f32_16x16x32_bf16 v[20:23], v[206:209], v[188:191], v[20:23]
	v_mfma_f32_16x16x32_bf16 v[16:19], v[214:217], v[188:191], v[16:19]
	v_mfma_f32_16x16x32_bf16 v[4:7], v[206:209], v[198:201], v[4:7]
	v_mfma_f32_16x16x32_bf16 v[0:3], v[214:217], v[198:201], v[0:3]
	s_barrier
	s_setprio 0
	s_cbranch_scc0 .LBB1_2078
	s_waitcnt lgkmcnt(0)
	v_mov_b32_e32 v152, v147
	v_mov_b32_e32 v144, v146
	s_lshl_b32 s2, s2, 8
	s_add_i32 s2, s2, s29
	s_lshl_b32 s3, s38, 8
	v_add_u32_e32 v152, s2, v152
	s_or_b32 s3, s3, s52
	v_ashrrev_i32_e32 v153, 31, v152
	v_lshl_add_u32 v144, v144, 3, s3
	v_lshlrev_b64 v[152:153], 12, v[152:153]
	v_ashrrev_i32_e32 v145, 31, v144
	v_lshl_add_u64 v[152:153], s[4:5], 0, v[152:153]
	v_lshl_add_u64 v[144:145], v[144:145], 1, v[152:153]
	global_load_dwordx4 v[160:163], v[144:145], off
	global_load_dwordx4 v[164:167], v[144:145], off offset:256
	s_mov_b64 s[98:99], 0x10000
	v_lshl_add_u64 v[154:155], v[144:145], 0, s[98:99]
	global_load_dwordx4 v[168:171], v[154:155], off
	global_load_dwordx4 v[172:175], v[154:155], off offset:256
	s_mov_b64 s[98:99], 0x20000
	v_lshl_add_u64 v[154:155], v[144:145], 0, s[98:99]
	global_load_dwordx4 v[176:179], v[154:155], off
	global_load_dwordx4 v[180:183], v[154:155], off offset:256
	s_mov_b64 s[98:99], 0x30000
	v_lshl_add_u64 v[154:155], v[144:145], 0, s[98:99]
	global_load_dwordx4 v[184:187], v[154:155], off
	global_load_dwordx4 v[188:191], v[154:155], off offset:256
	s_mov_b64 s[98:99], 0x80000
	v_lshl_add_u64 v[154:155], v[144:145], 0, s[98:99]
	global_load_dwordx4 v[192:195], v[154:155], off
	global_load_dwordx4 v[198:201], v[154:155], off offset:256
	s_mov_b64 s[98:99], 0x90000
	v_lshl_add_u64 v[154:155], v[144:145], 0, s[98:99]
	global_load_dwordx4 v[202:205], v[154:155], off
	global_load_dwordx4 v[206:209], v[154:155], off offset:256
	s_mov_b64 s[98:99], 0xa0000
	v_lshl_add_u64 v[154:155], v[144:145], 0, s[98:99]
	global_load_dwordx4 v[210:213], v[154:155], off
	global_load_dwordx4 v[214:217], v[154:155], off offset:256
	s_mov_b64 s[98:99], 0xb0000
	v_lshl_add_u64 v[154:155], v[144:145], 0, s[98:99]
	global_load_dwordx4 v[248:251], v[154:155], off
	global_load_dwordx4 v[252:255], v[154:155], off offset:256
	s_waitcnt vmcnt(15)
	s_nop 1
	v_mov_b32_e32 v152, v160
	v_mov_b32_e32 v153, v161
	v_mov_b32_e32 v154, v162
	v_mov_b32_e32 v155, v163
	s_mov_b64 s[2:3], 0x10000
	s_mov_b32 s38, s37
	s_mov_b64 s[10:11], s[6:7]
	s_mov_b64 s[8:9], s[42:43]
	s_waitcnt lgkmcnt(0)
	v_lshlrev_b32_e32 v156, 16, v152
	v_and_b32_e32 v157, 0xffff0000, v152
	v_lshlrev_b32_e32 v152, 16, v153
	v_and_b32_e32 v153, 0xffff0000, v153
	v_lshlrev_b32_e32 v158, 16, v154
	v_and_b32_e32 v159, 0xffff0000, v154
	v_lshlrev_b32_e32 v154, 16, v155
	v_and_b32_e32 v155, 0xffff0000, v155
	v_pk_add_f32 v[126:127], v[126:127], v[152:153]
	v_pk_add_f32 v[124:125], v[124:125], v[156:157]
	v_pk_add_f32 v[152:153], v[122:123], v[154:155]
	v_pk_add_f32 v[122:123], v[120:121], v[158:159]
	v_cvt_pk_bf16_f32 v120, v124, v125
	v_cvt_pk_bf16_f32 v121, v126, v127
	v_cvt_pk_bf16_f32 v122, v122, v123
	v_cvt_pk_bf16_f32 v123, v152, v153
	global_store_dwordx4 v[144:145], v[120:123], off
	s_waitcnt vmcnt(15)
; DI unsigned pack2(float a, float b) { f32x2 v = {a, b}; hwbf16x2 r = __builtin_convertvector(v, hwbf16x2); return __builtin_bit_cast(unsigned, r); }
; DI float bflo(unsigned w) { return __uint_as_float(w << 16); }
; DI float bfhi(unsigned w) { return __uint_as_float(w & 0xffff0000u); }
;     DI void operator()(const f32x4 (&acc)[2][2][4][2], const Unit& u, int wr, int wc, int fr, int fq) const {
;     ...
;         for (int ai = 0; ai < 2; ++ai)
; #pragma unroll
;             for (int m = 0; m < 4; ++m) { const size_t ro = (size_t)(row0 + ai * HALF + m * 16) * D + col0;
; #pragma unroll
;                 for (int bj = 0; bj < 2; ++bj) {
;                     f32x4 x0, x1;
;                     if constexpr (IB) { const u32x4 w = *(const u32x4*)((const bf16_t*)Xin + ro + bj * HALF);
;                         x0 = (f32x4){bflo(w[0]), bfhi(w[0]), bflo(w[1]), bfhi(w[1])}; x1 = (f32x4){bflo(w[2]), bfhi(w[2]), bflo(w[3]), bfhi(w[3])}; }
;                     else { x0 = *(const f32x4*)((const float*)Xin + ro + bj * HALF); x1 = *(const f32x4*)((const float*)Xin + ro + bj * HALF + 4); }
;                     x0 += acc[ai][bj][m][0] * sc[bj][0]; x1 += acc[ai][bj][m][1] * sc[bj][1];
;                     if constexpr (OB) { u32x4 o; o[0] = pack2(x0[0], x0[1]); o[1] = pack2(x0[2], x0[3]); o[2] = pack2(x1[0], x1[1]); o[3] = pack2(x1[2], x1[3]);
;                         *(u32x4*)((bf16_t*)Xout + ro + bj * HALF) = o; }
;                     else { *(f32x4*)((float*)Xout + ro + bj * HALF) = x0; *(f32x4*)((float*)Xout + ro + bj * HALF + 4) = x1; } } }
	s_nop 1
	v_mov_b32_e32 v120, v164
	v_mov_b32_e32 v121, v165
	v_mov_b32_e32 v122, v166
	v_mov_b32_e32 v123, v167
	s_waitcnt lgkmcnt(0)
	v_lshlrev_b32_e32 v124, 16, v120
	v_and_b32_e32 v125, 0xffff0000, v120
	v_lshlrev_b32_e32 v120, 16, v121
	v_and_b32_e32 v121, 0xffff0000, v121
	v_lshlrev_b32_e32 v126, 16, v122
	v_and_b32_e32 v127, 0xffff0000, v122
	v_lshlrev_b32_e32 v122, 16, v123
	v_and_b32_e32 v123, 0xffff0000, v123
	v_pk_add_f32 v[116:117], v[116:117], v[124:125]
	v_pk_add_f32 v[118:119], v[118:119], v[120:121]
	v_pk_add_f32 v[120:121], v[114:115], v[122:123]
	v_pk_add_f32 v[114:115], v[112:113], v[126:127]
	v_cvt_pk_bf16_f32 v112, v116, v117
	v_lshl_add_u64 v[116:117], v[144:145], 0, s[2:3]
	s_mov_b32 s2, 0x10000
	v_cvt_pk_bf16_f32 v113, v118, v119
	v_add_co_u32_e32 v118, vcc, s2, v144
	v_cvt_pk_bf16_f32 v114, v114, v115
	v_cvt_pk_bf16_f32 v115, v120, v121
	v_addc_co_u32_e32 v119, vcc, 0, v145, vcc
	global_store_dwordx4 v[144:145], v[112:115], off offset:256
	s_waitcnt vmcnt(15)
	s_nop 1
	v_mov_b32_e32 v112, v168
	v_mov_b32_e32 v113, v169
	v_mov_b32_e32 v114, v170
	v_mov_b32_e32 v115, v171
	s_mov_b64 s[2:3], 0x20000
	s_waitcnt lgkmcnt(0)
	v_lshlrev_b32_e32 v120, 16, v112
	v_and_b32_e32 v121, 0xffff0000, v112
	v_lshlrev_b32_e32 v112, 16, v113
	v_and_b32_e32 v113, 0xffff0000, v113
	v_lshlrev_b32_e32 v122, 16, v114
	v_and_b32_e32 v123, 0xffff0000, v114
	v_lshlrev_b32_e32 v114, 16, v115
	v_and_b32_e32 v115, 0xffff0000, v115
	v_pk_add_f32 v[110:111], v[110:111], v[112:113]
	v_pk_add_f32 v[108:109], v[108:109], v[120:121]
	v_pk_add_f32 v[112:113], v[106:107], v[114:115]
	v_pk_add_f32 v[106:107], v[104:105], v[122:123]
	v_cvt_pk_bf16_f32 v104, v108, v109
	v_cvt_pk_bf16_f32 v105, v110, v111
	v_cvt_pk_bf16_f32 v106, v106, v107
	v_cvt_pk_bf16_f32 v107, v112, v113
	global_store_dwordx4 v[118:119], v[104:107], off
	s_waitcnt vmcnt(15)
	s_nop 1
	v_mov_b32_e32 v104, v172
	v_mov_b32_e32 v105, v173
	v_mov_b32_e32 v106, v174
	v_mov_b32_e32 v107, v175
	s_waitcnt lgkmcnt(0)
	v_lshlrev_b32_e32 v108, 16, v104
	v_and_b32_e32 v109, 0xffff0000, v104
	v_lshlrev_b32_e32 v104, 16, v105
	v_and_b32_e32 v105, 0xffff0000, v105
	v_lshlrev_b32_e32 v110, 16, v106
	v_and_b32_e32 v111, 0xffff0000, v106
	v_lshlrev_b32_e32 v106, 16, v107
	v_and_b32_e32 v107, 0xffff0000, v107
	v_pk_add_f32 v[100:101], v[100:101], v[108:109]
	v_pk_add_f32 v[102:103], v[102:103], v[104:105]
	v_pk_add_f32 v[104:105], v[98:99], v[106:107]
	v_pk_add_f32 v[98:99], v[96:97], v[110:111]
	v_cvt_pk_bf16_f32 v96, v100, v101
	v_lshl_add_u64 v[100:101], v[144:145], 0, s[2:3]
	s_mov_b32 s2, 0x20000
	v_cvt_pk_bf16_f32 v97, v102, v103
	v_add_co_u32_e32 v102, vcc, s2, v144
	v_cvt_pk_bf16_f32 v98, v98, v99
	v_cvt_pk_bf16_f32 v99, v104, v105
	v_addc_co_u32_e32 v103, vcc, 0, v145, vcc
	global_store_dwordx4 v[116:117], v[96:99], off offset:256
	s_waitcnt vmcnt(15)
	s_nop 1
	v_mov_b32_e32 v96, v176
	v_mov_b32_e32 v97, v177
	v_mov_b32_e32 v98, v178
	v_mov_b32_e32 v99, v179
	s_mov_b64 s[2:3], 0x30000
	s_waitcnt lgkmcnt(0)
	v_lshlrev_b32_e32 v104, 16, v96
	v_and_b32_e32 v105, 0xffff0000, v96
	v_lshlrev_b32_e32 v96, 16, v97
	v_and_b32_e32 v97, 0xffff0000, v97
	v_lshlrev_b32_e32 v106, 16, v98
	v_and_b32_e32 v107, 0xffff0000, v98
	v_lshlrev_b32_e32 v98, 16, v99
	v_and_b32_e32 v99, 0xffff0000, v99
	v_pk_add_f32 v[94:95], v[94:95], v[96:97]
	v_pk_add_f32 v[92:93], v[92:93], v[104:105]
	v_pk_add_f32 v[96:97], v[90:91], v[98:99]
	v_pk_add_f32 v[90:91], v[88:89], v[106:107]
	v_cvt_pk_bf16_f32 v88, v92, v93
	v_cvt_pk_bf16_f32 v89, v94, v95
	v_cvt_pk_bf16_f32 v90, v90, v91
	v_cvt_pk_bf16_f32 v91, v96, v97
	global_store_dwordx4 v[102:103], v[88:91], off
	s_waitcnt vmcnt(15)
	s_nop 1
	v_mov_b32_e32 v88, v180
	v_mov_b32_e32 v89, v181
	v_mov_b32_e32 v90, v182
	v_mov_b32_e32 v91, v183
	s_waitcnt lgkmcnt(0)
	v_lshlrev_b32_e32 v92, 16, v88
	v_and_b32_e32 v93, 0xffff0000, v88
	v_lshlrev_b32_e32 v88, 16, v89
	v_and_b32_e32 v89, 0xffff0000, v89
	v_lshlrev_b32_e32 v94, 16, v90
	v_and_b32_e32 v95, 0xffff0000, v90
	v_lshlrev_b32_e32 v90, 16, v91
	v_and_b32_e32 v91, 0xffff0000, v91
	v_pk_add_f32 v[86:87], v[86:87], v[88:89]
	v_pk_add_f32 v[84:85], v[84:85], v[92:93]
	v_pk_add_f32 v[88:89], v[82:83], v[90:91]
	v_pk_add_f32 v[82:83], v[80:81], v[94:95]
	v_cvt_pk_bf16_f32 v80, v84, v85
	v_cvt_pk_bf16_f32 v81, v86, v87
	v_cvt_pk_bf16_f32 v82, v82, v83
	v_cvt_pk_bf16_f32 v83, v88, v89
	global_store_dwordx4 v[100:101], v[80:83], off offset:256
	s_nop 1
	v_lshl_add_u64 v[80:81], v[144:145], 0, s[2:3]
	s_mov_b32 s2, 0x30000
	v_add_co_u32_e32 v86, vcc, s2, v144
	s_mov_b64 s[2:3], 0x80000
	s_nop 0
	v_addc_co_u32_e32 v87, vcc, 0, v145, vcc
	s_waitcnt vmcnt(15)
	s_nop 1
	v_mov_b32_e32 v82, v184
	v_mov_b32_e32 v83, v185
	v_mov_b32_e32 v84, v186
	v_mov_b32_e32 v85, v187
	s_waitcnt lgkmcnt(0)
	v_lshlrev_b32_e32 v88, 16, v82
	v_and_b32_e32 v89, 0xffff0000, v82
	v_lshlrev_b32_e32 v82, 16, v83
	v_and_b32_e32 v83, 0xffff0000, v83
	v_lshlrev_b32_e32 v90, 16, v84
	v_and_b32_e32 v91, 0xffff0000, v84
	v_lshlrev_b32_e32 v84, 16, v85
	v_and_b32_e32 v85, 0xffff0000, v85
	v_pk_add_f32 v[78:79], v[78:79], v[82:83]
	v_pk_add_f32 v[76:77], v[76:77], v[88:89]
	v_pk_add_f32 v[82:83], v[74:75], v[84:85]
	v_pk_add_f32 v[74:75], v[72:73], v[90:91]
	v_cvt_pk_bf16_f32 v72, v76, v77
	v_cvt_pk_bf16_f32 v73, v78, v79
	v_cvt_pk_bf16_f32 v74, v74, v75
	v_cvt_pk_bf16_f32 v75, v82, v83
	global_store_dwordx4 v[86:87], v[72:75], off
	s_waitcnt vmcnt(15)
	s_nop 1
	v_mov_b32_e32 v72, v188
	v_mov_b32_e32 v73, v189
	v_mov_b32_e32 v74, v190
	v_mov_b32_e32 v75, v191
	s_waitcnt lgkmcnt(0)
; DI unsigned pack2(float a, float b) { f32x2 v = {a, b}; hwbf16x2 r = __builtin_convertvector(v, hwbf16x2); return __builtin_bit_cast(unsigned, r); }
; DI float bflo(unsigned w) { return __uint_as_float(w << 16); }
; DI float bfhi(unsigned w) { return __uint_as_float(w & 0xffff0000u); }
;     DI void operator()(const f32x4 (&acc)[2][2][4][2], const Unit& u, int wr, int wc, int fr, int fq) const {
;     ...
;         for (int ai = 0; ai < 2; ++ai)
; #pragma unroll
;             for (int m = 0; m < 4; ++m) { const size_t ro = (size_t)(row0 + ai * HALF + m * 16) * D + col0;
; #pragma unroll
;                 for (int bj = 0; bj < 2; ++bj) {
;                     f32x4 x0, x1;
;                     if constexpr (IB) { const u32x4 w = *(const u32x4*)((const bf16_t*)Xin + ro + bj * HALF);
;                         x0 = (f32x4){bflo(w[0]), bfhi(w[0]), bflo(w[1]), bfhi(w[1])}; x1 = (f32x4){bflo(w[2]), bfhi(w[2]), bflo(w[3]), bfhi(w[3])}; }
;                     else { x0 = *(const f32x4*)((const float*)Xin + ro + bj * HALF); x1 = *(const f32x4*)((const float*)Xin + ro + bj * HALF + 4); }
;                     x0 += acc[ai][bj][m][0] * sc[bj][0]; x1 += acc[ai][bj][m][1] * sc[bj][1];
;                     if constexpr (OB) { u32x4 o; o[0] = pack2(x0[0], x0[1]); o[1] = pack2(x0[2], x0[3]); o[2] = pack2(x1[0], x1[1]); o[3] = pack2(x1[2], x1[3]);
;                         *(u32x4*)((bf16_t*)Xout + ro + bj * HALF) = o; }
;                     else { *(f32x4*)((float*)Xout + ro + bj * HALF) = x0; *(f32x4*)((float*)Xout + ro + bj * HALF + 4) = x1; } } }
	v_lshlrev_b32_e32 v76, 16, v72
	v_and_b32_e32 v77, 0xffff0000, v72
	v_lshlrev_b32_e32 v72, 16, v73
	v_and_b32_e32 v73, 0xffff0000, v73
	v_lshlrev_b32_e32 v78, 16, v74
	v_and_b32_e32 v79, 0xffff0000, v74
	v_lshlrev_b32_e32 v74, 16, v75
	v_and_b32_e32 v75, 0xffff0000, v75
	v_pk_add_f32 v[70:71], v[70:71], v[72:73]
	v_pk_add_f32 v[68:69], v[68:69], v[76:77]
	v_pk_add_f32 v[72:73], v[66:67], v[74:75]
	v_pk_add_f32 v[66:67], v[64:65], v[78:79]
	v_cvt_pk_bf16_f32 v64, v68, v69
	v_cvt_pk_bf16_f32 v65, v70, v71
	v_cvt_pk_bf16_f32 v66, v66, v67
	v_cvt_pk_bf16_f32 v67, v72, v73
	global_store_dwordx4 v[80:81], v[64:67], off offset:256
	s_nop 1
	v_lshl_add_u64 v[64:65], v[144:145], 0, s[2:3]
	s_mov_b32 s2, 0x80000
	v_add_co_u32_e32 v70, vcc, s2, v144
	s_mov_b64 s[2:3], 0x90000
	s_nop 0
	v_addc_co_u32_e32 v71, vcc, 0, v145, vcc
	s_waitcnt vmcnt(15)
	s_nop 1
	v_mov_b32_e32 v66, v192
	v_mov_b32_e32 v67, v193
	v_mov_b32_e32 v68, v194
	v_mov_b32_e32 v69, v195
	s_waitcnt lgkmcnt(0)
	v_lshlrev_b32_e32 v72, 16, v66
	v_and_b32_e32 v73, 0xffff0000, v66
	v_lshlrev_b32_e32 v66, 16, v67
	v_and_b32_e32 v67, 0xffff0000, v67
	v_lshlrev_b32_e32 v74, 16, v68
	v_and_b32_e32 v75, 0xffff0000, v68
	v_lshlrev_b32_e32 v68, 16, v69
	v_and_b32_e32 v69, 0xffff0000, v69
	v_pk_add_f32 v[62:63], v[62:63], v[66:67]
	v_pk_add_f32 v[60:61], v[60:61], v[72:73]
	v_pk_add_f32 v[66:67], v[58:59], v[68:69]
	v_pk_add_f32 v[58:59], v[56:57], v[74:75]
	v_cvt_pk_bf16_f32 v56, v60, v61
	v_cvt_pk_bf16_f32 v57, v62, v63
	v_cvt_pk_bf16_f32 v58, v58, v59
	v_cvt_pk_bf16_f32 v59, v66, v67
	global_store_dwordx4 v[70:71], v[56:59], off
	s_waitcnt vmcnt(15)
	s_nop 1
	v_mov_b32_e32 v56, v198
	v_mov_b32_e32 v57, v199
	v_mov_b32_e32 v58, v200
	v_mov_b32_e32 v59, v201
	s_waitcnt lgkmcnt(0)
	v_lshlrev_b32_e32 v60, 16, v56
	v_and_b32_e32 v61, 0xffff0000, v56
	v_lshlrev_b32_e32 v56, 16, v57
	v_and_b32_e32 v57, 0xffff0000, v57
	v_lshlrev_b32_e32 v62, 16, v58
	v_and_b32_e32 v63, 0xffff0000, v58
	v_lshlrev_b32_e32 v58, 16, v59
	v_and_b32_e32 v59, 0xffff0000, v59
	v_pk_add_f32 v[54:55], v[54:55], v[56:57]
	v_pk_add_f32 v[52:53], v[52:53], v[60:61]
	v_pk_add_f32 v[56:57], v[50:51], v[58:59]
	v_pk_add_f32 v[50:51], v[48:49], v[62:63]
	v_cvt_pk_bf16_f32 v48, v52, v53
	v_cvt_pk_bf16_f32 v49, v54, v55
	v_cvt_pk_bf16_f32 v50, v50, v51
	v_cvt_pk_bf16_f32 v51, v56, v57
	global_store_dwordx4 v[64:65], v[48:51], off offset:256
	s_nop 1
	v_lshl_add_u64 v[48:49], v[144:145], 0, s[2:3]
	s_mov_b32 s2, 0x90000
	v_add_co_u32_e32 v54, vcc, s2, v144
	s_mov_b64 s[2:3], 0xa0000
	s_nop 0
	v_addc_co_u32_e32 v55, vcc, 0, v145, vcc
	s_waitcnt vmcnt(15)
	s_nop 1
	v_mov_b32_e32 v50, v202
	v_mov_b32_e32 v51, v203
	v_mov_b32_e32 v52, v204
	v_mov_b32_e32 v53, v205
	s_waitcnt lgkmcnt(0)
	v_lshlrev_b32_e32 v56, 16, v50
	v_and_b32_e32 v57, 0xffff0000, v50
	v_lshlrev_b32_e32 v50, 16, v51
	v_and_b32_e32 v51, 0xffff0000, v51
	v_lshlrev_b32_e32 v58, 16, v52
	v_and_b32_e32 v59, 0xffff0000, v52
	v_lshlrev_b32_e32 v52, 16, v53
	v_and_b32_e32 v53, 0xffff0000, v53
	v_pk_add_f32 v[46:47], v[46:47], v[50:51]
	v_pk_add_f32 v[44:45], v[44:45], v[56:57]
	v_pk_add_f32 v[50:51], v[42:43], v[52:53]
	v_pk_add_f32 v[42:43], v[40:41], v[58:59]
	v_cvt_pk_bf16_f32 v40, v44, v45
	v_cvt_pk_bf16_f32 v41, v46, v47
	v_cvt_pk_bf16_f32 v42, v42, v43
	v_cvt_pk_bf16_f32 v43, v50, v51
	global_store_dwordx4 v[54:55], v[40:43], off
	s_waitcnt vmcnt(15)
	s_nop 1
	v_mov_b32_e32 v40, v206
	v_mov_b32_e32 v41, v207
	v_mov_b32_e32 v42, v208
	v_mov_b32_e32 v43, v209
	s_waitcnt lgkmcnt(0)
; DI unsigned pack2(float a, float b) { f32x2 v = {a, b}; hwbf16x2 r = __builtin_convertvector(v, hwbf16x2); return __builtin_bit_cast(unsigned, r); }
; DI float bflo(unsigned w) { return __uint_as_float(w << 16); }
; DI float bfhi(unsigned w) { return __uint_as_float(w & 0xffff0000u); }
;     DI const char* a(const Unit& u) const { return (const char*)(A + (size_t)u.pm * BM * lda); }
;     DI const char* a(const Unit& u) const { return (const char*)(A + (size_t)u.pm * BM * 2048 + (u.pn >> 1) * 512); }
;     DI void operator()(const f32x4 (&acc)[2][2][4][2], const Unit& u, int wr, int wc, int fr, int fq) const {
;     ...
;         for (int ai = 0; ai < 2; ++ai)
; #pragma unroll
;             for (int m = 0; m < 4; ++m) { const size_t ro = (size_t)(row0 + ai * HALF + m * 16) * D + col0;
; #pragma unroll
;                 for (int bj = 0; bj < 2; ++bj) {
;                     f32x4 x0, x1;
;                     if constexpr (IB) { const u32x4 w = *(const u32x4*)((const bf16_t*)Xin + ro + bj * HALF);
;                         x0 = (f32x4){bflo(w[0]), bfhi(w[0]), bflo(w[1]), bfhi(w[1])}; x1 = (f32x4){bflo(w[2]), bfhi(w[2]), bflo(w[3]), bfhi(w[3])}; }
;                     else { x0 = *(const f32x4*)((const float*)Xin + ro + bj * HALF); x1 = *(const f32x4*)((const float*)Xin + ro + bj * HALF + 4); }
;                     x0 += acc[ai][bj][m][0] * sc[bj][0]; x1 += acc[ai][bj][m][1] * sc[bj][1];
;                     if constexpr (OB) { u32x4 o; o[0] = pack2(x0[0], x0[1]); o[1] = pack2(x0[2], x0[3]); o[2] = pack2(x1[0], x1[1]); o[3] = pack2(x1[2], x1[3]);
;                         *(u32x4*)((bf16_t*)Xout + ro + bj * HALF) = o; }
;                     else { *(f32x4*)((float*)Xout + ro + bj * HALF) = x0; *(f32x4*)((float*)Xout + ro + bj * HALF + 4) = x1; } } }
; template <class Map, class Epi>
; DI void gemm_phase(LAS unsigned char* lds, const Map& MP, const Epi& E, const int nM, const int nN, const int K, const int lda, const int ldb) {
;     ...
;         if (!has_next) break;
; #pragma unroll
;         for (int a = 0; a < 2; ++a)
; #pragma unroll
;             for (int b = 0; b < 2; ++b)
; #pragma unroll
;                 for (int m = 0; m < 4; ++m)
; #pragma unroll
;                     for (int n = 0; n < 2; ++n) acc[a][b][m][n] = (f32x4){0.f, 0.f, 0.f, 0.f};
;         cur = nxt; cA = nA; cB = nB; ++ui;
;     }
;     PG8_WAIT_V(0);
;     if (wr == 0) PG8_BAR;
;     PG8_BAR;
	v_lshlrev_b32_e32 v44, 16, v40
	v_and_b32_e32 v45, 0xffff0000, v40
	v_lshlrev_b32_e32 v40, 16, v41
	v_and_b32_e32 v41, 0xffff0000, v41
	v_lshlrev_b32_e32 v46, 16, v42
	v_and_b32_e32 v47, 0xffff0000, v42
	v_lshlrev_b32_e32 v42, 16, v43
	v_and_b32_e32 v43, 0xffff0000, v43
	v_pk_add_f32 v[38:39], v[38:39], v[40:41]
	v_pk_add_f32 v[36:37], v[36:37], v[44:45]
	v_pk_add_f32 v[40:41], v[34:35], v[42:43]
	v_pk_add_f32 v[34:35], v[32:33], v[46:47]
	v_cvt_pk_bf16_f32 v32, v36, v37
	v_cvt_pk_bf16_f32 v33, v38, v39
	v_cvt_pk_bf16_f32 v34, v34, v35
	v_cvt_pk_bf16_f32 v35, v40, v41
	global_store_dwordx4 v[48:49], v[32:35], off offset:256
	s_nop 1
	v_lshl_add_u64 v[32:33], v[144:145], 0, s[2:3]
	s_mov_b32 s2, 0xa0000
	v_add_co_u32_e32 v38, vcc, s2, v144
	s_mov_b64 s[2:3], 0xb0000
	s_nop 0
	v_addc_co_u32_e32 v39, vcc, 0, v145, vcc
	s_waitcnt vmcnt(15)
	s_nop 1
	v_mov_b32_e32 v34, v210
	v_mov_b32_e32 v35, v211
	v_mov_b32_e32 v36, v212
	v_mov_b32_e32 v37, v213
	s_waitcnt lgkmcnt(0)
	v_lshlrev_b32_e32 v40, 16, v34
	v_and_b32_e32 v41, 0xffff0000, v34
	v_lshlrev_b32_e32 v34, 16, v35
	v_and_b32_e32 v35, 0xffff0000, v35
	v_lshlrev_b32_e32 v42, 16, v36
	v_and_b32_e32 v43, 0xffff0000, v36
	v_lshlrev_b32_e32 v36, 16, v37
	v_and_b32_e32 v37, 0xffff0000, v37
	v_pk_add_f32 v[30:31], v[30:31], v[34:35]
	v_pk_add_f32 v[28:29], v[28:29], v[40:41]
	v_pk_add_f32 v[34:35], v[26:27], v[36:37]
	v_pk_add_f32 v[26:27], v[24:25], v[42:43]
	v_cvt_pk_bf16_f32 v24, v28, v29
	v_cvt_pk_bf16_f32 v25, v30, v31
	v_cvt_pk_bf16_f32 v26, v26, v27
	v_cvt_pk_bf16_f32 v27, v34, v35
	global_store_dwordx4 v[38:39], v[24:27], off
	s_waitcnt vmcnt(15)
	s_nop 1
	v_mov_b32_e32 v24, v214
	v_mov_b32_e32 v25, v215
	v_mov_b32_e32 v26, v216
	v_mov_b32_e32 v27, v217
	s_waitcnt lgkmcnt(0)
	v_lshlrev_b32_e32 v28, 16, v24
	v_and_b32_e32 v29, 0xffff0000, v24
	v_lshlrev_b32_e32 v24, 16, v25
	v_and_b32_e32 v25, 0xffff0000, v25
	v_lshlrev_b32_e32 v30, 16, v26
	v_and_b32_e32 v31, 0xffff0000, v26
	v_lshlrev_b32_e32 v26, 16, v27
	v_and_b32_e32 v27, 0xffff0000, v27
	v_pk_add_f32 v[22:23], v[22:23], v[24:25]
	v_pk_add_f32 v[20:21], v[20:21], v[28:29]
	v_pk_add_f32 v[24:25], v[18:19], v[26:27]
	v_pk_add_f32 v[18:19], v[16:17], v[30:31]
	v_cvt_pk_bf16_f32 v16, v20, v21
	v_cvt_pk_bf16_f32 v17, v22, v23
	v_cvt_pk_bf16_f32 v18, v18, v19
	v_cvt_pk_bf16_f32 v19, v24, v25
	global_store_dwordx4 v[32:33], v[16:19], off offset:256
	s_nop 1
	v_lshl_add_u64 v[16:17], v[144:145], 0, s[2:3]
	s_mov_b32 s2, 0xb0000
	v_add_co_u32_e32 v22, vcc, s2, v144
	s_mov_b32 s2, s53
	s_nop 0
	v_addc_co_u32_e32 v23, vcc, 0, v145, vcc
	s_waitcnt vmcnt(15)
	s_nop 1
	v_mov_b32_e32 v18, v248
	v_mov_b32_e32 v19, v249
	v_mov_b32_e32 v20, v250
	v_mov_b32_e32 v21, v251
	s_and_b64 vcc, exec, s[40:41]
	s_waitcnt lgkmcnt(0)
	v_lshlrev_b32_e32 v24, 16, v18
	v_and_b32_e32 v25, 0xffff0000, v18
	v_lshlrev_b32_e32 v18, 16, v19
	v_and_b32_e32 v19, 0xffff0000, v19
	v_lshlrev_b32_e32 v26, 16, v20
	v_and_b32_e32 v27, 0xffff0000, v20
	v_lshlrev_b32_e32 v20, 16, v21
	v_and_b32_e32 v21, 0xffff0000, v21
	v_pk_add_f32 v[14:15], v[14:15], v[18:19]
	v_pk_add_f32 v[12:13], v[12:13], v[24:25]
	v_pk_add_f32 v[18:19], v[10:11], v[20:21]
	v_pk_add_f32 v[10:11], v[8:9], v[26:27]
	v_cvt_pk_bf16_f32 v8, v12, v13
	v_cvt_pk_bf16_f32 v9, v14, v15
	v_cvt_pk_bf16_f32 v10, v10, v11
	v_cvt_pk_bf16_f32 v11, v18, v19
	global_store_dwordx4 v[22:23], v[8:11], off
	s_waitcnt vmcnt(15)
	s_nop 1
	v_mov_b32_e32 v8, v252
	v_mov_b32_e32 v9, v253
	v_mov_b32_e32 v10, v254
	v_mov_b32_e32 v11, v255
	s_waitcnt lgkmcnt(0)
	v_lshlrev_b32_e32 v12, 16, v8
	v_and_b32_e32 v13, 0xffff0000, v8
	v_lshlrev_b32_e32 v8, 16, v9
	v_and_b32_e32 v9, 0xffff0000, v9
	v_lshlrev_b32_e32 v14, 16, v10
	v_and_b32_e32 v15, 0xffff0000, v10
	v_lshlrev_b32_e32 v10, 16, v11
	v_and_b32_e32 v11, 0xffff0000, v11
	v_pk_add_f32 v[6:7], v[6:7], v[8:9]
	v_pk_add_f32 v[4:5], v[4:5], v[12:13]
	v_pk_add_f32 v[8:9], v[2:3], v[10:11]
	v_pk_add_f32 v[2:3], v[0:1], v[14:15]
	v_cvt_pk_bf16_f32 v0, v4, v5
	v_cvt_pk_bf16_f32 v1, v6, v7
	v_cvt_pk_bf16_f32 v2, v2, v3
	v_cvt_pk_bf16_f32 v3, v8, v9
	global_store_dwordx4 v[16:17], v[0:3], off offset:256
	s_cbranch_vccz .LBB1_2071
	s_waitcnt vmcnt(0)
	s_cmpk_gt_u32 s17, 0xff
	s_cbranch_scc1 .LBB1_2082
	s_barrier

; #define PG8_STAGE(bufoff, gbase, voff) do { _Pragma("unroll") for (int _i = 0; _i < 2; ++_i) \
;         __builtin_amdgcn_global_load_lds((const unsigned*)((const char*)(gbase) + (voff)[_i]), (LAS unsigned*)(lds + (bufoff) + ldsw + _i * 8192), 16, 0, 0); } while (0)
; #define PG8_LDA(dst, b, h) do { _Pragma("unroll") for (int m = 0; m < 4; ++m) _Pragma("unroll") for (int k = 0; k < 2; ++k) dst[m][k] = *(const LAS bf16x8*)(lds + PG8_SA(b, h) + aoff + m * 2048 + k * 1024); } while (0)
; #define PG8_LDB(dst, b, h) do { _Pragma("unroll") for (int n = 0; n < 2; ++n) _Pragma("unroll") for (int k = 0; k < 2; ++k) dst[n][k] = *(const LAS bf16x8*)(lds + PG8_SB(b, h) + boff + n * 2048 + k * 1024); } while (0)
; #define PG8_MMA(ai, bj, At, Bt) do { __builtin_amdgcn_s_setprio(1); _Pragma("unroll") for (int m = 0; m < 4; ++m) _Pragma("unroll") for (int n = 0; n < 2; ++n) _Pragma("unroll") for (int k = 0; k < 2; ++k) \
;         acc[ai][bj][m][n] = __builtin_amdgcn_mfma_f32_16x16x32_bf16(Bt[n][k], At[m][k], acc[ai][bj][m][n], 0, 0, 0); __builtin_amdgcn_s_setprio(0); } while (0)
; #define PG8_WAIT_V(n) asm volatile("s_waitcnt vmcnt(" #n ")" ::: "memory")
; #define PG8_WAIT_L(n) asm volatile("s_waitcnt lgkmcnt(" #n ")" ::: "memory")
; template <class Map, class Epi>
; DI void gemm_phase(LAS unsigned char* lds, const Map& MP, const Epi& E, const int nM, const int nN, const int K, const int lda, const int ldb) {
;     ...
;             const bool last = (t == nt - 2);
;             const char* a1 = cA + (size_t)(t + 1) * kstep;
;             const char* a2 = last ? nA : cA + (size_t)(t + 2) * kstep; const char* b2 = last ? nB : cB + (size_t)(t + 2) * kstep;
;             const char* a3 = a2 + kstep; const char* b3 = b2 + kstep;
;             PG8_LDB(B0, 0, 0); PG8_SCHED; PG8_LDA(At, 0, 0); PG8_STAGE(PG8_SA(1, 1), a1 + hstepA, voffA);
;             PG8_WAIT_L(8); PG8_BAR; PG8_WAIT_L(0); PG8_MMA(0, 0, At, B0); PG8_BAR; PG8_SCHED;
;             PG8_LDB(B1, 0, 1); PG8_STAGE(PG8_SB(0, 0), b2, voffB);
;             PG8_BAR; PG8_WAIT_L(0); PG8_MMA(0, 1, At, B1); PG8_BAR;
;             PG8_LDA(At, 0, 1); PG8_STAGE(PG8_SA(0, 0), a2, voffA);
;             PG8_BAR; PG8_WAIT_L(0); PG8_MMA(1, 0, At, B0); PG8_BAR; PG8_SCHED;
;             PG8_STAGE(PG8_SB(0, 1), b2 + hstepB, voffB);
;             PG8_WAIT_V(6); PG8_BAR; PG8_MMA(1, 1, At, B1); PG8_BAR;
.LBB1_2339:
	s_add_u32 s12, s10, 0xfff80080
	s_addc_u32 s13, s11, -1
	s_cmp_eq_u32 s3, 4
	s_cselect_b32 s15, s38, s13
	s_cselect_b32 s14, s39, s12
	s_cselect_b32 s13, s48, s56
	s_cselect_b32 s12, s49, s53
	s_add_i32 m0, s9, 0xc000
	ds_read_b128 v[168:171], v166
	ds_read_b128 v[172:175], v166 offset:1024
	ds_read_b128 v[176:179], v166 offset:2048
	ds_read_b128 v[180:183], v166 offset:3072
	ds_read_b128 v[184:187], v166 offset:4096
	ds_read_b128 v[188:191], v166 offset:5120
	ds_read_b128 v[192:195], v166 offset:6144
	ds_read_b128 v[198:201], v166 offset:7168
	global_load_lds_dwordx4 v154, s[10:11]
	s_add_i32 m0, s9, 0xe000
	s_setprio 1
	global_load_lds_dwordx4 v152, s[10:11]
	s_waitcnt lgkmcnt(8)
	s_barrier
	s_waitcnt lgkmcnt(7)
	v_mfma_f32_16x16x32_bf16 v[140:143], v[40:43], v[168:171], v[140:143]
	v_mfma_f32_16x16x32_bf16 v[136:139], v[56:59], v[168:171], v[136:139]
	s_waitcnt lgkmcnt(5)
	v_mfma_f32_16x16x32_bf16 v[124:127], v[40:43], v[176:179], v[124:127]
	v_mfma_f32_16x16x32_bf16 v[120:123], v[56:59], v[176:179], v[120:123]
	s_waitcnt lgkmcnt(3)
	v_mfma_f32_16x16x32_bf16 v[108:111], v[40:43], v[184:187], v[108:111]
	v_mfma_f32_16x16x32_bf16 v[104:107], v[56:59], v[184:187], v[104:107]
	s_waitcnt lgkmcnt(1)
	v_mfma_f32_16x16x32_bf16 v[92:95], v[40:43], v[192:195], v[92:95]
	v_mfma_f32_16x16x32_bf16 v[88:91], v[56:59], v[192:195], v[88:91]
	v_mfma_f32_16x16x32_bf16 v[140:143], v[44:47], v[172:175], v[140:143]
	s_add_i32 s57, s35, s22
	v_mfma_f32_16x16x32_bf16 v[136:139], v[60:63], v[172:175], v[136:139]
	v_lshl_add_u64 v[160:161], s[12:13], 0, v[148:149]
	v_mfma_f32_16x16x32_bf16 v[124:127], v[44:47], v[180:183], v[124:127]
	v_lshl_add_u64 v[218:219], s[12:13], 0, v[144:145]
	v_mfma_f32_16x16x32_bf16 v[120:123], v[60:63], v[180:183], v[120:123]
	v_mfma_f32_16x16x32_bf16 v[108:111], v[44:47], v[188:191], v[108:111]
	v_mfma_f32_16x16x32_bf16 v[104:107], v[60:63], v[188:191], v[104:107]
	s_waitcnt lgkmcnt(0)
	v_mfma_f32_16x16x32_bf16 v[92:95], v[44:47], v[198:201], v[92:95]
	v_mfma_f32_16x16x32_bf16 v[88:91], v[60:63], v[198:201], v[88:91]
	s_barrier
	s_setprio 0
	s_mov_b32 m0, s57
	ds_read_b128 v[202:205], v167
	ds_read_b128 v[206:209], v167 offset:1024
	ds_read_b128 v[210:213], v167 offset:2048
	ds_read_b128 v[214:217], v167 offset:3072
	global_load_lds_dwordx4 v[160:161], off
	s_add_i32 m0, s57, 0x2000
	s_setprio 1
	global_load_lds_dwordx4 v[218:219], off
	s_barrier
	s_waitcnt lgkmcnt(3)
	v_mfma_f32_16x16x32_bf16 v[132:135], v[202:205], v[168:171], v[132:135]
	s_waitcnt lgkmcnt(1)
	v_mfma_f32_16x16x32_bf16 v[128:131], v[210:213], v[168:171], v[128:131]
	v_mfma_f32_16x16x32_bf16 v[116:119], v[202:205], v[176:179], v[116:119]
	v_mfma_f32_16x16x32_bf16 v[112:115], v[210:213], v[176:179], v[112:115]
	v_mfma_f32_16x16x32_bf16 v[100:103], v[202:205], v[184:187], v[100:103]
	v_mfma_f32_16x16x32_bf16 v[96:99], v[210:213], v[184:187], v[96:99]
	v_mfma_f32_16x16x32_bf16 v[84:87], v[202:205], v[192:195], v[84:87]
	v_mfma_f32_16x16x32_bf16 v[80:83], v[210:213], v[192:195], v[80:83]
	v_mfma_f32_16x16x32_bf16 v[132:135], v[206:209], v[172:175], v[132:135]
	v_lshl_add_u64 v[222:223], s[14:15], 0, v[146:147]
	s_mov_b32 m0, s9
	s_waitcnt lgkmcnt(0)
	v_mfma_f32_16x16x32_bf16 v[128:131], v[214:217], v[172:175], v[128:131]
	v_lshl_add_u64 v[220:221], s[14:15], 0, v[150:151]
	v_mfma_f32_16x16x32_bf16 v[116:119], v[206:209], v[180:183], v[116:119]
	v_mfma_f32_16x16x32_bf16 v[112:115], v[214:217], v[180:183], v[112:115]
	v_mfma_f32_16x16x32_bf16 v[100:103], v[206:209], v[188:191], v[100:103]
	v_mfma_f32_16x16x32_bf16 v[96:99], v[214:217], v[188:191], v[96:99]
	v_mfma_f32_16x16x32_bf16 v[84:87], v[206:209], v[198:201], v[84:87]
	v_mfma_f32_16x16x32_bf16 v[80:83], v[214:217], v[198:201], v[80:83]
	s_barrier
	s_setprio 0
	ds_read_b128 v[168:171], v166 offset:16384
	ds_read_b128 v[172:175], v166 offset:17408
	ds_read_b128 v[176:179], v166 offset:18432
	ds_read_b128 v[180:183], v166 offset:19456
	ds_read_b128 v[184:187], v166 offset:20480
	ds_read_b128 v[188:191], v166 offset:21504
	ds_read_b128 v[192:195], v166 offset:22528
	ds_read_b128 v[198:201], v166 offset:23552
	global_load_lds_dwordx4 v[220:221], off
	s_mov_b32 m0, s24
	s_setprio 1
	global_load_lds_dwordx4 v[222:223], off
	s_waitcnt vmcnt(10)
	s_barrier
	s_waitcnt lgkmcnt(7)
	v_mfma_f32_16x16x32_bf16 v[76:79], v[40:43], v[168:171], v[76:79]
	v_mfma_f32_16x16x32_bf16 v[72:75], v[56:59], v[168:171], v[72:75]
	s_waitcnt lgkmcnt(5)
	v_mfma_f32_16x16x32_bf16 v[52:55], v[40:43], v[176:179], v[52:55]
	v_mfma_f32_16x16x32_bf16 v[48:51], v[56:59], v[176:179], v[48:51]
	s_waitcnt lgkmcnt(3)
	v_mfma_f32_16x16x32_bf16 v[28:31], v[40:43], v[184:187], v[28:31]
	v_mfma_f32_16x16x32_bf16 v[24:27], v[56:59], v[184:187], v[24:27]
	s_waitcnt lgkmcnt(1)
	v_mfma_f32_16x16x32_bf16 v[12:15], v[40:43], v[192:195], v[12:15]
	v_mfma_f32_16x16x32_bf16 v[8:11], v[56:59], v[192:195], v[8:11]
	v_mfma_f32_16x16x32_bf16 v[76:79], v[44:47], v[172:175], v[76:79]
	s_add_u32 s58, s12, 0x20000
	s_addc_u32 s59, s13, 0
	v_mfma_f32_16x16x32_bf16 v[72:75], v[60:63], v[172:175], v[72:75]
	s_add_i32 s57, s36, s22
	v_mfma_f32_16x16x32_bf16 v[52:55], v[44:47], v[180:183], v[52:55]
	v_mfma_f32_16x16x32_bf16 v[48:51], v[60:63], v[180:183], v[48:51]
	v_mfma_f32_16x16x32_bf16 v[28:31], v[44:47], v[188:191], v[28:31]
	v_mfma_f32_16x16x32_bf16 v[24:27], v[60:63], v[188:191], v[24:27]
	s_waitcnt lgkmcnt(0)
	v_mfma_f32_16x16x32_bf16 v[12:15], v[44:47], v[198:201], v[12:15]
	v_mfma_f32_16x16x32_bf16 v[8:11], v[60:63], v[198:201], v[8:11]
	s_barrier
	s_setprio 0
	s_mov_b32 m0, s57
	s_nop 0
	global_load_lds_dwordx4 v148, s[58:59]
	s_add_i32 m0, s57, 0x2000
	s_setprio 1
	global_load_lds_dwordx4 v144, s[58:59]
	s_waitcnt vmcnt(6)
	s_barrier
; #define PG8_STAGE(bufoff, gbase, voff) do { _Pragma("unroll") for (int _i = 0; _i < 2; ++_i) \
;         __builtin_amdgcn_global_load_lds((const unsigned*)((const char*)(gbase) + (voff)[_i]), (LAS unsigned*)(lds + (bufoff) + ldsw + _i * 8192), 16, 0, 0); } while (0)
; #define PG8_LDA(dst, b, h) do { _Pragma("unroll") for (int m = 0; m < 4; ++m) _Pragma("unroll") for (int k = 0; k < 2; ++k) dst[m][k] = *(const LAS bf16x8*)(lds + PG8_SA(b, h) + aoff + m * 2048 + k * 1024); } while (0)
; #define PG8_LDB(dst, b, h) do { _Pragma("unroll") for (int n = 0; n < 2; ++n) _Pragma("unroll") for (int k = 0; k < 2; ++k) dst[n][k] = *(const LAS bf16x8*)(lds + PG8_SB(b, h) + boff + n * 2048 + k * 1024); } while (0)
; #define PG8_MMA(ai, bj, At, Bt) do { __builtin_amdgcn_s_setprio(1); _Pragma("unroll") for (int m = 0; m < 4; ++m) _Pragma("unroll") for (int n = 0; n < 2; ++n) _Pragma("unroll") for (int k = 0; k < 2; ++k) \
;         acc[ai][bj][m][n] = __builtin_amdgcn_mfma_f32_16x16x32_bf16(Bt[n][k], At[m][k], acc[ai][bj][m][n], 0, 0, 0); __builtin_amdgcn_s_setprio(0); } while (0)
; #define PG8_WAIT_V(n) asm volatile("s_waitcnt vmcnt(" #n ")" ::: "memory")
; #define PG8_WAIT_L(n) asm volatile("s_waitcnt lgkmcnt(" #n ")" ::: "memory")
; #define PG8_BAR __builtin_amdgcn_s_barrier()
; #define PG8_SCHED __builtin_amdgcn_sched_barrier(0)
; template <class Map, class Epi>
; DI void gemm_phase(LAS unsigned char* lds, const Map& MP, const Epi& E, const int nM, const int nN, const int K, const int lda, const int ldb) {
;     ...
;             PG8_BAR; PG8_WAIT_L(0); PG8_MMA(1, 0, At, B0); PG8_BAR; PG8_SCHED;
;             PG8_STAGE(PG8_SB(0, 1), b2 + hstepB, voffB);
;             PG8_WAIT_V(6); PG8_BAR; PG8_MMA(1, 1, At, B1); PG8_BAR;
;             PG8_LDB(B0, 1, 0); PG8_SCHED; PG8_LDA(At, 1, 0); PG8_STAGE(PG8_SA(0, 1), a2 + hstepA, voffA);
;             PG8_WAIT_L(8); PG8_BAR; PG8_WAIT_L(0); PG8_MMA(0, 0, At, B0); PG8_BAR; PG8_SCHED;
;             PG8_LDB(B1, 1, 1); PG8_STAGE(PG8_SB(1, 0), b3, voffB);
;             PG8_BAR; PG8_WAIT_L(0); PG8_MMA(0, 1, At, B1); PG8_BAR;
;             PG8_LDA(At, 1, 1); PG8_STAGE(PG8_SA(1, 0), a3, voffA);
;             PG8_BAR; PG8_WAIT_L(0); PG8_MMA(1, 0, At, B0); PG8_BAR; PG8_SCHED;
	v_mfma_f32_16x16x32_bf16 v[36:39], v[202:205], v[176:179], v[36:39]
	v_mfma_f32_16x16x32_bf16 v[32:35], v[210:213], v[176:179], v[32:35]
	v_mfma_f32_16x16x32_bf16 v[20:23], v[202:205], v[184:187], v[20:23]
	v_mfma_f32_16x16x32_bf16 v[16:19], v[210:213], v[184:187], v[16:19]
	v_mfma_f32_16x16x32_bf16 v[4:7], v[202:205], v[192:195], v[4:7]
	v_mfma_f32_16x16x32_bf16 v[0:3], v[210:213], v[192:195], v[0:3]
	v_mfma_f32_16x16x32_bf16 v[40:43], v[202:205], v[168:171], v[68:71]
	s_add_i32 s57, 0, 0x18000
	v_add_u32_e32 v68, s57, v164
	ds_read_b128 v[56:59], v68
	ds_read_b128 v[60:63], v68 offset:1024
	v_mfma_f32_16x16x32_bf16 v[44:47], v[210:213], v[168:171], v[64:67]
	ds_read_b128 v[64:67], v68 offset:2048
	ds_read_b128 v[68:71], v68 offset:3072
	v_mfma_f32_16x16x32_bf16 v[36:39], v[206:209], v[180:183], v[36:39]
	s_add_u32 s14, s14, 0x80000
	s_addc_u32 s15, s15, 0
	v_mfma_f32_16x16x32_bf16 v[32:35], v[214:217], v[180:183], v[32:35]
	v_mfma_f32_16x16x32_bf16 v[20:23], v[206:209], v[188:191], v[20:23]
	v_mfma_f32_16x16x32_bf16 v[16:19], v[214:217], v[188:191], v[16:19]
	v_mfma_f32_16x16x32_bf16 v[4:7], v[206:209], v[198:201], v[4:7]
	v_mfma_f32_16x16x32_bf16 v[0:3], v[214:217], v[198:201], v[0:3]
	v_mfma_f32_16x16x32_bf16 v[40:43], v[206:209], v[172:175], v[40:43]
	v_mfma_f32_16x16x32_bf16 v[44:47], v[214:217], v[172:175], v[44:47]
	s_barrier
	s_setprio 0
	s_mov_b32 m0, s25
	ds_read_b128 v[168:171], v166 offset:32768
	ds_read_b128 v[172:175], v166 offset:33792
	ds_read_b128 v[176:179], v166 offset:34816
	ds_read_b128 v[180:183], v166 offset:35840
	ds_read_b128 v[184:187], v166 offset:36864
	ds_read_b128 v[188:191], v166 offset:37888
	ds_read_b128 v[192:195], v166 offset:38912
	ds_read_b128 v[198:201], v166 offset:39936
	global_load_lds_dwordx4 v150, s[14:15]
	s_mov_b32 m0, s26
	s_setprio 1
	global_load_lds_dwordx4 v146, s[14:15]
	s_waitcnt lgkmcnt(8)
	s_barrier
	s_waitcnt lgkmcnt(7)
	v_mfma_f32_16x16x32_bf16 v[140:143], v[56:59], v[168:171], v[140:143]
	v_mfma_f32_16x16x32_bf16 v[136:139], v[64:67], v[168:171], v[136:139]
	s_waitcnt lgkmcnt(5)
	v_mfma_f32_16x16x32_bf16 v[124:127], v[56:59], v[176:179], v[124:127]
	v_mfma_f32_16x16x32_bf16 v[120:123], v[64:67], v[176:179], v[120:123]
	s_waitcnt lgkmcnt(3)
	v_mfma_f32_16x16x32_bf16 v[108:111], v[56:59], v[184:187], v[108:111]
	v_mfma_f32_16x16x32_bf16 v[104:107], v[64:67], v[184:187], v[104:107]
	s_waitcnt lgkmcnt(1)
	v_mfma_f32_16x16x32_bf16 v[92:95], v[56:59], v[192:195], v[92:95]
	v_mfma_f32_16x16x32_bf16 v[88:91], v[64:67], v[192:195], v[88:91]
	v_mfma_f32_16x16x32_bf16 v[140:143], v[60:63], v[172:175], v[140:143]
	s_add_i32 s14, 0, 0x1c000
	v_mfma_f32_16x16x32_bf16 v[136:139], v[68:71], v[172:175], v[136:139]
	s_add_i32 s15, s57, s22
	v_mfma_f32_16x16x32_bf16 v[124:127], v[60:63], v[180:183], v[124:127]
	v_add_u32_e32 v196, s14, v164
	v_mfma_f32_16x16x32_bf16 v[120:123], v[68:71], v[180:183], v[120:123]
	v_lshl_add_u64 v[160:161], v[160:161], 0, s[46:47]
	v_mfma_f32_16x16x32_bf16 v[108:111], v[60:63], v[188:191], v[108:111]
	v_mfma_f32_16x16x32_bf16 v[104:107], v[68:71], v[188:191], v[104:107]
	s_waitcnt lgkmcnt(0)
	v_mfma_f32_16x16x32_bf16 v[92:95], v[60:63], v[198:201], v[92:95]
	v_mfma_f32_16x16x32_bf16 v[88:91], v[68:71], v[198:201], v[88:91]
	s_barrier
	s_setprio 0
	s_mov_b32 m0, s15
	ds_read_b128 v[202:205], v196
	ds_read_b128 v[206:209], v196 offset:1024
	ds_read_b128 v[210:213], v196 offset:2048
	ds_read_b128 v[214:217], v196 offset:3072
	global_load_lds_dwordx4 v[160:161], off
	v_lshl_add_u64 v[160:161], v[218:219], 0, s[46:47]
	s_add_i32 m0, s15, 0x2000
	s_setprio 1
	global_load_lds_dwordx4 v[160:161], off
	s_barrier
	s_waitcnt lgkmcnt(3)
	v_mfma_f32_16x16x32_bf16 v[132:135], v[202:205], v[168:171], v[132:135]
	s_waitcnt lgkmcnt(1)
	v_mfma_f32_16x16x32_bf16 v[128:131], v[210:213], v[168:171], v[128:131]
	v_mfma_f32_16x16x32_bf16 v[116:119], v[202:205], v[176:179], v[116:119]
	v_mfma_f32_16x16x32_bf16 v[112:115], v[210:213], v[176:179], v[112:115]
	v_mfma_f32_16x16x32_bf16 v[100:103], v[202:205], v[184:187], v[100:103]
	v_mfma_f32_16x16x32_bf16 v[96:99], v[210:213], v[184:187], v[96:99]
	v_mfma_f32_16x16x32_bf16 v[84:87], v[202:205], v[192:195], v[84:87]
	v_mfma_f32_16x16x32_bf16 v[80:83], v[210:213], v[192:195], v[80:83]
	v_mfma_f32_16x16x32_bf16 v[132:135], v[206:209], v[172:175], v[132:135]
	s_mov_b32 m0, s30
	s_waitcnt lgkmcnt(0)
	v_mfma_f32_16x16x32_bf16 v[128:131], v[214:217], v[172:175], v[128:131]
	v_lshl_add_u64 v[160:161], v[220:221], 0, s[46:47]
	v_mfma_f32_16x16x32_bf16 v[116:119], v[206:209], v[180:183], v[116:119]
	v_mfma_f32_16x16x32_bf16 v[112:115], v[214:217], v[180:183], v[112:115]
	v_mfma_f32_16x16x32_bf16 v[100:103], v[206:209], v[188:191], v[100:103]
	v_mfma_f32_16x16x32_bf16 v[96:99], v[214:217], v[188:191], v[96:99]
	v_mfma_f32_16x16x32_bf16 v[84:87], v[206:209], v[198:201], v[84:87]
	v_mfma_f32_16x16x32_bf16 v[80:83], v[214:217], v[198:201], v[80:83]
	s_barrier
	s_setprio 0
	ds_read_b128 v[168:171], v166 offset:49152
	ds_read_b128 v[172:175], v166 offset:50176
	ds_read_b128 v[176:179], v166 offset:51200
	ds_read_b128 v[180:183], v166 offset:52224
	ds_read_b128 v[184:187], v166 offset:53248
	ds_read_b128 v[188:191], v166 offset:54272
	ds_read_b128 v[192:195], v166 offset:55296
	ds_read_b128 v[198:201], v166 offset:56320
	global_load_lds_dwordx4 v[160:161], off
	v_lshl_add_u64 v[160:161], v[222:223], 0, s[46:47]
	s_mov_b32 m0, s31
	s_setprio 1
	global_load_lds_dwordx4 v[160:161], off
	s_waitcnt vmcnt(10)
	s_barrier
; DI unsigned pack2(float a, float b) { f32x2 v = {a, b}; hwbf16x2 r = __builtin_convertvector(v, hwbf16x2); return __builtin_bit_cast(unsigned, r); }
; DI float bflo(unsigned w) { return __uint_as_float(w << 16); }
; DI float bfhi(unsigned w) { return __uint_as_float(w & 0xffff0000u); }
; #define PG8_WAIT_V(n) asm volatile("s_waitcnt vmcnt(" #n ")" ::: "memory")
;     DI void operator()(const f32x4 (&acc)[2][2][4][2], const Unit& u, int wr, int wc, int fr, int fq) const {
;         const int row0 = u.pm * BM + wr * 64 + fr, col0 = u.pn * BM + wc * 32 + 8 * fq;
;         f32x4 sc[2][2];
; #pragma unroll
;         for (int bj = 0; bj < 2; ++bj)
; #pragma unroll
;             for (int n = 0; n < 2; ++n) sc[bj][n] = scale ? *(const f32x4*)(scale + col0 + bj * HALF + 4 * n) : (f32x4){1.f, 1.f, 1.f, 1.f};
; #pragma unroll
;         for (int ai = 0; ai < 2; ++ai)
; #pragma unroll
;             for (int m = 0; m < 4; ++m) { const size_t ro = (size_t)(row0 + ai * HALF + m * 16) * D + col0;
; #pragma unroll
;                 for (int bj = 0; bj < 2; ++bj) {
;                     f32x4 x0, x1;
;                     if constexpr (IB) { const u32x4 w = *(const u32x4*)((const bf16_t*)Xin + ro + bj * HALF);
;                         x0 = (f32x4){bflo(w[0]), bfhi(w[0]), bflo(w[1]), bfhi(w[1])}; x1 = (f32x4){bflo(w[2]), bfhi(w[2]), bflo(w[3]), bfhi(w[3])}; }
;                     else { x0 = *(const f32x4*)((const float*)Xin + ro + bj * HALF); x1 = *(const f32x4*)((const float*)Xin + ro + bj * HALF + 4); }
;                     x0 += acc[ai][bj][m][0] * sc[bj][0]; x1 += acc[ai][bj][m][1] * sc[bj][1];
;                     if constexpr (OB) { u32x4 o; o[0] = pack2(x0[0], x0[1]); o[1] = pack2(x0[2], x0[3]); o[2] = pack2(x1[0], x1[1]); o[3] = pack2(x1[2], x1[3]);
;                         *(u32x4*)((bf16_t*)Xout + ro + bj * HALF) = o; }
;                     else { *(f32x4*)((float*)Xout + ro + bj * HALF) = x0; *(f32x4*)((float*)Xout + ro + bj * HALF + 4) = x1; } } }
; template <class Map, class Epi>
; DI void gemm_phase(LAS unsigned char* lds, const Map& MP, const Epi& E, const int nM, const int nN, const int K, const int lda, const int ldb) {
;     ...
;             PG8_BAR; PG8_WAIT_L(0); PG8_MMA(1, 0, At, B0); PG8_BAR; PG8_SCHED;
;             PG8_STAGE(PG8_SB(1, 1), b3 + hstepB, voffB);
;             PG8_WAIT_V(6); PG8_BAR; PG8_MMA(1, 1, At, B1); PG8_BAR;
	s_waitcnt lgkmcnt(7)
	v_mfma_f32_16x16x32_bf16 v[76:79], v[56:59], v[168:171], v[76:79]
	v_mfma_f32_16x16x32_bf16 v[72:75], v[64:67], v[168:171], v[72:75]
	s_waitcnt lgkmcnt(5)
	v_mfma_f32_16x16x32_bf16 v[52:55], v[56:59], v[176:179], v[52:55]
	v_mfma_f32_16x16x32_bf16 v[48:51], v[64:67], v[176:179], v[48:51]
	s_waitcnt lgkmcnt(3)
	v_mfma_f32_16x16x32_bf16 v[28:31], v[56:59], v[184:187], v[28:31]
	v_mfma_f32_16x16x32_bf16 v[24:27], v[64:67], v[184:187], v[24:27]
	s_waitcnt lgkmcnt(1)
	v_mfma_f32_16x16x32_bf16 v[12:15], v[56:59], v[192:195], v[12:15]
	v_mfma_f32_16x16x32_bf16 v[8:11], v[64:67], v[192:195], v[8:11]
	v_mfma_f32_16x16x32_bf16 v[76:79], v[60:63], v[172:175], v[76:79]
	s_add_u32 s12, s12, 0x20080
	s_addc_u32 s13, s13, 0
	v_mfma_f32_16x16x32_bf16 v[72:75], v[68:71], v[172:175], v[72:75]
	s_add_i32 s14, s14, s22
	v_mfma_f32_16x16x32_bf16 v[52:55], v[60:63], v[180:183], v[52:55]
	v_mfma_f32_16x16x32_bf16 v[48:51], v[68:71], v[180:183], v[48:51]
	v_mfma_f32_16x16x32_bf16 v[28:31], v[60:63], v[188:191], v[28:31]
	v_mfma_f32_16x16x32_bf16 v[24:27], v[68:71], v[188:191], v[24:27]
	s_waitcnt lgkmcnt(0)
	v_mfma_f32_16x16x32_bf16 v[12:15], v[60:63], v[198:201], v[12:15]
	v_mfma_f32_16x16x32_bf16 v[8:11], v[68:71], v[198:201], v[8:11]
	s_barrier
	s_setprio 0
	s_mov_b32 m0, s14
	s_nop 0
	global_load_lds_dwordx4 v148, s[12:13]
	s_add_i32 m0, s14, 0x2000
	s_setprio 1
	global_load_lds_dwordx4 v144, s[12:13]
	s_waitcnt vmcnt(6)
	s_barrier
	v_mfma_f32_16x16x32_bf16 v[40:43], v[202:205], v[168:171], v[40:43]
	v_mfma_f32_16x16x32_bf16 v[68:71], v[206:209], v[172:175], v[40:43]
	v_mfma_f32_16x16x32_bf16 v[40:43], v[210:213], v[168:171], v[44:47]
	v_mfma_f32_16x16x32_bf16 v[36:39], v[202:205], v[176:179], v[36:39]
	v_mfma_f32_16x16x32_bf16 v[32:35], v[210:213], v[176:179], v[32:35]
	v_mfma_f32_16x16x32_bf16 v[20:23], v[202:205], v[184:187], v[20:23]
	v_mfma_f32_16x16x32_bf16 v[16:19], v[210:213], v[184:187], v[16:19]
	v_mfma_f32_16x16x32_bf16 v[4:7], v[202:205], v[192:195], v[4:7]
	v_mfma_f32_16x16x32_bf16 v[0:3], v[210:213], v[192:195], v[0:3]
	s_add_i32 s3, s3, 2
	v_mfma_f32_16x16x32_bf16 v[64:67], v[214:217], v[172:175], v[40:43]
	s_add_u32 s53, s53, 0x100
	s_addc_u32 s56, s56, 0
	ds_read_b128 v[40:43], v165
	ds_read_b128 v[44:47], v165 offset:1024
	ds_read_b128 v[56:59], v165 offset:2048
	ds_read_b128 v[60:63], v165 offset:3072
	v_mfma_f32_16x16x32_bf16 v[36:39], v[206:209], v[180:183], v[36:39]
	s_add_u32 s10, s10, 0x100
	s_addc_u32 s11, s11, 0
	v_mfma_f32_16x16x32_bf16 v[32:35], v[214:217], v[180:183], v[32:35]
	s_cmp_gt_u32 s3, 5
	v_mfma_f32_16x16x32_bf16 v[20:23], v[206:209], v[188:191], v[20:23]
	v_mfma_f32_16x16x32_bf16 v[16:19], v[214:217], v[188:191], v[16:19]
	v_mfma_f32_16x16x32_bf16 v[4:7], v[206:209], v[198:201], v[4:7]
	v_mfma_f32_16x16x32_bf16 v[0:3], v[214:217], v[198:201], v[0:3]
	s_barrier
	s_setprio 0
	s_cbranch_scc0 .LBB1_2339
	s_waitcnt lgkmcnt(0)
	s_lshl_b32 s2, s2, 8
	v_mov_b32_e32 v40, v163
	v_mov_b32_e32 v168, v162
	s_or_b32 s2, s2, s29
	s_and_b64 vcc, exec, s[40:41]
	v_lshl_add_u32 v160, v40, 3, s2
	s_lshl_b32 s2, s8, 8
	s_add_i32 s2, s2, s28
	v_add_u32_e32 v168, s2, v168
	v_ashrrev_i32_e32 v169, 31, v168
	v_ashrrev_i32_e32 v161, 31, v160
	v_lshlrev_b64 v[168:169], 11, v[168:169]
	v_lshl_add_u64 v[44:45], v[160:161], 2, s[44:45]
	v_lshl_add_u64 v[160:161], v[168:169], 0, v[160:161]
	v_lshlrev_b64 v[160:161], 1, v[160:161]
	v_lshl_add_u64 v[172:173], s[4:5], 0, v[160:161]
	global_load_dwordx4 v[56:59], v[44:45], off offset:16
	global_load_dwordx4 v[60:63], v[44:45], off
	global_load_dwordx4 v[40:43], v[44:45], off offset:528
	s_nop 0
	global_load_dwordx4 v[44:47], v[44:45], off offset:512
	s_mov_b64 s[2:3], 0x10000
	global_load_dwordx4 v[178:181], v[172:173], off
	global_load_dwordx4 v[182:185], v[172:173], off offset:256
	s_mov_b64 s[98:99], 0x10000
	v_lshl_add_u64 v[170:171], v[172:173], 0, s[98:99]
	global_load_dwordx4 v[186:189], v[170:171], off
	global_load_dwordx4 v[190:193], v[170:171], off offset:256
	s_mov_b64 s[98:99], 0x20000
	v_lshl_add_u64 v[170:171], v[172:173], 0, s[98:99]
	global_load_dwordx4 v[198:201], v[170:171], off
	global_load_dwordx4 v[202:205], v[170:171], off offset:256
	s_mov_b64 s[98:99], 0x30000
	v_lshl_add_u64 v[170:171], v[172:173], 0, s[98:99]
	global_load_dwordx4 v[206:209], v[170:171], off
	global_load_dwordx4 v[210:213], v[170:171], off offset:256
	s_mov_b64 s[98:99], 0x80000
	v_lshl_add_u64 v[170:171], v[172:173], 0, s[98:99]
	global_load_dwordx4 v[214:217], v[170:171], off
	global_load_dwordx4 v[248:251], v[170:171], off offset:256
	s_mov_b64 s[98:99], 0x90000
	v_lshl_add_u64 v[170:171], v[172:173], 0, s[98:99]
	global_load_dwordx4 v[252:255], v[170:171], off
	s_waitcnt vmcnt(10)
	s_nop 1
	v_mov_b32_e32 v168, v178
	v_mov_b32_e32 v169, v179
	v_mov_b32_e32 v170, v180
	v_mov_b32_e32 v171, v181
	s_mov_b32 s8, s52
	s_mov_b64 s[10:11], s[54:55]
	s_mov_b64 s[12:13], s[6:7]
	s_waitcnt lgkmcnt(0)
	v_lshlrev_b32_e32 v174, 16, v168
	v_and_b32_e32 v175, 0xffff0000, v168
	v_lshlrev_b32_e32 v168, 16, v169
	v_and_b32_e32 v169, 0xffff0000, v169
	v_lshlrev_b32_e32 v176, 16, v170
	v_and_b32_e32 v177, 0xffff0000, v170
	v_lshlrev_b32_e32 v170, 16, v171
	v_and_b32_e32 v171, 0xffff0000, v171
	v_pk_fma_f32 v[142:143], v[142:143], v[62:63], v[168:169]
	v_pk_fma_f32 v[140:141], v[140:141], v[60:61], v[174:175]
	v_pk_fma_f32 v[168:169], v[138:139], v[58:59], v[170:171]
	v_pk_fma_f32 v[138:139], v[136:137], v[56:57], v[176:177]
	v_cvt_pk_bf16_f32 v136, v140, v141
	v_cvt_pk_bf16_f32 v137, v142, v143
	v_cvt_pk_bf16_f32 v138, v138, v139
	v_cvt_pk_bf16_f32 v139, v168, v169
	v_lshl_add_u64 v[140:141], s[42:43], 0, v[160:161]
	global_store_dwordx4 v[140:141], v[136:139], off
	s_waitcnt vmcnt(10)
; DI unsigned pack2(float a, float b) { f32x2 v = {a, b}; hwbf16x2 r = __builtin_convertvector(v, hwbf16x2); return __builtin_bit_cast(unsigned, r); }
; DI float bflo(unsigned w) { return __uint_as_float(w << 16); }
; DI float bfhi(unsigned w) { return __uint_as_float(w & 0xffff0000u); }
;     DI void operator()(const f32x4 (&acc)[2][2][4][2], const Unit& u, int wr, int wc, int fr, int fq) const {
;     ...
;         for (int ai = 0; ai < 2; ++ai)
; #pragma unroll
;             for (int m = 0; m < 4; ++m) { const size_t ro = (size_t)(row0 + ai * HALF + m * 16) * D + col0;
; #pragma unroll
;                 for (int bj = 0; bj < 2; ++bj) {
;                     f32x4 x0, x1;
;                     if constexpr (IB) { const u32x4 w = *(const u32x4*)((const bf16_t*)Xin + ro + bj * HALF);
;                         x0 = (f32x4){bflo(w[0]), bfhi(w[0]), bflo(w[1]), bfhi(w[1])}; x1 = (f32x4){bflo(w[2]), bfhi(w[2]), bflo(w[3]), bfhi(w[3])}; }
;                     else { x0 = *(const f32x4*)((const float*)Xin + ro + bj * HALF); x1 = *(const f32x4*)((const float*)Xin + ro + bj * HALF + 4); }
;                     x0 += acc[ai][bj][m][0] * sc[bj][0]; x1 += acc[ai][bj][m][1] * sc[bj][1];
;                     if constexpr (OB) { u32x4 o; o[0] = pack2(x0[0], x0[1]); o[1] = pack2(x0[2], x0[3]); o[2] = pack2(x1[0], x1[1]); o[3] = pack2(x1[2], x1[3]);
;                         *(u32x4*)((bf16_t*)Xout + ro + bj * HALF) = o; }
;                     else { *(f32x4*)((float*)Xout + ro + bj * HALF) = x0; *(f32x4*)((float*)Xout + ro + bj * HALF + 4) = x1; } } }
	s_nop 1
	v_mov_b32_e32 v136, v182
	v_mov_b32_e32 v137, v183
	v_mov_b32_e32 v138, v184
	v_mov_b32_e32 v139, v185
	s_waitcnt lgkmcnt(0)
	v_lshlrev_b32_e32 v142, 16, v136
	v_and_b32_e32 v143, 0xffff0000, v136
	v_lshlrev_b32_e32 v136, 16, v137
	v_and_b32_e32 v137, 0xffff0000, v137
	v_lshlrev_b32_e32 v168, 16, v138
	v_and_b32_e32 v169, 0xffff0000, v138
	v_lshlrev_b32_e32 v138, 16, v139
	v_and_b32_e32 v139, 0xffff0000, v139
	v_pk_fma_f32 v[134:135], v[134:135], v[46:47], v[136:137]
	v_pk_fma_f32 v[132:133], v[132:133], v[44:45], v[142:143]
	v_pk_fma_f32 v[136:137], v[130:131], v[42:43], v[138:139]
	v_pk_fma_f32 v[130:131], v[128:129], v[40:41], v[168:169]
	v_cvt_pk_bf16_f32 v128, v132, v133
	v_cvt_pk_bf16_f32 v129, v134, v135
	v_cvt_pk_bf16_f32 v130, v130, v131
	v_cvt_pk_bf16_f32 v131, v136, v137
	v_lshl_add_u64 v[132:133], v[160:161], 0, s[2:3]
	global_store_dwordx4 v[140:141], v[128:131], off offset:256
	v_lshl_add_u64 v[134:135], s[4:5], 0, v[132:133]
	s_waitcnt vmcnt(10)
	s_nop 1
	v_mov_b32_e32 v128, v186
	v_mov_b32_e32 v129, v187
	v_mov_b32_e32 v130, v188
	v_mov_b32_e32 v131, v189
	s_mov_b64 s[2:3], 0x20000
	s_waitcnt lgkmcnt(0)
	v_lshlrev_b32_e32 v136, 16, v128
	v_and_b32_e32 v137, 0xffff0000, v128
	v_lshlrev_b32_e32 v128, 16, v129
	v_and_b32_e32 v129, 0xffff0000, v129
	v_lshlrev_b32_e32 v138, 16, v130
	v_and_b32_e32 v139, 0xffff0000, v130
	v_lshlrev_b32_e32 v130, 16, v131
	v_and_b32_e32 v131, 0xffff0000, v131
	v_pk_fma_f32 v[126:127], v[126:127], v[62:63], v[128:129]
	v_pk_fma_f32 v[124:125], v[124:125], v[60:61], v[136:137]
	v_pk_fma_f32 v[128:129], v[122:123], v[58:59], v[130:131]
	v_pk_fma_f32 v[122:123], v[120:121], v[56:57], v[138:139]
	v_cvt_pk_bf16_f32 v120, v124, v125
	v_cvt_pk_bf16_f32 v121, v126, v127
	v_cvt_pk_bf16_f32 v122, v122, v123
	v_cvt_pk_bf16_f32 v123, v128, v129
	v_lshl_add_u64 v[124:125], s[42:43], 0, v[132:133]
	global_store_dwordx4 v[124:125], v[120:123], off
	s_waitcnt vmcnt(10)
	s_nop 1
	v_mov_b32_e32 v120, v190
	v_mov_b32_e32 v121, v191
	v_mov_b32_e32 v122, v192
	v_mov_b32_e32 v123, v193
	s_waitcnt lgkmcnt(0)
	v_lshlrev_b32_e32 v126, 16, v120
	v_and_b32_e32 v127, 0xffff0000, v120
	v_lshlrev_b32_e32 v120, 16, v121
	v_and_b32_e32 v121, 0xffff0000, v121
	v_lshlrev_b32_e32 v128, 16, v122
	v_and_b32_e32 v129, 0xffff0000, v122
	v_lshlrev_b32_e32 v122, 16, v123
	v_and_b32_e32 v123, 0xffff0000, v123
	v_pk_fma_f32 v[118:119], v[118:119], v[46:47], v[120:121]
	v_pk_fma_f32 v[116:117], v[116:117], v[44:45], v[126:127]
	v_pk_fma_f32 v[120:121], v[114:115], v[42:43], v[122:123]
	v_pk_fma_f32 v[114:115], v[112:113], v[40:41], v[128:129]
	v_cvt_pk_bf16_f32 v112, v116, v117
	v_cvt_pk_bf16_f32 v113, v118, v119
	v_cvt_pk_bf16_f32 v114, v114, v115
	v_cvt_pk_bf16_f32 v115, v120, v121
	v_lshl_add_u64 v[116:117], v[160:161], 0, s[2:3]
	global_store_dwordx4 v[124:125], v[112:115], off offset:256
	v_lshl_add_u64 v[118:119], s[4:5], 0, v[116:117]
	s_waitcnt vmcnt(10)
	s_nop 1
	v_mov_b32_e32 v112, v198
	v_mov_b32_e32 v113, v199
	v_mov_b32_e32 v114, v200
	v_mov_b32_e32 v115, v201
	s_mov_b64 s[2:3], 0x30000
	s_waitcnt lgkmcnt(0)
	v_lshlrev_b32_e32 v120, 16, v112
	v_and_b32_e32 v121, 0xffff0000, v112
	v_lshlrev_b32_e32 v112, 16, v113
	v_and_b32_e32 v113, 0xffff0000, v113
	v_lshlrev_b32_e32 v122, 16, v114
	v_and_b32_e32 v123, 0xffff0000, v114
	v_lshlrev_b32_e32 v114, 16, v115
	v_and_b32_e32 v115, 0xffff0000, v115
	v_pk_fma_f32 v[110:111], v[110:111], v[62:63], v[112:113]
	v_pk_fma_f32 v[108:109], v[108:109], v[60:61], v[120:121]
	v_pk_fma_f32 v[112:113], v[106:107], v[58:59], v[114:115]
	v_pk_fma_f32 v[106:107], v[104:105], v[56:57], v[122:123]
	v_cvt_pk_bf16_f32 v104, v108, v109
	v_cvt_pk_bf16_f32 v105, v110, v111
	v_cvt_pk_bf16_f32 v106, v106, v107
	v_cvt_pk_bf16_f32 v107, v112, v113
	v_lshl_add_u64 v[108:109], s[42:43], 0, v[116:117]
	global_store_dwordx4 v[108:109], v[104:107], off
	s_waitcnt vmcnt(10)
	s_nop 1
	v_mov_b32_e32 v104, v202
	v_mov_b32_e32 v105, v203
	v_mov_b32_e32 v106, v204
	v_mov_b32_e32 v107, v205
	s_waitcnt lgkmcnt(0)
	v_lshlrev_b32_e32 v110, 16, v104
	v_and_b32_e32 v111, 0xffff0000, v104
	v_lshlrev_b32_e32 v104, 16, v105
	v_and_b32_e32 v105, 0xffff0000, v105
	v_lshlrev_b32_e32 v112, 16, v106
	v_and_b32_e32 v113, 0xffff0000, v106
	v_lshlrev_b32_e32 v106, 16, v107
	v_and_b32_e32 v107, 0xffff0000, v107
	v_pk_fma_f32 v[102:103], v[102:103], v[46:47], v[104:105]
	v_pk_fma_f32 v[100:101], v[100:101], v[44:45], v[110:111]
	v_pk_fma_f32 v[104:105], v[98:99], v[42:43], v[106:107]
	v_pk_fma_f32 v[98:99], v[96:97], v[40:41], v[112:113]
	v_cvt_pk_bf16_f32 v96, v100, v101
	v_cvt_pk_bf16_f32 v97, v102, v103
	v_cvt_pk_bf16_f32 v98, v98, v99
	v_cvt_pk_bf16_f32 v99, v104, v105
	v_lshl_add_u64 v[100:101], v[160:161], 0, s[2:3]
	global_store_dwordx4 v[108:109], v[96:99], off offset:256
	v_lshl_add_u64 v[102:103], s[4:5], 0, v[100:101]
	s_waitcnt vmcnt(10)
	s_nop 1
	v_mov_b32_e32 v96, v206
	v_mov_b32_e32 v97, v207
	v_mov_b32_e32 v98, v208
	v_mov_b32_e32 v99, v209
	s_mov_b64 s[2:3], 0x80000
	s_waitcnt lgkmcnt(0)
	v_lshlrev_b32_e32 v104, 16, v96
	v_and_b32_e32 v105, 0xffff0000, v96
	v_lshlrev_b32_e32 v96, 16, v97
	v_and_b32_e32 v97, 0xffff0000, v97
	v_lshlrev_b32_e32 v106, 16, v98
	v_and_b32_e32 v107, 0xffff0000, v98
	v_lshlrev_b32_e32 v98, 16, v99
	v_and_b32_e32 v99, 0xffff0000, v99
	v_pk_fma_f32 v[94:95], v[94:95], v[62:63], v[96:97]
	v_pk_fma_f32 v[92:93], v[92:93], v[60:61], v[104:105]
	v_pk_fma_f32 v[96:97], v[90:91], v[58:59], v[98:99]
	v_pk_fma_f32 v[90:91], v[88:89], v[56:57], v[106:107]
	v_cvt_pk_bf16_f32 v88, v92, v93
	v_cvt_pk_bf16_f32 v89, v94, v95
	v_cvt_pk_bf16_f32 v90, v90, v91
	v_cvt_pk_bf16_f32 v91, v96, v97
	v_lshl_add_u64 v[92:93], s[42:43], 0, v[100:101]
	global_store_dwordx4 v[92:93], v[88:91], off
	s_waitcnt vmcnt(10)
; DI unsigned pack2(float a, float b) { f32x2 v = {a, b}; hwbf16x2 r = __builtin_convertvector(v, hwbf16x2); return __builtin_bit_cast(unsigned, r); }
; DI float bflo(unsigned w) { return __uint_as_float(w << 16); }
; DI float bfhi(unsigned w) { return __uint_as_float(w & 0xffff0000u); }
;     DI void operator()(const f32x4 (&acc)[2][2][4][2], const Unit& u, int wr, int wc, int fr, int fq) const {
;     ...
;         for (int ai = 0; ai < 2; ++ai)
; #pragma unroll
;             for (int m = 0; m < 4; ++m) { const size_t ro = (size_t)(row0 + ai * HALF + m * 16) * D + col0;
; #pragma unroll
;                 for (int bj = 0; bj < 2; ++bj) {
;                     f32x4 x0, x1;
;                     if constexpr (IB) { const u32x4 w = *(const u32x4*)((const bf16_t*)Xin + ro + bj * HALF);
;                         x0 = (f32x4){bflo(w[0]), bfhi(w[0]), bflo(w[1]), bfhi(w[1])}; x1 = (f32x4){bflo(w[2]), bfhi(w[2]), bflo(w[3]), bfhi(w[3])}; }
;                     else { x0 = *(const f32x4*)((const float*)Xin + ro + bj * HALF); x1 = *(const f32x4*)((const float*)Xin + ro + bj * HALF + 4); }
;                     x0 += acc[ai][bj][m][0] * sc[bj][0]; x1 += acc[ai][bj][m][1] * sc[bj][1];
;                     if constexpr (OB) { u32x4 o; o[0] = pack2(x0[0], x0[1]); o[1] = pack2(x0[2], x0[3]); o[2] = pack2(x1[0], x1[1]); o[3] = pack2(x1[2], x1[3]);
;                         *(u32x4*)((bf16_t*)Xout + ro + bj * HALF) = o; }
;                     else { *(f32x4*)((float*)Xout + ro + bj * HALF) = x0; *(f32x4*)((float*)Xout + ro + bj * HALF + 4) = x1; } } }
	s_nop 1
	v_mov_b32_e32 v88, v210
	v_mov_b32_e32 v89, v211
	v_mov_b32_e32 v90, v212
	v_mov_b32_e32 v91, v213
	s_waitcnt lgkmcnt(0)
	v_lshlrev_b32_e32 v94, 16, v88
	v_and_b32_e32 v95, 0xffff0000, v88
	v_lshlrev_b32_e32 v88, 16, v89
	v_and_b32_e32 v89, 0xffff0000, v89
	v_lshlrev_b32_e32 v96, 16, v90
	v_and_b32_e32 v97, 0xffff0000, v90
	v_lshlrev_b32_e32 v90, 16, v91
	v_and_b32_e32 v91, 0xffff0000, v91
	v_pk_fma_f32 v[86:87], v[86:87], v[46:47], v[88:89]
	v_pk_fma_f32 v[84:85], v[84:85], v[44:45], v[94:95]
	v_pk_fma_f32 v[88:89], v[82:83], v[42:43], v[90:91]
	v_pk_fma_f32 v[82:83], v[80:81], v[40:41], v[96:97]
	v_cvt_pk_bf16_f32 v80, v84, v85
	v_cvt_pk_bf16_f32 v81, v86, v87
	v_cvt_pk_bf16_f32 v82, v82, v83
	v_cvt_pk_bf16_f32 v83, v88, v89
	v_lshl_add_u64 v[84:85], v[160:161], 0, s[2:3]
	global_store_dwordx4 v[92:93], v[80:83], off offset:256
	v_lshl_add_u64 v[86:87], s[4:5], 0, v[84:85]
	s_waitcnt vmcnt(10)
	s_nop 1
	v_mov_b32_e32 v80, v214
	v_mov_b32_e32 v81, v215
	v_mov_b32_e32 v82, v216
	v_mov_b32_e32 v83, v217
	s_mov_b64 s[2:3], 0x90000
	s_waitcnt lgkmcnt(0)
	v_lshlrev_b32_e32 v88, 16, v80
	v_and_b32_e32 v89, 0xffff0000, v80
	v_lshlrev_b32_e32 v80, 16, v81
	v_and_b32_e32 v81, 0xffff0000, v81
	v_lshlrev_b32_e32 v90, 16, v82
	v_and_b32_e32 v91, 0xffff0000, v82
	v_lshlrev_b32_e32 v82, 16, v83
	v_and_b32_e32 v83, 0xffff0000, v83
	v_pk_fma_f32 v[78:79], v[78:79], v[62:63], v[80:81]
	v_pk_fma_f32 v[76:77], v[76:77], v[60:61], v[88:89]
	v_pk_fma_f32 v[80:81], v[74:75], v[58:59], v[82:83]
	v_pk_fma_f32 v[74:75], v[72:73], v[56:57], v[90:91]
	v_cvt_pk_bf16_f32 v72, v76, v77
	v_cvt_pk_bf16_f32 v73, v78, v79
	v_cvt_pk_bf16_f32 v74, v74, v75
	v_cvt_pk_bf16_f32 v75, v80, v81
	v_lshl_add_u64 v[76:77], s[42:43], 0, v[84:85]
	global_store_dwordx4 v[76:77], v[72:75], off
	s_waitcnt vmcnt(10)
	s_nop 1
	v_mov_b32_e32 v72, v248
	v_mov_b32_e32 v73, v249
	v_mov_b32_e32 v74, v250
	v_mov_b32_e32 v75, v251
	s_waitcnt lgkmcnt(0)
	v_lshlrev_b32_e32 v78, 16, v72
	v_and_b32_e32 v79, 0xffff0000, v72
	v_lshlrev_b32_e32 v72, 16, v73
	v_and_b32_e32 v73, 0xffff0000, v73
	v_lshlrev_b32_e32 v80, 16, v74
	v_and_b32_e32 v81, 0xffff0000, v74
	v_lshlrev_b32_e32 v74, 16, v75
	v_and_b32_e32 v75, 0xffff0000, v75
	v_pk_fma_f32 v[70:71], v[70:71], v[46:47], v[72:73]
	v_pk_fma_f32 v[68:69], v[68:69], v[44:45], v[78:79]
	v_pk_fma_f32 v[72:73], v[66:67], v[42:43], v[74:75]
	v_pk_fma_f32 v[66:67], v[64:65], v[40:41], v[80:81]
	v_cvt_pk_bf16_f32 v64, v68, v69
	v_cvt_pk_bf16_f32 v65, v70, v71
	v_cvt_pk_bf16_f32 v66, v66, v67
	v_cvt_pk_bf16_f32 v67, v72, v73
	v_lshl_add_u64 v[68:69], v[160:161], 0, s[2:3]
	global_store_dwordx4 v[76:77], v[64:67], off offset:256
	v_lshl_add_u64 v[70:71], s[4:5], 0, v[68:69]
	s_waitcnt vmcnt(10)
	s_nop 1
	v_mov_b32_e32 v64, v252
	v_mov_b32_e32 v65, v253
	v_mov_b32_e32 v66, v254
	v_mov_b32_e32 v67, v255
	s_mov_b64 s[2:3], 0xa0000
	s_waitcnt lgkmcnt(0)
	v_lshlrev_b32_e32 v72, 16, v64
	v_and_b32_e32 v73, 0xffff0000, v64
	v_lshlrev_b32_e32 v64, 16, v65
	v_and_b32_e32 v65, 0xffff0000, v65
	v_lshlrev_b32_e32 v74, 16, v66
	v_and_b32_e32 v75, 0xffff0000, v66
	v_lshlrev_b32_e32 v66, 16, v67
	v_and_b32_e32 v67, 0xffff0000, v67
	v_pk_fma_f32 v[54:55], v[54:55], v[62:63], v[64:65]
	v_pk_fma_f32 v[52:53], v[52:53], v[60:61], v[72:73]
	v_pk_fma_f32 v[64:65], v[50:51], v[58:59], v[66:67]
	v_pk_fma_f32 v[50:51], v[48:49], v[56:57], v[74:75]
	v_cvt_pk_bf16_f32 v48, v52, v53
	v_cvt_pk_bf16_f32 v49, v54, v55
	v_cvt_pk_bf16_f32 v50, v50, v51
	v_cvt_pk_bf16_f32 v51, v64, v65
	v_lshl_add_u64 v[52:53], s[42:43], 0, v[68:69]
	global_store_dwordx4 v[52:53], v[48:51], off
	global_load_dwordx4 v[48:51], v[70:71], off offset:256
	s_waitcnt vmcnt(0) lgkmcnt(0)
; DI unsigned pack2(float a, float b) { f32x2 v = {a, b}; hwbf16x2 r = __builtin_convertvector(v, hwbf16x2); return __builtin_bit_cast(unsigned, r); }
; DI float bflo(unsigned w) { return __uint_as_float(w << 16); }
; DI float bfhi(unsigned w) { return __uint_as_float(w & 0xffff0000u); }
;     DI const char* a(const Unit& u) const { return (const char*)(A + (size_t)u.pm * BM * lda); }
;     DI const char* a(const Unit& u) const { return (const char*)(A + (size_t)u.pm * BM * 2048 + (u.pn >> 1) * 512); }
;     DI void operator()(const f32x4 (&acc)[2][2][4][2], const Unit& u, int wr, int wc, int fr, int fq) const {
;     ...
;         for (int ai = 0; ai < 2; ++ai)
; #pragma unroll
;             for (int m = 0; m < 4; ++m) { const size_t ro = (size_t)(row0 + ai * HALF + m * 16) * D + col0;
; #pragma unroll
;                 for (int bj = 0; bj < 2; ++bj) {
;                     f32x4 x0, x1;
;                     if constexpr (IB) { const u32x4 w = *(const u32x4*)((const bf16_t*)Xin + ro + bj * HALF);
;                         x0 = (f32x4){bflo(w[0]), bfhi(w[0]), bflo(w[1]), bfhi(w[1])}; x1 = (f32x4){bflo(w[2]), bfhi(w[2]), bflo(w[3]), bfhi(w[3])}; }
;                     else { x0 = *(const f32x4*)((const float*)Xin + ro + bj * HALF); x1 = *(const f32x4*)((const float*)Xin + ro + bj * HALF + 4); }
;                     x0 += acc[ai][bj][m][0] * sc[bj][0]; x1 += acc[ai][bj][m][1] * sc[bj][1];
;                     if constexpr (OB) { u32x4 o; o[0] = pack2(x0[0], x0[1]); o[1] = pack2(x0[2], x0[3]); o[2] = pack2(x1[0], x1[1]); o[3] = pack2(x1[2], x1[3]);
;                         *(u32x4*)((bf16_t*)Xout + ro + bj * HALF) = o; }
;                     else { *(f32x4*)((float*)Xout + ro + bj * HALF) = x0; *(f32x4*)((float*)Xout + ro + bj * HALF + 4) = x1; } } }
; template <class Map, class Epi>
; DI void gemm_phase(LAS unsigned char* lds, const Map& MP, const Epi& E, const int nM, const int nN, const int K, const int lda, const int ldb) {
;     ...
;         if (!has_next) break;
; #pragma unroll
;         for (int a = 0; a < 2; ++a)
; #pragma unroll
;             for (int b = 0; b < 2; ++b)
; #pragma unroll
;                 for (int m = 0; m < 4; ++m)
; #pragma unroll
;                     for (int n = 0; n < 2; ++n) acc[a][b][m][n] = (f32x4){0.f, 0.f, 0.f, 0.f};
;         cur = nxt; cA = nA; cB = nB; ++ui;
;     }
;     PG8_WAIT_V(0);
;     if (wr == 0) PG8_BAR;
;     PG8_BAR;
	v_lshlrev_b32_e32 v54, 16, v48
	v_and_b32_e32 v55, 0xffff0000, v48
	v_lshlrev_b32_e32 v48, 16, v49
	v_and_b32_e32 v49, 0xffff0000, v49
	v_lshlrev_b32_e32 v64, 16, v50
	v_and_b32_e32 v65, 0xffff0000, v50
	v_lshlrev_b32_e32 v50, 16, v51
	v_and_b32_e32 v51, 0xffff0000, v51
	v_pk_fma_f32 v[38:39], v[38:39], v[46:47], v[48:49]
	v_pk_fma_f32 v[36:37], v[36:37], v[44:45], v[54:55]
	v_pk_fma_f32 v[48:49], v[34:35], v[42:43], v[50:51]
	v_pk_fma_f32 v[34:35], v[32:33], v[40:41], v[64:65]
	v_cvt_pk_bf16_f32 v32, v36, v37
	v_cvt_pk_bf16_f32 v33, v38, v39
	v_cvt_pk_bf16_f32 v34, v34, v35
	v_cvt_pk_bf16_f32 v35, v48, v49
	v_lshl_add_u64 v[36:37], v[160:161], 0, s[2:3]
	global_store_dwordx4 v[52:53], v[32:35], off offset:256
	v_lshl_add_u64 v[38:39], s[4:5], 0, v[36:37]
	global_load_dwordx4 v[32:35], v[38:39], off
	s_mov_b64 s[2:3], 0xb0000
	s_waitcnt vmcnt(0) lgkmcnt(0)
	v_lshlrev_b32_e32 v48, 16, v32
	v_and_b32_e32 v49, 0xffff0000, v32
	v_lshlrev_b32_e32 v32, 16, v33
	v_and_b32_e32 v33, 0xffff0000, v33
	v_lshlrev_b32_e32 v50, 16, v34
	v_and_b32_e32 v51, 0xffff0000, v34
	v_lshlrev_b32_e32 v34, 16, v35
	v_and_b32_e32 v35, 0xffff0000, v35
	v_pk_fma_f32 v[30:31], v[30:31], v[62:63], v[32:33]
	v_pk_fma_f32 v[28:29], v[28:29], v[60:61], v[48:49]
	v_pk_fma_f32 v[32:33], v[26:27], v[58:59], v[34:35]
	v_pk_fma_f32 v[26:27], v[24:25], v[56:57], v[50:51]
	v_cvt_pk_bf16_f32 v24, v28, v29
	v_cvt_pk_bf16_f32 v25, v30, v31
	v_cvt_pk_bf16_f32 v26, v26, v27
	v_cvt_pk_bf16_f32 v27, v32, v33
	v_lshl_add_u64 v[28:29], s[42:43], 0, v[36:37]
	global_store_dwordx4 v[28:29], v[24:27], off
	global_load_dwordx4 v[24:27], v[38:39], off offset:256
	s_waitcnt vmcnt(0) lgkmcnt(0)
	v_lshlrev_b32_e32 v30, 16, v24
	v_and_b32_e32 v31, 0xffff0000, v24
	v_lshlrev_b32_e32 v24, 16, v25
	v_and_b32_e32 v25, 0xffff0000, v25
	v_lshlrev_b32_e32 v32, 16, v26
	v_and_b32_e32 v33, 0xffff0000, v26
	v_lshlrev_b32_e32 v26, 16, v27
	v_and_b32_e32 v27, 0xffff0000, v27
	v_pk_fma_f32 v[22:23], v[22:23], v[46:47], v[24:25]
	v_pk_fma_f32 v[20:21], v[20:21], v[44:45], v[30:31]
	v_pk_fma_f32 v[24:25], v[18:19], v[42:43], v[26:27]
	v_pk_fma_f32 v[18:19], v[16:17], v[40:41], v[32:33]
	v_cvt_pk_bf16_f32 v16, v20, v21
	v_cvt_pk_bf16_f32 v17, v22, v23
	v_cvt_pk_bf16_f32 v18, v18, v19
	v_cvt_pk_bf16_f32 v19, v24, v25
	v_lshl_add_u64 v[20:21], v[160:161], 0, s[2:3]
	global_store_dwordx4 v[28:29], v[16:19], off offset:256
	v_lshl_add_u64 v[22:23], s[4:5], 0, v[20:21]
	global_load_dwordx4 v[16:19], v[22:23], off
	s_mov_b32 s2, s37
	s_waitcnt vmcnt(0) lgkmcnt(0)
	v_lshlrev_b32_e32 v24, 16, v16
	v_and_b32_e32 v25, 0xffff0000, v16
	v_lshlrev_b32_e32 v16, 16, v17
	v_and_b32_e32 v17, 0xffff0000, v17
	v_lshlrev_b32_e32 v26, 16, v18
	v_and_b32_e32 v27, 0xffff0000, v18
	v_lshlrev_b32_e32 v18, 16, v19
	v_and_b32_e32 v19, 0xffff0000, v19
	v_pk_fma_f32 v[14:15], v[14:15], v[62:63], v[16:17]
	v_pk_fma_f32 v[12:13], v[12:13], v[60:61], v[24:25]
	v_pk_fma_f32 v[16:17], v[10:11], v[58:59], v[18:19]
	v_pk_fma_f32 v[10:11], v[8:9], v[56:57], v[26:27]
	v_cvt_pk_bf16_f32 v8, v12, v13
	v_cvt_pk_bf16_f32 v9, v14, v15
	v_cvt_pk_bf16_f32 v10, v10, v11
	v_cvt_pk_bf16_f32 v11, v16, v17
	v_lshl_add_u64 v[12:13], s[42:43], 0, v[20:21]
	global_store_dwordx4 v[12:13], v[8:11], off
	global_load_dwordx4 v[8:11], v[22:23], off offset:256
	s_waitcnt vmcnt(0) lgkmcnt(0)
	v_lshlrev_b32_e32 v14, 16, v8
	v_and_b32_e32 v15, 0xffff0000, v8
	v_lshlrev_b32_e32 v8, 16, v9
	v_and_b32_e32 v9, 0xffff0000, v9
	v_lshlrev_b32_e32 v16, 16, v10
	v_and_b32_e32 v17, 0xffff0000, v10
	v_lshlrev_b32_e32 v10, 16, v11
	v_and_b32_e32 v11, 0xffff0000, v11
	v_pk_fma_f32 v[6:7], v[6:7], v[46:47], v[8:9]
	v_pk_fma_f32 v[4:5], v[4:5], v[44:45], v[14:15]
	v_pk_fma_f32 v[8:9], v[2:3], v[42:43], v[10:11]
	v_pk_fma_f32 v[2:3], v[0:1], v[40:41], v[16:17]
	v_cvt_pk_bf16_f32 v0, v4, v5
	v_cvt_pk_bf16_f32 v1, v6, v7
	v_cvt_pk_bf16_f32 v2, v2, v3
	v_cvt_pk_bf16_f32 v3, v8, v9
	global_store_dwordx4 v[12:13], v[0:3], off offset:256
	s_cbranch_vccz .LBB1_2336
	s_waitcnt vmcnt(0)
	s_cmpk_gt_u32 s17, 0xff
	s_cbranch_scc1 .LBB1_2343
	s_barrier

; #define PG8_STAGE(bufoff, gbase, voff) do { _Pragma("unroll") for (int _i = 0; _i < 2; ++_i) \
;         __builtin_amdgcn_global_load_lds((const unsigned*)((const char*)(gbase) + (voff)[_i]), (LAS unsigned*)(lds + (bufoff) + ldsw + _i * 8192), 16, 0, 0); } while (0)
; #define PG8_LDA(dst, b, h) do { _Pragma("unroll") for (int m = 0; m < 4; ++m) _Pragma("unroll") for (int k = 0; k < 2; ++k) dst[m][k] = *(const LAS bf16x8*)(lds + PG8_SA(b, h) + aoff + m * 2048 + k * 1024); } while (0)
; #define PG8_LDB(dst, b, h) do { _Pragma("unroll") for (int n = 0; n < 2; ++n) _Pragma("unroll") for (int k = 0; k < 2; ++k) dst[n][k] = *(const LAS bf16x8*)(lds + PG8_SB(b, h) + boff + n * 2048 + k * 1024); } while (0)
; #define PG8_MMA(ai, bj, At, Bt) do { __builtin_amdgcn_s_setprio(1); _Pragma("unroll") for (int m = 0; m < 4; ++m) _Pragma("unroll") for (int n = 0; n < 2; ++n) _Pragma("unroll") for (int k = 0; k < 2; ++k) \
;         acc[ai][bj][m][n] = __builtin_amdgcn_mfma_f32_16x16x32_bf16(Bt[n][k], At[m][k], acc[ai][bj][m][n], 0, 0, 0); __builtin_amdgcn_s_setprio(0); } while (0)
; #define PG8_WAIT_V(n) asm volatile("s_waitcnt vmcnt(" #n ")" ::: "memory")
; #define PG8_WAIT_L(n) asm volatile("s_waitcnt lgkmcnt(" #n ")" ::: "memory")
; template <class Map, class Epi>
; DI void gemm_phase(LAS unsigned char* lds, const Map& MP, const Epi& E, const int nM, const int nN, const int K, const int lda, const int ldb) {
;     ...
;             const bool last = (t == nt - 2);
;             const char* a1 = cA + (size_t)(t + 1) * kstep;
;             const char* a2 = last ? nA : cA + (size_t)(t + 2) * kstep; const char* b2 = last ? nB : cB + (size_t)(t + 2) * kstep;
;             const char* a3 = a2 + kstep; const char* b3 = b2 + kstep;
;             PG8_LDB(B0, 0, 0); PG8_SCHED; PG8_LDA(At, 0, 0); PG8_STAGE(PG8_SA(1, 1), a1 + hstepA, voffA);
;             PG8_WAIT_L(8); PG8_BAR; PG8_WAIT_L(0); PG8_MMA(0, 0, At, B0); PG8_BAR; PG8_SCHED;
;             PG8_LDB(B1, 0, 1); PG8_STAGE(PG8_SB(0, 0), b2, voffB);
;             PG8_BAR; PG8_WAIT_L(0); PG8_MMA(0, 1, At, B1); PG8_BAR;
;             PG8_LDA(At, 0, 1); PG8_STAGE(PG8_SA(0, 0), a2, voffA);
;             PG8_BAR; PG8_WAIT_L(0); PG8_MMA(1, 0, At, B0); PG8_BAR; PG8_SCHED;
;             PG8_STAGE(PG8_SB(0, 1), b2 + hstepB, voffB);
;             PG8_WAIT_V(6); PG8_BAR; PG8_MMA(1, 1, At, B1); PG8_BAR;
.LBB1_2483:
	s_add_u32 s28, s42, 0xfff80080
	s_addc_u32 s29, s43, -1
	s_cmp_eq_u32 s3, 28
	s_cselect_b32 s47, s23, s29
	s_cselect_b32 s46, s58, s28
	s_cselect_b32 s29, s21, vcc_hi
	s_cselect_b32 s28, s59, vcc_lo
	s_add_i32 m0, s38, 0xc000
	ds_read_b128 v[96:99], v190
	ds_read_b128 v[100:103], v190 offset:1024
	ds_read_b128 v[108:111], v190 offset:2048
	ds_read_b128 v[112:115], v190 offset:3072
	ds_read_b128 v[160:163], v190 offset:4096
	ds_read_b128 v[164:167], v190 offset:5120
	ds_read_b128 v[198:201], v190 offset:6144
	ds_read_b128 v[202:205], v190 offset:7168
	global_load_lds_dwordx4 v178, s[42:43]
	s_add_i32 m0, s38, 0xe000
	s_setprio 1
	global_load_lds_dwordx4 v176, s[42:43]
	s_waitcnt lgkmcnt(8)
	s_barrier
	s_waitcnt lgkmcnt(7)
	v_mfma_f32_16x16x32_bf16 v[148:151], v[80:83], v[96:99], v[148:151]
	v_mfma_f32_16x16x32_bf16 v[144:147], v[88:91], v[96:99], v[144:147]
	s_waitcnt lgkmcnt(5)
	v_mfma_f32_16x16x32_bf16 v[136:139], v[80:83], v[108:111], v[136:139]
	v_mfma_f32_16x16x32_bf16 v[128:131], v[88:91], v[108:111], v[128:131]
	s_waitcnt lgkmcnt(3)
	v_mfma_f32_16x16x32_bf16 v[120:123], v[80:83], v[160:163], v[120:123]
	v_mfma_f32_16x16x32_bf16 v[104:107], v[88:91], v[160:163], v[104:107]
	s_waitcnt lgkmcnt(1)
	v_mfma_f32_16x16x32_bf16 v[76:79], v[80:83], v[198:201], v[76:79]
	v_mfma_f32_16x16x32_bf16 v[72:75], v[88:91], v[198:201], v[72:75]
	v_mfma_f32_16x16x32_bf16 v[148:151], v[84:87], v[100:103], v[148:151]
	s_add_i32 s68, s2, s37
	v_mfma_f32_16x16x32_bf16 v[144:147], v[92:95], v[100:103], v[144:147]
	v_lshl_add_u64 v[184:185], s[28:29], 0, v[172:173]
	v_mfma_f32_16x16x32_bf16 v[136:139], v[84:87], v[112:115], v[136:139]
	v_lshl_add_u64 v[194:195], s[28:29], 0, v[168:169]
	v_mfma_f32_16x16x32_bf16 v[128:131], v[92:95], v[112:115], v[128:131]
	v_mfma_f32_16x16x32_bf16 v[120:123], v[84:87], v[164:167], v[120:123]
	v_mfma_f32_16x16x32_bf16 v[104:107], v[92:95], v[164:167], v[104:107]
	s_waitcnt lgkmcnt(0)
	v_mfma_f32_16x16x32_bf16 v[76:79], v[84:87], v[202:205], v[76:79]
	v_mfma_f32_16x16x32_bf16 v[72:75], v[92:95], v[202:205], v[72:75]
	s_barrier
	s_setprio 0
	s_mov_b32 m0, s68
	ds_read_b128 v[206:209], v191
	ds_read_b128 v[210:213], v191 offset:1024
	ds_read_b128 v[214:217], v191 offset:2048
	ds_read_b128 v[218:221], v191 offset:3072
	global_load_lds_dwordx4 v[184:185], off
	s_add_i32 m0, s68, 0x2000
	s_setprio 1
	global_load_lds_dwordx4 v[194:195], off
	s_barrier
	s_waitcnt lgkmcnt(3)
	v_mfma_f32_16x16x32_bf16 v[156:159], v[206:209], v[96:99], v[156:159]
	s_waitcnt lgkmcnt(1)
	v_mfma_f32_16x16x32_bf16 v[96:99], v[214:217], v[96:99], v[152:155]
	v_mfma_f32_16x16x32_bf16 v[156:159], v[210:213], v[100:103], v[156:159]
	s_waitcnt lgkmcnt(0)
	v_mfma_f32_16x16x32_bf16 v[96:99], v[218:221], v[100:103], v[96:99]
	v_mfma_f32_16x16x32_bf16 v[100:103], v[206:209], v[108:111], v[140:143]
	v_mfma_f32_16x16x32_bf16 v[108:111], v[214:217], v[108:111], v[132:135]
	v_mfma_f32_16x16x32_bf16 v[116:119], v[214:217], v[160:163], v[116:119]
	v_mfma_f32_16x16x32_bf16 v[68:71], v[206:209], v[198:201], v[68:71]
	v_mfma_f32_16x16x32_bf16 v[64:67], v[214:217], v[198:201], v[64:67]
	v_lshl_add_u64 v[232:233], s[46:47], 0, v[170:171]
	s_mov_b32 m0, s38
	v_mfma_f32_16x16x32_bf16 v[100:103], v[210:213], v[112:115], v[100:103]
	v_lshl_add_u64 v[230:231], s[46:47], 0, v[174:175]
	v_mfma_f32_16x16x32_bf16 v[108:111], v[218:221], v[112:115], v[108:111]
	v_mfma_f32_16x16x32_bf16 v[112:115], v[206:209], v[160:163], v[124:127]
	v_mfma_f32_16x16x32_bf16 v[116:119], v[218:221], v[164:167], v[116:119]
	v_mfma_f32_16x16x32_bf16 v[68:71], v[210:213], v[202:205], v[68:71]
	v_mfma_f32_16x16x32_bf16 v[64:67], v[218:221], v[202:205], v[64:67]
	v_mfma_f32_16x16x32_bf16 v[112:115], v[210:213], v[164:167], v[112:115]
	s_barrier
	s_setprio 0
	ds_read_b128 v[124:127], v190 offset:16384
	ds_read_b128 v[132:135], v190 offset:17408
	ds_read_b128 v[140:143], v190 offset:18432
	ds_read_b128 v[152:155], v190 offset:19456
	ds_read_b128 v[160:163], v190 offset:20480
	ds_read_b128 v[164:167], v190 offset:21504
	ds_read_b128 v[198:201], v190 offset:22528
	ds_read_b128 v[202:205], v190 offset:23552
	global_load_lds_dwordx4 v[230:231], off
	s_mov_b32 m0, s39
	s_setprio 1
	global_load_lds_dwordx4 v[232:233], off
	s_waitcnt vmcnt(10)
	s_barrier
	s_waitcnt lgkmcnt(7)
	v_mfma_f32_16x16x32_bf16 v[60:63], v[80:83], v[124:127], v[60:63]
	v_mfma_f32_16x16x32_bf16 v[48:51], v[88:91], v[124:127], v[48:51]
	s_waitcnt lgkmcnt(5)
	v_mfma_f32_16x16x32_bf16 v[40:43], v[80:83], v[140:143], v[40:43]
	v_mfma_f32_16x16x32_bf16 v[32:35], v[88:91], v[140:143], v[32:35]
	s_waitcnt lgkmcnt(3)
	v_mfma_f32_16x16x32_bf16 v[24:27], v[80:83], v[160:163], v[24:27]
	v_mfma_f32_16x16x32_bf16 v[16:19], v[88:91], v[160:163], v[16:19]
	s_waitcnt lgkmcnt(1)
	v_mfma_f32_16x16x32_bf16 v[12:15], v[80:83], v[198:201], v[12:15]
	v_mfma_f32_16x16x32_bf16 v[8:11], v[88:91], v[198:201], v[8:11]
	v_mfma_f32_16x16x32_bf16 v[60:63], v[84:87], v[132:135], v[60:63]
	s_add_u32 s68, s28, 0x80000
	s_addc_u32 s69, s29, 0
	v_mfma_f32_16x16x32_bf16 v[48:51], v[92:95], v[132:135], v[48:51]
	s_add_i32 s70, s67, s37
	v_mfma_f32_16x16x32_bf16 v[40:43], v[84:87], v[152:155], v[40:43]
	v_mfma_f32_16x16x32_bf16 v[32:35], v[92:95], v[152:155], v[32:35]
	v_mfma_f32_16x16x32_bf16 v[24:27], v[84:87], v[164:167], v[24:27]
	v_mfma_f32_16x16x32_bf16 v[16:19], v[92:95], v[164:167], v[16:19]
	s_waitcnt lgkmcnt(0)
	v_mfma_f32_16x16x32_bf16 v[12:15], v[84:87], v[202:205], v[12:15]
	v_mfma_f32_16x16x32_bf16 v[8:11], v[92:95], v[202:205], v[8:11]
	s_barrier
	s_setprio 0
	s_mov_b32 m0, s70
	s_nop 0
	global_load_lds_dwordx4 v172, s[68:69]
	s_add_i32 m0, s70, 0x2000
	s_setprio 1
	global_load_lds_dwordx4 v168, s[68:69]
	s_waitcnt vmcnt(6)
	s_barrier
; #define PG8_STAGE(bufoff, gbase, voff) do { _Pragma("unroll") for (int _i = 0; _i < 2; ++_i) \
;         __builtin_amdgcn_global_load_lds((const unsigned*)((const char*)(gbase) + (voff)[_i]), (LAS unsigned*)(lds + (bufoff) + ldsw + _i * 8192), 16, 0, 0); } while (0)
; #define PG8_LDA(dst, b, h) do { _Pragma("unroll") for (int m = 0; m < 4; ++m) _Pragma("unroll") for (int k = 0; k < 2; ++k) dst[m][k] = *(const LAS bf16x8*)(lds + PG8_SA(b, h) + aoff + m * 2048 + k * 1024); } while (0)
; #define PG8_LDB(dst, b, h) do { _Pragma("unroll") for (int n = 0; n < 2; ++n) _Pragma("unroll") for (int k = 0; k < 2; ++k) dst[n][k] = *(const LAS bf16x8*)(lds + PG8_SB(b, h) + boff + n * 2048 + k * 1024); } while (0)
; #define PG8_MMA(ai, bj, At, Bt) do { __builtin_amdgcn_s_setprio(1); _Pragma("unroll") for (int m = 0; m < 4; ++m) _Pragma("unroll") for (int n = 0; n < 2; ++n) _Pragma("unroll") for (int k = 0; k < 2; ++k) \
;         acc[ai][bj][m][n] = __builtin_amdgcn_mfma_f32_16x16x32_bf16(Bt[n][k], At[m][k], acc[ai][bj][m][n], 0, 0, 0); __builtin_amdgcn_s_setprio(0); } while (0)
; #define PG8_WAIT_V(n) asm volatile("s_waitcnt vmcnt(" #n ")" ::: "memory")
; #define PG8_WAIT_L(n) asm volatile("s_waitcnt lgkmcnt(" #n ")" ::: "memory")
; #define PG8_BAR __builtin_amdgcn_s_barrier()
; #define PG8_SCHED __builtin_amdgcn_sched_barrier(0)
; template <class Map, class Epi>
; DI void gemm_phase(LAS unsigned char* lds, const Map& MP, const Epi& E, const int nM, const int nN, const int K, const int lda, const int ldb) {
;     ...
;             PG8_BAR; PG8_WAIT_L(0); PG8_MMA(1, 0, At, B0); PG8_BAR; PG8_SCHED;
;             PG8_STAGE(PG8_SB(0, 1), b2 + hstepB, voffB);
;             PG8_WAIT_V(6); PG8_BAR; PG8_MMA(1, 1, At, B1); PG8_BAR;
;             PG8_LDB(B0, 1, 0); PG8_SCHED; PG8_LDA(At, 1, 0); PG8_STAGE(PG8_SA(0, 1), a2 + hstepA, voffA);
;             PG8_WAIT_L(8); PG8_BAR; PG8_WAIT_L(0); PG8_MMA(0, 0, At, B0); PG8_BAR; PG8_SCHED;
;             PG8_LDB(B1, 1, 1); PG8_STAGE(PG8_SB(1, 0), b3, voffB);
;             PG8_BAR; PG8_WAIT_L(0); PG8_MMA(0, 1, At, B1); PG8_BAR;
;             PG8_LDA(At, 1, 1); PG8_STAGE(PG8_SA(1, 0), a3, voffA);
;             PG8_BAR; PG8_WAIT_L(0); PG8_MMA(1, 0, At, B0); PG8_BAR; PG8_SCHED;
	v_mfma_f32_16x16x32_bf16 v[56:59], v[206:209], v[124:127], v[56:59]
	v_mfma_f32_16x16x32_bf16 v[52:55], v[214:217], v[124:127], v[52:55]
	s_add_i32 s68, 0, 0x18000
	v_add_u32_e32 v92, s68, v188
	ds_read_b128 v[80:83], v92
	v_mfma_f32_16x16x32_bf16 v[44:47], v[206:209], v[140:143], v[44:47]
	v_mfma_f32_16x16x32_bf16 v[36:39], v[214:217], v[140:143], v[36:39]
	ds_read_b128 v[84:87], v92 offset:1024
	v_mfma_f32_16x16x32_bf16 v[28:31], v[206:209], v[160:163], v[28:31]
	v_mfma_f32_16x16x32_bf16 v[20:23], v[214:217], v[160:163], v[20:23]
	ds_read_b128 v[88:91], v92 offset:2048
	v_mfma_f32_16x16x32_bf16 v[4:7], v[206:209], v[198:201], v[4:7]
	v_mfma_f32_16x16x32_bf16 v[0:3], v[214:217], v[198:201], v[0:3]
	ds_read_b128 v[92:95], v92 offset:3072
	v_mfma_f32_16x16x32_bf16 v[56:59], v[210:213], v[132:135], v[56:59]
	s_add_u32 s46, s46, 0x80000
	s_addc_u32 s47, s47, 0
	v_mfma_f32_16x16x32_bf16 v[52:55], v[218:221], v[132:135], v[52:55]
	v_mfma_f32_16x16x32_bf16 v[44:47], v[210:213], v[152:155], v[44:47]
	v_mfma_f32_16x16x32_bf16 v[36:39], v[218:221], v[152:155], v[36:39]
	v_mfma_f32_16x16x32_bf16 v[28:31], v[210:213], v[164:167], v[28:31]
	v_mfma_f32_16x16x32_bf16 v[20:23], v[218:221], v[164:167], v[20:23]
	v_mfma_f32_16x16x32_bf16 v[4:7], v[210:213], v[202:205], v[4:7]
	v_mfma_f32_16x16x32_bf16 v[0:3], v[218:221], v[202:205], v[0:3]
	s_barrier
	s_setprio 0
	s_mov_b32 m0, s55
	ds_read_b128 v[124:127], v190 offset:32768
	ds_read_b128 v[132:135], v190 offset:33792
	ds_read_b128 v[160:163], v190 offset:34816
	ds_read_b128 v[164:167], v190 offset:35840
	ds_read_b128 v[198:201], v190 offset:36864
	ds_read_b128 v[202:205], v190 offset:37888
	ds_read_b128 v[206:209], v190 offset:38912
	ds_read_b128 v[210:213], v190 offset:39936
	global_load_lds_dwordx4 v174, s[46:47]
	s_mov_b32 m0, s56
	s_setprio 1
	global_load_lds_dwordx4 v170, s[46:47]
	s_waitcnt lgkmcnt(8)
	s_barrier
	s_waitcnt lgkmcnt(7)
	v_mfma_f32_16x16x32_bf16 v[140:143], v[80:83], v[124:127], v[148:151]
	s_waitcnt lgkmcnt(6)
	v_mfma_f32_16x16x32_bf16 v[148:151], v[84:87], v[132:135], v[140:143]
	v_mfma_f32_16x16x32_bf16 v[140:143], v[88:91], v[124:127], v[144:147]
	s_waitcnt lgkmcnt(5)
	v_mfma_f32_16x16x32_bf16 v[136:139], v[80:83], v[160:163], v[136:139]
	v_mfma_f32_16x16x32_bf16 v[128:131], v[88:91], v[160:163], v[128:131]
	s_waitcnt lgkmcnt(3)
	v_mfma_f32_16x16x32_bf16 v[120:123], v[80:83], v[198:201], v[120:123]
	v_mfma_f32_16x16x32_bf16 v[104:107], v[88:91], v[198:201], v[104:107]
	s_waitcnt lgkmcnt(1)
	v_mfma_f32_16x16x32_bf16 v[76:79], v[80:83], v[206:209], v[76:79]
	v_mfma_f32_16x16x32_bf16 v[72:75], v[88:91], v[206:209], v[72:75]
	s_add_i32 s46, 0, 0x1c000
	v_mfma_f32_16x16x32_bf16 v[144:147], v[92:95], v[132:135], v[140:143]
	v_add_u32_e32 v140, s46, v188
	v_mfma_f32_16x16x32_bf16 v[136:139], v[84:87], v[164:167], v[136:139]
	s_add_i32 s47, s68, s37
	v_mfma_f32_16x16x32_bf16 v[128:131], v[92:95], v[164:167], v[128:131]
	v_mfma_f32_16x16x32_bf16 v[120:123], v[84:87], v[202:205], v[120:123]
	v_mfma_f32_16x16x32_bf16 v[104:107], v[92:95], v[202:205], v[104:107]
	s_waitcnt lgkmcnt(0)
	v_mfma_f32_16x16x32_bf16 v[76:79], v[84:87], v[210:213], v[76:79]
	v_mfma_f32_16x16x32_bf16 v[72:75], v[92:95], v[210:213], v[72:75]
	s_barrier
	s_setprio 0
	ds_read_b128 v[214:217], v140
	ds_read_b128 v[218:221], v140 offset:1024
	ds_read_b128 v[222:225], v140 offset:2048
	ds_read_b128 v[226:229], v140 offset:3072
	v_lshl_add_u64 v[140:141], v[184:185], 0, s[14:15]
	s_mov_b32 m0, s47
	s_nop 0
	global_load_lds_dwordx4 v[140:141], off
	v_lshl_add_u64 v[140:141], v[194:195], 0, s[14:15]
	s_add_i32 m0, s47, 0x2000
	s_setprio 1
	global_load_lds_dwordx4 v[140:141], off
	s_barrier
	s_waitcnt lgkmcnt(1)
	v_mfma_f32_16x16x32_bf16 v[96:99], v[222:225], v[124:127], v[96:99]
	v_mfma_f32_16x16x32_bf16 v[140:143], v[214:217], v[124:127], v[156:159]
	s_waitcnt lgkmcnt(0)
	v_mfma_f32_16x16x32_bf16 v[152:155], v[226:229], v[132:135], v[96:99]
	v_mfma_f32_16x16x32_bf16 v[96:99], v[214:217], v[160:163], v[100:103]
	v_mfma_f32_16x16x32_bf16 v[156:159], v[218:221], v[132:135], v[140:143]
	v_mfma_f32_16x16x32_bf16 v[140:143], v[218:221], v[164:167], v[96:99]
	v_mfma_f32_16x16x32_bf16 v[96:99], v[222:225], v[160:163], v[108:111]
	v_mfma_f32_16x16x32_bf16 v[132:135], v[226:229], v[164:167], v[96:99]
	v_mfma_f32_16x16x32_bf16 v[96:99], v[214:217], v[198:201], v[112:115]
	s_mov_b32 m0, s62
	v_mfma_f32_16x16x32_bf16 v[124:127], v[218:221], v[202:205], v[96:99]
	v_lshl_add_u64 v[184:185], v[230:231], 0, s[14:15]
	v_mfma_f32_16x16x32_bf16 v[96:99], v[222:225], v[198:201], v[116:119]
	v_mfma_f32_16x16x32_bf16 v[68:71], v[214:217], v[206:209], v[68:71]
	v_mfma_f32_16x16x32_bf16 v[64:67], v[222:225], v[206:209], v[64:67]
	v_mfma_f32_16x16x32_bf16 v[116:119], v[226:229], v[202:205], v[96:99]
	v_mfma_f32_16x16x32_bf16 v[68:71], v[218:221], v[210:213], v[68:71]
	v_mfma_f32_16x16x32_bf16 v[64:67], v[226:229], v[210:213], v[64:67]
	s_barrier
	s_setprio 0
	ds_read_b128 v[96:99], v190 offset:49152
	ds_read_b128 v[100:103], v190 offset:50176
	ds_read_b128 v[108:111], v190 offset:51200
	ds_read_b128 v[112:115], v190 offset:52224
	ds_read_b128 v[160:163], v190 offset:53248
	ds_read_b128 v[164:167], v190 offset:54272
	ds_read_b128 v[198:201], v190 offset:55296
	ds_read_b128 v[202:205], v190 offset:56320
	global_load_lds_dwordx4 v[184:185], off
	v_lshl_add_u64 v[184:185], v[232:233], 0, s[14:15]
	s_mov_b32 m0, s63
	s_setprio 1
	global_load_lds_dwordx4 v[184:185], off
	s_waitcnt vmcnt(10)
	s_barrier
; #define PG8_STAGE(bufoff, gbase, voff) do { _Pragma("unroll") for (int _i = 0; _i < 2; ++_i) \
;         __builtin_amdgcn_global_load_lds((const unsigned*)((const char*)(gbase) + (voff)[_i]), (LAS unsigned*)(lds + (bufoff) + ldsw + _i * 8192), 16, 0, 0); } while (0)
; #define PG8_MMA(ai, bj, At, Bt) do { __builtin_amdgcn_s_setprio(1); _Pragma("unroll") for (int m = 0; m < 4; ++m) _Pragma("unroll") for (int n = 0; n < 2; ++n) _Pragma("unroll") for (int k = 0; k < 2; ++k) \
;         acc[ai][bj][m][n] = __builtin_amdgcn_mfma_f32_16x16x32_bf16(Bt[n][k], At[m][k], acc[ai][bj][m][n], 0, 0, 0); __builtin_amdgcn_s_setprio(0); } while (0)
; #define PG8_WAIT_V(n) asm volatile("s_waitcnt vmcnt(" #n ")" ::: "memory")
; #define PG8_WAIT_L(n) asm volatile("s_waitcnt lgkmcnt(" #n ")" ::: "memory")
; #define PG8_BAR __builtin_amdgcn_s_barrier()
; #define PG8_SCHED __builtin_amdgcn_sched_barrier(0)
; template <class Map, class Epi>
; DI void gemm_phase(LAS unsigned char* lds, const Map& MP, const Epi& E, const int nM, const int nN, const int K, const int lda, const int ldb) {
;     ...
;             PG8_BAR; PG8_WAIT_L(0); PG8_MMA(1, 0, At, B0); PG8_BAR; PG8_SCHED;
;             PG8_STAGE(PG8_SB(1, 1), b3 + hstepB, voffB);
;             PG8_WAIT_V(6); PG8_BAR; PG8_MMA(1, 1, At, B1); PG8_BAR;
	s_waitcnt lgkmcnt(7)
	v_mfma_f32_16x16x32_bf16 v[60:63], v[80:83], v[96:99], v[60:63]
	v_mfma_f32_16x16x32_bf16 v[48:51], v[88:91], v[96:99], v[48:51]
	s_waitcnt lgkmcnt(5)
	v_mfma_f32_16x16x32_bf16 v[40:43], v[80:83], v[108:111], v[40:43]
	v_mfma_f32_16x16x32_bf16 v[32:35], v[88:91], v[108:111], v[32:35]
	s_waitcnt lgkmcnt(3)
	v_mfma_f32_16x16x32_bf16 v[24:27], v[80:83], v[160:163], v[24:27]
	v_mfma_f32_16x16x32_bf16 v[16:19], v[88:91], v[160:163], v[16:19]
	s_waitcnt lgkmcnt(1)
	v_mfma_f32_16x16x32_bf16 v[12:15], v[80:83], v[198:201], v[12:15]
	v_mfma_f32_16x16x32_bf16 v[8:11], v[88:91], v[198:201], v[8:11]
	v_mfma_f32_16x16x32_bf16 v[60:63], v[84:87], v[100:103], v[60:63]
	s_add_u32 s28, s28, 0x80080
	s_addc_u32 s29, s29, 0
	v_mfma_f32_16x16x32_bf16 v[48:51], v[92:95], v[100:103], v[48:51]
	s_add_i32 s46, s46, s37
	v_mfma_f32_16x16x32_bf16 v[40:43], v[84:87], v[112:115], v[40:43]
	v_mfma_f32_16x16x32_bf16 v[32:35], v[92:95], v[112:115], v[32:35]
	v_mfma_f32_16x16x32_bf16 v[24:27], v[84:87], v[164:167], v[24:27]
	v_mfma_f32_16x16x32_bf16 v[16:19], v[92:95], v[164:167], v[16:19]
	s_waitcnt lgkmcnt(0)
	v_mfma_f32_16x16x32_bf16 v[12:15], v[84:87], v[202:205], v[12:15]
	v_mfma_f32_16x16x32_bf16 v[8:11], v[92:95], v[202:205], v[8:11]
	s_barrier
	s_setprio 0
	s_mov_b32 m0, s46
	s_nop 0
	global_load_lds_dwordx4 v172, s[28:29]
	s_add_i32 m0, s46, 0x2000
	s_setprio 1
	global_load_lds_dwordx4 v168, s[28:29]
	s_waitcnt vmcnt(6)
	s_barrier
	v_mfma_f32_16x16x32_bf16 v[56:59], v[214:217], v[96:99], v[56:59]
	v_mfma_f32_16x16x32_bf16 v[52:55], v[222:225], v[96:99], v[52:55]
	ds_read_b128 v[80:83], v189
	v_mfma_f32_16x16x32_bf16 v[44:47], v[214:217], v[108:111], v[44:47]
	v_mfma_f32_16x16x32_bf16 v[36:39], v[222:225], v[108:111], v[36:39]
	ds_read_b128 v[84:87], v189 offset:1024
	v_mfma_f32_16x16x32_bf16 v[28:31], v[214:217], v[160:163], v[28:31]
	v_mfma_f32_16x16x32_bf16 v[20:23], v[222:225], v[160:163], v[20:23]
	ds_read_b128 v[88:91], v189 offset:2048
	v_mfma_f32_16x16x32_bf16 v[4:7], v[214:217], v[198:201], v[4:7]
	v_mfma_f32_16x16x32_bf16 v[0:3], v[222:225], v[198:201], v[0:3]
	ds_read_b128 v[92:95], v189 offset:3072
	v_mfma_f32_16x16x32_bf16 v[56:59], v[218:221], v[100:103], v[56:59]
	s_add_i32 s3, s3, 2
	v_mfma_f32_16x16x32_bf16 v[52:55], v[226:229], v[100:103], v[52:55]
	s_add_u32 vcc_lo, vcc_lo, 0x100
	s_addc_u32 vcc_hi, vcc_hi, 0
	v_mfma_f32_16x16x32_bf16 v[44:47], v[218:221], v[112:115], v[44:47]
	s_add_u32 s42, s42, 0x100
	s_addc_u32 s43, s43, 0
	v_mfma_f32_16x16x32_bf16 v[36:39], v[226:229], v[112:115], v[36:39]
	s_cmp_gt_u32 s3, 29
	v_mfma_f32_16x16x32_bf16 v[28:31], v[218:221], v[164:167], v[28:31]
	v_mfma_f32_16x16x32_bf16 v[20:23], v[226:229], v[164:167], v[20:23]
	v_mfma_f32_16x16x32_bf16 v[4:7], v[218:221], v[202:205], v[4:7]
	v_mfma_f32_16x16x32_bf16 v[0:3], v[226:229], v[202:205], v[0:3]
	s_barrier
	s_setprio 0
	s_cbranch_scc0 .LBB1_2483
; DI float silu_mul(float g, float v) { return g * v * __builtin_amdgcn_rcpf(1.0f + __builtin_amdgcn_exp2f(-LOG2E * g)); }
;     DI void operator()(const f32x4 (&acc)[2][2][4][2], const Unit& u, int wr, int wc, int fr, int fq) const {
;         const int row0 = u.pm * BM + wr * 64 + fr, ch0 = u.pn * 128 + wc * 32 + 8 * fq;
;         f32x4 w0[2], w1[2], w2[2], bb[2];
; #pragma unroll
;         for (int n = 0; n < 2; ++n) { w0[n] = *(const f32x4*)(cw + ch0 + 4 * n); w1[n] = *(const f32x4*)(cw + DFF + ch0 + 4 * n); w2[n] = *(const f32x4*)(cw + 2 * DFF + ch0 + 4 * n); bb[n] = *(const f32x4*)(cb + ch0 + 4 * n); }
; #pragma unroll
;         for (int ai = 0; ai < 2; ++ai)
; #pragma unroll
;             for (int m = 0; m < 4; ++m) {
;                 const bool efirst = (m == 0) && (fr == 0), elast = (m == 3) && (fr == 15);
;                 const int row = row0 + ai * HALF + m * 16;
;                 f32x4 gc[2];
; #pragma unroll
;                 for (int n = 0; n < 2; ++n) {
;                     const f32x4 g = acc[ai][0][m][n];
;                     const f32x4 gprev = acc[ai][0][m > 0 ? m - 1 : 0][n], gnext = acc[ai][0][m < 3 ? m + 1 : 3][n];
;                     f32x4 up, dn;
; #pragma unroll
;                     for (int e = 0; e < 4; ++e) {
;                         const float pu = (m > 0 && fr == 15) ? gprev[e] : g[e];
;                         const float pd = (m < 3 && fr == 0) ? gnext[e] : g[e];
;                         up[e] = dpp_ror1(pu); dn[e] = dpp_ror15(pd);
;                     }
;                     if (efirst) up = (f32x4){0.f, 0.f, 0.f, 0.f};
;                     if (elast) dn = (f32x4){0.f, 0.f, 0.f, 0.f};
;                     gc[n] = w0[n] * up + w1[n] * g + w2[n] * dn + bb[n];
;                 }
;                 if (efirst || elast) {
;                     const size_t eo = (size_t)((row >> 6) * 2 + (elast ? 1 : 0)) * DFF + ch0;
; #pragma unroll
;                     for (int n = 0; n < 2; ++n) { *(f32x4*)(EP + eo + 4 * n) = gc[n]; *(f32x4*)(ER + eo + 4 * n) = acc[ai][0][m][n]; *(f32x4*)(EV + eo + 4 * n) = acc[ai][1][m][n]; }
;                 } else {
;                     const f32x4 v0 = acc[ai][1][m][0], v1 = acc[ai][1][m][1];
;                     u32x4 o;
;                     o[0] = pack2(silu_mul(gc[0][0], v0[0]), silu_mul(gc[0][1], v0[1])); o[1] = pack2(silu_mul(gc[0][2], v0[2]), silu_mul(gc[0][3], v0[3]));
	s_waitcnt lgkmcnt(0)
	s_lshl_b32 s21, s45, 7
	v_mov_b32_e32 v80, v187
	v_mov_b32_e32 v194, v186
	s_or_b32 s21, s21, s57
	v_lshl_add_u32 v184, v80, 3, s21
	v_ashrrev_i32_e32 v185, 31, v184
	v_lshlrev_b64 v[80:81], 2, v[184:185]
	v_lshl_add_u64 v[84:85], s[4:5], 0, v[80:81]
	v_lshl_add_u64 v[88:89], s[16:17], 0, v[80:81]
	v_lshl_add_u64 v[92:93], s[18:19], 0, v[80:81]
	v_lshl_add_u64 v[112:113], s[6:7], 0, v[80:81]
	global_load_dwordx4 v[80:83], v[84:85], off offset:16
	global_load_dwordx4 v[96:99], v[84:85], off
	s_nop 0
	global_load_dwordx4 v[84:87], v[88:89], off offset:16
	global_load_dwordx4 v[100:103], v[88:89], off
	s_nop 0
	global_load_dwordx4 v[88:91], v[92:93], off offset:16
	global_load_dwordx4 v[108:111], v[92:93], off
	s_nop 0
	global_load_dwordx4 v[92:95], v[112:113], off offset:16
	s_nop 0
	global_load_dwordx4 v[112:115], v[112:113], off
	v_cmp_eq_u32_e32 vcc, 0, v194
	s_nop 0
	s_nop 0
	v_cndmask_b32_e32 v161, v148, v136, vcc
	v_cndmask_b32_e32 v162, v149, v137, vcc
	v_cndmask_b32_e32 v163, v150, v138, vcc
	v_mov_b32_dpp v160, v161 row_ror:15 row_mask:0xf bank_mask:0xf
	s_nop 0
	s_nop 0
	v_mov_b32_dpp v161, v162 row_ror:15 row_mask:0xf bank_mask:0xf
	v_mov_b32_dpp v164, v150 row_ror:1 row_mask:0xf bank_mask:0xf
	v_cndmask_b32_e32 v165, v151, v139, vcc
	v_mov_b32_dpp v162, v163 row_ror:15 row_mask:0xf bank_mask:0xf
	v_mov_b32_dpp v195, v151 row_ror:1 row_mask:0xf bank_mask:0xf
	v_mov_b32_dpp v166, v148 row_ror:1 row_mask:0xf bank_mask:0xf
	v_mov_b32_dpp v167, v149 row_ror:1 row_mask:0xf bank_mask:0xf
	v_mov_b32_dpp v163, v165 row_ror:15 row_mask:0xf bank_mask:0xf
	v_cndmask_b32_e64 v165, v195, 0, vcc
	v_cndmask_b32_e64 v164, v164, 0, vcc
	v_cndmask_b32_e64 v167, v167, 0, vcc
	v_cndmask_b32_e64 v166, v166, 0, vcc
	s_nop 0
	s_nop 0
	v_mov_b32_dpp v195, v144 row_ror:1 row_mask:0xf bank_mask:0xf
	v_mov_b32_dpp v196, v145 row_ror:1 row_mask:0xf bank_mask:0xf
	v_mov_b32_dpp v198, v146 row_ror:1 row_mask:0xf bank_mask:0xf
	v_cndmask_b32_e32 v199, v147, v131, vcc
	v_mov_b32_dpp v200, v147 row_ror:1 row_mask:0xf bank_mask:0xf
	v_cndmask_b32_e64 v198, v198, 0, vcc
	v_cndmask_b32_e64 v201, v196, 0, vcc
	s_lshl_b32 s3, s44, 8
	s_add_i32 s3, s3, s49
	v_add_u32_e32 v193, s3, v194
	v_cmp_ne_u32_e64 s[46:47], 0, v194
	s_waitcnt vmcnt(0)
	v_pk_mul_f32 v[164:165], v[98:99], v[164:165]
	v_pk_mul_f32 v[166:167], v[96:97], v[166:167]
	v_pk_fma_f32 v[164:165], v[150:151], v[102:103], v[164:165]
	v_pk_fma_f32 v[166:167], v[148:149], v[100:101], v[166:167]
	v_pk_fma_f32 v[162:163], v[110:111], v[162:163], v[164:165]
	v_cndmask_b32_e32 v165, v144, v128, vcc
	v_pk_fma_f32 v[160:161], v[108:109], v[160:161], v[166:167]
	v_cndmask_b32_e32 v166, v145, v129, vcc
	v_mov_b32_dpp v164, v165 row_ror:15 row_mask:0xf bank_mask:0xf
	v_cndmask_b32_e32 v167, v146, v130, vcc
	v_pk_add_f32 v[162:163], v[114:115], v[162:163]
	v_mov_b32_dpp v165, v166 row_ror:15 row_mask:0xf bank_mask:0xf
	v_pk_add_f32 v[160:161], v[112:113], v[160:161]
	s_nop 0
	v_mov_b32_dpp v166, v167 row_ror:15 row_mask:0xf bank_mask:0xf
	s_nop 1
	v_mov_b32_dpp v167, v199 row_ror:15 row_mask:0xf bank_mask:0xf
	v_cndmask_b32_e64 v199, v200, 0, vcc
	v_cndmask_b32_e64 v200, v195, 0, vcc
	v_pk_mul_f32 v[200:201], v[80:81], v[200:201]
	v_pk_mul_f32 v[198:199], v[82:83], v[198:199]
	v_pk_fma_f32 v[200:201], v[144:145], v[84:85], v[200:201]
	v_pk_fma_f32 v[198:199], v[146:147], v[86:87], v[198:199]
	v_pk_fma_f32 v[164:165], v[88:89], v[164:165], v[200:201]
	v_pk_fma_f32 v[166:167], v[90:91], v[166:167], v[198:199]
	v_pk_add_f32 v[164:165], v[92:93], v[164:165]
	v_pk_add_f32 v[166:167], v[94:95], v[166:167]
	s_and_saveexec_b64 s[28:29], s[46:47]
	s_xor_b64 s[28:29], exec, s[28:29]
	s_cbranch_execz .LBB1_2486
	v_mul_f32_e32 v195, 0xbfb8aa3b, v160
	v_exp_f32_e32 v195, v195
	v_mul_f32_e32 v196, 0xbfb8aa3b, v161
	v_exp_f32_e32 v196, v196
	v_pk_mul_f32 v[160:161], v[156:157], v[160:161]
	v_add_f32_e32 v195, 1.0, v195
	v_rcp_f32_e32 v198, v195
	v_add_f32_e32 v196, 1.0, v196
	v_mul_f32_e32 v195, 0xbfb8aa3b, v162
	v_rcp_f32_e32 v199, v196
	v_exp_f32_e32 v195, v195
	v_mul_f32_e32 v196, 0xbfb8aa3b, v163
	v_exp_f32_e32 v196, v196
	v_pk_mul_f32 v[160:161], v[160:161], v[198:199]
	v_add_f32_e32 v195, 1.0, v195
	v_rcp_f32_e32 v200, v195
	v_add_f32_e32 v195, 1.0, v196
	v_rcp_f32_e32 v201, v195
	v_cvt_pk_bf16_f32 v160, v160, v161
	v_mul_f32_e32 v161, 0xbfb8aa3b, v164
	v_exp_f32_e32 v195, v161
	v_mul_f32_e32 v161, 0xbfb8aa3b, v165
	v_exp_f32_e32 v196, v161
	v_pk_mul_f32 v[162:163], v[158:159], v[162:163]
	v_pk_mul_f32 v[164:165], v[152:153], v[164:165]
	v_pk_mul_f32 v[162:163], v[162:163], v[200:201]
	s_nop 0
	v_cvt_pk_bf16_f32 v161, v162, v163
	v_add_f32_e32 v162, 1.0, v195
	v_mul_f32_e32 v195, 0xbfb8aa3b, v166
	v_add_f32_e32 v163, 1.0, v196
	v_exp_f32_e32 v195, v195
	v_mul_f32_e32 v196, 0xbfb8aa3b, v167
	v_exp_f32_e32 v196, v196
	v_rcp_f32_e32 v162, v162
	v_add_f32_e32 v195, 1.0, v195
	v_rcp_f32_e32 v198, v195
	v_add_f32_e32 v195, 1.0, v196
	v_rcp_f32_e32 v163, v163
	v_rcp_f32_e32 v199, v195
	v_pk_mul_f32 v[166:167], v[154:155], v[166:167]
	v_pk_mul_f32 v[162:163], v[164:165], v[162:163]
	v_pk_mul_f32 v[164:165], v[166:167], v[198:199]
	v_cvt_pk_bf16_f32 v162, v162, v163
	v_cvt_pk_bf16_f32 v163, v164, v165
	v_mov_b64_e32 v[164:165], s[52:53]
	v_mad_i64_i32 v[164:165], s[42:43], v193, s60, v[164:165]
	v_lshl_add_u64 v[164:165], v[184:185], 1, v[164:165]
	global_store_dwordx4 v[164:165], v[160:163], off

; #define PG8_STAGE(bufoff, gbase, voff) do { _Pragma("unroll") for (int _i = 0; _i < 2; ++_i) \
;         __builtin_amdgcn_global_load_lds((const unsigned*)((const char*)(gbase) + (voff)[_i]), (LAS unsigned*)(lds + (bufoff) + ldsw + _i * 8192), 16, 0, 0); } while (0)
; #define PG8_LDA(dst, b, h) do { _Pragma("unroll") for (int m = 0; m < 4; ++m) _Pragma("unroll") for (int k = 0; k < 2; ++k) dst[m][k] = *(const LAS bf16x8*)(lds + PG8_SA(b, h) + aoff + m * 2048 + k * 1024); } while (0)
; #define PG8_LDB(dst, b, h) do { _Pragma("unroll") for (int n = 0; n < 2; ++n) _Pragma("unroll") for (int k = 0; k < 2; ++k) dst[n][k] = *(const LAS bf16x8*)(lds + PG8_SB(b, h) + boff + n * 2048 + k * 1024); } while (0)
; #define PG8_MMA(ai, bj, At, Bt) do { __builtin_amdgcn_s_setprio(1); _Pragma("unroll") for (int m = 0; m < 4; ++m) _Pragma("unroll") for (int n = 0; n < 2; ++n) _Pragma("unroll") for (int k = 0; k < 2; ++k) \
;         acc[ai][bj][m][n] = __builtin_amdgcn_mfma_f32_16x16x32_bf16(Bt[n][k], At[m][k], acc[ai][bj][m][n], 0, 0, 0); __builtin_amdgcn_s_setprio(0); } while (0)
; #define PG8_WAIT_V(n) asm volatile("s_waitcnt vmcnt(" #n ")" ::: "memory")
; #define PG8_WAIT_L(n) asm volatile("s_waitcnt lgkmcnt(" #n ")" ::: "memory")
; template <class Map, class Epi>
; DI void gemm_phase(LAS unsigned char* lds, const Map& MP, const Epi& E, const int nM, const int nN, const int K, const int lda, const int ldb) {
;     ...
;             const bool last = (t == nt - 2);
;             const char* a1 = cA + (size_t)(t + 1) * kstep;
;             const char* a2 = last ? nA : cA + (size_t)(t + 2) * kstep; const char* b2 = last ? nB : cB + (size_t)(t + 2) * kstep;
;             const char* a3 = a2 + kstep; const char* b3 = b2 + kstep;
;             PG8_LDB(B0, 0, 0); PG8_SCHED; PG8_LDA(At, 0, 0); PG8_STAGE(PG8_SA(1, 1), a1 + hstepA, voffA);
;             PG8_WAIT_L(8); PG8_BAR; PG8_WAIT_L(0); PG8_MMA(0, 0, At, B0); PG8_BAR; PG8_SCHED;
;             PG8_LDB(B1, 0, 1); PG8_STAGE(PG8_SB(0, 0), b2, voffB);
;             PG8_BAR; PG8_WAIT_L(0); PG8_MMA(0, 1, At, B1); PG8_BAR;
;             PG8_LDA(At, 0, 1); PG8_STAGE(PG8_SA(0, 0), a2, voffA);
;             PG8_BAR; PG8_WAIT_L(0); PG8_MMA(1, 0, At, B0); PG8_BAR; PG8_SCHED;
;             PG8_STAGE(PG8_SB(0, 1), b2 + hstepB, voffB);
;             PG8_WAIT_V(6); PG8_BAR; PG8_MMA(1, 1, At, B1); PG8_BAR;
.LBB1_2653:
	s_add_u32 s10, s8, 0x100
	s_addc_u32 s11, s9, 0
	s_cmpk_eq_i32 s48, 0x54
	s_cselect_b32 s15, s43, s11
	s_cselect_b32 s14, s42, s10
	s_cselect_b32 s13, s45, s39
	s_cselect_b32 s12, s44, s38
	s_add_i32 m0, s22, 0xc000
	ds_read_b128 v[168:171], v150
	ds_read_b128 v[172:175], v150 offset:1024
	ds_read_b128 v[176:179], v150 offset:2048
	ds_read_b128 v[180:183], v150 offset:3072
	ds_read_b128 v[184:187], v150 offset:4096
	ds_read_b128 v[188:191], v150 offset:5120
	ds_read_b128 v[192:195], v150 offset:6144
	ds_read_b128 v[196:199], v150 offset:7168
	global_load_lds_dwordx4 v138, s[8:9]
	s_add_i32 m0, s22, 0xe000
	s_setprio 1
	global_load_lds_dwordx4 v136, s[8:9]
	s_waitcnt lgkmcnt(8)
	s_barrier
	s_waitcnt lgkmcnt(7)
	v_mfma_f32_16x16x32_bf16 v[124:127], v[152:155], v[168:171], v[124:127]
	v_mfma_f32_16x16x32_bf16 v[120:123], v[160:163], v[168:171], v[120:123]
	s_waitcnt lgkmcnt(5)
	v_mfma_f32_16x16x32_bf16 v[108:111], v[152:155], v[176:179], v[108:111]
	v_mfma_f32_16x16x32_bf16 v[104:107], v[160:163], v[176:179], v[104:107]
	s_waitcnt lgkmcnt(3)
	v_mfma_f32_16x16x32_bf16 v[92:95], v[152:155], v[184:187], v[92:95]
	v_mfma_f32_16x16x32_bf16 v[88:91], v[160:163], v[184:187], v[88:91]
	s_waitcnt lgkmcnt(1)
	v_mfma_f32_16x16x32_bf16 v[76:79], v[152:155], v[192:195], v[76:79]
	v_mfma_f32_16x16x32_bf16 v[72:75], v[160:163], v[192:195], v[72:75]
	v_mfma_f32_16x16x32_bf16 v[124:127], v[156:159], v[172:175], v[124:127]
	s_add_i32 s8, s33, s20
	v_mfma_f32_16x16x32_bf16 v[120:123], v[164:167], v[172:175], v[120:123]
	v_lshl_add_u64 v[144:145], s[12:13], 0, v[132:133]
	v_mfma_f32_16x16x32_bf16 v[108:111], v[156:159], v[180:183], v[108:111]
	v_lshl_add_u64 v[216:217], s[12:13], 0, v[128:129]
	v_mfma_f32_16x16x32_bf16 v[104:107], v[164:167], v[180:183], v[104:107]
	v_mfma_f32_16x16x32_bf16 v[92:95], v[156:159], v[188:191], v[92:95]
	v_mfma_f32_16x16x32_bf16 v[88:91], v[164:167], v[188:191], v[88:91]
	s_waitcnt lgkmcnt(0)
	v_mfma_f32_16x16x32_bf16 v[76:79], v[156:159], v[196:199], v[76:79]
	v_mfma_f32_16x16x32_bf16 v[72:75], v[164:167], v[196:199], v[72:75]
	s_barrier
	s_setprio 0
	s_mov_b32 m0, s8
	ds_read_b128 v[200:203], v151
	ds_read_b128 v[204:207], v151 offset:1024
	ds_read_b128 v[208:211], v151 offset:2048
	ds_read_b128 v[212:215], v151 offset:3072
	global_load_lds_dwordx4 v[144:145], off
	s_add_i32 m0, s8, 0x2000
	s_setprio 1
	global_load_lds_dwordx4 v[216:217], off
	s_barrier
	s_waitcnt lgkmcnt(3)
	v_mfma_f32_16x16x32_bf16 v[116:119], v[200:203], v[168:171], v[116:119]
	s_waitcnt lgkmcnt(1)
	v_mfma_f32_16x16x32_bf16 v[112:115], v[208:211], v[168:171], v[112:115]
	v_mfma_f32_16x16x32_bf16 v[100:103], v[200:203], v[176:179], v[100:103]
	v_mfma_f32_16x16x32_bf16 v[96:99], v[208:211], v[176:179], v[96:99]
	v_mfma_f32_16x16x32_bf16 v[84:87], v[200:203], v[184:187], v[84:87]
	v_mfma_f32_16x16x32_bf16 v[80:83], v[208:211], v[184:187], v[80:83]
	v_mfma_f32_16x16x32_bf16 v[68:71], v[200:203], v[192:195], v[68:71]
	v_mfma_f32_16x16x32_bf16 v[64:67], v[208:211], v[192:195], v[64:67]
	v_mfma_f32_16x16x32_bf16 v[116:119], v[204:207], v[172:175], v[116:119]
	v_lshl_add_u64 v[220:221], s[14:15], 0, v[130:131]
	s_mov_b32 m0, s22
	s_waitcnt lgkmcnt(0)
	v_mfma_f32_16x16x32_bf16 v[112:115], v[212:215], v[172:175], v[112:115]
	v_lshl_add_u64 v[218:219], s[14:15], 0, v[134:135]
	v_mfma_f32_16x16x32_bf16 v[100:103], v[204:207], v[180:183], v[100:103]
	v_mfma_f32_16x16x32_bf16 v[96:99], v[212:215], v[180:183], v[96:99]
	v_mfma_f32_16x16x32_bf16 v[84:87], v[204:207], v[188:191], v[84:87]
	v_mfma_f32_16x16x32_bf16 v[80:83], v[212:215], v[188:191], v[80:83]
	v_mfma_f32_16x16x32_bf16 v[68:71], v[204:207], v[196:199], v[68:71]
	v_mfma_f32_16x16x32_bf16 v[64:67], v[212:215], v[196:199], v[64:67]
	s_barrier
	s_setprio 0
	ds_read_b128 v[168:171], v150 offset:16384
	ds_read_b128 v[172:175], v150 offset:17408
	ds_read_b128 v[176:179], v150 offset:18432
	ds_read_b128 v[180:183], v150 offset:19456
	ds_read_b128 v[184:187], v150 offset:20480
	ds_read_b128 v[188:191], v150 offset:21504
	ds_read_b128 v[192:195], v150 offset:22528
	ds_read_b128 v[196:199], v150 offset:23552
	global_load_lds_dwordx4 v[218:219], off
	s_mov_b32 m0, s23
	s_setprio 1
	global_load_lds_dwordx4 v[220:221], off
	s_waitcnt vmcnt(10)
	s_barrier
	s_waitcnt lgkmcnt(7)
	v_mfma_f32_16x16x32_bf16 v[60:63], v[152:155], v[168:171], v[60:63]
	v_mfma_f32_16x16x32_bf16 v[56:59], v[160:163], v[168:171], v[56:59]
	s_waitcnt lgkmcnt(5)
	v_mfma_f32_16x16x32_bf16 v[44:47], v[152:155], v[176:179], v[44:47]
	v_mfma_f32_16x16x32_bf16 v[40:43], v[160:163], v[176:179], v[40:43]
	s_waitcnt lgkmcnt(3)
	v_mfma_f32_16x16x32_bf16 v[28:31], v[152:155], v[184:187], v[28:31]
	v_mfma_f32_16x16x32_bf16 v[24:27], v[160:163], v[184:187], v[24:27]
	s_waitcnt lgkmcnt(1)
	v_mfma_f32_16x16x32_bf16 v[12:15], v[152:155], v[192:195], v[12:15]
	v_mfma_f32_16x16x32_bf16 v[8:11], v[160:163], v[192:195], v[8:11]
	v_mfma_f32_16x16x32_bf16 v[60:63], v[156:159], v[172:175], v[60:63]
	s_add_u32 s8, s12, 0x160000
	s_addc_u32 s9, s13, 0
	v_mfma_f32_16x16x32_bf16 v[56:59], v[164:167], v[172:175], v[56:59]
	s_add_i32 s49, s34, s20
	v_mfma_f32_16x16x32_bf16 v[44:47], v[156:159], v[180:183], v[44:47]
	v_mfma_f32_16x16x32_bf16 v[40:43], v[164:167], v[180:183], v[40:43]
	v_mfma_f32_16x16x32_bf16 v[28:31], v[156:159], v[188:191], v[28:31]
	v_mfma_f32_16x16x32_bf16 v[24:27], v[164:167], v[188:191], v[24:27]
	s_waitcnt lgkmcnt(0)
	v_mfma_f32_16x16x32_bf16 v[12:15], v[156:159], v[196:199], v[12:15]
	v_mfma_f32_16x16x32_bf16 v[8:11], v[164:167], v[196:199], v[8:11]
	s_barrier
; #define PG8_STAGE(bufoff, gbase, voff) do { _Pragma("unroll") for (int _i = 0; _i < 2; ++_i) \
;         __builtin_amdgcn_global_load_lds((const unsigned*)((const char*)(gbase) + (voff)[_i]), (LAS unsigned*)(lds + (bufoff) + ldsw + _i * 8192), 16, 0, 0); } while (0)
; #define PG8_LDA(dst, b, h) do { _Pragma("unroll") for (int m = 0; m < 4; ++m) _Pragma("unroll") for (int k = 0; k < 2; ++k) dst[m][k] = *(const LAS bf16x8*)(lds + PG8_SA(b, h) + aoff + m * 2048 + k * 1024); } while (0)
; #define PG8_LDB(dst, b, h) do { _Pragma("unroll") for (int n = 0; n < 2; ++n) _Pragma("unroll") for (int k = 0; k < 2; ++k) dst[n][k] = *(const LAS bf16x8*)(lds + PG8_SB(b, h) + boff + n * 2048 + k * 1024); } while (0)
; #define PG8_MMA(ai, bj, At, Bt) do { __builtin_amdgcn_s_setprio(1); _Pragma("unroll") for (int m = 0; m < 4; ++m) _Pragma("unroll") for (int n = 0; n < 2; ++n) _Pragma("unroll") for (int k = 0; k < 2; ++k) \
;         acc[ai][bj][m][n] = __builtin_amdgcn_mfma_f32_16x16x32_bf16(Bt[n][k], At[m][k], acc[ai][bj][m][n], 0, 0, 0); __builtin_amdgcn_s_setprio(0); } while (0)
; #define PG8_WAIT_V(n) asm volatile("s_waitcnt vmcnt(" #n ")" ::: "memory")
; #define PG8_WAIT_L(n) asm volatile("s_waitcnt lgkmcnt(" #n ")" ::: "memory")
; #define PG8_BAR __builtin_amdgcn_s_barrier()
; #define PG8_SCHED __builtin_amdgcn_sched_barrier(0)
; template <class Map, class Epi>
; DI void gemm_phase(LAS unsigned char* lds, const Map& MP, const Epi& E, const int nM, const int nN, const int K, const int lda, const int ldb) {
;     ...
;             PG8_BAR; PG8_WAIT_L(0); PG8_MMA(1, 0, At, B0); PG8_BAR; PG8_SCHED;
;             PG8_STAGE(PG8_SB(0, 1), b2 + hstepB, voffB);
;             PG8_WAIT_V(6); PG8_BAR; PG8_MMA(1, 1, At, B1); PG8_BAR;
;             PG8_LDB(B0, 1, 0); PG8_SCHED; PG8_LDA(At, 1, 0); PG8_STAGE(PG8_SA(0, 1), a2 + hstepA, voffA);
;             PG8_WAIT_L(8); PG8_BAR; PG8_WAIT_L(0); PG8_MMA(0, 0, At, B0); PG8_BAR; PG8_SCHED;
;             PG8_LDB(B1, 1, 1); PG8_STAGE(PG8_SB(1, 0), b3, voffB);
;             PG8_BAR; PG8_WAIT_L(0); PG8_MMA(0, 1, At, B1); PG8_BAR;
;             PG8_LDA(At, 1, 1); PG8_STAGE(PG8_SA(1, 0), a3, voffA);
;             PG8_BAR; PG8_WAIT_L(0); PG8_MMA(1, 0, At, B0); PG8_BAR; PG8_SCHED;
	s_setprio 0
	s_mov_b32 m0, s49
	s_nop 0
	global_load_lds_dwordx4 v132, s[8:9]
	s_add_i32 m0, s49, 0x2000
	s_setprio 1
	global_load_lds_dwordx4 v128, s[8:9]
	s_waitcnt vmcnt(6)
	s_barrier
	v_mfma_f32_16x16x32_bf16 v[52:55], v[200:203], v[168:171], v[52:55]
	v_mfma_f32_16x16x32_bf16 v[48:51], v[208:211], v[168:171], v[48:51]
	s_add_i32 s49, 0, 0x18000
	v_add_u32_e32 v164, s49, v148
	ds_read_b128 v[152:155], v164
	v_mfma_f32_16x16x32_bf16 v[36:39], v[200:203], v[176:179], v[36:39]
	v_mfma_f32_16x16x32_bf16 v[32:35], v[208:211], v[176:179], v[32:35]
	ds_read_b128 v[156:159], v164 offset:1024
	v_mfma_f32_16x16x32_bf16 v[20:23], v[200:203], v[184:187], v[20:23]
	v_mfma_f32_16x16x32_bf16 v[16:19], v[208:211], v[184:187], v[16:19]
	ds_read_b128 v[160:163], v164 offset:2048
	v_mfma_f32_16x16x32_bf16 v[4:7], v[200:203], v[192:195], v[4:7]
	v_mfma_f32_16x16x32_bf16 v[0:3], v[208:211], v[192:195], v[0:3]
	ds_read_b128 v[164:167], v164 offset:3072
	v_mfma_f32_16x16x32_bf16 v[52:55], v[204:207], v[172:175], v[52:55]
	s_add_u32 s8, s14, 0x160000
	s_addc_u32 s9, s15, 0
	v_mfma_f32_16x16x32_bf16 v[48:51], v[212:215], v[172:175], v[48:51]
	v_mfma_f32_16x16x32_bf16 v[36:39], v[204:207], v[180:183], v[36:39]
	v_mfma_f32_16x16x32_bf16 v[32:35], v[212:215], v[180:183], v[32:35]
	v_mfma_f32_16x16x32_bf16 v[20:23], v[204:207], v[188:191], v[20:23]
	v_mfma_f32_16x16x32_bf16 v[16:19], v[212:215], v[188:191], v[16:19]
	v_mfma_f32_16x16x32_bf16 v[4:7], v[204:207], v[196:199], v[4:7]
	v_mfma_f32_16x16x32_bf16 v[0:3], v[212:215], v[196:199], v[0:3]
	s_barrier
	s_setprio 0
	s_mov_b32 m0, s24
	ds_read_b128 v[168:171], v150 offset:32768
	ds_read_b128 v[172:175], v150 offset:33792
	ds_read_b128 v[176:179], v150 offset:34816
	ds_read_b128 v[180:183], v150 offset:35840
	ds_read_b128 v[184:187], v150 offset:36864
	ds_read_b128 v[188:191], v150 offset:37888
	ds_read_b128 v[192:195], v150 offset:38912
	ds_read_b128 v[196:199], v150 offset:39936
	global_load_lds_dwordx4 v134, s[8:9]
	s_mov_b32 m0, s25
	s_setprio 1
	global_load_lds_dwordx4 v130, s[8:9]
	s_waitcnt lgkmcnt(8)
	s_barrier
	s_waitcnt lgkmcnt(7)
	v_mfma_f32_16x16x32_bf16 v[124:127], v[152:155], v[168:171], v[124:127]
	v_mfma_f32_16x16x32_bf16 v[120:123], v[160:163], v[168:171], v[120:123]
	s_waitcnt lgkmcnt(5)
	v_mfma_f32_16x16x32_bf16 v[108:111], v[152:155], v[176:179], v[108:111]
	v_mfma_f32_16x16x32_bf16 v[104:107], v[160:163], v[176:179], v[104:107]
	s_waitcnt lgkmcnt(3)
	v_mfma_f32_16x16x32_bf16 v[92:95], v[152:155], v[184:187], v[92:95]
	v_mfma_f32_16x16x32_bf16 v[88:91], v[160:163], v[184:187], v[88:91]
	s_waitcnt lgkmcnt(1)
	v_mfma_f32_16x16x32_bf16 v[76:79], v[152:155], v[192:195], v[76:79]
	v_mfma_f32_16x16x32_bf16 v[72:75], v[160:163], v[192:195], v[72:75]
	v_mfma_f32_16x16x32_bf16 v[124:127], v[156:159], v[172:175], v[124:127]
	s_add_i32 s14, 0, 0x1c000
	v_mfma_f32_16x16x32_bf16 v[120:123], v[164:167], v[172:175], v[120:123]
	s_add_i32 s8, s49, s20
	v_mfma_f32_16x16x32_bf16 v[108:111], v[156:159], v[180:183], v[108:111]
	v_add_u32_e32 v212, s14, v148
	v_mfma_f32_16x16x32_bf16 v[104:107], v[164:167], v[180:183], v[104:107]
	v_lshl_add_u64 v[144:145], v[144:145], 0, s[46:47]
	v_mfma_f32_16x16x32_bf16 v[92:95], v[156:159], v[188:191], v[92:95]
	v_mfma_f32_16x16x32_bf16 v[88:91], v[164:167], v[188:191], v[88:91]
	s_waitcnt lgkmcnt(0)
	v_mfma_f32_16x16x32_bf16 v[76:79], v[156:159], v[196:199], v[76:79]
	v_mfma_f32_16x16x32_bf16 v[72:75], v[164:167], v[196:199], v[72:75]
	s_barrier
	s_setprio 0
	s_mov_b32 m0, s8
	ds_read_b128 v[200:203], v212
	ds_read_b128 v[204:207], v212 offset:1024
	ds_read_b128 v[208:211], v212 offset:2048
	ds_read_b128 v[212:215], v212 offset:3072
	global_load_lds_dwordx4 v[144:145], off
	v_lshl_add_u64 v[144:145], v[216:217], 0, s[46:47]
	s_add_i32 m0, s8, 0x2000
	s_setprio 1
	global_load_lds_dwordx4 v[144:145], off
	s_barrier
	s_waitcnt lgkmcnt(3)
	v_mfma_f32_16x16x32_bf16 v[116:119], v[200:203], v[168:171], v[116:119]
	s_waitcnt lgkmcnt(1)
	v_mfma_f32_16x16x32_bf16 v[112:115], v[208:211], v[168:171], v[112:115]
	v_mfma_f32_16x16x32_bf16 v[100:103], v[200:203], v[176:179], v[100:103]
	v_mfma_f32_16x16x32_bf16 v[96:99], v[208:211], v[176:179], v[96:99]
	v_mfma_f32_16x16x32_bf16 v[84:87], v[200:203], v[184:187], v[84:87]
	v_mfma_f32_16x16x32_bf16 v[80:83], v[208:211], v[184:187], v[80:83]
	v_mfma_f32_16x16x32_bf16 v[68:71], v[200:203], v[192:195], v[68:71]
	v_mfma_f32_16x16x32_bf16 v[64:67], v[208:211], v[192:195], v[64:67]
	v_mfma_f32_16x16x32_bf16 v[116:119], v[204:207], v[172:175], v[116:119]
	s_mov_b32 m0, s29
	s_waitcnt lgkmcnt(0)
	v_mfma_f32_16x16x32_bf16 v[112:115], v[212:215], v[172:175], v[112:115]
	v_lshl_add_u64 v[144:145], v[218:219], 0, s[46:47]
	v_mfma_f32_16x16x32_bf16 v[100:103], v[204:207], v[180:183], v[100:103]
	v_mfma_f32_16x16x32_bf16 v[96:99], v[212:215], v[180:183], v[96:99]
	v_mfma_f32_16x16x32_bf16 v[84:87], v[204:207], v[188:191], v[84:87]
	v_mfma_f32_16x16x32_bf16 v[80:83], v[212:215], v[188:191], v[80:83]
	v_mfma_f32_16x16x32_bf16 v[68:71], v[204:207], v[196:199], v[68:71]
	v_mfma_f32_16x16x32_bf16 v[64:67], v[212:215], v[196:199], v[64:67]
	s_barrier
	s_setprio 0
	ds_read_b128 v[168:171], v150 offset:49152
	ds_read_b128 v[172:175], v150 offset:50176
	ds_read_b128 v[176:179], v150 offset:51200
	ds_read_b128 v[180:183], v150 offset:52224
	ds_read_b128 v[184:187], v150 offset:53248
	ds_read_b128 v[188:191], v150 offset:54272
	ds_read_b128 v[192:195], v150 offset:55296
	ds_read_b128 v[196:199], v150 offset:56320
	global_load_lds_dwordx4 v[144:145], off
	v_lshl_add_u64 v[144:145], v[220:221], 0, s[46:47]
	s_mov_b32 m0, s30
	s_setprio 1
	global_load_lds_dwordx4 v[144:145], off
	s_waitcnt vmcnt(10)
	s_barrier
; DI unsigned pack2(float a, float b) { f32x2 v = {a, b}; hwbf16x2 r = __builtin_convertvector(v, hwbf16x2); return __builtin_bit_cast(unsigned, r); }
; DI float bflo(unsigned w) { return __uint_as_float(w << 16); }
; DI float bfhi(unsigned w) { return __uint_as_float(w & 0xffff0000u); }
; #define PG8_WAIT_V(n) asm volatile("s_waitcnt vmcnt(" #n ")" ::: "memory")
;     DI void operator()(const f32x4 (&acc)[2][2][4][2], const Unit& u, int wr, int wc, int fr, int fq) const {
;         const int row0 = u.pm * BM + wr * 64 + fr, col0 = u.pn * BM + wc * 32 + 8 * fq;
;         f32x4 sc[2][2];
; #pragma unroll
;         for (int bj = 0; bj < 2; ++bj)
; #pragma unroll
;             for (int n = 0; n < 2; ++n) sc[bj][n] = scale ? *(const f32x4*)(scale + col0 + bj * HALF + 4 * n) : (f32x4){1.f, 1.f, 1.f, 1.f};
; #pragma unroll
;         for (int ai = 0; ai < 2; ++ai)
; #pragma unroll
;             for (int m = 0; m < 4; ++m) { const size_t ro = (size_t)(row0 + ai * HALF + m * 16) * D + col0;
; #pragma unroll
;                 for (int bj = 0; bj < 2; ++bj) {
;                     f32x4 x0, x1;
;                     if constexpr (IB) { const u32x4 w = *(const u32x4*)((const bf16_t*)Xin + ro + bj * HALF);
;                         x0 = (f32x4){bflo(w[0]), bfhi(w[0]), bflo(w[1]), bfhi(w[1])}; x1 = (f32x4){bflo(w[2]), bfhi(w[2]), bflo(w[3]), bfhi(w[3])}; }
;                     else { x0 = *(const f32x4*)((const float*)Xin + ro + bj * HALF); x1 = *(const f32x4*)((const float*)Xin + ro + bj * HALF + 4); }
;                     x0 += acc[ai][bj][m][0] * sc[bj][0]; x1 += acc[ai][bj][m][1] * sc[bj][1];
;                     if constexpr (OB) { u32x4 o; o[0] = pack2(x0[0], x0[1]); o[1] = pack2(x0[2], x0[3]); o[2] = pack2(x1[0], x1[1]); o[3] = pack2(x1[2], x1[3]);
;                         *(u32x4*)((bf16_t*)Xout + ro + bj * HALF) = o; }
;                     else { *(f32x4*)((float*)Xout + ro + bj * HALF) = x0; *(f32x4*)((float*)Xout + ro + bj * HALF + 4) = x1; } } }
; template <class Map, class Epi>
; DI void gemm_phase(LAS unsigned char* lds, const Map& MP, const Epi& E, const int nM, const int nN, const int K, const int lda, const int ldb) {
;     ...
;             PG8_BAR; PG8_WAIT_L(0); PG8_MMA(1, 0, At, B0); PG8_BAR; PG8_SCHED;
;             PG8_STAGE(PG8_SB(1, 1), b3 + hstepB, voffB);
;             PG8_WAIT_V(6); PG8_BAR; PG8_MMA(1, 1, At, B1); PG8_BAR;
	s_waitcnt lgkmcnt(7)
	v_mfma_f32_16x16x32_bf16 v[60:63], v[152:155], v[168:171], v[60:63]
	v_mfma_f32_16x16x32_bf16 v[56:59], v[160:163], v[168:171], v[56:59]
	s_waitcnt lgkmcnt(5)
	v_mfma_f32_16x16x32_bf16 v[44:47], v[152:155], v[176:179], v[44:47]
	v_mfma_f32_16x16x32_bf16 v[40:43], v[160:163], v[176:179], v[40:43]
	s_waitcnt lgkmcnt(3)
	v_mfma_f32_16x16x32_bf16 v[28:31], v[152:155], v[184:187], v[28:31]
	v_mfma_f32_16x16x32_bf16 v[24:27], v[160:163], v[184:187], v[24:27]
	s_waitcnt lgkmcnt(1)
	v_mfma_f32_16x16x32_bf16 v[12:15], v[152:155], v[192:195], v[12:15]
	v_mfma_f32_16x16x32_bf16 v[8:11], v[160:163], v[192:195], v[8:11]
	v_mfma_f32_16x16x32_bf16 v[60:63], v[156:159], v[172:175], v[60:63]
	s_add_u32 s8, s12, 0x160080
	s_addc_u32 s9, s13, 0
	v_mfma_f32_16x16x32_bf16 v[56:59], v[164:167], v[172:175], v[56:59]
	s_add_i32 s12, s14, s20
	v_mfma_f32_16x16x32_bf16 v[44:47], v[156:159], v[180:183], v[44:47]
	v_mfma_f32_16x16x32_bf16 v[40:43], v[164:167], v[180:183], v[40:43]
	v_mfma_f32_16x16x32_bf16 v[28:31], v[156:159], v[188:191], v[28:31]
	v_mfma_f32_16x16x32_bf16 v[24:27], v[164:167], v[188:191], v[24:27]
	s_waitcnt lgkmcnt(0)
	v_mfma_f32_16x16x32_bf16 v[12:15], v[156:159], v[196:199], v[12:15]
	v_mfma_f32_16x16x32_bf16 v[8:11], v[164:167], v[196:199], v[8:11]
	s_barrier
	s_setprio 0
	s_mov_b32 m0, s12
	s_nop 0
	global_load_lds_dwordx4 v132, s[8:9]
	s_add_i32 m0, s12, 0x2000
	s_setprio 1
	global_load_lds_dwordx4 v128, s[8:9]
	s_waitcnt vmcnt(6)
	s_barrier
	v_mfma_f32_16x16x32_bf16 v[52:55], v[200:203], v[168:171], v[52:55]
	v_mfma_f32_16x16x32_bf16 v[48:51], v[208:211], v[168:171], v[48:51]
	ds_read_b128 v[152:155], v149
	v_mfma_f32_16x16x32_bf16 v[36:39], v[200:203], v[176:179], v[36:39]
	v_mfma_f32_16x16x32_bf16 v[32:35], v[208:211], v[176:179], v[32:35]
	ds_read_b128 v[156:159], v149 offset:1024
	v_mfma_f32_16x16x32_bf16 v[20:23], v[200:203], v[184:187], v[20:23]
	v_mfma_f32_16x16x32_bf16 v[16:19], v[208:211], v[184:187], v[16:19]
	ds_read_b128 v[160:163], v149 offset:2048
	v_mfma_f32_16x16x32_bf16 v[4:7], v[200:203], v[192:195], v[4:7]
	v_mfma_f32_16x16x32_bf16 v[0:3], v[208:211], v[192:195], v[0:3]
	ds_read_b128 v[164:167], v149 offset:3072
	v_mfma_f32_16x16x32_bf16 v[52:55], v[204:207], v[172:175], v[52:55]
	s_add_i32 s48, s48, 2
	v_mfma_f32_16x16x32_bf16 v[48:51], v[212:215], v[172:175], v[48:51]
	s_add_u32 s38, s38, 0x100
	s_addc_u32 s39, s39, 0
	v_mfma_f32_16x16x32_bf16 v[36:39], v[204:207], v[180:183], v[36:39]
	s_cmpk_gt_u32 s48, 0x55
	v_mfma_f32_16x16x32_bf16 v[32:35], v[212:215], v[180:183], v[32:35]
	s_mov_b64 s[8:9], s[10:11]
	v_mfma_f32_16x16x32_bf16 v[20:23], v[204:207], v[188:191], v[20:23]
	v_mfma_f32_16x16x32_bf16 v[16:19], v[212:215], v[188:191], v[16:19]
	v_mfma_f32_16x16x32_bf16 v[4:7], v[204:207], v[196:199], v[4:7]
	v_mfma_f32_16x16x32_bf16 v[0:3], v[212:215], v[196:199], v[0:3]
	s_barrier
	s_setprio 0
	s_cbranch_scc0 .LBB1_2653
	s_waitcnt lgkmcnt(0)
	v_mov_b32_e32 v144, v147
	v_mov_b32_e32 v152, v146
	s_lshl_b32 s2, s2, 8
	s_lshl_b32 s8, s37, 8
	s_add_i32 s2, s2, s27
	s_or_b32 s8, s8, s28
	v_add_u32_e32 v152, s2, v152
	v_lshl_add_u32 v144, v144, 3, s8
	v_ashrrev_i32_e32 v153, 31, v152
	v_ashrrev_i32_e32 v145, 31, v144
	v_lshlrev_b64 v[152:153], 11, v[152:153]
	v_lshl_add_u64 v[144:145], v[152:153], 0, v[144:145]
	v_lshl_add_u64 v[156:157], v[144:145], 1, s[6:7]
	global_load_dwordx4 v[162:165], v[156:157], off
	global_load_dwordx4 v[166:169], v[156:157], off offset:256
	s_mov_b64 s[98:99], 0x10000
	v_lshl_add_u64 v[154:155], v[156:157], 0, s[98:99]
	global_load_dwordx4 v[170:173], v[154:155], off
	global_load_dwordx4 v[174:177], v[154:155], off offset:256
	s_mov_b64 s[98:99], 0x20000
	v_lshl_add_u64 v[154:155], v[156:157], 0, s[98:99]
	global_load_dwordx4 v[178:181], v[154:155], off
	global_load_dwordx4 v[182:185], v[154:155], off offset:256
	s_mov_b64 s[98:99], 0x30000
	v_lshl_add_u64 v[154:155], v[156:157], 0, s[98:99]
	global_load_dwordx4 v[186:189], v[154:155], off
	global_load_dwordx4 v[190:193], v[154:155], off offset:256
	s_mov_b64 s[98:99], 0x80000
	v_lshl_add_u64 v[154:155], v[156:157], 0, s[98:99]
	global_load_dwordx4 v[194:197], v[154:155], off
	global_load_dwordx4 v[198:201], v[154:155], off offset:256
	s_mov_b64 s[98:99], 0x90000
	v_lshl_add_u64 v[154:155], v[156:157], 0, s[98:99]
	global_load_dwordx4 v[202:205], v[154:155], off
	global_load_dwordx4 v[206:209], v[154:155], off offset:256
	s_mov_b64 s[98:99], 0xa0000
	v_lshl_add_u64 v[154:155], v[156:157], 0, s[98:99]
	global_load_dwordx4 v[210:213], v[154:155], off
	global_load_dwordx4 v[248:251], v[154:155], off offset:256
	s_mov_b64 s[98:99], 0xb0000
	v_lshl_add_u64 v[154:155], v[156:157], 0, s[98:99]
	global_load_dwordx4 v[252:255], v[154:155], off
	s_waitcnt vmcnt(14)
	s_nop 1
	v_mov_b32_e32 v152, v162
	v_mov_b32_e32 v153, v163
	v_mov_b32_e32 v154, v164
	v_mov_b32_e32 v155, v165
	s_mov_b64 s[8:9], 0x8000
	s_and_b64 vcc, exec, s[40:41]
	s_mov_b32 s37, s35
	s_mov_b32 s2, s36
	s_mov_b64 s[10:11], s[44:45]
	s_waitcnt lgkmcnt(0)
	v_lshlrev_b32_e32 v158, 16, v152
	v_and_b32_e32 v159, 0xffff0000, v152
	v_lshlrev_b32_e32 v152, 16, v153
	v_and_b32_e32 v153, 0xffff0000, v153
	v_lshlrev_b32_e32 v160, 16, v154
	v_and_b32_e32 v161, 0xffff0000, v154
	v_lshlrev_b32_e32 v154, 16, v155
	v_and_b32_e32 v155, 0xffff0000, v155
	v_pk_add_f32 v[126:127], v[126:127], v[152:153]
	v_pk_add_f32 v[124:125], v[124:125], v[158:159]
	v_lshl_add_u64 v[152:153], v[144:145], 2, s[4:5]
	v_pk_add_f32 v[122:123], v[122:123], v[154:155]
	v_pk_add_f32 v[120:121], v[120:121], v[160:161]
	global_store_dwordx4 v[152:153], v[124:127], off
	global_store_dwordx4 v[152:153], v[120:123], off offset:16
	s_waitcnt vmcnt(15)
; DI unsigned pack2(float a, float b) { f32x2 v = {a, b}; hwbf16x2 r = __builtin_convertvector(v, hwbf16x2); return __builtin_bit_cast(unsigned, r); }
; DI float bflo(unsigned w) { return __uint_as_float(w << 16); }
; DI float bfhi(unsigned w) { return __uint_as_float(w & 0xffff0000u); }
;     DI void operator()(const f32x4 (&acc)[2][2][4][2], const Unit& u, int wr, int wc, int fr, int fq) const {
;     ...
;         for (int ai = 0; ai < 2; ++ai)
; #pragma unroll
;             for (int m = 0; m < 4; ++m) { const size_t ro = (size_t)(row0 + ai * HALF + m * 16) * D + col0;
; #pragma unroll
;                 for (int bj = 0; bj < 2; ++bj) {
;                     f32x4 x0, x1;
;                     if constexpr (IB) { const u32x4 w = *(const u32x4*)((const bf16_t*)Xin + ro + bj * HALF);
;                         x0 = (f32x4){bflo(w[0]), bfhi(w[0]), bflo(w[1]), bfhi(w[1])}; x1 = (f32x4){bflo(w[2]), bfhi(w[2]), bflo(w[3]), bfhi(w[3])}; }
;                     else { x0 = *(const f32x4*)((const float*)Xin + ro + bj * HALF); x1 = *(const f32x4*)((const float*)Xin + ro + bj * HALF + 4); }
;                     x0 += acc[ai][bj][m][0] * sc[bj][0]; x1 += acc[ai][bj][m][1] * sc[bj][1];
;                     if constexpr (OB) { u32x4 o; o[0] = pack2(x0[0], x0[1]); o[1] = pack2(x0[2], x0[3]); o[2] = pack2(x1[0], x1[1]); o[3] = pack2(x1[2], x1[3]);
;                         *(u32x4*)((bf16_t*)Xout + ro + bj * HALF) = o; }
;                     else { *(f32x4*)((float*)Xout + ro + bj * HALF) = x0; *(f32x4*)((float*)Xout + ro + bj * HALF + 4) = x1; } } }
	s_nop 1
	v_mov_b32_e32 v120, v166
	v_mov_b32_e32 v121, v167
	v_mov_b32_e32 v122, v168
	v_mov_b32_e32 v123, v169
	s_waitcnt lgkmcnt(0)
	v_lshlrev_b32_e32 v124, 16, v120
	v_and_b32_e32 v125, 0xffff0000, v120
	v_lshlrev_b32_e32 v120, 16, v121
	v_and_b32_e32 v121, 0xffff0000, v121
	v_lshlrev_b32_e32 v126, 16, v122
	v_and_b32_e32 v127, 0xffff0000, v122
	v_lshlrev_b32_e32 v122, 16, v123
	v_and_b32_e32 v123, 0xffff0000, v123
	v_pk_add_f32 v[118:119], v[118:119], v[120:121]
	v_pk_add_f32 v[116:117], v[116:117], v[124:125]
	v_pk_add_f32 v[114:115], v[114:115], v[122:123]
	v_pk_add_f32 v[112:113], v[112:113], v[126:127]
	global_store_dwordx4 v[152:153], v[116:119], off offset:512
	global_store_dwordx4 v[152:153], v[112:115], off offset:528
	s_nop 0
	v_lshl_add_u64 v[116:117], v[144:145], 0, s[8:9]
	v_lshl_add_u64 v[118:119], v[116:117], 1, s[6:7]
	s_waitcnt vmcnt(16)
	s_nop 1
	v_mov_b32_e32 v112, v170
	v_mov_b32_e32 v113, v171
	v_mov_b32_e32 v114, v172
	v_mov_b32_e32 v115, v173
	s_mov_b64 s[8:9], 0x10000
	s_waitcnt lgkmcnt(0)
	v_lshlrev_b32_e32 v120, 16, v112
	v_and_b32_e32 v121, 0xffff0000, v112
	v_lshlrev_b32_e32 v112, 16, v113
	v_and_b32_e32 v113, 0xffff0000, v113
	v_lshlrev_b32_e32 v122, 16, v114
	v_and_b32_e32 v123, 0xffff0000, v114
	v_lshlrev_b32_e32 v114, 16, v115
	v_and_b32_e32 v115, 0xffff0000, v115
	v_pk_add_f32 v[110:111], v[110:111], v[112:113]
	v_pk_add_f32 v[108:109], v[108:109], v[120:121]
	v_lshl_add_u64 v[112:113], v[116:117], 2, s[4:5]
	v_pk_add_f32 v[106:107], v[106:107], v[114:115]
	v_pk_add_f32 v[104:105], v[104:105], v[122:123]
	global_store_dwordx4 v[112:113], v[108:111], off
	global_store_dwordx4 v[112:113], v[104:107], off offset:16
	s_waitcnt vmcnt(17)
	s_nop 1
	v_mov_b32_e32 v104, v174
	v_mov_b32_e32 v105, v175
	v_mov_b32_e32 v106, v176
	v_mov_b32_e32 v107, v177
	s_waitcnt lgkmcnt(0)
	v_lshlrev_b32_e32 v108, 16, v104
	v_and_b32_e32 v109, 0xffff0000, v104
	v_lshlrev_b32_e32 v104, 16, v105
	v_and_b32_e32 v105, 0xffff0000, v105
	v_lshlrev_b32_e32 v110, 16, v106
	v_and_b32_e32 v111, 0xffff0000, v106
	v_lshlrev_b32_e32 v106, 16, v107
	v_and_b32_e32 v107, 0xffff0000, v107
	v_pk_add_f32 v[102:103], v[102:103], v[104:105]
	v_pk_add_f32 v[100:101], v[100:101], v[108:109]
	v_pk_add_f32 v[98:99], v[98:99], v[106:107]
	v_pk_add_f32 v[96:97], v[96:97], v[110:111]
	global_store_dwordx4 v[112:113], v[100:103], off offset:512
	global_store_dwordx4 v[112:113], v[96:99], off offset:528
	s_nop 0
	v_lshl_add_u64 v[100:101], v[144:145], 0, s[8:9]
	v_lshl_add_u64 v[102:103], v[100:101], 1, s[6:7]
	s_waitcnt vmcnt(18)
	s_nop 1
	v_mov_b32_e32 v96, v178
	v_mov_b32_e32 v97, v179
	v_mov_b32_e32 v98, v180
	v_mov_b32_e32 v99, v181
	s_mov_b64 s[8:9], 0x18000
	s_waitcnt lgkmcnt(0)
	v_lshlrev_b32_e32 v104, 16, v96
	v_and_b32_e32 v105, 0xffff0000, v96
	v_lshlrev_b32_e32 v96, 16, v97
	v_and_b32_e32 v97, 0xffff0000, v97
	v_lshlrev_b32_e32 v106, 16, v98
	v_and_b32_e32 v107, 0xffff0000, v98
	v_lshlrev_b32_e32 v98, 16, v99
	v_and_b32_e32 v99, 0xffff0000, v99
	v_pk_add_f32 v[94:95], v[94:95], v[96:97]
	v_pk_add_f32 v[92:93], v[92:93], v[104:105]
	v_lshl_add_u64 v[96:97], v[100:101], 2, s[4:5]
	v_pk_add_f32 v[90:91], v[90:91], v[98:99]
	v_pk_add_f32 v[88:89], v[88:89], v[106:107]
	global_store_dwordx4 v[96:97], v[92:95], off
	global_store_dwordx4 v[96:97], v[88:91], off offset:16
	s_waitcnt vmcnt(19)
	s_nop 1
	v_mov_b32_e32 v88, v182
	v_mov_b32_e32 v89, v183
	v_mov_b32_e32 v90, v184
	v_mov_b32_e32 v91, v185
	s_waitcnt lgkmcnt(0)
	v_lshlrev_b32_e32 v92, 16, v88
	v_and_b32_e32 v93, 0xffff0000, v88
	v_lshlrev_b32_e32 v88, 16, v89
	v_and_b32_e32 v89, 0xffff0000, v89
	v_lshlrev_b32_e32 v94, 16, v90
	v_and_b32_e32 v95, 0xffff0000, v90
	v_lshlrev_b32_e32 v90, 16, v91
	v_and_b32_e32 v91, 0xffff0000, v91
	v_pk_add_f32 v[86:87], v[86:87], v[88:89]
	v_pk_add_f32 v[84:85], v[84:85], v[92:93]
	v_pk_add_f32 v[82:83], v[82:83], v[90:91]
	v_pk_add_f32 v[80:81], v[80:81], v[94:95]
	global_store_dwordx4 v[96:97], v[84:87], off offset:512
	global_store_dwordx4 v[96:97], v[80:83], off offset:528
	s_nop 0
	v_lshl_add_u64 v[84:85], v[144:145], 0, s[8:9]
	v_lshl_add_u64 v[86:87], v[84:85], 1, s[6:7]
	s_waitcnt vmcnt(20)
	s_nop 1
	v_mov_b32_e32 v80, v186
	v_mov_b32_e32 v81, v187
	v_mov_b32_e32 v82, v188
	v_mov_b32_e32 v83, v189
	s_mov_b64 s[8:9], 0x40000
	s_waitcnt lgkmcnt(0)
	v_lshlrev_b32_e32 v88, 16, v80
	v_and_b32_e32 v89, 0xffff0000, v80
	v_lshlrev_b32_e32 v80, 16, v81
	v_and_b32_e32 v81, 0xffff0000, v81
	v_lshlrev_b32_e32 v90, 16, v82
	v_and_b32_e32 v91, 0xffff0000, v82
	v_lshlrev_b32_e32 v82, 16, v83
	v_and_b32_e32 v83, 0xffff0000, v83
	v_pk_add_f32 v[78:79], v[78:79], v[80:81]
	v_pk_add_f32 v[76:77], v[76:77], v[88:89]
	v_lshl_add_u64 v[80:81], v[84:85], 2, s[4:5]
	v_pk_add_f32 v[74:75], v[74:75], v[82:83]
	v_pk_add_f32 v[72:73], v[72:73], v[90:91]
	global_store_dwordx4 v[80:81], v[76:79], off
	global_store_dwordx4 v[80:81], v[72:75], off offset:16
	s_waitcnt vmcnt(21)
	s_nop 1
	v_mov_b32_e32 v72, v190
	v_mov_b32_e32 v73, v191
	v_mov_b32_e32 v74, v192
	v_mov_b32_e32 v75, v193
	s_waitcnt lgkmcnt(0)
	v_lshlrev_b32_e32 v76, 16, v72
	v_and_b32_e32 v77, 0xffff0000, v72
	v_lshlrev_b32_e32 v72, 16, v73
	v_and_b32_e32 v73, 0xffff0000, v73
	v_lshlrev_b32_e32 v78, 16, v74
	v_and_b32_e32 v79, 0xffff0000, v74
	v_lshlrev_b32_e32 v74, 16, v75
	v_and_b32_e32 v75, 0xffff0000, v75
	v_pk_add_f32 v[70:71], v[70:71], v[72:73]
	v_pk_add_f32 v[68:69], v[68:69], v[76:77]
	v_pk_add_f32 v[66:67], v[66:67], v[74:75]
	v_pk_add_f32 v[64:65], v[64:65], v[78:79]
	global_store_dwordx4 v[80:81], v[68:71], off offset:512
	global_store_dwordx4 v[80:81], v[64:67], off offset:528
	s_nop 0
	v_lshl_add_u64 v[68:69], v[144:145], 0, s[8:9]
	v_lshl_add_u64 v[70:71], v[68:69], 1, s[6:7]
	s_waitcnt vmcnt(22)
; DI unsigned pack2(float a, float b) { f32x2 v = {a, b}; hwbf16x2 r = __builtin_convertvector(v, hwbf16x2); return __builtin_bit_cast(unsigned, r); }
; DI float bflo(unsigned w) { return __uint_as_float(w << 16); }
; DI float bfhi(unsigned w) { return __uint_as_float(w & 0xffff0000u); }
;     DI const char* a(const Unit& u) const { return (const char*)(A + (size_t)u.pm * BM * lda); }
;     DI const char* a(const Unit& u) const { return (const char*)(A + (size_t)u.pm * BM * 2048 + (u.pn >> 1) * 512); }
;     DI void operator()(const f32x4 (&acc)[2][2][4][2], const Unit& u, int wr, int wc, int fr, int fq) const {
;     ...
;         for (int ai = 0; ai < 2; ++ai)
; #pragma unroll
;             for (int m = 0; m < 4; ++m) { const size_t ro = (size_t)(row0 + ai * HALF + m * 16) * D + col0;
; #pragma unroll
;                 for (int bj = 0; bj < 2; ++bj) {
;                     f32x4 x0, x1;
;                     if constexpr (IB) { const u32x4 w = *(const u32x4*)((const bf16_t*)Xin + ro + bj * HALF);
;                         x0 = (f32x4){bflo(w[0]), bfhi(w[0]), bflo(w[1]), bfhi(w[1])}; x1 = (f32x4){bflo(w[2]), bfhi(w[2]), bflo(w[3]), bfhi(w[3])}; }
;                     else { x0 = *(const f32x4*)((const float*)Xin + ro + bj * HALF); x1 = *(const f32x4*)((const float*)Xin + ro + bj * HALF + 4); }
;                     x0 += acc[ai][bj][m][0] * sc[bj][0]; x1 += acc[ai][bj][m][1] * sc[bj][1];
;                     if constexpr (OB) { u32x4 o; o[0] = pack2(x0[0], x0[1]); o[1] = pack2(x0[2], x0[3]); o[2] = pack2(x1[0], x1[1]); o[3] = pack2(x1[2], x1[3]);
;                         *(u32x4*)((bf16_t*)Xout + ro + bj * HALF) = o; }
;                     else { *(f32x4*)((float*)Xout + ro + bj * HALF) = x0; *(f32x4*)((float*)Xout + ro + bj * HALF + 4) = x1; } } }
; template <class Map, class Epi>
; DI void gemm_phase(LAS unsigned char* lds, const Map& MP, const Epi& E, const int nM, const int nN, const int K, const int lda, const int ldb) {
;     ...
;         if (!has_next) break;
; #pragma unroll
;         for (int a = 0; a < 2; ++a)
; #pragma unroll
;             for (int b = 0; b < 2; ++b)
; #pragma unroll
;                 for (int m = 0; m < 4; ++m)
; #pragma unroll
;                     for (int n = 0; n < 2; ++n) acc[a][b][m][n] = (f32x4){0.f, 0.f, 0.f, 0.f};
;         cur = nxt; cA = nA; cB = nB; ++ui;
;     }
;     PG8_WAIT_V(0);
;     if (wr == 0) PG8_BAR;
;     PG8_BAR;
	s_nop 1
	v_mov_b32_e32 v64, v194
	v_mov_b32_e32 v65, v195
	v_mov_b32_e32 v66, v196
	v_mov_b32_e32 v67, v197
	s_mov_b64 s[8:9], 0x48000
	s_waitcnt lgkmcnt(0)
	v_lshlrev_b32_e32 v72, 16, v64
	v_and_b32_e32 v73, 0xffff0000, v64
	v_lshlrev_b32_e32 v64, 16, v65
	v_and_b32_e32 v65, 0xffff0000, v65
	v_lshlrev_b32_e32 v74, 16, v66
	v_and_b32_e32 v75, 0xffff0000, v66
	v_lshlrev_b32_e32 v66, 16, v67
	v_and_b32_e32 v67, 0xffff0000, v67
	v_pk_add_f32 v[62:63], v[62:63], v[64:65]
	v_pk_add_f32 v[60:61], v[60:61], v[72:73]
	v_lshl_add_u64 v[64:65], v[68:69], 2, s[4:5]
	v_pk_add_f32 v[58:59], v[58:59], v[66:67]
	v_pk_add_f32 v[56:57], v[56:57], v[74:75]
	global_store_dwordx4 v[64:65], v[60:63], off
	global_store_dwordx4 v[64:65], v[56:59], off offset:16
	s_waitcnt vmcnt(23)
	s_nop 1
	v_mov_b32_e32 v56, v198
	v_mov_b32_e32 v57, v199
	v_mov_b32_e32 v58, v200
	v_mov_b32_e32 v59, v201
	s_waitcnt lgkmcnt(0)
	v_lshlrev_b32_e32 v60, 16, v56
	v_and_b32_e32 v61, 0xffff0000, v56
	v_lshlrev_b32_e32 v56, 16, v57
	v_and_b32_e32 v57, 0xffff0000, v57
	v_lshlrev_b32_e32 v62, 16, v58
	v_and_b32_e32 v63, 0xffff0000, v58
	v_lshlrev_b32_e32 v58, 16, v59
	v_and_b32_e32 v59, 0xffff0000, v59
	v_pk_add_f32 v[54:55], v[54:55], v[56:57]
	v_pk_add_f32 v[52:53], v[52:53], v[60:61]
	v_pk_add_f32 v[50:51], v[50:51], v[58:59]
	v_pk_add_f32 v[48:49], v[48:49], v[62:63]
	global_store_dwordx4 v[64:65], v[52:55], off offset:512
	global_store_dwordx4 v[64:65], v[48:51], off offset:528
	s_nop 0
	v_lshl_add_u64 v[52:53], v[144:145], 0, s[8:9]
	v_lshl_add_u64 v[54:55], v[52:53], 1, s[6:7]
	s_waitcnt vmcnt(24)
	s_nop 1
	v_mov_b32_e32 v48, v202
	v_mov_b32_e32 v49, v203
	v_mov_b32_e32 v50, v204
	v_mov_b32_e32 v51, v205
	s_mov_b64 s[8:9], 0x50000
	s_waitcnt lgkmcnt(0)
	v_lshlrev_b32_e32 v56, 16, v48
	v_and_b32_e32 v57, 0xffff0000, v48
	v_lshlrev_b32_e32 v48, 16, v49
	v_and_b32_e32 v49, 0xffff0000, v49
	v_lshlrev_b32_e32 v58, 16, v50
	v_and_b32_e32 v59, 0xffff0000, v50
	v_lshlrev_b32_e32 v50, 16, v51
	v_and_b32_e32 v51, 0xffff0000, v51
	v_pk_add_f32 v[46:47], v[46:47], v[48:49]
	v_pk_add_f32 v[44:45], v[44:45], v[56:57]
	v_lshl_add_u64 v[48:49], v[52:53], 2, s[4:5]
	v_pk_add_f32 v[42:43], v[42:43], v[50:51]
	v_pk_add_f32 v[40:41], v[40:41], v[58:59]
	global_store_dwordx4 v[48:49], v[44:47], off
	global_store_dwordx4 v[48:49], v[40:43], off offset:16
	s_waitcnt vmcnt(25)
	s_nop 1
	v_mov_b32_e32 v40, v206
	v_mov_b32_e32 v41, v207
	v_mov_b32_e32 v42, v208
	v_mov_b32_e32 v43, v209
	s_waitcnt lgkmcnt(0)
	v_lshlrev_b32_e32 v44, 16, v40
	v_and_b32_e32 v45, 0xffff0000, v40
	v_lshlrev_b32_e32 v40, 16, v41
	v_and_b32_e32 v41, 0xffff0000, v41
	v_lshlrev_b32_e32 v46, 16, v42
	v_and_b32_e32 v47, 0xffff0000, v42
	v_lshlrev_b32_e32 v42, 16, v43
	v_and_b32_e32 v43, 0xffff0000, v43
	v_pk_add_f32 v[38:39], v[38:39], v[40:41]
	v_pk_add_f32 v[36:37], v[36:37], v[44:45]
	v_pk_add_f32 v[34:35], v[34:35], v[42:43]
	v_pk_add_f32 v[32:33], v[32:33], v[46:47]
	global_store_dwordx4 v[48:49], v[36:39], off offset:512
	global_store_dwordx4 v[48:49], v[32:35], off offset:528
	s_nop 0
	v_lshl_add_u64 v[36:37], v[144:145], 0, s[8:9]
	v_lshl_add_u64 v[38:39], v[36:37], 1, s[6:7]
	s_waitcnt vmcnt(26)
	s_nop 1
	v_mov_b32_e32 v32, v210
	v_mov_b32_e32 v33, v211
	v_mov_b32_e32 v34, v212
	v_mov_b32_e32 v35, v213
	s_mov_b64 s[8:9], 0x58000
	s_waitcnt lgkmcnt(0)
	v_lshlrev_b32_e32 v40, 16, v32
	v_and_b32_e32 v41, 0xffff0000, v32
	v_lshlrev_b32_e32 v32, 16, v33
	v_and_b32_e32 v33, 0xffff0000, v33
	v_lshlrev_b32_e32 v42, 16, v34
	v_and_b32_e32 v43, 0xffff0000, v34
	v_lshlrev_b32_e32 v34, 16, v35
	v_and_b32_e32 v35, 0xffff0000, v35
	v_pk_add_f32 v[30:31], v[30:31], v[32:33]
	v_pk_add_f32 v[28:29], v[28:29], v[40:41]
	v_lshl_add_u64 v[32:33], v[36:37], 2, s[4:5]
	v_pk_add_f32 v[26:27], v[26:27], v[34:35]
	v_pk_add_f32 v[24:25], v[24:25], v[42:43]
	global_store_dwordx4 v[32:33], v[28:31], off
	global_store_dwordx4 v[32:33], v[24:27], off offset:16
	s_waitcnt vmcnt(27)
	s_nop 1
	v_mov_b32_e32 v24, v248
	v_mov_b32_e32 v25, v249
	v_mov_b32_e32 v26, v250
	v_mov_b32_e32 v27, v251
	s_waitcnt lgkmcnt(0)
	v_lshlrev_b32_e32 v28, 16, v24
	v_and_b32_e32 v29, 0xffff0000, v24
	v_lshlrev_b32_e32 v24, 16, v25
	v_and_b32_e32 v25, 0xffff0000, v25
	v_lshlrev_b32_e32 v30, 16, v26
	v_and_b32_e32 v31, 0xffff0000, v26
	v_lshlrev_b32_e32 v26, 16, v27
	v_and_b32_e32 v27, 0xffff0000, v27
	v_pk_add_f32 v[22:23], v[22:23], v[24:25]
	v_pk_add_f32 v[20:21], v[20:21], v[28:29]
	v_pk_add_f32 v[18:19], v[18:19], v[26:27]
	v_pk_add_f32 v[16:17], v[16:17], v[30:31]
	global_store_dwordx4 v[32:33], v[20:23], off offset:512
	global_store_dwordx4 v[32:33], v[16:19], off offset:528
	s_nop 0
	v_lshl_add_u64 v[20:21], v[144:145], 0, s[8:9]
	v_lshl_add_u64 v[22:23], v[20:21], 1, s[6:7]
	s_waitcnt vmcnt(28)
	s_nop 1
	v_mov_b32_e32 v16, v252
	v_mov_b32_e32 v17, v253
	v_mov_b32_e32 v18, v254
	v_mov_b32_e32 v19, v255
	s_mov_b64 s[8:9], s[42:43]
	s_waitcnt lgkmcnt(0)
	v_lshlrev_b32_e32 v24, 16, v16
	v_and_b32_e32 v25, 0xffff0000, v16
	v_lshlrev_b32_e32 v16, 16, v17
	v_and_b32_e32 v17, 0xffff0000, v17
	v_lshlrev_b32_e32 v26, 16, v18
	v_and_b32_e32 v27, 0xffff0000, v18
	v_lshlrev_b32_e32 v18, 16, v19
	v_and_b32_e32 v19, 0xffff0000, v19
	v_pk_add_f32 v[14:15], v[14:15], v[16:17]
	v_pk_add_f32 v[12:13], v[12:13], v[24:25]
	v_lshl_add_u64 v[16:17], v[20:21], 2, s[4:5]
	v_pk_add_f32 v[10:11], v[10:11], v[18:19]
	v_pk_add_f32 v[8:9], v[8:9], v[26:27]
	global_store_dwordx4 v[16:17], v[12:15], off
	global_store_dwordx4 v[16:17], v[8:11], off offset:16
	global_load_dwordx4 v[8:11], v[22:23], off offset:256
	s_waitcnt vmcnt(0) lgkmcnt(0)
	v_lshlrev_b32_e32 v12, 16, v8
	v_and_b32_e32 v13, 0xffff0000, v8
	v_lshlrev_b32_e32 v8, 16, v9
	v_and_b32_e32 v9, 0xffff0000, v9
	v_lshlrev_b32_e32 v14, 16, v10
	v_and_b32_e32 v15, 0xffff0000, v10
	v_lshlrev_b32_e32 v10, 16, v11
	v_and_b32_e32 v11, 0xffff0000, v11
	v_pk_add_f32 v[6:7], v[6:7], v[8:9]
	v_pk_add_f32 v[4:5], v[4:5], v[12:13]
	v_pk_add_f32 v[2:3], v[2:3], v[10:11]
	v_pk_add_f32 v[0:1], v[0:1], v[14:15]
	global_store_dwordx4 v[16:17], v[4:7], off offset:512
	global_store_dwordx4 v[16:17], v[0:3], off offset:528
	s_cbranch_vccz .LBB1_2646
	s_waitcnt vmcnt(0)
	s_cmpk_gt_u32 s3, 0xff
	s_cbranch_scc1 .LBB1_2657
	s_barrier
